# instruction selection: 51 xor-16 cross-lane reductions use v_permlane16_swap (VALU) instead of ds_swizzle + LDS wait
# speedup vs baseline: 1.0096x; 1.0022x over previous
; __device__ __forceinline__ float xor16(float v) { return __int_as_float(__builtin_amdgcn_ds_swizzle(__float_as_int(v), 0x401F)); }
;   __device__ __forceinline__ void operator()(const f32x4 (&acc)[2][2][4][2], const g8::Unit& u, int ui, int wr, int wc, int fr, int fq) const {
;     ...
;         const int rl = 128 * ai + 64 * wr + 16 * m + fr;
;         float r = rsl[ui * 256 + rl];
;         if (gi >= 0) {
;           float ss = 0.f;
; #pragma unroll
;           for (int bj = 0; bj < 2; ++bj)
; #pragma unroll
;             for (int n = 0; n < 2; ++n)
; #pragma unroll
;               for (int j = 0; j < 4; ++j) ss += acc[ai][bj][m][n][j] * acc[ai][bj][m][n][j];
;           ss += xor16(ss);
;           ss += __shfl_xor(ss, 32);
;           r *= rsqrtf(ss * r * r * (1.f / 64.f) + EPS);
;         }
.Lg1_nopre:
	s_waitcnt vmcnt(0)
	ds_read_b32 v140, v177
	s_xor_b64 s[14:15], s[26:27], -1
	s_and_b64 vcc, exec, s[14:15]
	s_cbranch_vccnz .LBB0_212
	v_mul_f32_e32 v141, v127, v127
	v_fmac_f32_e32 v141, v126, v126
	v_fmac_f32_e32 v141, v128, v128
	v_fmac_f32_e32 v141, v129, v129
	v_fmac_f32_e32 v141, v122, v122
	v_fmac_f32_e32 v141, v123, v123
	v_fmac_f32_e32 v141, v124, v124
	v_fmac_f32_e32 v141, v125, v125
	v_fmac_f32_e32 v141, v118, v118
	v_fmac_f32_e32 v141, v119, v119
	v_pk_mul_f32 v[152:153], v[120:121], v[120:121]
	v_pk_mul_f32 v[154:155], v[114:115], v[114:115]
	v_add_f32_e32 v141, v152, v141
	v_add_f32_e32 v141, v153, v141
	v_add_f32_e32 v141, v154, v141
	v_pk_mul_f32 v[152:153], v[116:117], v[116:117]
	v_add_f32_e32 v141, v155, v141
	v_add_f32_e32 v141, v152, v141
	v_add_f32_e32 v141, v153, v141
	v_mov_b32_e32 v152, v141
	s_nop 1
	v_permlane16_swap_b32_e32 v152, v141
	v_xor_b32_e32 v153, 32, v199
	s_waitcnt lgkmcnt(0)
	v_add_f32_e32 v141, v141, v152
	v_and_b32_e32 v152, 64, v199
	v_add_u32_e32 v152, 64, v152
	v_cmp_lt_i32_e32 vcc, v153, v152
	s_nop 1
	v_cndmask_b32_e32 v152, v199, v153, vcc
	v_lshlrev_b32_e32 v152, 2, v152
	ds_bpermute_b32 v152, v152, v141
	s_waitcnt lgkmcnt(0)
	v_add_f32_e32 v141, v141, v152
	v_mul_f32_e32 v141, v140, v141
	v_mul_f32_e32 v141, v140, v141
	v_fmamk_f32 v141, v141, 0x3c800000, v144
	v_mul_f32_e32 v152, 0x4b800000, v141
	v_cmp_gt_f32_e32 vcc, s75, v141
	s_nop 1
	v_cndmask_b32_e32 v141, v141, v152, vcc
	v_rsq_f32_e32 v141, v141
	s_nop 0
	v_mul_f32_e32 v152, 0x45800000, v141
	v_cndmask_b32_e32 v141, v141, v152, vcc
	v_mul_f32_e32 v140, v140, v141

; __device__ __forceinline__ float xor16(float v) { return __int_as_float(__builtin_amdgcn_ds_swizzle(__float_as_int(v), 0x401F)); }
; __device__ __forceinline__ float sigmoidf(float x) { return 1.f / (1.f + __expf(-x)); }
;   __device__ __forceinline__ void operator()(const f32x4 (&acc)[2][2][4][2], const g8::Unit& u, int ui, int wr, int wc, int fr, int fq) const {
;     ...
;         float r = rsl[ui * 256 + rl];
;         if (gi >= 0) {
;           float ss = 0.f;
; #pragma unroll
;           for (int bj = 0; bj < 2; ++bj)
; #pragma unroll
;             for (int n = 0; n < 2; ++n)
; #pragma unroll
;               for (int j = 0; j < 4; ++j) ss += acc[ai][bj][m][n][j] * acc[ai][bj][m][n][j];
;           ss += xor16(ss);
;           ss += __shfl_xor(ss, 32);
;           r *= rsqrtf(ss * r * r * (1.f / 64.f) + EPS);
;         }
;         h16* rowp = P + (size_t)(u.pm * 256 + rl) * IWP + 64 * hs + 8 * fq;
; #pragma unroll
;         for (int bj = 0; bj < 2; ++bj) {
;           f32x4 v[2];
; #pragma unroll
;           for (int n = 0; n < 2; ++n) {
;             v[n] = acc[ai][bj][m][n] * r;
;             if (gi >= 0) {
;               const float4 g4 = *(const float4*)(qkg + gi * 64 + 32 * bj + 8 * fq + 4 * n);
;               v[n][0] *= g4.x; v[n][1] *= g4.y; v[n][2] *= g4.z; v[n][3] *= g4.w;
;             } else if (gate) {
; #pragma unroll
;               for (int j = 0; j < 4; ++j) v[n][j] = (32 * bj + 8 * fq + 4 * n + j) < 12 ? sigmoidf(v[n][j]) : 0.f;
;             }
;           }
;           *(h16x8*)(rowp + 32 * bj) = pack8(v[0], v[1]);
.LBB0_251:
	ds_read_b32 v114, v177 offset:64
	v_cndmask_b32_e64 v115, 0, 1, s[26:27]
	v_cvt_pk_f16_f32 v155, v124, v125
	v_cvt_pk_f16_f32 v154, v128, v129
	v_cvt_pk_f16_f32 v153, v118, v119
	v_cvt_pk_f16_f32 v152, v120, v121
	v_cmp_ne_u32_e64 s[14:15], 1, v115
	s_andn2_b64 vcc, exec, s[26:27]
	global_store_dwordx4 v[122:123], v[152:155], off offset:64
	s_cbranch_vccnz .LBB0_253
	v_mul_f32_e32 v115, v111, v111
	v_fmac_f32_e32 v115, v110, v110
	v_fmac_f32_e32 v115, v112, v112
	v_fmac_f32_e32 v115, v113, v113
	v_fmac_f32_e32 v115, v106, v106
	v_fmac_f32_e32 v115, v107, v107
	v_fmac_f32_e32 v115, v108, v108
	v_fmac_f32_e32 v115, v109, v109
	v_fmac_f32_e32 v115, v102, v102
	v_fmac_f32_e32 v115, v103, v103
	v_pk_mul_f32 v[116:117], v[104:105], v[104:105]
	v_pk_mul_f32 v[118:119], v[98:99], v[98:99]
	v_add_f32_e32 v115, v116, v115
	v_add_f32_e32 v115, v117, v115
	v_add_f32_e32 v115, v118, v115
	v_pk_mul_f32 v[116:117], v[100:101], v[100:101]
	v_add_f32_e32 v115, v119, v115
	v_add_f32_e32 v115, v116, v115
	v_add_f32_e32 v115, v117, v115
	v_mov_b32_e32 v116, v115
	s_nop 1
	v_permlane16_swap_b32_e32 v116, v115
	v_xor_b32_e32 v117, 32, v199
	s_waitcnt lgkmcnt(0)
	v_add_f32_e32 v115, v115, v116
	v_and_b32_e32 v116, 64, v199
	v_add_u32_e32 v116, 64, v116
	v_cmp_lt_i32_e32 vcc, v117, v116
	s_nop 1
	v_cndmask_b32_e32 v116, v199, v117, vcc
	v_lshlrev_b32_e32 v116, 2, v116
	ds_bpermute_b32 v116, v116, v115
	s_waitcnt lgkmcnt(0)
	v_add_f32_e32 v115, v115, v116
	v_mul_f32_e32 v115, v114, v115
	v_mul_f32_e32 v115, v114, v115
	v_fmamk_f32 v115, v115, 0x3c800000, v144
	v_mul_f32_e32 v116, 0x4b800000, v115
	v_cmp_gt_f32_e32 vcc, s75, v115
	s_nop 1
	v_cndmask_b32_e32 v115, v115, v116, vcc
	v_rsq_f32_e32 v115, v115
	s_nop 0
	v_mul_f32_e32 v116, 0x45800000, v115
	v_cndmask_b32_e32 v115, v115, v116, vcc
	v_mul_f32_e32 v114, v114, v115

; __device__ __forceinline__ float xor16(float v) { return __int_as_float(__builtin_amdgcn_ds_swizzle(__float_as_int(v), 0x401F)); }
; __device__ __forceinline__ float sigmoidf(float x) { return 1.f / (1.f + __expf(-x)); }
;   __device__ __forceinline__ void operator()(const f32x4 (&acc)[2][2][4][2], const g8::Unit& u, int ui, int wr, int wc, int fr, int fq) const {
;     ...
;         float r = rsl[ui * 256 + rl];
;         if (gi >= 0) {
;           float ss = 0.f;
; #pragma unroll
;           for (int bj = 0; bj < 2; ++bj)
; #pragma unroll
;             for (int n = 0; n < 2; ++n)
; #pragma unroll
;               for (int j = 0; j < 4; ++j) ss += acc[ai][bj][m][n][j] * acc[ai][bj][m][n][j];
;           ss += xor16(ss);
;           ss += __shfl_xor(ss, 32);
;           r *= rsqrtf(ss * r * r * (1.f / 64.f) + EPS);
;         }
;         h16* rowp = P + (size_t)(u.pm * 256 + rl) * IWP + 64 * hs + 8 * fq;
; #pragma unroll
;         for (int bj = 0; bj < 2; ++bj) {
;           f32x4 v[2];
; #pragma unroll
;           for (int n = 0; n < 2; ++n) {
;             v[n] = acc[ai][bj][m][n] * r;
;             if (gi >= 0) {
;               const float4 g4 = *(const float4*)(qkg + gi * 64 + 32 * bj + 8 * fq + 4 * n);
;               v[n][0] *= g4.x; v[n][1] *= g4.y; v[n][2] *= g4.z; v[n][3] *= g4.w;
;             } else if (gate) {
; #pragma unroll
;               for (int j = 0; j < 4; ++j) v[n][j] = (32 * bj + 8 * fq + 4 * n + j) < 12 ? sigmoidf(v[n][j]) : 0.f;
;             }
;           }
;           *(h16x8*)(rowp + 32 * bj) = pack8(v[0], v[1]);
.LBB0_295:
	ds_read_b32 v98, v177 offset:128
	v_cvt_pk_f16_f32 v113, v108, v109
	v_cvt_pk_f16_f32 v112, v110, v111
	v_cvt_pk_f16_f32 v111, v102, v103
	v_cvt_pk_f16_f32 v110, v104, v105
	s_and_b64 vcc, exec, s[14:15]
	global_store_dwordx4 v[106:107], v[110:113], off offset:64
	s_cbranch_vccnz .LBB0_297
	v_mul_f32_e32 v99, v95, v95
	v_fmac_f32_e32 v99, v94, v94
	v_fmac_f32_e32 v99, v96, v96
	v_fmac_f32_e32 v99, v97, v97
	v_fmac_f32_e32 v99, v90, v90
	v_fmac_f32_e32 v99, v91, v91
	v_fmac_f32_e32 v99, v92, v92
	v_fmac_f32_e32 v99, v93, v93
	v_fmac_f32_e32 v99, v86, v86
	v_fmac_f32_e32 v99, v87, v87
	v_pk_mul_f32 v[100:101], v[88:89], v[88:89]
	v_pk_mul_f32 v[102:103], v[82:83], v[82:83]
	v_add_f32_e32 v99, v100, v99
	v_add_f32_e32 v99, v101, v99
	v_add_f32_e32 v99, v102, v99
	v_pk_mul_f32 v[100:101], v[84:85], v[84:85]
	v_add_f32_e32 v99, v103, v99
	v_add_f32_e32 v99, v100, v99
	v_add_f32_e32 v99, v101, v99
	v_mov_b32_e32 v100, v99
	s_nop 1
	v_permlane16_swap_b32_e32 v100, v99
	v_xor_b32_e32 v101, 32, v199
	s_waitcnt lgkmcnt(0)
	v_add_f32_e32 v99, v99, v100
	v_and_b32_e32 v100, 64, v199
	v_add_u32_e32 v100, 64, v100
	v_cmp_lt_i32_e32 vcc, v101, v100
	s_nop 1
	v_cndmask_b32_e32 v100, v199, v101, vcc
	v_lshlrev_b32_e32 v100, 2, v100
	ds_bpermute_b32 v100, v100, v99
	s_waitcnt lgkmcnt(0)
	v_add_f32_e32 v99, v99, v100
	v_mul_f32_e32 v99, v98, v99
	v_mul_f32_e32 v99, v98, v99
	v_fmamk_f32 v99, v99, 0x3c800000, v144
	v_mul_f32_e32 v100, 0x4b800000, v99
	v_cmp_gt_f32_e32 vcc, s75, v99
	s_nop 1
	v_cndmask_b32_e32 v99, v99, v100, vcc
	v_rsq_f32_e32 v99, v99
	s_nop 0
	v_mul_f32_e32 v100, 0x45800000, v99
	v_cndmask_b32_e32 v99, v99, v100, vcc
	v_mul_f32_e32 v98, v98, v99

; __device__ __forceinline__ float xor16(float v) { return __int_as_float(__builtin_amdgcn_ds_swizzle(__float_as_int(v), 0x401F)); }
; __device__ __forceinline__ float sigmoidf(float x) { return 1.f / (1.f + __expf(-x)); }
;   __device__ __forceinline__ void operator()(const f32x4 (&acc)[2][2][4][2], const g8::Unit& u, int ui, int wr, int wc, int fr, int fq) const {
;     ...
;         float r = rsl[ui * 256 + rl];
;         if (gi >= 0) {
;           float ss = 0.f;
; #pragma unroll
;           for (int bj = 0; bj < 2; ++bj)
; #pragma unroll
;             for (int n = 0; n < 2; ++n)
; #pragma unroll
;               for (int j = 0; j < 4; ++j) ss += acc[ai][bj][m][n][j] * acc[ai][bj][m][n][j];
;           ss += xor16(ss);
;           ss += __shfl_xor(ss, 32);
;           r *= rsqrtf(ss * r * r * (1.f / 64.f) + EPS);
;         }
;         h16* rowp = P + (size_t)(u.pm * 256 + rl) * IWP + 64 * hs + 8 * fq;
; #pragma unroll
;         for (int bj = 0; bj < 2; ++bj) {
;           f32x4 v[2];
; #pragma unroll
;           for (int n = 0; n < 2; ++n) {
;             v[n] = acc[ai][bj][m][n] * r;
;             if (gi >= 0) {
;               const float4 g4 = *(const float4*)(qkg + gi * 64 + 32 * bj + 8 * fq + 4 * n);
;               v[n][0] *= g4.x; v[n][1] *= g4.y; v[n][2] *= g4.z; v[n][3] *= g4.w;
;             } else if (gate) {
; #pragma unroll
;               for (int j = 0; j < 4; ++j) v[n][j] = (32 * bj + 8 * fq + 4 * n + j) < 12 ? sigmoidf(v[n][j]) : 0.f;
;             }
;           }
;           *(h16x8*)(rowp + 32 * bj) = pack8(v[0], v[1]);
.LBB0_339:
	ds_read_b32 v82, v177 offset:192
	v_cvt_pk_f16_f32 v97, v92, v93
	v_cvt_pk_f16_f32 v96, v94, v95
	v_cvt_pk_f16_f32 v95, v86, v87
	v_cvt_pk_f16_f32 v94, v88, v89
	s_and_b64 vcc, exec, s[14:15]
	global_store_dwordx4 v[90:91], v[94:97], off offset:64
	s_cbranch_vccnz .LBB0_341
	v_mul_f32_e32 v83, v79, v79
	v_fmac_f32_e32 v83, v78, v78
	v_fmac_f32_e32 v83, v80, v80
	v_fmac_f32_e32 v83, v81, v81
	v_fmac_f32_e32 v83, v74, v74
	v_fmac_f32_e32 v83, v75, v75
	v_fmac_f32_e32 v83, v76, v76
	v_fmac_f32_e32 v83, v77, v77
	v_fmac_f32_e32 v83, v70, v70
	v_fmac_f32_e32 v83, v71, v71
	v_pk_mul_f32 v[84:85], v[72:73], v[72:73]
	v_pk_mul_f32 v[86:87], v[66:67], v[66:67]
	v_add_f32_e32 v83, v84, v83
	v_add_f32_e32 v83, v85, v83
	v_add_f32_e32 v83, v86, v83
	v_pk_mul_f32 v[84:85], v[68:69], v[68:69]
	v_add_f32_e32 v83, v87, v83
	v_add_f32_e32 v83, v84, v83
	v_add_f32_e32 v83, v85, v83
	v_mov_b32_e32 v84, v83
	s_nop 1
	v_permlane16_swap_b32_e32 v84, v83
	v_xor_b32_e32 v85, 32, v199
	s_waitcnt lgkmcnt(0)
	v_add_f32_e32 v83, v83, v84
	v_and_b32_e32 v84, 64, v199
	v_add_u32_e32 v84, 64, v84
	v_cmp_lt_i32_e32 vcc, v85, v84
	s_nop 1
	v_cndmask_b32_e32 v84, v199, v85, vcc
	v_lshlrev_b32_e32 v84, 2, v84
	ds_bpermute_b32 v84, v84, v83
	s_waitcnt lgkmcnt(0)
	v_add_f32_e32 v83, v83, v84
	v_mul_f32_e32 v83, v82, v83
	v_mul_f32_e32 v83, v82, v83
	v_fmamk_f32 v83, v83, 0x3c800000, v144
	v_mul_f32_e32 v84, 0x4b800000, v83
	v_cmp_gt_f32_e32 vcc, s75, v83
	s_nop 1
	v_cndmask_b32_e32 v83, v83, v84, vcc
	v_rsq_f32_e32 v83, v83
	s_nop 0
	v_mul_f32_e32 v84, 0x45800000, v83
	v_cndmask_b32_e32 v83, v83, v84, vcc
	v_mul_f32_e32 v82, v82, v83

; __device__ __forceinline__ float xor16(float v) { return __int_as_float(__builtin_amdgcn_ds_swizzle(__float_as_int(v), 0x401F)); }
; __device__ __forceinline__ float sigmoidf(float x) { return 1.f / (1.f + __expf(-x)); }
;   __device__ __forceinline__ void operator()(const f32x4 (&acc)[2][2][4][2], const g8::Unit& u, int ui, int wr, int wc, int fr, int fq) const {
;     ...
;         float r = rsl[ui * 256 + rl];
;         if (gi >= 0) {
;           float ss = 0.f;
; #pragma unroll
;           for (int bj = 0; bj < 2; ++bj)
; #pragma unroll
;             for (int n = 0; n < 2; ++n)
; #pragma unroll
;               for (int j = 0; j < 4; ++j) ss += acc[ai][bj][m][n][j] * acc[ai][bj][m][n][j];
;           ss += xor16(ss);
;           ss += __shfl_xor(ss, 32);
;           r *= rsqrtf(ss * r * r * (1.f / 64.f) + EPS);
;         }
;         h16* rowp = P + (size_t)(u.pm * 256 + rl) * IWP + 64 * hs + 8 * fq;
; #pragma unroll
;         for (int bj = 0; bj < 2; ++bj) {
;           f32x4 v[2];
; #pragma unroll
;           for (int n = 0; n < 2; ++n) {
;             v[n] = acc[ai][bj][m][n] * r;
;             if (gi >= 0) {
;               const float4 g4 = *(const float4*)(qkg + gi * 64 + 32 * bj + 8 * fq + 4 * n);
;               v[n][0] *= g4.x; v[n][1] *= g4.y; v[n][2] *= g4.z; v[n][3] *= g4.w;
;             } else if (gate) {
; #pragma unroll
;               for (int j = 0; j < 4; ++j) v[n][j] = (32 * bj + 8 * fq + 4 * n + j) < 12 ? sigmoidf(v[n][j]) : 0.f;
;             }
;           }
;           *(h16x8*)(rowp + 32 * bj) = pack8(v[0], v[1]);
.LBB0_383:
	ds_read_b32 v66, v177 offset:512
	v_cvt_pk_f16_f32 v81, v76, v77
	v_cvt_pk_f16_f32 v80, v78, v79
	v_cvt_pk_f16_f32 v79, v70, v71
	v_cvt_pk_f16_f32 v78, v72, v73
	s_and_b64 vcc, exec, s[14:15]
	global_store_dwordx4 v[74:75], v[78:81], off offset:64
	s_cbranch_vccnz .LBB0_385
	v_mul_f32_e32 v67, v63, v63
	v_fmac_f32_e32 v67, v62, v62
	v_fmac_f32_e32 v67, v64, v64
	v_fmac_f32_e32 v67, v65, v65
	v_fmac_f32_e32 v67, v58, v58
	v_fmac_f32_e32 v67, v59, v59
	v_fmac_f32_e32 v67, v60, v60
	v_fmac_f32_e32 v67, v61, v61
	v_fmac_f32_e32 v67, v54, v54
	v_fmac_f32_e32 v67, v55, v55
	v_pk_mul_f32 v[68:69], v[56:57], v[56:57]
	v_pk_mul_f32 v[70:71], v[50:51], v[50:51]
	v_add_f32_e32 v67, v68, v67
	v_add_f32_e32 v67, v69, v67
	v_add_f32_e32 v67, v70, v67
	v_pk_mul_f32 v[68:69], v[52:53], v[52:53]
	v_add_f32_e32 v67, v71, v67
	v_add_f32_e32 v67, v68, v67
	v_add_f32_e32 v67, v69, v67
	v_mov_b32_e32 v68, v67
	s_nop 1
	v_permlane16_swap_b32_e32 v68, v67
	v_xor_b32_e32 v69, 32, v199
	s_waitcnt lgkmcnt(0)
	v_add_f32_e32 v67, v67, v68
	v_and_b32_e32 v68, 64, v199
	v_add_u32_e32 v68, 64, v68
	v_cmp_lt_i32_e32 vcc, v69, v68
	s_nop 1
	v_cndmask_b32_e32 v68, v199, v69, vcc
	v_lshlrev_b32_e32 v68, 2, v68
	ds_bpermute_b32 v68, v68, v67
	s_waitcnt lgkmcnt(0)
	v_add_f32_e32 v67, v67, v68
	v_mul_f32_e32 v67, v66, v67
	v_mul_f32_e32 v67, v66, v67
	v_fmamk_f32 v67, v67, 0x3c800000, v144
	v_mul_f32_e32 v68, 0x4b800000, v67
	v_cmp_gt_f32_e32 vcc, s75, v67
	s_nop 1
	v_cndmask_b32_e32 v67, v67, v68, vcc
	v_rsq_f32_e32 v67, v67
	s_nop 0
	v_mul_f32_e32 v68, 0x45800000, v67
	v_cndmask_b32_e32 v67, v67, v68, vcc
	v_mul_f32_e32 v66, v66, v67

; __device__ __forceinline__ float xor16(float v) { return __int_as_float(__builtin_amdgcn_ds_swizzle(__float_as_int(v), 0x401F)); }
; __device__ __forceinline__ float sigmoidf(float x) { return 1.f / (1.f + __expf(-x)); }
;   __device__ __forceinline__ void operator()(const f32x4 (&acc)[2][2][4][2], const g8::Unit& u, int ui, int wr, int wc, int fr, int fq) const {
;     ...
;         float r = rsl[ui * 256 + rl];
;         if (gi >= 0) {
;           float ss = 0.f;
; #pragma unroll
;           for (int bj = 0; bj < 2; ++bj)
; #pragma unroll
;             for (int n = 0; n < 2; ++n)
; #pragma unroll
;               for (int j = 0; j < 4; ++j) ss += acc[ai][bj][m][n][j] * acc[ai][bj][m][n][j];
;           ss += xor16(ss);
;           ss += __shfl_xor(ss, 32);
;           r *= rsqrtf(ss * r * r * (1.f / 64.f) + EPS);
;         }
;         h16* rowp = P + (size_t)(u.pm * 256 + rl) * IWP + 64 * hs + 8 * fq;
; #pragma unroll
;         for (int bj = 0; bj < 2; ++bj) {
;           f32x4 v[2];
; #pragma unroll
;           for (int n = 0; n < 2; ++n) {
;             v[n] = acc[ai][bj][m][n] * r;
;             if (gi >= 0) {
;               const float4 g4 = *(const float4*)(qkg + gi * 64 + 32 * bj + 8 * fq + 4 * n);
;               v[n][0] *= g4.x; v[n][1] *= g4.y; v[n][2] *= g4.z; v[n][3] *= g4.w;
;             } else if (gate) {
; #pragma unroll
;               for (int j = 0; j < 4; ++j) v[n][j] = (32 * bj + 8 * fq + 4 * n + j) < 12 ? sigmoidf(v[n][j]) : 0.f;
;             }
;           }
;           *(h16x8*)(rowp + 32 * bj) = pack8(v[0], v[1]);
.LBB0_427:
	ds_read_b32 v50, v177 offset:576
	v_cvt_pk_f16_f32 v65, v60, v61
	v_cvt_pk_f16_f32 v64, v62, v63
	v_cvt_pk_f16_f32 v63, v54, v55
	v_cvt_pk_f16_f32 v62, v56, v57
	s_and_b64 vcc, exec, s[14:15]
	global_store_dwordx4 v[58:59], v[62:65], off offset:64
	s_cbranch_vccnz .LBB0_429
	v_mul_f32_e32 v51, v47, v47
	v_fmac_f32_e32 v51, v46, v46
	v_fmac_f32_e32 v51, v48, v48
	v_fmac_f32_e32 v51, v49, v49
	v_fmac_f32_e32 v51, v42, v42
	v_fmac_f32_e32 v51, v43, v43
	v_fmac_f32_e32 v51, v44, v44
	v_fmac_f32_e32 v51, v45, v45
	v_fmac_f32_e32 v51, v38, v38
	v_fmac_f32_e32 v51, v39, v39
	v_pk_mul_f32 v[52:53], v[40:41], v[40:41]
	v_pk_mul_f32 v[54:55], v[34:35], v[34:35]
	v_add_f32_e32 v51, v52, v51
	v_add_f32_e32 v51, v53, v51
	v_add_f32_e32 v51, v54, v51
	v_pk_mul_f32 v[52:53], v[36:37], v[36:37]
	v_add_f32_e32 v51, v55, v51
	v_add_f32_e32 v51, v52, v51
	v_add_f32_e32 v51, v53, v51
	v_mov_b32_e32 v52, v51
	s_nop 1
	v_permlane16_swap_b32_e32 v52, v51
	v_xor_b32_e32 v53, 32, v199
	s_waitcnt lgkmcnt(0)
	v_add_f32_e32 v51, v51, v52
	v_and_b32_e32 v52, 64, v199
	v_add_u32_e32 v52, 64, v52
	v_cmp_lt_i32_e32 vcc, v53, v52
	s_nop 1
	v_cndmask_b32_e32 v52, v199, v53, vcc
	v_lshlrev_b32_e32 v52, 2, v52
	ds_bpermute_b32 v52, v52, v51
	s_waitcnt lgkmcnt(0)
	v_add_f32_e32 v51, v51, v52
	v_mul_f32_e32 v51, v50, v51
	v_mul_f32_e32 v51, v50, v51
	v_fmamk_f32 v51, v51, 0x3c800000, v144
	v_mul_f32_e32 v52, 0x4b800000, v51
	v_cmp_gt_f32_e32 vcc, s75, v51
	s_nop 1
	v_cndmask_b32_e32 v51, v51, v52, vcc
	v_rsq_f32_e32 v51, v51
	s_nop 0
	v_mul_f32_e32 v52, 0x45800000, v51
	v_cndmask_b32_e32 v51, v51, v52, vcc
	v_mul_f32_e32 v50, v50, v51

; __device__ __forceinline__ float xor16(float v) { return __int_as_float(__builtin_amdgcn_ds_swizzle(__float_as_int(v), 0x401F)); }
; __device__ __forceinline__ float sigmoidf(float x) { return 1.f / (1.f + __expf(-x)); }
;   __device__ __forceinline__ void operator()(const f32x4 (&acc)[2][2][4][2], const g8::Unit& u, int ui, int wr, int wc, int fr, int fq) const {
;     ...
;         float r = rsl[ui * 256 + rl];
;         if (gi >= 0) {
;           float ss = 0.f;
; #pragma unroll
;           for (int bj = 0; bj < 2; ++bj)
; #pragma unroll
;             for (int n = 0; n < 2; ++n)
; #pragma unroll
;               for (int j = 0; j < 4; ++j) ss += acc[ai][bj][m][n][j] * acc[ai][bj][m][n][j];
;           ss += xor16(ss);
;           ss += __shfl_xor(ss, 32);
;           r *= rsqrtf(ss * r * r * (1.f / 64.f) + EPS);
;         }
;         h16* rowp = P + (size_t)(u.pm * 256 + rl) * IWP + 64 * hs + 8 * fq;
; #pragma unroll
;         for (int bj = 0; bj < 2; ++bj) {
;           f32x4 v[2];
; #pragma unroll
;           for (int n = 0; n < 2; ++n) {
;             v[n] = acc[ai][bj][m][n] * r;
;             if (gi >= 0) {
;               const float4 g4 = *(const float4*)(qkg + gi * 64 + 32 * bj + 8 * fq + 4 * n);
;               v[n][0] *= g4.x; v[n][1] *= g4.y; v[n][2] *= g4.z; v[n][3] *= g4.w;
;             } else if (gate) {
; #pragma unroll
;               for (int j = 0; j < 4; ++j) v[n][j] = (32 * bj + 8 * fq + 4 * n + j) < 12 ? sigmoidf(v[n][j]) : 0.f;
;             }
;           }
;           *(h16x8*)(rowp + 32 * bj) = pack8(v[0], v[1]);
.LBB0_471:
	ds_read_b32 v34, v177 offset:640
	v_cvt_pk_f16_f32 v49, v44, v45
	v_cvt_pk_f16_f32 v48, v46, v47
	v_cvt_pk_f16_f32 v47, v38, v39
	v_cvt_pk_f16_f32 v46, v40, v41
	s_and_b64 vcc, exec, s[14:15]
	global_store_dwordx4 v[42:43], v[46:49], off offset:64
	s_cbranch_vccnz .LBB0_473
	v_mul_f32_e32 v35, v31, v31
	v_fmac_f32_e32 v35, v30, v30
	v_fmac_f32_e32 v35, v32, v32
	v_fmac_f32_e32 v35, v33, v33
	v_fmac_f32_e32 v35, v26, v26
	v_fmac_f32_e32 v35, v27, v27
	v_fmac_f32_e32 v35, v28, v28
	v_fmac_f32_e32 v35, v29, v29
	v_fmac_f32_e32 v35, v22, v22
	v_fmac_f32_e32 v35, v23, v23
	v_pk_mul_f32 v[36:37], v[24:25], v[24:25]
	v_pk_mul_f32 v[38:39], v[18:19], v[18:19]
	v_add_f32_e32 v35, v36, v35
	v_add_f32_e32 v35, v37, v35
	v_add_f32_e32 v35, v38, v35
	v_pk_mul_f32 v[36:37], v[20:21], v[20:21]
	v_add_f32_e32 v35, v39, v35
	v_add_f32_e32 v35, v36, v35
	v_add_f32_e32 v35, v37, v35
	v_mov_b32_e32 v36, v35
	s_nop 1
	v_permlane16_swap_b32_e32 v36, v35
	v_xor_b32_e32 v37, 32, v199
	s_waitcnt lgkmcnt(0)
	v_add_f32_e32 v35, v35, v36
	v_and_b32_e32 v36, 64, v199
	v_add_u32_e32 v36, 64, v36
	v_cmp_lt_i32_e32 vcc, v37, v36
	s_nop 1
	v_cndmask_b32_e32 v36, v199, v37, vcc
	v_lshlrev_b32_e32 v36, 2, v36
	ds_bpermute_b32 v36, v36, v35
	s_waitcnt lgkmcnt(0)
	v_add_f32_e32 v35, v35, v36
	v_mul_f32_e32 v35, v34, v35
	v_mul_f32_e32 v35, v34, v35
	v_fmamk_f32 v35, v35, 0x3c800000, v144
	v_mul_f32_e32 v36, 0x4b800000, v35
	v_cmp_gt_f32_e32 vcc, s75, v35
	s_nop 1
	v_cndmask_b32_e32 v35, v35, v36, vcc
	v_rsq_f32_e32 v35, v35
	s_nop 0
	v_mul_f32_e32 v36, 0x45800000, v35
	v_cndmask_b32_e32 v35, v35, v36, vcc
	v_mul_f32_e32 v34, v34, v35

; __device__ __forceinline__ float xor16(float v) { return __int_as_float(__builtin_amdgcn_ds_swizzle(__float_as_int(v), 0x401F)); }
; __device__ __forceinline__ float sigmoidf(float x) { return 1.f / (1.f + __expf(-x)); }
;   __device__ __forceinline__ void operator()(const f32x4 (&acc)[2][2][4][2], const g8::Unit& u, int ui, int wr, int wc, int fr, int fq) const {
;     ...
;         float r = rsl[ui * 256 + rl];
;         if (gi >= 0) {
;           float ss = 0.f;
; #pragma unroll
;           for (int bj = 0; bj < 2; ++bj)
; #pragma unroll
;             for (int n = 0; n < 2; ++n)
; #pragma unroll
;               for (int j = 0; j < 4; ++j) ss += acc[ai][bj][m][n][j] * acc[ai][bj][m][n][j];
;           ss += xor16(ss);
;           ss += __shfl_xor(ss, 32);
;           r *= rsqrtf(ss * r * r * (1.f / 64.f) + EPS);
;         }
;         h16* rowp = P + (size_t)(u.pm * 256 + rl) * IWP + 64 * hs + 8 * fq;
; #pragma unroll
;         for (int bj = 0; bj < 2; ++bj) {
;           f32x4 v[2];
; #pragma unroll
;           for (int n = 0; n < 2; ++n) {
;             v[n] = acc[ai][bj][m][n] * r;
;             if (gi >= 0) {
;               const float4 g4 = *(const float4*)(qkg + gi * 64 + 32 * bj + 8 * fq + 4 * n);
;               v[n][0] *= g4.x; v[n][1] *= g4.y; v[n][2] *= g4.z; v[n][3] *= g4.w;
;             } else if (gate) {
; #pragma unroll
;               for (int j = 0; j < 4; ++j) v[n][j] = (32 * bj + 8 * fq + 4 * n + j) < 12 ? sigmoidf(v[n][j]) : 0.f;
;             }
;           }
;           *(h16x8*)(rowp + 32 * bj) = pack8(v[0], v[1]);
.LBB0_515:
	ds_read_b32 v18, v177 offset:704
	v_cvt_pk_f16_f32 v33, v28, v29
	v_cvt_pk_f16_f32 v32, v30, v31
	v_cvt_pk_f16_f32 v31, v22, v23
	v_cvt_pk_f16_f32 v30, v24, v25
	s_and_b64 vcc, exec, s[14:15]
	global_store_dwordx4 v[26:27], v[30:33], off offset:64
	s_cbranch_vccnz .LBB0_517
	v_mul_f32_e32 v19, v15, v15
	v_fmac_f32_e32 v19, v14, v14
	v_fmac_f32_e32 v19, v16, v16
	v_fmac_f32_e32 v19, v17, v17
	v_fmac_f32_e32 v19, v10, v10
	v_fmac_f32_e32 v19, v11, v11
	v_fmac_f32_e32 v19, v12, v12
	v_fmac_f32_e32 v19, v13, v13
	v_fmac_f32_e32 v19, v6, v6
	v_fmac_f32_e32 v19, v7, v7
	v_pk_mul_f32 v[20:21], v[8:9], v[8:9]
	v_pk_mul_f32 v[22:23], v[2:3], v[2:3]
	v_add_f32_e32 v19, v20, v19
	v_add_f32_e32 v19, v21, v19
	v_add_f32_e32 v19, v22, v19
	v_pk_mul_f32 v[20:21], v[4:5], v[4:5]
	v_add_f32_e32 v19, v23, v19
	v_add_f32_e32 v19, v20, v19
	v_add_f32_e32 v19, v21, v19
	v_mov_b32_e32 v20, v19
	s_nop 1
	v_permlane16_swap_b32_e32 v20, v19
	v_xor_b32_e32 v21, 32, v199
	s_waitcnt lgkmcnt(0)
	v_add_f32_e32 v19, v19, v20
	v_and_b32_e32 v20, 64, v199
	v_add_u32_e32 v20, 64, v20
	v_cmp_lt_i32_e32 vcc, v21, v20
	s_nop 1
	v_cndmask_b32_e32 v20, v199, v21, vcc
	v_lshlrev_b32_e32 v20, 2, v20
	ds_bpermute_b32 v20, v20, v19
	s_waitcnt lgkmcnt(0)
	v_add_f32_e32 v19, v19, v20
	v_mul_f32_e32 v19, v18, v19
	v_mul_f32_e32 v19, v18, v19
	v_fmamk_f32 v19, v19, 0x3c800000, v144
	v_mul_f32_e32 v20, 0x4b800000, v19
	v_cmp_gt_f32_e32 vcc, s75, v19
	s_nop 1
	v_cndmask_b32_e32 v19, v19, v20, vcc
	v_rsq_f32_e32 v19, v19
	s_nop 0
	v_mul_f32_e32 v20, 0x45800000, v19
	v_cndmask_b32_e32 v19, v19, v20, vcc
	v_mul_f32_e32 v18, v18, v19

; template <int MODE, int TM> ...
;     ...
;     float mx = -1e30f;
; #pragma unroll
;     for (int t = 0; t < 2; ++t) {
;       if (!(TM & (1 << t))) continue;
;       float mt = -1e30f;
; #pragma unroll
;       for (int kt = 0; kt < 4; ++kt)
; #pragma unroll
;         for (int j = 0; j < 4; ++j) mt = fmaxf(mt, S[t][kt][j]);
;       mx = fmaxf(mx, mt * sclc[t] + addc[t]);
;     }
;     mx = max4q(mx);
;     const float mn = fmaxf(st.m, mx);
;     const float corr = __builtin_amdgcn_exp2f(st.m - mn);
;     st.m = mn;
;     const float mm = fmaxf(mn, -1e20f);
;     float ls = 0.f;
; #pragma unroll
;     for (int t = 0; t < 2; ++t) {
;       if (!(TM & (1 << t))) continue;
;       const float am = addc[t] - mm;
; #pragma unroll
;       for (int kt = 0; kt < 4; ++kt) {
;         const f32x4 e = S[t][kt] * sclc[t] + am;
; #pragma unroll
;         for (int j = 0; j < 4; ++j) {
;           float pv = __builtin_amdgcn_exp2f(e[j]);
;           S[t][kt][j] = pv;
;           ls += pv;
;         }
;       }
;     }
;     st.l = st.l * corr + ls;
.LBB0_765:
	s_waitcnt lgkmcnt(0)
	v_max3_f32 v0, v28, s67, v29
	v_max3_f32 v3, v60, s67, v61
	v_max3_f32 v0, v0, v30, v31
	v_max3_f32 v3, v3, v62, v63
	v_max3_f32 v0, v0, v48, v49
	v_max3_f32 v3, v3, v64, v65
	v_max3_f32 v0, v0, v50, v51
	v_max3_f32 v3, v3, v66, v67
	v_max3_f32 v0, v0, v52, v53
	v_max3_f32 v3, v3, v68, v69
	v_max3_f32 v0, v0, v54, v55
	v_max3_f32 v3, v3, v70, v71
	v_max3_f32 v0, v0, v56, v57
	v_max3_f32 v3, v3, v72, v73
	v_max3_f32 v0, v0, v58, v59
	v_max3_f32 v3, v3, v74, v75
	v_fma_f32 v0, s3, v0, v78
	v_fma_f32 v3, s2, v3, v79
	v_max3_f32 v0, v0, s67, v3
	v_mov_b32_e32 v3, v0
	s_nop 1
	v_permlane16_swap_b32_e32 v3, v0
	s_waitcnt lgkmcnt(0)
	v_max_f32_e32 v3, v3, v3
	v_max_f32_e32 v0, v0, v3
	v_mov_b32_e32 v3, v0
	s_nop 1
	v_permlane32_swap_b32_e32 v0, v3
	v_max3_f32 v125, v77, v0, v3
	v_max_f32_e32 v0, 0xe0ad78ec, v125
	v_sub_f32_e32 v3, v78, v0
	v_fma_f32 v28, s3, v28, v3
	v_exp_f32_e32 v28, v28
	v_fma_f32 v29, s3, v29, v3
	v_exp_f32_e32 v29, v29
	v_fma_f32 v30, s3, v30, v3
	v_exp_f32_e32 v30, v30
	v_fma_f32 v31, s3, v31, v3
	v_exp_f32_e32 v31, v31
	v_add_f32_e32 v28, 0, v28
	v_add_f32_e32 v28, v29, v28
	v_fma_f32 v29, s3, v48, v3
	v_add_f32_e32 v28, v30, v28
	v_exp_f32_e32 v29, v29
	v_fma_f32 v30, s3, v49, v3
	v_add_f32_e32 v28, v31, v28
	v_exp_f32_e32 v30, v30
	v_fma_f32 v31, s3, v50, v3
	v_exp_f32_e32 v31, v31
	v_fma_f32 v32, s3, v51, v3
	v_exp_f32_e32 v32, v32
	v_add_f32_e32 v28, v29, v28
	v_fma_f32 v29, s3, v52, v3
	v_add_f32_e32 v28, v30, v28
	v_exp_f32_e32 v29, v29
	v_fma_f32 v30, s3, v53, v3
	v_add_f32_e32 v28, v31, v28
	v_exp_f32_e32 v30, v30
	v_fma_f32 v31, s3, v54, v3
	v_exp_f32_e32 v31, v31
	v_add_f32_e32 v28, v32, v28
	v_fma_f32 v32, s3, v55, v3
	v_exp_f32_e32 v32, v32
	v_add_f32_e32 v28, v29, v28
	v_fma_f32 v29, s3, v56, v3
	v_add_f32_e32 v28, v30, v28
	v_exp_f32_e32 v29, v29
	v_fma_f32 v30, s3, v57, v3
	v_add_f32_e32 v28, v31, v28
	v_exp_f32_e32 v30, v30
	v_fma_f32 v31, s3, v58, v3
	v_exp_f32_e32 v31, v31
	v_fmac_f32_e32 v3, s3, v59
	v_add_f32_e32 v28, v32, v28
	v_exp_f32_e32 v3, v3
	v_add_f32_e32 v28, v29, v28
	v_add_f32_e32 v28, v30, v28
	v_add_f32_e32 v28, v31, v28
	v_add_f32_e32 v3, v3, v28
	v_sub_f32_e32 v28, v79, v0
	v_fma_f32 v0, s2, v60, v28
	v_exp_f32_e32 v0, v0
	v_fma_f32 v29, s2, v61, v28
	v_exp_f32_e32 v29, v29
	v_fma_f32 v30, s2, v62, v28
	v_exp_f32_e32 v30, v30
	v_fma_f32 v31, s2, v63, v28
	v_exp_f32_e32 v31, v31
	v_add_f32_e32 v0, v0, v3
	v_fma_f32 v3, s2, v64, v28
	v_add_f32_e32 v0, v29, v0
	v_exp_f32_e32 v3, v3
	v_fma_f32 v29, s2, v65, v28
	v_add_f32_e32 v0, v30, v0
	v_exp_f32_e32 v29, v29
	v_fma_f32 v30, s2, v66, v28
	v_exp_f32_e32 v30, v30
	v_add_f32_e32 v0, v31, v0
	v_fma_f32 v31, s2, v67, v28
	v_exp_f32_e32 v31, v31
	v_add_f32_e32 v0, v3, v0
	v_fma_f32 v3, s2, v68, v28
	v_add_f32_e32 v0, v29, v0
	v_exp_f32_e32 v3, v3
	v_fma_f32 v29, s2, v69, v28
	v_add_f32_e32 v0, v30, v0
	v_exp_f32_e32 v29, v29
	v_fma_f32 v30, s2, v70, v28
	v_exp_f32_e32 v30, v30
	v_add_f32_e32 v0, v31, v0
	v_fma_f32 v31, s2, v71, v28
	v_exp_f32_e32 v31, v31
	v_add_f32_e32 v0, v3, v0
	v_fma_f32 v3, s2, v72, v28
	v_add_f32_e32 v0, v29, v0
	v_exp_f32_e32 v3, v3
	v_fma_f32 v29, s2, v73, v28
	v_add_f32_e32 v0, v30, v0
	v_exp_f32_e32 v30, v29
	v_fma_f32 v29, s2, v74, v28
	v_exp_f32_e32 v29, v29
	v_add_f32_e32 v0, v31, v0
	v_add_f32_e32 v0, v3, v0
	v_add_f32_e32 v31, v30, v0
	v_mul_f32_e32 v30, s2, v75
	v_pk_add_f32 v[36:37], v[28:29], v[30:31]

; template <int MODE, int TM> ...
;     ...
;     float mx = -1e30f;
; #pragma unroll
;     for (int t = 0; t < 2; ++t) {
;       if (!(TM & (1 << t))) continue;
;       float mt = -1e30f;
; #pragma unroll
;       for (int kt = 0; kt < 4; ++kt)
; #pragma unroll
;         for (int j = 0; j < 4; ++j) mt = fmaxf(mt, S[t][kt][j]);
;       mx = fmaxf(mx, mt * sclc[t] + addc[t]);
;     }
;     mx = max4q(mx);
;     const float mn = fmaxf(st.m, mx);
;     const float corr = __builtin_amdgcn_exp2f(st.m - mn);
;     st.m = mn;
;     const float mm = fmaxf(mn, -1e20f);
;     float ls = 0.f;
; #pragma unroll
;     for (int t = 0; t < 2; ++t) {
;       if (!(TM & (1 << t))) continue;
;       const float am = addc[t] - mm;
; #pragma unroll
;       for (int kt = 0; kt < 4; ++kt) {
;         const f32x4 e = S[t][kt] * sclc[t] + am;
; #pragma unroll
;         for (int j = 0; j < 4; ++j) {
;           float pv = __builtin_amdgcn_exp2f(e[j]);
;           S[t][kt][j] = pv;
;           ls += pv;
;         }
;       }
;     }
;     st.l = st.l * corr + ls;
.LBB0_813:
	v_max3_f32 v52, v48, s67, v49
	v_max3_f32 v52, v52, v50, v51
	v_max3_f32 v52, v52, v44, v45
	v_max3_f32 v52, v52, v46, v47
	v_max3_f32 v52, v52, v40, v41
	v_max3_f32 v52, v52, v42, v43
	v_max3_f32 v52, v52, v36, v37
	v_max3_f32 v52, v52, v38, v39
	s_waitcnt lgkmcnt(0)
	v_fma_f32 v52, s50, v52, v0
	v_max_f32_e32 v52, 0xf149f2ca, v52
	v_mov_b32_e32 v53, v52
	s_nop 1
	v_permlane16_swap_b32_e32 v53, v52
	s_waitcnt lgkmcnt(0)
	v_max_f32_e32 v53, v53, v53
	v_max_f32_e32 v52, v52, v53
	v_mov_b32_e32 v53, v52
	s_nop 1
	v_permlane32_swap_b32_e32 v52, v53
	v_max3_f32 v77, v125, v52, v53
	v_max_f32_e32 v52, 0xe0ad78ec, v77
	v_sub_f32_e32 v52, v0, v52
	v_fma_f32 v0, s50, v48, v52
	v_fma_f32 v48, s50, v49, v52
	v_exp_f32_e32 v0, v0
	v_fma_f32 v49, s50, v50, v52
	v_exp_f32_e32 v48, v48
	v_fma_f32 v50, s50, v51, v52
	v_exp_f32_e32 v49, v49
	v_exp_f32_e32 v50, v50
	v_fma_f32 v44, s50, v44, v52
	v_add_f32_e32 v0, 0, v0
	v_exp_f32_e32 v44, v44
	v_fma_f32 v45, s50, v45, v52
	v_add_f32_e32 v0, v48, v0
	v_exp_f32_e32 v45, v45
	v_fma_f32 v46, s50, v46, v52
	v_add_f32_e32 v0, v49, v0
	v_exp_f32_e32 v46, v46
	v_fma_f32 v47, s50, v47, v52
	v_add_f32_e32 v0, v50, v0
	v_exp_f32_e32 v47, v47
	v_fma_f32 v40, s50, v40, v52
	v_add_f32_e32 v0, v44, v0
	v_exp_f32_e32 v40, v40
	v_fma_f32 v41, s50, v41, v52
	v_add_f32_e32 v0, v45, v0
	v_exp_f32_e32 v41, v41
	v_fma_f32 v42, s50, v42, v52
	v_add_f32_e32 v0, v46, v0
	v_exp_f32_e32 v42, v42
	v_fma_f32 v43, s50, v43, v52
	v_add_f32_e32 v0, v47, v0
	v_exp_f32_e32 v43, v43
	v_fma_f32 v36, s50, v36, v52
	v_add_f32_e32 v0, v40, v0
	v_exp_f32_e32 v36, v36
	v_fma_f32 v37, s50, v37, v52
	v_add_f32_e32 v0, v41, v0
	v_exp_f32_e32 v37, v37
	v_fma_f32 v38, s50, v38, v52
	v_add_f32_e32 v0, v42, v0
	v_exp_f32_e32 v53, v38
	v_add_f32_e32 v0, v43, v0
	v_add_f32_e32 v0, v36, v0
	v_add_f32_e32 v37, v37, v0
	v_mul_f32_e32 v36, s50, v39
	v_pk_add_f32 v[36:37], v[52:53], v[36:37]
	s_mov_b64 s[50:51], 0

; template <int MODE, int TM> ...
;     ...
;     float mx = -1e30f;
; #pragma unroll
;     for (int t = 0; t < 2; ++t) {
;       if (!(TM & (1 << t))) continue;
;       float mt = -1e30f;
; #pragma unroll
;       for (int kt = 0; kt < 4; ++kt)
; #pragma unroll
;         for (int j = 0; j < 4; ++j) mt = fmaxf(mt, S[t][kt][j]);
;       mx = fmaxf(mx, mt * sclc[t] + addc[t]);
;     }
;     mx = max4q(mx);
;     const float mn = fmaxf(st.m, mx);
;     const float corr = __builtin_amdgcn_exp2f(st.m - mn);
;     st.m = mn;
;     const float mm = fmaxf(mn, -1e20f);
;     float ls = 0.f;
; #pragma unroll
;     for (int t = 0; t < 2; ++t) {
;       if (!(TM & (1 << t))) continue;
;       const float am = addc[t] - mm;
; #pragma unroll
;       for (int kt = 0; kt < 4; ++kt) {
;         const f32x4 e = S[t][kt] * sclc[t] + am;
; #pragma unroll
;         for (int j = 0; j < 4; ++j) {
;           float pv = __builtin_amdgcn_exp2f(e[j]);
;           S[t][kt][j] = pv;
;           ls += pv;
;         }
;       }
;     }
;     st.l = st.l * corr + ls;
.LBB0_887:
	s_waitcnt lgkmcnt(0)
	v_max3_f32 v0, v40, s67, v41
	v_max3_f32 v44, v60, s67, v61
	v_max3_f32 v0, v0, v42, v43
	v_max3_f32 v44, v44, v62, v63
	v_max3_f32 v0, v0, v36, v37
	v_max3_f32 v44, v44, v64, v65
	v_max3_f32 v0, v0, v38, v39
	v_max3_f32 v44, v44, v66, v67
	v_max3_f32 v0, v0, v32, v33
	v_max3_f32 v44, v44, v68, v69
	v_max3_f32 v0, v0, v34, v35
	v_max3_f32 v44, v44, v70, v71
	v_max3_f32 v0, v0, v28, v29
	v_max3_f32 v44, v44, v72, v73
	v_max3_f32 v0, v0, v30, v31
	v_max3_f32 v44, v44, v74, v75
	v_fma_f32 v0, s50, v0, v78
	v_fma_f32 v44, s3, v44, v79
	v_max3_f32 v0, v0, s67, v44
	v_mov_b32_e32 v44, v0
	s_nop 1
	v_permlane16_swap_b32_e32 v44, v0
	s_waitcnt lgkmcnt(0)
	v_max_f32_e32 v44, v44, v44
	v_max_f32_e32 v0, v0, v44
	v_mov_b32_e32 v44, v0
	s_nop 1
	v_permlane32_swap_b32_e32 v0, v44
	v_max3_f32 v77, v125, v0, v44
	v_max_f32_e32 v0, 0xe0ad78ec, v77
	v_sub_f32_e32 v44, v78, v0
	v_fma_f32 v40, s50, v40, v44
	v_exp_f32_e32 v40, v40
	v_fma_f32 v41, s50, v41, v44
	v_exp_f32_e32 v41, v41
	v_fma_f32 v42, s50, v42, v44
	v_exp_f32_e32 v42, v42
	v_fma_f32 v43, s50, v43, v44
	v_exp_f32_e32 v43, v43
	v_fma_f32 v36, s50, v36, v44
	v_add_f32_e32 v40, 0, v40
	v_exp_f32_e32 v36, v36
	v_fma_f32 v37, s50, v37, v44
	v_add_f32_e32 v40, v41, v40
	v_exp_f32_e32 v37, v37
	v_fma_f32 v38, s50, v38, v44
	v_add_f32_e32 v40, v42, v40
	v_exp_f32_e32 v38, v38
	v_fma_f32 v39, s50, v39, v44
	v_add_f32_e32 v40, v43, v40
	v_exp_f32_e32 v39, v39
	v_fma_f32 v32, s50, v32, v44
	v_add_f32_e32 v36, v36, v40
	v_exp_f32_e32 v32, v32
	v_fma_f32 v33, s50, v33, v44
	v_add_f32_e32 v36, v37, v36
	v_exp_f32_e32 v33, v33
	v_fma_f32 v34, s50, v34, v44
	v_add_f32_e32 v36, v38, v36
	v_exp_f32_e32 v34, v34
	v_fma_f32 v35, s50, v35, v44
	v_add_f32_e32 v36, v39, v36
	v_exp_f32_e32 v35, v35
	v_fma_f32 v28, s50, v28, v44
	v_add_f32_e32 v32, v32, v36
	v_exp_f32_e32 v28, v28
	v_fma_f32 v29, s50, v29, v44
	v_add_f32_e32 v32, v33, v32
	v_exp_f32_e32 v29, v29
	v_fma_f32 v30, s50, v30, v44
	v_add_f32_e32 v32, v34, v32
	v_exp_f32_e32 v30, v30
	v_fmac_f32_e32 v44, s50, v31
	v_add_f32_e32 v32, v35, v32
	v_exp_f32_e32 v31, v44
	v_add_f32_e32 v28, v28, v32
	v_add_f32_e32 v28, v29, v28
	v_add_f32_e32 v28, v30, v28
	v_add_f32_e32 v29, v31, v28
	v_sub_f32_e32 v28, v79, v0
	v_fma_f32 v0, s3, v60, v28
	v_exp_f32_e32 v0, v0
	v_fma_f32 v30, s3, v61, v28
	v_exp_f32_e32 v30, v30
	v_fma_f32 v31, s3, v62, v28
	v_exp_f32_e32 v31, v31
	v_fma_f32 v32, s3, v63, v28
	v_exp_f32_e32 v32, v32
	v_add_f32_e32 v0, v0, v29
	v_fma_f32 v29, s3, v64, v28
	v_add_f32_e32 v0, v30, v0
	v_exp_f32_e32 v29, v29
	v_fma_f32 v30, s3, v65, v28
	v_add_f32_e32 v0, v31, v0
	v_exp_f32_e32 v30, v30
	v_fma_f32 v31, s3, v66, v28
	v_exp_f32_e32 v31, v31
	v_add_f32_e32 v0, v32, v0
	v_fma_f32 v32, s3, v67, v28
	v_exp_f32_e32 v32, v32
	v_add_f32_e32 v0, v29, v0
	v_fma_f32 v29, s3, v68, v28
	v_add_f32_e32 v0, v30, v0
	v_exp_f32_e32 v29, v29
	v_fma_f32 v30, s3, v69, v28
	v_add_f32_e32 v0, v31, v0
	v_exp_f32_e32 v30, v30
	v_fma_f32 v31, s3, v70, v28
	v_exp_f32_e32 v31, v31
	v_add_f32_e32 v0, v32, v0
	v_fma_f32 v32, s3, v71, v28
	v_exp_f32_e32 v32, v32
	v_add_f32_e32 v0, v29, v0
	v_fma_f32 v29, s3, v72, v28
	v_add_f32_e32 v0, v30, v0
	v_exp_f32_e32 v30, v29
	v_fma_f32 v29, s3, v73, v28
	v_add_f32_e32 v0, v31, v0
	v_exp_f32_e32 v31, v29
	v_fma_f32 v29, s3, v74, v28
	v_exp_f32_e32 v29, v29
	v_add_f32_e32 v0, v32, v0
	v_add_f32_e32 v0, v30, v0
	v_add_f32_e32 v31, v31, v0
	v_mul_f32_e32 v30, s3, v75
	v_pk_add_f32 v[36:37], v[28:29], v[30:31]

; template <int MODE, int TM> ...
;     ...
;     float mx = -1e30f;
; #pragma unroll
;     for (int t = 0; t < 2; ++t) {
;       if (!(TM & (1 << t))) continue;
;       float mt = -1e30f;
; #pragma unroll
;       for (int kt = 0; kt < 4; ++kt)
; #pragma unroll
;         for (int j = 0; j < 4; ++j) mt = fmaxf(mt, S[t][kt][j]);
;       mx = fmaxf(mx, mt * sclc[t] + addc[t]);
;     }
;     mx = max4q(mx);
;     const float mn = fmaxf(st.m, mx);
;     const float corr = __builtin_amdgcn_exp2f(st.m - mn);
;     st.m = mn;
;     const float mm = fmaxf(mn, -1e20f);
;     float ls = 0.f;
; #pragma unroll
;     for (int t = 0; t < 2; ++t) {
;       if (!(TM & (1 << t))) continue;
;       const float am = addc[t] - mm;
; #pragma unroll
;       for (int kt = 0; kt < 4; ++kt) {
;         const f32x4 e = S[t][kt] * sclc[t] + am;
; #pragma unroll
;         for (int j = 0; j < 4; ++j) {
;           float pv = __builtin_amdgcn_exp2f(e[j]);
;           S[t][kt][j] = pv;
;           ls += pv;
;         }
;       }
;     }
;     st.l = st.l * corr + ls;
.LBB0_930:
	v_max3_f32 v3, v36, s67, v37
	v_max3_f32 v3, v3, v38, v39
	v_max3_f32 v3, v3, v56, v57
	v_max3_f32 v3, v3, v58, v59
	v_max3_f32 v3, v3, v60, v61
	v_max3_f32 v3, v3, v62, v63
	v_max3_f32 v3, v3, v64, v65
	v_max3_f32 v3, v3, v66, v67
	s_waitcnt lgkmcnt(0)
	v_fma_f32 v3, s0, v3, v0
	v_max_f32_e32 v3, 0xf149f2ca, v3
	v_mov_b32_e32 v40, v3
	s_nop 1
	v_permlane16_swap_b32_e32 v40, v3
	s_waitcnt lgkmcnt(0)
	v_max_f32_e32 v40, v40, v40
	v_max_f32_e32 v3, v3, v40
	v_mov_b32_e32 v40, v3
	s_nop 1
	v_permlane32_swap_b32_e32 v3, v40
	v_max3_f32 v125, v77, v3, v40
	v_max_f32_e32 v3, 0xe0ad78ec, v125
	v_sub_f32_e32 v40, v0, v3
	v_fma_f32 v0, s0, v36, v40
	v_fma_f32 v3, s0, v37, v40
	v_exp_f32_e32 v0, v0
	v_fma_f32 v36, s0, v38, v40
	v_exp_f32_e32 v3, v3
	v_fma_f32 v37, s0, v39, v40
	v_exp_f32_e32 v36, v36
	v_exp_f32_e32 v37, v37
	v_add_f32_e32 v0, 0, v0
	v_add_f32_e32 v0, v3, v0
	v_fma_f32 v3, s0, v56, v40
	v_add_f32_e32 v0, v36, v0
	v_exp_f32_e32 v3, v3
	v_fma_f32 v36, s0, v57, v40
	v_add_f32_e32 v0, v37, v0
	v_exp_f32_e32 v36, v36
	v_fma_f32 v37, s0, v58, v40
	v_exp_f32_e32 v37, v37
	v_fma_f32 v38, s0, v59, v40
	v_exp_f32_e32 v38, v38
	v_add_f32_e32 v0, v3, v0
	v_fma_f32 v3, s0, v60, v40
	v_add_f32_e32 v0, v36, v0
	v_exp_f32_e32 v3, v3
	v_fma_f32 v36, s0, v61, v40
	v_add_f32_e32 v0, v37, v0
	v_exp_f32_e32 v36, v36
	v_fma_f32 v37, s0, v62, v40
	v_exp_f32_e32 v37, v37
	v_add_f32_e32 v0, v38, v0
	v_fma_f32 v38, s0, v63, v40
	v_exp_f32_e32 v38, v38
	v_add_f32_e32 v0, v3, v0
	v_fma_f32 v3, s0, v64, v40
	v_add_f32_e32 v0, v36, v0
	v_exp_f32_e32 v3, v3
	v_fma_f32 v36, s0, v65, v40
	v_add_f32_e32 v0, v37, v0
	v_exp_f32_e32 v36, v36
	v_fma_f32 v37, s0, v66, v40
	v_exp_f32_e32 v41, v37
	v_add_f32_e32 v0, v38, v0
	v_add_f32_e32 v0, v3, v0
	v_add_f32_e32 v37, v36, v0
	v_mul_f32_e32 v36, s0, v67
	v_pk_add_f32 v[36:37], v[40:41], v[36:37]
	s_mov_b64 s[0:1], 0

; __device__ __forceinline__ float xor16(float v) { return __int_as_float(__builtin_amdgcn_ds_swizzle(__float_as_int(v), 0x401F)); }
; __device__ __forceinline__ float sum4q(float v) {
;   v += xor16(v);
;   auto r = __builtin_amdgcn_permlane32_swap(__float_as_int(v), __float_as_int(v), false, false);
;   return __int_as_float(r[0]) + __int_as_float(r[1]);
; }
;     ...
;     {
;       const float ls = sum4q(st.l);
;       st.l = ls > 0.f ? 1.f / ls : 0.f;
;     }
; #pragma unroll
;     for (int nt = 0; nt < 4; ++nt) O[nt] = f32x4{0.f, 0.f, 0.f, 0.f};
;     float carry = 0.f;
;     if (parts & 1) pair_pipeline<PFD>(npc,
;       [&](int i, h16x8 (&r)[4]) {
;         r[0] = ld_row8(KC, 64, (2 * i) * 64 + srow, 512, c8); r[1] = ld_row8(VC, 64, (2 * i) * 64 + srow, 512, c8);
;         r[2] = ld_row8(KC, 64, (2 * i + 1) * 64 + srow, 512, c8); r[3] = ld_row8(VC, 64, (2 * i + 1) * 64 + srow, 512, c8); },
.LBB0_1004:
	v_mov_b32_e32 v0, v3
	s_nop 1
	v_permlane16_swap_b32_e32 v0, v3
	v_mov_b32_e32 v28, 0
	v_mov_b32_e32 v32, 0
	v_mov_b32_e32 v33, 0
	v_mov_b32_e32 v34, 0
	s_waitcnt vmcnt(0) lgkmcnt(0)
	v_add_f32_e32 v12, v3, v0
	v_mov_b32_e32 v13, v12
	s_nop 1
	v_permlane32_swap_b32_e32 v12, v13
	v_mov_b32_e32 v35, 0
	v_mov_b32_e32 v36, 0
	v_mov_b32_e32 v37, 0
	v_mov_b32_e32 v38, 0
	v_mov_b32_e32 v39, 0
	v_mov_b32_e32 v40, 0
	v_mov_b32_e32 v41, 0
	v_mov_b32_e32 v42, 0
	v_mov_b32_e32 v43, 0
	v_mov_b32_e32 v44, 0
	v_mov_b32_e32 v45, 0
	v_mov_b32_e32 v46, 0
	v_mov_b32_e32 v47, 0
	v_mov_b32_e32 v48, 0
	v_mov_b32_e32 v49, 0
	v_mov_b32_e32 v50, 0
	v_mov_b32_e32 v51, 0
	s_and_saveexec_b64 s[0:1], s[4:5]
	s_cbranch_execz .LBB0_1006
	v_mov_b32_e32 v77, v1
	v_lshl_add_u64 v[14:15], s[44:45], 0, v[76:77]
	v_mov_b32_e32 v173, v1
	v_lshl_add_u64 v[14:15], v[14:15], 0, v[172:173]
	global_load_dwordx4 v[32:35], v[14:15], off
	v_mov_b32_e32 v36, 0
	v_mov_b32_e32 v37, 0
	v_mov_b32_e32 v38, 0
	v_mov_b32_e32 v39, 0
	v_mov_b32_e32 v40, 0
	v_mov_b32_e32 v41, 0
	v_mov_b32_e32 v42, 0
	v_mov_b32_e32 v43, 0
	v_mov_b32_e32 v44, 0
	v_mov_b32_e32 v45, 0
	v_mov_b32_e32 v46, 0
	v_mov_b32_e32 v47, 0
	v_mov_b32_e32 v48, 0
	v_mov_b32_e32 v49, 0
	v_mov_b32_e32 v50, 0
	v_mov_b32_e32 v51, 0

; #define LAS __attribute__((address_space(3)))
; template <int MODE, int TM> ...
;     ...
;     float mx = -1e30f;
; #pragma unroll
;     for (int t = 0; t < 2; ++t) {
;       if (!(TM & (1 << t))) continue;
;       float mt = -1e30f;
; #pragma unroll
;       for (int kt = 0; kt < 4; ++kt)
; #pragma unroll
;         for (int j = 0; j < 4; ++j) mt = fmaxf(mt, S[t][kt][j]);
;       mx = fmaxf(mx, mt * sclc[t] + addc[t]);
;     }
;     mx = max4q(mx);
;     const float mn = fmaxf(st.m, mx);
;     const float corr = __builtin_amdgcn_exp2f(st.m - mn);
;     st.m = mn;
;     const float mm = fmaxf(mn, -1e20f);
;     float ls = 0.f;
; #pragma unroll
;     for (int t = 0; t < 2; ++t) {
;       if (!(TM & (1 << t))) continue;
;       const float am = addc[t] - mm;
; #pragma unroll
;       for (int kt = 0; kt < 4; ++kt) {
;         const f32x4 e = S[t][kt] * sclc[t] + am;
; #pragma unroll
;         for (int j = 0; j < 4; ++j) {
;           float pv = __builtin_amdgcn_exp2f(e[j]);
;           S[t][kt][j] = pv;
;           ls += pv;
;         }
;       }
;     }
;     st.l = st.l * corr + ls;
;     if (MODE != M_CMPA) {
; #pragma unroll
;       for (int nt = 0; nt < 4; ++nt) O[nt] *= corr;
;     }
;   }
;   if (MODE == M_CMPA) return;
;   __builtin_amdgcn_s_setprio(1);
; #pragma unroll
;   for (int t = 0; t < 2; ++t) {
;     if (!(TM & (1 << t))) continue;
;     const h16* Vt = t ? Vt1 : Vt0;
; #pragma unroll
;     for (int ks = 0; ks < 2; ++ks) {
;       h16x8 Pf;
; #pragma unroll
;       for (int i = 0; i < 4; ++i) { Pf[i] = (h16)S[t][2 * ks][i]; Pf[4 + i] = (h16)S[t][2 * ks + 1][i]; }
; #pragma unroll
;       for (int nt = 0; nt < 4; ++nt) {
;         const h16* vp = Vt + (ks * 32 + q4 * 4 + (col >> 2)) * KP + nt * 16 + 4 * (col & 3);
;         const s16x4v r0 = __builtin_amdgcn_ds_read_tr16_b64_v4i16((LAS s16x4v*)vp);
;         const s16x4v r1 = __builtin_amdgcn_ds_read_tr16_b64_v4i16((LAS s16x4v*)(vp + 16 * KP));
;         const h16x4 v0 = __builtin_bit_cast(h16x4, r0), v1 = __builtin_bit_cast(h16x4, r1);
;         const h16x8 Vf = {v0[0], v0[1], v0[2], v0[3], v1[0], v1[1], v1[2], v1[3]};
;         O[nt] = __builtin_amdgcn_mfma_f32_16x16x32_f16(Vf, Pf, O[nt], 0, 0, 0);
;       }
.LBB0_1522:
	v_max3_f32 v96, v92, s67, v93
	v_max3_f32 v96, v96, v94, v95
	v_max3_f32 v96, v96, v88, v89
	v_max3_f32 v96, v96, v90, v91
	v_max3_f32 v96, v96, v84, v85
	v_max3_f32 v96, v96, v86, v87
	v_max3_f32 v96, v96, v80, v81
	v_max3_f32 v96, v96, v82, v83
	s_waitcnt lgkmcnt(0)
	v_fma_f32 v96, s0, v96, v112
	v_max_f32_e32 v96, 0xf149f2ca, v96
	v_mov_b32_e32 v97, v96
	s_nop 1
	v_permlane16_swap_b32_e32 v97, v96
	s_waitcnt lgkmcnt(0)
	v_max_f32_e32 v97, v97, v97
	v_max_f32_e32 v96, v96, v97
	v_mov_b32_e32 v97, v96
	s_nop 1
	v_permlane32_swap_b32_e32 v96, v97
	v_max3_f32 v244, v173, v96, v97
	v_max_f32_e32 v97, 0xe0ad78ec, v244
	v_sub_f32_e32 v97, v112, v97
	v_fma_f32 v92, s0, v92, v97
	v_fma_f32 v93, s0, v93, v97
	v_exp_f32_e32 v100, v92
	v_fma_f32 v94, s0, v94, v97
	v_exp_f32_e32 v101, v93
	v_fma_f32 v92, s0, v95, v97
	v_exp_f32_e32 v102, v94
	v_exp_f32_e32 v103, v92
	v_fma_f32 v88, s0, v88, v97
	v_add_f32_e32 v93, 0, v100
	v_exp_f32_e32 v98, v88
	v_fma_f32 v89, s0, v89, v97
	v_add_f32_e32 v88, v101, v93
	v_exp_f32_e32 v104, v89
	v_fma_f32 v89, s0, v90, v97
	v_add_f32_e32 v88, v102, v88
	v_exp_f32_e32 v99, v89
	v_fma_f32 v89, s0, v91, v97
	v_add_f32_e32 v88, v103, v88
	v_exp_f32_e32 v105, v89
	v_fma_f32 v84, s0, v84, v97
	v_add_f32_e32 v88, v98, v88
	v_exp_f32_e32 v108, v84
	v_fma_f32 v85, s0, v85, v97
	v_add_f32_e32 v84, v104, v88
	v_exp_f32_e32 v109, v85
	v_fma_f32 v85, s0, v86, v97
	v_add_f32_e32 v84, v99, v84
	v_exp_f32_e32 v110, v85
	v_fma_f32 v85, s0, v87, v97
	v_add_f32_e32 v84, v105, v84
	v_exp_f32_e32 v111, v85
	v_fma_f32 v80, s0, v80, v97
	v_add_f32_e32 v84, v108, v84
	v_exp_f32_e32 v112, v80
	v_fma_f32 v81, s0, v81, v97
	v_add_f32_e32 v80, v109, v84
	v_exp_f32_e32 v113, v81
	v_fma_f32 v81, s0, v82, v97
	v_add_f32_e32 v80, v110, v80
	v_exp_f32_e32 v114, v81
	v_fmac_f32_e32 v97, s0, v83
	v_sub_f32_e32 v96, v173, v244
	v_add_f32_e32 v80, v111, v80
	v_exp_f32_e32 v115, v97
	v_add_f32_e32 v80, v112, v80
	v_exp_f32_e32 v92, v96
	v_add_f32_e32 v80, v113, v80
	v_add_f32_e32 v80, v114, v80
	v_add_f32_e32 v188, v115, v80
	v_fmac_f32_e32 v188, v243, v92
	v_pk_mul_f32 v[82:83], v[30:31], v[92:93] op_sel_hi:[1,0]
	v_pk_mul_f32 v[80:81], v[28:29], v[92:93] op_sel_hi:[1,0]
	v_pk_mul_f32 v[86:87], v[34:35], v[92:93] op_sel_hi:[1,0]
	v_pk_mul_f32 v[84:85], v[32:33], v[92:93] op_sel_hi:[1,0]
	v_pk_mul_f32 v[90:91], v[38:39], v[92:93] op_sel_hi:[1,0]
	v_pk_mul_f32 v[88:89], v[36:37], v[92:93] op_sel_hi:[1,0]
	v_pk_mul_f32 v[94:95], v[42:43], v[92:93] op_sel_hi:[1,0]
	v_pk_mul_f32 v[92:93], v[40:41], v[92:93] op_sel_hi:[1,0]
	s_setprio 1
	v_cvt_pk_f16_f32 v99, v99, v105
	v_cvt_pk_f16_f32 v98, v98, v104
	v_cvt_pk_f16_f32 v97, v102, v103
	v_cvt_pk_f16_f32 v96, v100, v101
	ds_read_b64_tr_b16 v[102:103], v205 offset:25600
	ds_read_b64_tr_b16 v[100:101], v205 offset:23040
	ds_read_b64_tr_b16 v[104:105], v205 offset:23072
	s_waitcnt lgkmcnt(1)
	v_mfma_f32_16x16x32_f16 v[80:83], v[100:103], v[96:99], v[80:83]
	ds_read_b64_tr_b16 v[106:107], v205 offset:25632
	ds_read_b64_tr_b16 v[100:101], v205 offset:23104
	ds_read_b64_tr_b16 v[102:103], v205 offset:25664
	s_mov_b64 s[52:53], -1
	s_waitcnt lgkmcnt(0)
	v_mfma_f32_16x16x32_f16 v[88:91], v[100:103], v[96:99], v[88:91]
	ds_read_b64_tr_b16 v[100:101], v205 offset:23136
	ds_read_b64_tr_b16 v[102:103], v205 offset:25696
	s_waitcnt lgkmcnt(0)
	v_mfma_f32_16x16x32_f16 v[92:95], v[100:103], v[96:99], v[92:95]
	ds_read_b64_tr_b16 v[100:101], v205 offset:28160
	ds_read_b64_tr_b16 v[102:103], v205 offset:30720
	v_mfma_f32_16x16x32_f16 v[84:87], v[104:107], v[96:99], v[84:87]
	v_cvt_pk_f16_f32 v99, v114, v115
	v_cvt_pk_f16_f32 v98, v112, v113
	v_cvt_pk_f16_f32 v97, v110, v111
	v_cvt_pk_f16_f32 v96, v108, v109
	s_waitcnt lgkmcnt(0)
	s_nop 0
	v_mfma_f32_16x16x32_f16 v[80:83], v[100:103], v[96:99], v[80:83]
	ds_read_b64_tr_b16 v[100:101], v205 offset:28192
	ds_read_b64_tr_b16 v[102:103], v205 offset:30752
	s_waitcnt lgkmcnt(0)
	v_mfma_f32_16x16x32_f16 v[84:87], v[100:103], v[96:99], v[84:87]
	ds_read_b64_tr_b16 v[100:101], v205 offset:28224
	ds_read_b64_tr_b16 v[102:103], v205 offset:30784
	s_waitcnt lgkmcnt(0)
	v_mfma_f32_16x16x32_f16 v[88:91], v[100:103], v[96:99], v[88:91]
	ds_read_b64_tr_b16 v[100:101], v205 offset:28256
	ds_read_b64_tr_b16 v[102:103], v205 offset:30816
	s_waitcnt lgkmcnt(0)
	v_mfma_f32_16x16x32_f16 v[92:95], v[100:103], v[96:99], v[92:95]
	s_branch .LBB0_1603

; #define LAS __attribute__((address_space(3)))
; template <int MODE, int TM> ...
;     ...
;     float mx = -1e30f;
; #pragma unroll
;     for (int t = 0; t < 2; ++t) {
;       if (!(TM & (1 << t))) continue;
;       float mt = -1e30f;
; #pragma unroll
;       for (int kt = 0; kt < 4; ++kt)
; #pragma unroll
;         for (int j = 0; j < 4; ++j) mt = fmaxf(mt, S[t][kt][j]);
;       mx = fmaxf(mx, mt * sclc[t] + addc[t]);
;     }
;     mx = max4q(mx);
;     const float mn = fmaxf(st.m, mx);
;     const float corr = __builtin_amdgcn_exp2f(st.m - mn);
;     st.m = mn;
;     const float mm = fmaxf(mn, -1e20f);
;     float ls = 0.f;
; #pragma unroll
;     for (int t = 0; t < 2; ++t) {
;       if (!(TM & (1 << t))) continue;
;       const float am = addc[t] - mm;
; #pragma unroll
;       for (int kt = 0; kt < 4; ++kt) {
;         const f32x4 e = S[t][kt] * sclc[t] + am;
; #pragma unroll
;         for (int j = 0; j < 4; ++j) {
;           float pv = __builtin_amdgcn_exp2f(e[j]);
;           S[t][kt][j] = pv;
;           ls += pv;
;         }
;       }
;     }
;     st.l = st.l * corr + ls;
;     if (MODE != M_CMPA) {
; #pragma unroll
;       for (int nt = 0; nt < 4; ++nt) O[nt] *= corr;
;     }
;   }
;   if (MODE == M_CMPA) return;
;   __builtin_amdgcn_s_setprio(1);
; #pragma unroll
;   for (int t = 0; t < 2; ++t) {
;     if (!(TM & (1 << t))) continue;
;     const h16* Vt = t ? Vt1 : Vt0;
; #pragma unroll
;     for (int ks = 0; ks < 2; ++ks) {
;       h16x8 Pf;
; #pragma unroll
;       for (int i = 0; i < 4; ++i) { Pf[i] = (h16)S[t][2 * ks][i]; Pf[4 + i] = (h16)S[t][2 * ks + 1][i]; }
; #pragma unroll
;       for (int nt = 0; nt < 4; ++nt) {
;         const h16* vp = Vt + (ks * 32 + q4 * 4 + (col >> 2)) * KP + nt * 16 + 4 * (col & 3);
;         const s16x4v r0 = __builtin_amdgcn_ds_read_tr16_b64_v4i16((LAS s16x4v*)vp);
;         const s16x4v r1 = __builtin_amdgcn_ds_read_tr16_b64_v4i16((LAS s16x4v*)(vp + 16 * KP));
;         const h16x4 v0 = __builtin_bit_cast(h16x4, r0), v1 = __builtin_bit_cast(h16x4, r1);
;         const h16x8 Vf = {v0[0], v0[1], v0[2], v0[3], v1[0], v1[1], v1[2], v1[3]};
;         O[nt] = __builtin_amdgcn_mfma_f32_16x16x32_f16(Vf, Pf, O[nt], 0, 0, 0);
;       }
.LBB0_1524:
	v_max3_f32 v96, v84, s67, v85
	v_max3_f32 v96, v96, v86, v87
	v_max3_f32 v96, v96, v80, v81
	v_max3_f32 v96, v96, v82, v83
	v_max3_f32 v96, v96, v92, v93
	v_max3_f32 v96, v96, v94, v95
	v_max3_f32 v96, v96, v88, v89
	v_max3_f32 v96, v96, v90, v91
	s_waitcnt lgkmcnt(0)
	v_fma_f32 v96, s3, v96, v112
	v_max_f32_e32 v96, 0xf149f2ca, v96
	v_mov_b32_e32 v97, v96
	s_nop 1
	v_permlane16_swap_b32_e32 v97, v96
	s_waitcnt lgkmcnt(0)
	v_max_f32_e32 v97, v97, v97
	v_max_f32_e32 v96, v96, v97
	v_mov_b32_e32 v97, v96
	s_nop 1
	v_permlane32_swap_b32_e32 v96, v97
	v_max3_f32 v244, v173, v96, v97
	v_max_f32_e32 v97, 0xe0ad78ec, v244
	v_sub_f32_e32 v97, v112, v97
	v_fma_f32 v80, s3, v80, v97
	v_exp_f32_e32 v98, v80
	v_fma_f32 v80, s3, v81, v97
	v_exp_f32_e32 v104, v80
	v_fma_f32 v80, s3, v82, v97
	v_exp_f32_e32 v99, v80
	v_fma_f32 v80, s3, v83, v97
	v_exp_f32_e32 v105, v80
	v_fma_f32 v80, s3, v92, v97
	v_exp_f32_e32 v108, v80
	v_fma_f32 v80, s3, v93, v97
	v_fma_f32 v84, s3, v84, v97
	v_exp_f32_e32 v109, v80
	v_fma_f32 v80, s3, v94, v97
	v_fma_f32 v85, s3, v85, v97
	v_exp_f32_e32 v100, v84
	v_exp_f32_e32 v110, v80
	v_fma_f32 v80, s3, v95, v97
	v_exp_f32_e32 v101, v85
	v_fma_f32 v84, s3, v86, v97
	v_exp_f32_e32 v111, v80
	v_fma_f32 v80, s3, v88, v97
	v_exp_f32_e32 v102, v84
	v_fma_f32 v84, s3, v87, v97
	v_exp_f32_e32 v112, v80
	v_fma_f32 v80, s3, v89, v97
	v_exp_f32_e32 v103, v84
	v_exp_f32_e32 v113, v80
	v_fma_f32 v80, s3, v90, v97
	v_exp_f32_e32 v114, v80
	v_add_f32_e32 v80, 0, v100
	v_add_f32_e32 v80, v101, v80
	v_add_f32_e32 v80, v102, v80
	v_add_f32_e32 v80, v103, v80
	v_add_f32_e32 v80, v98, v80
	v_add_f32_e32 v80, v104, v80
	v_add_f32_e32 v80, v99, v80
	v_add_f32_e32 v80, v105, v80
	v_add_f32_e32 v80, v108, v80
	v_add_f32_e32 v80, v109, v80
	v_fmac_f32_e32 v97, s3, v91
	v_add_f32_e32 v80, v110, v80
	v_sub_f32_e32 v96, v173, v244
	v_exp_f32_e32 v115, v97
	v_add_f32_e32 v80, v111, v80
	v_add_f32_e32 v80, v112, v80
	v_exp_f32_e32 v92, v96
	v_add_f32_e32 v80, v113, v80
	v_add_f32_e32 v80, v114, v80
	v_add_f32_e32 v188, v115, v80
	v_fmac_f32_e32 v188, v243, v92
	v_pk_mul_f32 v[82:83], v[30:31], v[92:93] op_sel_hi:[1,0]
	v_pk_mul_f32 v[80:81], v[28:29], v[92:93] op_sel_hi:[1,0]
	v_pk_mul_f32 v[86:87], v[34:35], v[92:93] op_sel_hi:[1,0]
	v_pk_mul_f32 v[84:85], v[32:33], v[92:93] op_sel_hi:[1,0]
	v_pk_mul_f32 v[90:91], v[38:39], v[92:93] op_sel_hi:[1,0]
	v_pk_mul_f32 v[88:89], v[36:37], v[92:93] op_sel_hi:[1,0]
	v_pk_mul_f32 v[94:95], v[42:43], v[92:93] op_sel_hi:[1,0]
	v_pk_mul_f32 v[92:93], v[40:41], v[92:93] op_sel_hi:[1,0]
	s_setprio 1
	v_cvt_pk_f16_f32 v99, v99, v105
	v_cvt_pk_f16_f32 v98, v98, v104
	v_cvt_pk_f16_f32 v97, v102, v103
	v_cvt_pk_f16_f32 v96, v100, v101
	ds_read_b64_tr_b16 v[102:103], v205 offset:46080
	ds_read_b64_tr_b16 v[100:101], v205 offset:43520
	ds_read_b64_tr_b16 v[104:105], v205 offset:43552
	s_waitcnt lgkmcnt(1)
	v_mfma_f32_16x16x32_f16 v[80:83], v[100:103], v[96:99], v[80:83]
	ds_read_b64_tr_b16 v[106:107], v205 offset:46112
	ds_read_b64_tr_b16 v[100:101], v205 offset:43584
	ds_read_b64_tr_b16 v[102:103], v205 offset:46144
	s_mov_b64 s[52:53], -1
	s_waitcnt lgkmcnt(0)
	v_mfma_f32_16x16x32_f16 v[88:91], v[100:103], v[96:99], v[88:91]
	ds_read_b64_tr_b16 v[100:101], v205 offset:43616
	ds_read_b64_tr_b16 v[102:103], v205 offset:46176
	s_waitcnt lgkmcnt(0)
	v_mfma_f32_16x16x32_f16 v[92:95], v[100:103], v[96:99], v[92:95]
	ds_read_b64_tr_b16 v[100:101], v205 offset:48640
	ds_read_b64_tr_b16 v[102:103], v205 offset:51200
	v_mfma_f32_16x16x32_f16 v[84:87], v[104:107], v[96:99], v[84:87]
	v_cvt_pk_f16_f32 v99, v114, v115
	v_cvt_pk_f16_f32 v98, v112, v113
	v_cvt_pk_f16_f32 v97, v110, v111
	v_cvt_pk_f16_f32 v96, v108, v109
	s_waitcnt lgkmcnt(0)
	s_nop 0
	v_mfma_f32_16x16x32_f16 v[80:83], v[100:103], v[96:99], v[80:83]
	ds_read_b64_tr_b16 v[100:101], v205 offset:48672
	ds_read_b64_tr_b16 v[102:103], v205 offset:51232
	s_waitcnt lgkmcnt(0)
	v_mfma_f32_16x16x32_f16 v[84:87], v[100:103], v[96:99], v[84:87]
	ds_read_b64_tr_b16 v[100:101], v205 offset:48704
	ds_read_b64_tr_b16 v[102:103], v205 offset:51264
	s_waitcnt lgkmcnt(0)
	v_mfma_f32_16x16x32_f16 v[88:91], v[100:103], v[96:99], v[88:91]
	ds_read_b64_tr_b16 v[100:101], v205 offset:48736
	ds_read_b64_tr_b16 v[102:103], v205 offset:51296
	s_waitcnt lgkmcnt(0)
	v_mfma_f32_16x16x32_f16 v[92:95], v[100:103], v[96:99], v[92:95]
	s_and_b64 vcc, exec, s[0:1]
	s_cbranch_vccnz .LBB0_1483

; #define LAS __attribute__((address_space(3)))
; template <int MODE, int TM> ...
;     ...
;     float mx = -1e30f;
; #pragma unroll
;     for (int t = 0; t < 2; ++t) {
;       if (!(TM & (1 << t))) continue;
;       float mt = -1e30f;
; #pragma unroll
;       for (int kt = 0; kt < 4; ++kt)
; #pragma unroll
;         for (int j = 0; j < 4; ++j) mt = fmaxf(mt, S[t][kt][j]);
;       mx = fmaxf(mx, mt * sclc[t] + addc[t]);
;     }
;     mx = max4q(mx);
;     const float mn = fmaxf(st.m, mx);
;     const float corr = __builtin_amdgcn_exp2f(st.m - mn);
;     st.m = mn;
;     const float mm = fmaxf(mn, -1e20f);
;     float ls = 0.f;
; #pragma unroll
;     for (int t = 0; t < 2; ++t) {
;       if (!(TM & (1 << t))) continue;
;       const float am = addc[t] - mm;
; #pragma unroll
;       for (int kt = 0; kt < 4; ++kt) {
;         const f32x4 e = S[t][kt] * sclc[t] + am;
; #pragma unroll
;         for (int j = 0; j < 4; ++j) {
;           float pv = __builtin_amdgcn_exp2f(e[j]);
;           S[t][kt][j] = pv;
;           ls += pv;
;         }
;       }
;     }
;     st.l = st.l * corr + ls;
;     if (MODE != M_CMPA) {
; #pragma unroll
;       for (int nt = 0; nt < 4; ++nt) O[nt] *= corr;
;     }
;   }
;   if (MODE == M_CMPA) return;
;   __builtin_amdgcn_s_setprio(1);
; #pragma unroll
;   for (int t = 0; t < 2; ++t) {
;     if (!(TM & (1 << t))) continue;
;     const h16* Vt = t ? Vt1 : Vt0;
; #pragma unroll
;     for (int ks = 0; ks < 2; ++ks) {
;       h16x8 Pf;
; #pragma unroll
;       for (int i = 0; i < 4; ++i) { Pf[i] = (h16)S[t][2 * ks][i]; Pf[4 + i] = (h16)S[t][2 * ks + 1][i]; }
; #pragma unroll
;       for (int nt = 0; nt < 4; ++nt) {
;         const h16* vp = Vt + (ks * 32 + q4 * 4 + (col >> 2)) * KP + nt * 16 + 4 * (col & 3);
;         const s16x4v r0 = __builtin_amdgcn_ds_read_tr16_b64_v4i16((LAS s16x4v*)vp);
;         const s16x4v r1 = __builtin_amdgcn_ds_read_tr16_b64_v4i16((LAS s16x4v*)(vp + 16 * KP));
;         const h16x4 v0 = __builtin_bit_cast(h16x4, r0), v1 = __builtin_bit_cast(h16x4, r1);
;         const h16x8 Vf = {v0[0], v0[1], v0[2], v0[3], v1[0], v1[1], v1[2], v1[3]};
;         O[nt] = __builtin_amdgcn_mfma_f32_16x16x32_f16(Vf, Pf, O[nt], 0, 0, 0);
;       }
.LBB0_1602:
	s_waitcnt lgkmcnt(0)
	v_max3_f32 v0, v92, s67, v93
	v_max3_f32 v96, v112, s67, v113
	v_max3_f32 v0, v0, v94, v95
	v_max3_f32 v96, v96, v114, v115
	v_max3_f32 v0, v0, v88, v89
	v_max3_f32 v96, v96, v116, v117
	v_max3_f32 v0, v0, v90, v91
	v_max3_f32 v96, v96, v118, v119
	v_max3_f32 v0, v0, v84, v85
	v_max3_f32 v96, v96, v120, v121
	v_max3_f32 v0, v0, v86, v87
	v_max3_f32 v96, v96, v122, v123
	v_max3_f32 v0, v0, v80, v81
	v_max3_f32 v96, v96, v124, v125
	v_max3_f32 v0, v0, v82, v83
	v_max3_f32 v96, v96, v126, v127
	v_fma_f32 v0, s2, v0, v188
	v_fma_f32 v96, s3, v96, v189
	v_max3_f32 v0, v0, s67, v96
	v_mov_b32_e32 v96, v0
	s_nop 1
	v_permlane16_swap_b32_e32 v96, v0
	s_waitcnt lgkmcnt(0)
	v_max_f32_e32 v96, v96, v96
	v_max_f32_e32 v0, v0, v96
	v_mov_b32_e32 v96, v0
	s_nop 1
	v_permlane32_swap_b32_e32 v0, v96
	v_max3_f32 v244, v173, v0, v96
	v_max_f32_e32 v0, 0xe0ad78ec, v244
	v_sub_f32_e32 v96, v188, v0
	v_fma_f32 v92, s2, v92, v96
	v_exp_f32_e32 v92, v92
	v_fma_f32 v93, s2, v93, v96
	v_exp_f32_e32 v93, v93
	v_fma_f32 v94, s2, v94, v96
	v_exp_f32_e32 v94, v94
	v_fma_f32 v95, s2, v95, v96
	v_exp_f32_e32 v95, v95
	v_fma_f32 v88, s2, v88, v96
	v_add_f32_e32 v98, 0, v92
	v_exp_f32_e32 v88, v88
	v_fma_f32 v89, s2, v89, v96
	v_add_f32_e32 v98, v93, v98
	v_exp_f32_e32 v89, v89
	v_fma_f32 v90, s2, v90, v96
	v_add_f32_e32 v98, v94, v98
	v_exp_f32_e32 v90, v90
	v_fma_f32 v91, s2, v91, v96
	v_add_f32_e32 v98, v95, v98
	v_exp_f32_e32 v91, v91
	v_fma_f32 v84, s2, v84, v96
	v_add_f32_e32 v98, v88, v98
	v_exp_f32_e32 v99, v84
	v_fma_f32 v85, s2, v85, v96
	v_add_f32_e32 v84, v89, v98
	v_exp_f32_e32 v98, v85
	v_fma_f32 v85, s2, v86, v96
	v_add_f32_e32 v84, v90, v84
	v_exp_f32_e32 v100, v85
	v_fma_f32 v85, s2, v87, v96
	v_add_f32_e32 v84, v91, v84
	v_exp_f32_e32 v101, v85
	v_fma_f32 v80, s2, v80, v96
	v_add_f32_e32 v84, v99, v84
	v_exp_f32_e32 v102, v80
	v_fma_f32 v81, s2, v81, v96
	v_add_f32_e32 v80, v98, v84
	v_exp_f32_e32 v103, v81
	v_fma_f32 v81, s2, v82, v96
	v_add_f32_e32 v80, v100, v80
	v_exp_f32_e32 v104, v81
	v_fmac_f32_e32 v96, s2, v83
	v_sub_f32_e32 v0, v189, v0
	v_add_f32_e32 v80, v101, v80
	v_exp_f32_e32 v96, v96
	v_fma_f32 v81, s3, v112, v0
	v_add_f32_e32 v80, v102, v80
	v_exp_f32_e32 v105, v81
	v_fma_f32 v81, s3, v113, v0
	v_add_f32_e32 v80, v103, v80
	v_exp_f32_e32 v106, v81
	v_fma_f32 v81, s3, v114, v0
	v_add_f32_e32 v80, v104, v80
	v_exp_f32_e32 v107, v81
	v_fma_f32 v81, s3, v115, v0
	v_add_f32_e32 v80, v96, v80
	v_exp_f32_e32 v108, v81
	v_fma_f32 v81, s3, v116, v0
	v_add_f32_e32 v80, v105, v80
	v_exp_f32_e32 v109, v81
	v_fma_f32 v81, s3, v117, v0
	v_add_f32_e32 v80, v106, v80
	v_exp_f32_e32 v110, v81
	v_fma_f32 v81, s3, v118, v0
	v_add_f32_e32 v80, v107, v80
	v_exp_f32_e32 v111, v81
	v_fma_f32 v81, s3, v119, v0
	v_add_f32_e32 v80, v108, v80
	v_exp_f32_e32 v112, v81
	v_fma_f32 v81, s3, v120, v0
	v_add_f32_e32 v80, v109, v80
	v_exp_f32_e32 v113, v81
	v_fma_f32 v81, s3, v121, v0
	v_add_f32_e32 v80, v110, v80
	v_exp_f32_e32 v114, v81
	v_fma_f32 v81, s3, v122, v0
	v_add_f32_e32 v80, v111, v80
	v_exp_f32_e32 v115, v81
	v_fma_f32 v81, s3, v123, v0
	v_add_f32_e32 v80, v112, v80
	v_exp_f32_e32 v116, v81
	v_fma_f32 v81, s3, v124, v0
	v_add_f32_e32 v80, v113, v80
	v_exp_f32_e32 v117, v81
	v_fma_f32 v81, s3, v125, v0
	v_add_f32_e32 v80, v114, v80
	v_exp_f32_e32 v118, v81
	v_fma_f32 v81, s3, v126, v0
	v_add_f32_e32 v80, v115, v80
	v_exp_f32_e32 v119, v81
	v_fmac_f32_e32 v0, s3, v127
	v_sub_f32_e32 v97, v173, v244
	v_add_f32_e32 v80, v116, v80
	v_exp_f32_e32 v120, v0
	v_add_f32_e32 v80, v117, v80
	v_exp_f32_e32 v0, v97
	v_add_f32_e32 v80, v118, v80
	v_add_f32_e32 v80, v119, v80
	v_add_f32_e32 v188, v120, v80
	v_fmac_f32_e32 v188, v243, v0
	v_pk_mul_f32 v[30:31], v[30:31], v[0:1] op_sel_hi:[1,0]
	v_pk_mul_f32 v[28:29], v[28:29], v[0:1] op_sel_hi:[1,0]
	v_pk_mul_f32 v[34:35], v[34:35], v[0:1] op_sel_hi:[1,0]
	v_pk_mul_f32 v[32:33], v[32:33], v[0:1] op_sel_hi:[1,0]
	v_pk_mul_f32 v[38:39], v[38:39], v[0:1] op_sel_hi:[1,0]
	v_pk_mul_f32 v[36:37], v[36:37], v[0:1] op_sel_hi:[1,0]
	v_pk_mul_f32 v[42:43], v[42:43], v[0:1] op_sel_hi:[1,0]
	v_pk_mul_f32 v[40:41], v[40:41], v[0:1] op_sel_hi:[1,0]
	s_setprio 1
	v_cvt_pk_f16_f32 v82, v88, v89
	ds_read_b64_tr_b16 v[86:87], v205 offset:25600
	ds_read_b64_tr_b16 v[84:85], v205 offset:23040
	ds_read_b64_tr_b16 v[88:89], v205 offset:23072
	v_cvt_pk_f16_f32 v83, v90, v91
	v_cvt_pk_f16_f32 v81, v94, v95
	v_cvt_pk_f16_f32 v80, v92, v93
	ds_read_b64_tr_b16 v[90:91], v205 offset:25632
	v_cvt_pk_f16_f32 v95, v119, v120
	s_waitcnt lgkmcnt(2)
; #define LAS __attribute__((address_space(3)))
; template <int MODE, int TM> ...
;     ...
;   __builtin_amdgcn_s_setprio(1);
; #pragma unroll
;   for (int t = 0; t < 2; ++t) {
;     if (!(TM & (1 << t))) continue;
;     const h16* Vt = t ? Vt1 : Vt0;
; #pragma unroll
;     for (int ks = 0; ks < 2; ++ks) {
;       h16x8 Pf;
; #pragma unroll
;       for (int i = 0; i < 4; ++i) { Pf[i] = (h16)S[t][2 * ks][i]; Pf[4 + i] = (h16)S[t][2 * ks + 1][i]; }
; #pragma unroll
;       for (int nt = 0; nt < 4; ++nt) {
;         const h16* vp = Vt + (ks * 32 + q4 * 4 + (col >> 2)) * KP + nt * 16 + 4 * (col & 3);
;         const s16x4v r0 = __builtin_amdgcn_ds_read_tr16_b64_v4i16((LAS s16x4v*)vp);
;         const s16x4v r1 = __builtin_amdgcn_ds_read_tr16_b64_v4i16((LAS s16x4v*)(vp + 16 * KP));
;         const h16x4 v0 = __builtin_bit_cast(h16x4, r0), v1 = __builtin_bit_cast(h16x4, r1);
;         const h16x8 Vf = {v0[0], v0[1], v0[2], v0[3], v1[0], v1[1], v1[2], v1[3]};
;         O[nt] = __builtin_amdgcn_mfma_f32_16x16x32_f16(Vf, Pf, O[nt], 0, 0, 0);
;       }
;     }
;   }
;   __builtin_amdgcn_s_setprio(0);
	v_mfma_f32_16x16x32_f16 v[28:31], v[84:87], v[80:83], v[28:31]
	ds_read_b64_tr_b16 v[84:85], v205 offset:23104
	ds_read_b64_tr_b16 v[86:87], v205 offset:25664
	v_cvt_pk_f16_f32 v94, v117, v118
	v_cvt_pk_f16_f32 v93, v115, v116
	s_waitcnt lgkmcnt(0)
	v_mfma_f32_16x16x32_f16 v[36:39], v[84:87], v[80:83], v[36:39]
	ds_read_b64_tr_b16 v[84:85], v205 offset:23136
	ds_read_b64_tr_b16 v[86:87], v205 offset:25696
	v_cvt_pk_f16_f32 v92, v113, v114
	s_mov_b64 s[52:53], -1
	s_waitcnt lgkmcnt(0)
	v_mfma_f32_16x16x32_f16 v[40:43], v[84:87], v[80:83], v[40:43]
	ds_read_b64_tr_b16 v[84:85], v205 offset:28160
	ds_read_b64_tr_b16 v[86:87], v205 offset:30720
	v_mfma_f32_16x16x32_f16 v[32:35], v[88:91], v[80:83], v[32:35]
	v_cvt_pk_f16_f32 v83, v104, v96
	v_cvt_pk_f16_f32 v82, v102, v103
	v_cvt_pk_f16_f32 v81, v100, v101
	v_cvt_pk_f16_f32 v80, v99, v98
	s_waitcnt lgkmcnt(0)
	s_nop 0
	v_mfma_f32_16x16x32_f16 v[28:31], v[84:87], v[80:83], v[28:31]
	ds_read_b64_tr_b16 v[84:85], v205 offset:28192
	ds_read_b64_tr_b16 v[86:87], v205 offset:30752
	s_waitcnt lgkmcnt(0)
	v_mfma_f32_16x16x32_f16 v[32:35], v[84:87], v[80:83], v[32:35]
	ds_read_b64_tr_b16 v[84:85], v205 offset:28224
	ds_read_b64_tr_b16 v[86:87], v205 offset:30784
	s_waitcnt lgkmcnt(0)
	v_mfma_f32_16x16x32_f16 v[36:39], v[84:87], v[80:83], v[36:39]
	ds_read_b64_tr_b16 v[84:85], v205 offset:28256
	ds_read_b64_tr_b16 v[86:87], v205 offset:30816
	s_waitcnt lgkmcnt(0)
	v_mfma_f32_16x16x32_f16 v[40:43], v[84:87], v[80:83], v[40:43]
	ds_read_b64_tr_b16 v[84:85], v205 offset:43520
	ds_read_b64_tr_b16 v[86:87], v205 offset:46080
	v_cvt_pk_f16_f32 v83, v111, v112
	v_cvt_pk_f16_f32 v82, v109, v110
	v_cvt_pk_f16_f32 v81, v107, v108
	v_cvt_pk_f16_f32 v80, v105, v106
	s_waitcnt lgkmcnt(0)
	s_nop 0
	v_mfma_f32_16x16x32_f16 v[28:31], v[84:87], v[80:83], v[28:31]
	ds_read_b64_tr_b16 v[84:85], v205 offset:43552
	ds_read_b64_tr_b16 v[86:87], v205 offset:46112
	s_waitcnt lgkmcnt(0)
	v_mfma_f32_16x16x32_f16 v[32:35], v[84:87], v[80:83], v[32:35]
	ds_read_b64_tr_b16 v[84:85], v205 offset:43584
	ds_read_b64_tr_b16 v[86:87], v205 offset:46144
	s_waitcnt lgkmcnt(0)
	v_mfma_f32_16x16x32_f16 v[36:39], v[84:87], v[80:83], v[36:39]
	ds_read_b64_tr_b16 v[84:85], v205 offset:43616
	ds_read_b64_tr_b16 v[86:87], v205 offset:46176
	s_waitcnt lgkmcnt(0)
	v_mfma_f32_16x16x32_f16 v[40:43], v[84:87], v[80:83], v[40:43]
	ds_read_b64_tr_b16 v[80:81], v205 offset:48640
	ds_read_b64_tr_b16 v[82:83], v205 offset:51200
	s_waitcnt lgkmcnt(0)
	v_mfma_f32_16x16x32_f16 v[80:83], v[80:83], v[92:95], v[28:31]
	s_nop 2
	ds_read_b64_tr_b16 v[28:29], v205 offset:48672
	ds_read_b64_tr_b16 v[30:31], v205 offset:51232
	s_waitcnt lgkmcnt(0)
	v_mfma_f32_16x16x32_f16 v[84:87], v[28:31], v[92:95], v[32:35]
	ds_read_b64_tr_b16 v[28:29], v205 offset:48704
	ds_read_b64_tr_b16 v[30:31], v205 offset:51264
	s_waitcnt lgkmcnt(0)
	v_mfma_f32_16x16x32_f16 v[88:91], v[28:31], v[92:95], v[36:39]
	ds_read_b64_tr_b16 v[28:29], v205 offset:48736
	ds_read_b64_tr_b16 v[30:31], v205 offset:51296
	s_waitcnt lgkmcnt(0)
	v_mfma_f32_16x16x32_f16 v[92:95], v[28:31], v[92:95], v[40:43]

; #define LAS __attribute__((address_space(3)))
; template <int MODE, int TM> ...
;     ...
;     float mx = -1e30f;
; #pragma unroll
;     for (int t = 0; t < 2; ++t) {
;       if (!(TM & (1 << t))) continue;
;       float mt = -1e30f;
; #pragma unroll
;       for (int kt = 0; kt < 4; ++kt)
; #pragma unroll
;         for (int j = 0; j < 4; ++j) mt = fmaxf(mt, S[t][kt][j]);
;       mx = fmaxf(mx, mt * sclc[t] + addc[t]);
;     }
;     mx = max4q(mx);
;     const float mn = fmaxf(st.m, mx);
;     const float corr = __builtin_amdgcn_exp2f(st.m - mn);
;     st.m = mn;
;     const float mm = fmaxf(mn, -1e20f);
;     float ls = 0.f;
; #pragma unroll
;     for (int t = 0; t < 2; ++t) {
;       if (!(TM & (1 << t))) continue;
;       const float am = addc[t] - mm;
; #pragma unroll
;       for (int kt = 0; kt < 4; ++kt) {
;         const f32x4 e = S[t][kt] * sclc[t] + am;
; #pragma unroll
;         for (int j = 0; j < 4; ++j) {
;           float pv = __builtin_amdgcn_exp2f(e[j]);
;           S[t][kt][j] = pv;
;           ls += pv;
;         }
;       }
;     }
;     st.l = st.l * corr + ls;
;     if (MODE != M_CMPA) {
; #pragma unroll
;       for (int nt = 0; nt < 4; ++nt) O[nt] *= corr;
;     }
;   }
;   if (MODE == M_CMPA) return;
;   __builtin_amdgcn_s_setprio(1);
; #pragma unroll
;   for (int t = 0; t < 2; ++t) {
;     if (!(TM & (1 << t))) continue;
;     const h16* Vt = t ? Vt1 : Vt0;
; #pragma unroll
;     for (int ks = 0; ks < 2; ++ks) {
;       h16x8 Pf;
; #pragma unroll
;       for (int i = 0; i < 4; ++i) { Pf[i] = (h16)S[t][2 * ks][i]; Pf[4 + i] = (h16)S[t][2 * ks + 1][i]; }
; #pragma unroll
;       for (int nt = 0; nt < 4; ++nt) {
;         const h16* vp = Vt + (ks * 32 + q4 * 4 + (col >> 2)) * KP + nt * 16 + 4 * (col & 3);
;         const s16x4v r0 = __builtin_amdgcn_ds_read_tr16_b64_v4i16((LAS s16x4v*)vp);
;         const s16x4v r1 = __builtin_amdgcn_ds_read_tr16_b64_v4i16((LAS s16x4v*)(vp + 16 * KP));
;         const h16x4 v0 = __builtin_bit_cast(h16x4, r0), v1 = __builtin_bit_cast(h16x4, r1);
;         const h16x8 Vf = {v0[0], v0[1], v0[2], v0[3], v1[0], v1[1], v1[2], v1[3]};
;         O[nt] = __builtin_amdgcn_mfma_f32_16x16x32_f16(Vf, Pf, O[nt], 0, 0, 0);
;       }
.LBB0_1702:
	v_max3_f32 v3, v40, s67, v41
	v_max3_f32 v3, v3, v42, v43
	v_max3_f32 v3, v3, v36, v37
	v_max3_f32 v3, v3, v38, v39
	v_max3_f32 v3, v3, v32, v33
	v_max3_f32 v3, v3, v34, v35
	v_max3_f32 v3, v3, v28, v29
	v_max3_f32 v3, v3, v30, v31
	s_waitcnt lgkmcnt(0)
	v_fma_f32 v3, s0, v3, v2
	v_max_f32_e32 v3, 0xf149f2ca, v3
	v_mov_b32_e32 v96, v3
	s_nop 1
	v_permlane16_swap_b32_e32 v96, v3
	s_waitcnt lgkmcnt(0)
	v_max_f32_e32 v96, v96, v96
	v_max_f32_e32 v3, v3, v96
	v_mov_b32_e32 v96, v3
	s_nop 1
	v_permlane32_swap_b32_e32 v3, v96
	v_max3_f32 v173, v244, v3, v96
	v_max_f32_e32 v96, 0xe0ad78ec, v173
	v_sub_f32_e32 v2, v2, v96
	v_fma_f32 v40, s0, v40, v2
	v_fma_f32 v41, s0, v41, v2
	v_exp_f32_e32 v96, v40
	v_fma_f32 v42, s0, v42, v2
	v_exp_f32_e32 v100, v41
	v_fma_f32 v40, s0, v43, v2
	v_exp_f32_e32 v97, v42
	v_exp_f32_e32 v101, v40
	v_fma_f32 v36, s0, v36, v2
	v_add_f32_e32 v41, 0, v96
	v_exp_f32_e32 v98, v36
	v_fma_f32 v37, s0, v37, v2
	v_add_f32_e32 v36, v100, v41
	v_exp_f32_e32 v102, v37
	v_fma_f32 v37, s0, v38, v2
	v_add_f32_e32 v36, v97, v36
	v_exp_f32_e32 v99, v37
	v_fma_f32 v37, s0, v39, v2
	v_add_f32_e32 v36, v101, v36
	v_exp_f32_e32 v103, v37
	v_fma_f32 v32, s0, v32, v2
	v_add_f32_e32 v36, v98, v36
	v_exp_f32_e32 v108, v32
	v_fma_f32 v33, s0, v33, v2
	v_add_f32_e32 v32, v102, v36
	v_exp_f32_e32 v109, v33
	v_fma_f32 v33, s0, v34, v2
	v_add_f32_e32 v32, v99, v32
	v_exp_f32_e32 v110, v33
	v_fma_f32 v33, s0, v35, v2
	v_add_f32_e32 v32, v103, v32
	v_exp_f32_e32 v111, v33
	v_fma_f32 v28, s0, v28, v2
	v_add_f32_e32 v32, v108, v32
	v_exp_f32_e32 v112, v28
	v_fma_f32 v29, s0, v29, v2
	v_add_f32_e32 v28, v109, v32
	v_exp_f32_e32 v113, v29
	v_fma_f32 v29, s0, v30, v2
	v_add_f32_e32 v28, v110, v28
	v_exp_f32_e32 v114, v29
	v_fmac_f32_e32 v2, s0, v31
	v_sub_f32_e32 v3, v244, v173
	v_add_f32_e32 v28, v111, v28
	v_exp_f32_e32 v115, v2
	v_add_f32_e32 v28, v112, v28
	v_exp_f32_e32 v2, v3
	v_add_f32_e32 v3, v113, v28
	v_add_f32_e32 v3, v114, v3
	v_add_f32_e32 v243, v115, v3
	v_fmac_f32_e32 v243, v188, v2
	v_pk_mul_f32 v[30:31], v[82:83], v[2:3] op_sel_hi:[1,0]
	v_pk_mul_f32 v[28:29], v[80:81], v[2:3] op_sel_hi:[1,0]
	v_pk_mul_f32 v[34:35], v[86:87], v[2:3] op_sel_hi:[1,0]
	v_pk_mul_f32 v[32:33], v[84:85], v[2:3] op_sel_hi:[1,0]
	v_pk_mul_f32 v[38:39], v[90:91], v[2:3] op_sel_hi:[1,0]
	v_pk_mul_f32 v[36:37], v[88:89], v[2:3] op_sel_hi:[1,0]
	v_pk_mul_f32 v[42:43], v[94:95], v[2:3] op_sel_hi:[1,0]
	v_pk_mul_f32 v[40:41], v[92:93], v[2:3] op_sel_hi:[1,0]
	s_setprio 1
	v_cvt_pk_f16_f32 v99, v99, v103
	v_cvt_pk_f16_f32 v98, v98, v102
	v_cvt_pk_f16_f32 v97, v97, v101
	v_cvt_pk_f16_f32 v96, v96, v100
	ds_read_b64_tr_b16 v[102:103], v206 offset:2560
	ds_read_b64_tr_b16 v[106:107], v206 offset:2592
	ds_read_b64_tr_b16 v[100:101], v205 offset:64000
	ds_read_b64_tr_b16 v[104:105], v205 offset:64032
	s_waitcnt lgkmcnt(1)
	v_mfma_f32_16x16x32_f16 v[28:31], v[100:103], v[96:99], v[28:31]
	ds_read_b64_tr_b16 v[100:101], v205 offset:64064
	ds_read_b64_tr_b16 v[102:103], v206 offset:2624
	s_mov_b64 s[48:49], -1
	s_waitcnt lgkmcnt(0)
	v_mfma_f32_16x16x32_f16 v[36:39], v[100:103], v[96:99], v[36:39]
	ds_read_b64_tr_b16 v[100:101], v205 offset:64096
	ds_read_b64_tr_b16 v[102:103], v206 offset:2656
	s_waitcnt lgkmcnt(0)
	v_mfma_f32_16x16x32_f16 v[40:43], v[100:103], v[96:99], v[40:43]
	ds_read_b64_tr_b16 v[100:101], v206 offset:5120
	ds_read_b64_tr_b16 v[102:103], v206 offset:7680
	v_mfma_f32_16x16x32_f16 v[32:35], v[104:107], v[96:99], v[32:35]
	v_cvt_pk_f16_f32 v99, v114, v115
	v_cvt_pk_f16_f32 v98, v112, v113
	v_cvt_pk_f16_f32 v97, v110, v111
	v_cvt_pk_f16_f32 v96, v108, v109
	s_waitcnt lgkmcnt(0)
	s_nop 0
	v_mfma_f32_16x16x32_f16 v[28:31], v[100:103], v[96:99], v[28:31]
	ds_read_b64_tr_b16 v[100:101], v206 offset:5152
	ds_read_b64_tr_b16 v[102:103], v206 offset:7712
	s_waitcnt lgkmcnt(0)
	v_mfma_f32_16x16x32_f16 v[32:35], v[100:103], v[96:99], v[32:35]
	ds_read_b64_tr_b16 v[100:101], v206 offset:5184
	ds_read_b64_tr_b16 v[102:103], v206 offset:7744
	s_waitcnt lgkmcnt(0)
	v_mfma_f32_16x16x32_f16 v[36:39], v[100:103], v[96:99], v[36:39]
	ds_read_b64_tr_b16 v[100:101], v206 offset:5216
	ds_read_b64_tr_b16 v[102:103], v206 offset:7776
	s_waitcnt lgkmcnt(0)
	v_mfma_f32_16x16x32_f16 v[40:43], v[100:103], v[96:99], v[40:43]
	s_branch .LBB0_1783

; #define LAS __attribute__((address_space(3)))
; template <int MODE, int TM> ...
;     ...
;     float mx = -1e30f;
; #pragma unroll
;     for (int t = 0; t < 2; ++t) {
;       if (!(TM & (1 << t))) continue;
;       float mt = -1e30f;
; #pragma unroll
;       for (int kt = 0; kt < 4; ++kt)
; #pragma unroll
;         for (int j = 0; j < 4; ++j) mt = fmaxf(mt, S[t][kt][j]);
;       mx = fmaxf(mx, mt * sclc[t] + addc[t]);
;     }
;     mx = max4q(mx);
;     const float mn = fmaxf(st.m, mx);
;     const float corr = __builtin_amdgcn_exp2f(st.m - mn);
;     st.m = mn;
;     const float mm = fmaxf(mn, -1e20f);
;     float ls = 0.f;
; #pragma unroll
;     for (int t = 0; t < 2; ++t) {
;       if (!(TM & (1 << t))) continue;
;       const float am = addc[t] - mm;
; #pragma unroll
;       for (int kt = 0; kt < 4; ++kt) {
;         const f32x4 e = S[t][kt] * sclc[t] + am;
; #pragma unroll
;         for (int j = 0; j < 4; ++j) {
;           float pv = __builtin_amdgcn_exp2f(e[j]);
;           S[t][kt][j] = pv;
;           ls += pv;
;         }
;       }
;     }
;     st.l = st.l * corr + ls;
;     if (MODE != M_CMPA) {
; #pragma unroll
;       for (int nt = 0; nt < 4; ++nt) O[nt] *= corr;
;     }
;   }
;   if (MODE == M_CMPA) return;
;   __builtin_amdgcn_s_setprio(1);
; #pragma unroll
;   for (int t = 0; t < 2; ++t) {
;     if (!(TM & (1 << t))) continue;
;     const h16* Vt = t ? Vt1 : Vt0;
; #pragma unroll
;     for (int ks = 0; ks < 2; ++ks) {
;       h16x8 Pf;
; #pragma unroll
;       for (int i = 0; i < 4; ++i) { Pf[i] = (h16)S[t][2 * ks][i]; Pf[4 + i] = (h16)S[t][2 * ks + 1][i]; }
; #pragma unroll
;       for (int nt = 0; nt < 4; ++nt) {
;         const h16* vp = Vt + (ks * 32 + q4 * 4 + (col >> 2)) * KP + nt * 16 + 4 * (col & 3);
;         const s16x4v r0 = __builtin_amdgcn_ds_read_tr16_b64_v4i16((LAS s16x4v*)vp);
;         const s16x4v r1 = __builtin_amdgcn_ds_read_tr16_b64_v4i16((LAS s16x4v*)(vp + 16 * KP));
;         const h16x4 v0 = __builtin_bit_cast(h16x4, r0), v1 = __builtin_bit_cast(h16x4, r1);
;         const h16x8 Vf = {v0[0], v0[1], v0[2], v0[3], v1[0], v1[1], v1[2], v1[3]};
;         O[nt] = __builtin_amdgcn_mfma_f32_16x16x32_f16(Vf, Pf, O[nt], 0, 0, 0);
;       }
.LBB0_1704:
	v_max3_f32 v3, v32, s67, v33
	v_max3_f32 v3, v3, v34, v35
	v_max3_f32 v3, v3, v28, v29
	v_max3_f32 v3, v3, v30, v31
	v_max3_f32 v3, v3, v40, v41
	v_max3_f32 v3, v3, v42, v43
	v_max3_f32 v3, v3, v36, v37
	v_max3_f32 v3, v3, v38, v39
	s_waitcnt lgkmcnt(0)
	v_fma_f32 v3, s3, v3, v2
	v_max_f32_e32 v3, 0xf149f2ca, v3
	v_mov_b32_e32 v96, v3
	s_nop 1
	v_permlane16_swap_b32_e32 v96, v3
	s_waitcnt lgkmcnt(0)
	v_max_f32_e32 v96, v96, v96
	v_max_f32_e32 v3, v3, v96
	v_mov_b32_e32 v96, v3
	s_nop 1
	v_permlane32_swap_b32_e32 v3, v96
	v_max3_f32 v173, v244, v3, v96
	v_max_f32_e32 v96, 0xe0ad78ec, v173
	v_sub_f32_e32 v2, v2, v96
	v_fma_f32 v28, s3, v28, v2
	v_exp_f32_e32 v98, v28
	v_fma_f32 v28, s3, v29, v2
	v_exp_f32_e32 v102, v28
	v_fma_f32 v28, s3, v30, v2
	v_exp_f32_e32 v99, v28
	v_fma_f32 v28, s3, v31, v2
	v_exp_f32_e32 v103, v28
	v_fma_f32 v28, s3, v40, v2
	v_exp_f32_e32 v108, v28
	v_fma_f32 v28, s3, v41, v2
	v_fma_f32 v32, s3, v32, v2
	v_exp_f32_e32 v109, v28
	v_fma_f32 v28, s3, v42, v2
	v_fma_f32 v33, s3, v33, v2
	v_exp_f32_e32 v96, v32
	v_exp_f32_e32 v110, v28
	v_fma_f32 v28, s3, v43, v2
	v_exp_f32_e32 v100, v33
	v_fma_f32 v32, s3, v34, v2
	v_exp_f32_e32 v111, v28
	v_fma_f32 v28, s3, v36, v2
	v_exp_f32_e32 v97, v32
	v_fma_f32 v32, s3, v35, v2
	v_exp_f32_e32 v112, v28
	v_fma_f32 v28, s3, v37, v2
	v_exp_f32_e32 v101, v32
	v_exp_f32_e32 v113, v28
	v_fma_f32 v28, s3, v38, v2
	v_fmac_f32_e32 v2, s3, v39
	v_exp_f32_e32 v115, v2
	v_add_f32_e32 v2, 0, v96
	v_add_f32_e32 v2, v100, v2
	v_add_f32_e32 v2, v97, v2
	v_add_f32_e32 v2, v101, v2
	v_add_f32_e32 v2, v98, v2
	v_add_f32_e32 v2, v102, v2
	v_add_f32_e32 v2, v99, v2
	v_add_f32_e32 v2, v103, v2
	v_add_f32_e32 v2, v108, v2
	v_add_f32_e32 v2, v109, v2
	v_exp_f32_e32 v114, v28
	v_add_f32_e32 v2, v110, v2
	v_sub_f32_e32 v3, v244, v173
	v_add_f32_e32 v2, v111, v2
	v_add_f32_e32 v28, v112, v2
	v_exp_f32_e32 v2, v3
	v_add_f32_e32 v3, v113, v28
	v_add_f32_e32 v3, v114, v3
	v_add_f32_e32 v243, v115, v3
	v_fmac_f32_e32 v243, v188, v2
	v_pk_mul_f32 v[30:31], v[82:83], v[2:3] op_sel_hi:[1,0]
	v_pk_mul_f32 v[28:29], v[80:81], v[2:3] op_sel_hi:[1,0]
	v_pk_mul_f32 v[34:35], v[86:87], v[2:3] op_sel_hi:[1,0]
	v_pk_mul_f32 v[32:33], v[84:85], v[2:3] op_sel_hi:[1,0]
	v_pk_mul_f32 v[38:39], v[90:91], v[2:3] op_sel_hi:[1,0]
	v_pk_mul_f32 v[36:37], v[88:89], v[2:3] op_sel_hi:[1,0]
	v_pk_mul_f32 v[42:43], v[94:95], v[2:3] op_sel_hi:[1,0]
	v_pk_mul_f32 v[40:41], v[92:93], v[2:3] op_sel_hi:[1,0]
	s_setprio 1
	v_cvt_pk_f16_f32 v99, v99, v103
	v_cvt_pk_f16_f32 v98, v98, v102
	v_cvt_pk_f16_f32 v97, v97, v101
	v_cvt_pk_f16_f32 v96, v96, v100
	ds_read_b64_tr_b16 v[102:103], v208 offset:2560
	ds_read_b64_tr_b16 v[100:101], v208
	ds_read_b64_tr_b16 v[104:105], v208 offset:32
	s_waitcnt lgkmcnt(1)
	v_mfma_f32_16x16x32_f16 v[28:31], v[100:103], v[96:99], v[28:31]
	ds_read_b64_tr_b16 v[106:107], v208 offset:2592
	ds_read_b64_tr_b16 v[100:101], v208 offset:64
	ds_read_b64_tr_b16 v[102:103], v208 offset:2624
	s_mov_b64 s[48:49], -1
	s_waitcnt lgkmcnt(0)
	v_mfma_f32_16x16x32_f16 v[36:39], v[100:103], v[96:99], v[36:39]
	ds_read_b64_tr_b16 v[100:101], v208 offset:96
	ds_read_b64_tr_b16 v[102:103], v208 offset:2656
	s_waitcnt lgkmcnt(0)
	v_mfma_f32_16x16x32_f16 v[40:43], v[100:103], v[96:99], v[40:43]
	ds_read_b64_tr_b16 v[100:101], v208 offset:5120
	ds_read_b64_tr_b16 v[102:103], v208 offset:7680
	v_mfma_f32_16x16x32_f16 v[32:35], v[104:107], v[96:99], v[32:35]
	v_cvt_pk_f16_f32 v99, v114, v115
	v_cvt_pk_f16_f32 v98, v112, v113
	v_cvt_pk_f16_f32 v97, v110, v111
	v_cvt_pk_f16_f32 v96, v108, v109
	s_waitcnt lgkmcnt(0)
	s_nop 0
	v_mfma_f32_16x16x32_f16 v[28:31], v[100:103], v[96:99], v[28:31]
	ds_read_b64_tr_b16 v[100:101], v208 offset:5152
	ds_read_b64_tr_b16 v[102:103], v208 offset:7712
	s_waitcnt lgkmcnt(0)
	v_mfma_f32_16x16x32_f16 v[32:35], v[100:103], v[96:99], v[32:35]
	ds_read_b64_tr_b16 v[100:101], v208 offset:5184
	ds_read_b64_tr_b16 v[102:103], v208 offset:7744
	s_waitcnt lgkmcnt(0)
	v_mfma_f32_16x16x32_f16 v[36:39], v[100:103], v[96:99], v[36:39]
	ds_read_b64_tr_b16 v[100:101], v208 offset:5216
	ds_read_b64_tr_b16 v[102:103], v208 offset:7776
	s_waitcnt lgkmcnt(0)
	v_mfma_f32_16x16x32_f16 v[40:43], v[100:103], v[96:99], v[40:43]
	s_and_b64 vcc, exec, s[0:1]
	s_cbranch_vccnz .LBB0_1663

; #define LAS __attribute__((address_space(3)))
; template <int MODE, int TM> ...
;     ...
;     float mx = -1e30f;
; #pragma unroll
;     for (int t = 0; t < 2; ++t) {
;       if (!(TM & (1 << t))) continue;
;       float mt = -1e30f;
; #pragma unroll
;       for (int kt = 0; kt < 4; ++kt)
; #pragma unroll
;         for (int j = 0; j < 4; ++j) mt = fmaxf(mt, S[t][kt][j]);
;       mx = fmaxf(mx, mt * sclc[t] + addc[t]);
;     }
;     mx = max4q(mx);
;     const float mn = fmaxf(st.m, mx);
;     const float corr = __builtin_amdgcn_exp2f(st.m - mn);
;     st.m = mn;
;     const float mm = fmaxf(mn, -1e20f);
;     float ls = 0.f;
; #pragma unroll
;     for (int t = 0; t < 2; ++t) {
;       if (!(TM & (1 << t))) continue;
;       const float am = addc[t] - mm;
; #pragma unroll
;       for (int kt = 0; kt < 4; ++kt) {
;         const f32x4 e = S[t][kt] * sclc[t] + am;
; #pragma unroll
;         for (int j = 0; j < 4; ++j) {
;           float pv = __builtin_amdgcn_exp2f(e[j]);
;           S[t][kt][j] = pv;
;           ls += pv;
;         }
;       }
;     }
;     st.l = st.l * corr + ls;
;     if (MODE != M_CMPA) {
; #pragma unroll
;       for (int nt = 0; nt < 4; ++nt) O[nt] *= corr;
;     }
;   }
;   if (MODE == M_CMPA) return;
;   __builtin_amdgcn_s_setprio(1);
; #pragma unroll
;   for (int t = 0; t < 2; ++t) {
;     if (!(TM & (1 << t))) continue;
;     const h16* Vt = t ? Vt1 : Vt0;
; #pragma unroll
;     for (int ks = 0; ks < 2; ++ks) {
;       h16x8 Pf;
; #pragma unroll
;       for (int i = 0; i < 4; ++i) { Pf[i] = (h16)S[t][2 * ks][i]; Pf[4 + i] = (h16)S[t][2 * ks + 1][i]; }
; #pragma unroll
;       for (int nt = 0; nt < 4; ++nt) {
;         const h16* vp = Vt + (ks * 32 + q4 * 4 + (col >> 2)) * KP + nt * 16 + 4 * (col & 3);
;         const s16x4v r0 = __builtin_amdgcn_ds_read_tr16_b64_v4i16((LAS s16x4v*)vp);
;         const s16x4v r1 = __builtin_amdgcn_ds_read_tr16_b64_v4i16((LAS s16x4v*)(vp + 16 * KP));
;         const h16x4 v0 = __builtin_bit_cast(h16x4, r0), v1 = __builtin_bit_cast(h16x4, r1);
;         const h16x8 Vf = {v0[0], v0[1], v0[2], v0[3], v1[0], v1[1], v1[2], v1[3]};
;         O[nt] = __builtin_amdgcn_mfma_f32_16x16x32_f16(Vf, Pf, O[nt], 0, 0, 0);
;       }
.LBB0_1782:
	s_waitcnt lgkmcnt(0)
	v_max3_f32 v0, v40, s67, v41
	v_max3_f32 v96, v112, s67, v113
	v_max3_f32 v0, v0, v42, v43
	v_max3_f32 v96, v96, v114, v115
	v_max3_f32 v0, v0, v36, v37
	v_max3_f32 v96, v96, v116, v117
	v_max3_f32 v0, v0, v38, v39
	v_max3_f32 v96, v96, v118, v119
	v_max3_f32 v0, v0, v32, v33
	v_max3_f32 v96, v96, v120, v121
	v_max3_f32 v0, v0, v34, v35
	v_max3_f32 v96, v96, v122, v123
	v_max3_f32 v0, v0, v28, v29
	v_max3_f32 v96, v96, v124, v125
	v_max3_f32 v0, v0, v30, v31
	v_max3_f32 v96, v96, v126, v127
	v_fma_f32 v0, s2, v0, v2
	v_fma_f32 v96, s3, v96, v3
	v_max3_f32 v0, v0, s67, v96
	v_mov_b32_e32 v96, v0
	s_nop 1
	v_permlane16_swap_b32_e32 v96, v0
	s_waitcnt lgkmcnt(0)
	v_max_f32_e32 v96, v96, v96
	v_max_f32_e32 v0, v0, v96
	v_mov_b32_e32 v96, v0
	s_nop 1
	v_permlane32_swap_b32_e32 v0, v96
	v_max3_f32 v173, v244, v0, v96
	v_max_f32_e32 v0, 0xe0ad78ec, v173
	v_sub_f32_e32 v2, v2, v0
	v_fma_f32 v40, s2, v40, v2
	v_exp_f32_e32 v96, v40
	v_fma_f32 v41, s2, v41, v2
	v_exp_f32_e32 v98, v41
	v_fma_f32 v41, s2, v42, v2
	v_exp_f32_e32 v99, v41
	v_fma_f32 v41, s2, v43, v2
	v_exp_f32_e32 v100, v41
	v_fma_f32 v36, s2, v36, v2
	v_add_f32_e32 v97, 0, v96
	v_exp_f32_e32 v101, v36
	v_fma_f32 v37, s2, v37, v2
	v_add_f32_e32 v36, v98, v97
	v_exp_f32_e32 v97, v37
	v_fma_f32 v37, s2, v38, v2
	v_add_f32_e32 v36, v99, v36
	v_exp_f32_e32 v102, v37
	v_fma_f32 v37, s2, v39, v2
	v_add_f32_e32 v36, v100, v36
	v_exp_f32_e32 v103, v37
	v_fma_f32 v32, s2, v32, v2
	v_add_f32_e32 v36, v101, v36
	v_exp_f32_e32 v104, v32
	v_fma_f32 v33, s2, v33, v2
	v_add_f32_e32 v32, v97, v36
	v_exp_f32_e32 v105, v33
	v_fma_f32 v33, s2, v34, v2
	v_add_f32_e32 v32, v102, v32
	v_exp_f32_e32 v106, v33
	v_fma_f32 v33, s2, v35, v2
	v_add_f32_e32 v32, v103, v32
	v_exp_f32_e32 v107, v33
	v_fma_f32 v28, s2, v28, v2
	v_add_f32_e32 v32, v104, v32
	v_exp_f32_e32 v108, v28
	v_fma_f32 v29, s2, v29, v2
	v_add_f32_e32 v28, v105, v32
	v_exp_f32_e32 v109, v29
	v_fma_f32 v29, s2, v30, v2
	v_add_f32_e32 v28, v106, v28
	v_exp_f32_e32 v110, v29
	v_fmac_f32_e32 v2, s2, v31
	v_sub_f32_e32 v0, v3, v0
	v_add_f32_e32 v28, v107, v28
	v_exp_f32_e32 v2, v2
	v_fma_f32 v3, s3, v112, v0
	v_add_f32_e32 v28, v108, v28
	v_exp_f32_e32 v3, v3
	v_fma_f32 v29, s3, v113, v0
	v_add_f32_e32 v28, v109, v28
	v_exp_f32_e32 v111, v29
	v_fma_f32 v29, s3, v114, v0
	v_add_f32_e32 v28, v110, v28
	v_exp_f32_e32 v112, v29
	v_fma_f32 v29, s3, v115, v0
	v_add_f32_e32 v28, v2, v28
	v_exp_f32_e32 v113, v29
	v_fma_f32 v29, s3, v116, v0
	v_add_f32_e32 v28, v3, v28
	v_exp_f32_e32 v114, v29
	v_fma_f32 v29, s3, v117, v0
	v_add_f32_e32 v28, v111, v28
	v_exp_f32_e32 v115, v29
	v_fma_f32 v29, s3, v118, v0
	v_add_f32_e32 v28, v112, v28
	v_exp_f32_e32 v116, v29
	v_fma_f32 v29, s3, v119, v0
	v_add_f32_e32 v28, v113, v28
	v_exp_f32_e32 v117, v29
	v_fma_f32 v29, s3, v120, v0
	v_add_f32_e32 v28, v114, v28
	v_exp_f32_e32 v118, v29
	v_fma_f32 v29, s3, v121, v0
	v_add_f32_e32 v28, v115, v28
	v_exp_f32_e32 v119, v29
	v_fma_f32 v29, s3, v122, v0
	v_add_f32_e32 v28, v116, v28
	v_exp_f32_e32 v120, v29
	v_fma_f32 v29, s3, v123, v0
	v_add_f32_e32 v28, v117, v28
	v_exp_f32_e32 v121, v29
	v_fma_f32 v29, s3, v124, v0
	v_add_f32_e32 v28, v118, v28
	v_exp_f32_e32 v122, v29
	v_fma_f32 v29, s3, v125, v0
	v_add_f32_e32 v28, v119, v28
	v_exp_f32_e32 v123, v29
	v_fma_f32 v29, s3, v126, v0
	v_add_f32_e32 v28, v120, v28
	v_exp_f32_e32 v124, v29
	v_fmac_f32_e32 v0, s3, v127
	v_sub_f32_e32 v40, v244, v173
	v_add_f32_e32 v28, v121, v28
	v_exp_f32_e32 v125, v0
	v_add_f32_e32 v28, v122, v28
	v_exp_f32_e32 v0, v40
	v_add_f32_e32 v28, v123, v28
	v_add_f32_e32 v28, v124, v28
	v_add_f32_e32 v243, v125, v28
	v_fmac_f32_e32 v243, v188, v0
	v_pk_mul_f32 v[30:31], v[82:83], v[0:1] op_sel_hi:[1,0]
	v_pk_mul_f32 v[28:29], v[80:81], v[0:1] op_sel_hi:[1,0]
	v_pk_mul_f32 v[34:35], v[86:87], v[0:1] op_sel_hi:[1,0]
	v_pk_mul_f32 v[32:33], v[84:85], v[0:1] op_sel_hi:[1,0]
	v_pk_mul_f32 v[38:39], v[90:91], v[0:1] op_sel_hi:[1,0]
	v_pk_mul_f32 v[36:37], v[88:89], v[0:1] op_sel_hi:[1,0]
	v_pk_mul_f32 v[42:43], v[94:95], v[0:1] op_sel_hi:[1,0]
	v_pk_mul_f32 v[40:41], v[92:93], v[0:1] op_sel_hi:[1,0]
	s_setprio 1
	ds_read_b64_tr_b16 v[86:87], v206 offset:2560
	ds_read_b64_tr_b16 v[90:91], v206 offset:2592
	ds_read_b64_tr_b16 v[84:85], v205 offset:64000
	ds_read_b64_tr_b16 v[88:89], v205 offset:64032
	v_cvt_pk_f16_f32 v83, v102, v103
	v_cvt_pk_f16_f32 v82, v101, v97
	v_cvt_pk_f16_f32 v81, v99, v100
	v_cvt_pk_f16_f32 v80, v96, v98
	s_mov_b64 s[48:49], -1
	s_waitcnt lgkmcnt(1)
; #define LAS __attribute__((address_space(3)))
; template <int MODE, int TM> ...
;     ...
;   __builtin_amdgcn_s_setprio(1);
; #pragma unroll
;   for (int t = 0; t < 2; ++t) {
;     if (!(TM & (1 << t))) continue;
;     const h16* Vt = t ? Vt1 : Vt0;
; #pragma unroll
;     for (int ks = 0; ks < 2; ++ks) {
;       h16x8 Pf;
; #pragma unroll
;       for (int i = 0; i < 4; ++i) { Pf[i] = (h16)S[t][2 * ks][i]; Pf[4 + i] = (h16)S[t][2 * ks + 1][i]; }
; #pragma unroll
;       for (int nt = 0; nt < 4; ++nt) {
;         const h16* vp = Vt + (ks * 32 + q4 * 4 + (col >> 2)) * KP + nt * 16 + 4 * (col & 3);
;         const s16x4v r0 = __builtin_amdgcn_ds_read_tr16_b64_v4i16((LAS s16x4v*)vp);
;         const s16x4v r1 = __builtin_amdgcn_ds_read_tr16_b64_v4i16((LAS s16x4v*)(vp + 16 * KP));
;         const h16x4 v0 = __builtin_bit_cast(h16x4, r0), v1 = __builtin_bit_cast(h16x4, r1);
;         const h16x8 Vf = {v0[0], v0[1], v0[2], v0[3], v1[0], v1[1], v1[2], v1[3]};
;         O[nt] = __builtin_amdgcn_mfma_f32_16x16x32_f16(Vf, Pf, O[nt], 0, 0, 0);
;       }
;     }
;   }
;   __builtin_amdgcn_s_setprio(0);
	v_mfma_f32_16x16x32_f16 v[28:31], v[84:87], v[80:83], v[28:31]
	ds_read_b64_tr_b16 v[84:85], v205 offset:64064
	ds_read_b64_tr_b16 v[86:87], v206 offset:2624
	s_waitcnt lgkmcnt(0)
	v_mfma_f32_16x16x32_f16 v[36:39], v[84:87], v[80:83], v[36:39]
	ds_read_b64_tr_b16 v[84:85], v205 offset:64096
	ds_read_b64_tr_b16 v[86:87], v206 offset:2656
	v_mfma_f32_16x16x32_f16 v[32:35], v[88:91], v[80:83], v[32:35]
	s_waitcnt lgkmcnt(0)
	v_mfma_f32_16x16x32_f16 v[40:43], v[84:87], v[80:83], v[40:43]
	ds_read_b64_tr_b16 v[86:87], v207 offset:2560
	ds_read_b64_tr_b16 v[84:85], v207
	ds_read_b64_tr_b16 v[88:89], v207 offset:32
	v_cvt_pk_f16_f32 v83, v110, v2
	v_cvt_pk_f16_f32 v82, v108, v109
	v_cvt_pk_f16_f32 v81, v106, v107
	v_cvt_pk_f16_f32 v80, v104, v105
	ds_read_b64_tr_b16 v[90:91], v207 offset:2592
	s_waitcnt lgkmcnt(2)
	v_mfma_f32_16x16x32_f16 v[28:31], v[84:87], v[80:83], v[28:31]
	ds_read_b64_tr_b16 v[84:85], v207 offset:64
	ds_read_b64_tr_b16 v[86:87], v207 offset:2624
	s_waitcnt lgkmcnt(0)
	v_mfma_f32_16x16x32_f16 v[36:39], v[84:87], v[80:83], v[36:39]
	ds_read_b64_tr_b16 v[84:85], v207 offset:96
	ds_read_b64_tr_b16 v[86:87], v207 offset:2656
	v_mfma_f32_16x16x32_f16 v[32:35], v[88:91], v[80:83], v[32:35]
	s_waitcnt lgkmcnt(0)
	v_mfma_f32_16x16x32_f16 v[40:43], v[84:87], v[80:83], v[40:43]
	ds_read_b64_tr_b16 v[86:87], v208 offset:2560
	ds_read_b64_tr_b16 v[84:85], v208
	ds_read_b64_tr_b16 v[88:89], v208 offset:32
	v_cvt_pk_f16_f32 v83, v116, v117
	v_cvt_pk_f16_f32 v82, v114, v115
	v_cvt_pk_f16_f32 v81, v112, v113
	v_cvt_pk_f16_f32 v80, v3, v111
	ds_read_b64_tr_b16 v[90:91], v208 offset:2592
	s_waitcnt lgkmcnt(2)
	v_mfma_f32_16x16x32_f16 v[28:31], v[84:87], v[80:83], v[28:31]
	ds_read_b64_tr_b16 v[84:85], v208 offset:64
	ds_read_b64_tr_b16 v[86:87], v208 offset:2624
	s_waitcnt lgkmcnt(0)
	v_mfma_f32_16x16x32_f16 v[36:39], v[84:87], v[80:83], v[36:39]
	ds_read_b64_tr_b16 v[84:85], v208 offset:96
	ds_read_b64_tr_b16 v[86:87], v208 offset:2656
	s_waitcnt lgkmcnt(0)
	v_mfma_f32_16x16x32_f16 v[40:43], v[84:87], v[80:83], v[40:43]
	ds_read_b64_tr_b16 v[84:85], v208 offset:5120
	ds_read_b64_tr_b16 v[86:87], v208 offset:7680
	v_mfma_f32_16x16x32_f16 v[32:35], v[88:91], v[80:83], v[32:35]
	v_cvt_pk_f16_f32 v83, v124, v125
	v_cvt_pk_f16_f32 v82, v122, v123
	v_cvt_pk_f16_f32 v81, v120, v121
	v_cvt_pk_f16_f32 v80, v118, v119
	s_waitcnt lgkmcnt(0)
	s_nop 0
	v_mfma_f32_16x16x32_f16 v[28:31], v[84:87], v[80:83], v[28:31]
	ds_read_b64_tr_b16 v[84:85], v208 offset:5152
	ds_read_b64_tr_b16 v[86:87], v208 offset:7712
	s_waitcnt lgkmcnt(0)
	v_mfma_f32_16x16x32_f16 v[32:35], v[84:87], v[80:83], v[32:35]
	ds_read_b64_tr_b16 v[84:85], v208 offset:5184
	ds_read_b64_tr_b16 v[86:87], v208 offset:7744
	s_waitcnt lgkmcnt(0)
	v_mfma_f32_16x16x32_f16 v[36:39], v[84:87], v[80:83], v[36:39]
	ds_read_b64_tr_b16 v[84:85], v208 offset:5216
	ds_read_b64_tr_b16 v[86:87], v208 offset:7776
	s_waitcnt lgkmcnt(0)
	v_mfma_f32_16x16x32_f16 v[40:43], v[84:87], v[80:83], v[40:43]

; #define LAS __attribute__((address_space(3)))
; template <int MODE, int TM> ...
;     ...
;     float mx = -1e30f;
; #pragma unroll
;     for (int t = 0; t < 2; ++t) {
;       if (!(TM & (1 << t))) continue;
;       float mt = -1e30f;
; #pragma unroll
;       for (int kt = 0; kt < 4; ++kt)
; #pragma unroll
;         for (int j = 0; j < 4; ++j) mt = fmaxf(mt, S[t][kt][j]);
;       mx = fmaxf(mx, mt * sclc[t] + addc[t]);
;     }
;     mx = max4q(mx);
;     const float mn = fmaxf(st.m, mx);
;     const float corr = __builtin_amdgcn_exp2f(st.m - mn);
;     st.m = mn;
;     const float mm = fmaxf(mn, -1e20f);
;     float ls = 0.f;
; #pragma unroll
;     for (int t = 0; t < 2; ++t) {
;       if (!(TM & (1 << t))) continue;
;       const float am = addc[t] - mm;
; #pragma unroll
;       for (int kt = 0; kt < 4; ++kt) {
;         const f32x4 e = S[t][kt] * sclc[t] + am;
; #pragma unroll
;         for (int j = 0; j < 4; ++j) {
;           float pv = __builtin_amdgcn_exp2f(e[j]);
;           S[t][kt][j] = pv;
;           ls += pv;
;         }
;       }
;     }
;     st.l = st.l * corr + ls;
;     if (MODE != M_CMPA) {
; #pragma unroll
;       for (int nt = 0; nt < 4; ++nt) O[nt] *= corr;
;     }
;   }
;   if (MODE == M_CMPA) return;
;   __builtin_amdgcn_s_setprio(1);
; #pragma unroll
;   for (int t = 0; t < 2; ++t) {
;     if (!(TM & (1 << t))) continue;
;     const h16* Vt = t ? Vt1 : Vt0;
; #pragma unroll
;     for (int ks = 0; ks < 2; ++ks) {
;       h16x8 Pf;
; #pragma unroll
;       for (int i = 0; i < 4; ++i) { Pf[i] = (h16)S[t][2 * ks][i]; Pf[4 + i] = (h16)S[t][2 * ks + 1][i]; }
; #pragma unroll
;       for (int nt = 0; nt < 4; ++nt) {
;         const h16* vp = Vt + (ks * 32 + q4 * 4 + (col >> 2)) * KP + nt * 16 + 4 * (col & 3);
;         const s16x4v r0 = __builtin_amdgcn_ds_read_tr16_b64_v4i16((LAS s16x4v*)vp);
;         const s16x4v r1 = __builtin_amdgcn_ds_read_tr16_b64_v4i16((LAS s16x4v*)(vp + 16 * KP));
;         const h16x4 v0 = __builtin_bit_cast(h16x4, r0), v1 = __builtin_bit_cast(h16x4, r1);
;         const h16x8 Vf = {v0[0], v0[1], v0[2], v0[3], v1[0], v1[1], v1[2], v1[3]};
;         O[nt] = __builtin_amdgcn_mfma_f32_16x16x32_f16(Vf, Pf, O[nt], 0, 0, 0);
;       }
.LBB0_1819:
	s_or_b64 exec, exec, s[0:1]
	v_max3_f32 v0, v173, s67, v127
	v_max3_f32 v78, v111, s67, v110
	v_max3_f32 v0, v0, v121, v120
	v_max3_f32 v78, v78, v89, v88
	v_max3_f32 v0, v0, v123, v122
	v_max3_f32 v78, v78, v91, v90
	v_max3_f32 v0, v0, v117, v116
	v_max3_f32 v78, v78, v85, v84
	v_max3_f32 v0, v0, v119, v118
	v_max3_f32 v78, v78, v87, v86
	v_max3_f32 v0, v0, v113, v112
	v_max3_f32 v78, v78, v81, v80
	v_max3_f32 v0, v0, v115, v114
	v_max3_f32 v78, v78, v83, v82
	v_max3_f32 v0, v0, v109, v108
	v_max3_f32 v78, v78, v77, v76
	v_add_f32_e32 v0, 0, v0
	v_add_f32_e32 v78, 0, v78
	v_max3_f32 v0, v0, s67, v78
	v_mov_b32_e32 v78, v0
	s_nop 1
	v_permlane16_swap_b32_e32 v78, v0
	s_waitcnt lgkmcnt(0)
	v_max_f32_e32 v78, v78, v78
	v_max_f32_e32 v0, v0, v78
	v_mov_b32_e32 v78, v0
	s_nop 1
	v_permlane32_swap_b32_e32 v0, v78
	v_max3_f32 v126, v2, v0, v78
	v_max_f32_e32 v0, 0xe0ad78ec, v126
	v_add_f32_e64 v78, v173, -v0
	v_exp_f32_e32 v173, v78
	v_add_f32_e64 v79, v127, -v0
	v_exp_f32_e32 v188, v79
	v_add_f32_e64 v79, v121, -v0
	v_exp_f32_e32 v121, v79
	v_add_f32_e64 v79, v120, -v0
	v_exp_f32_e32 v120, v79
	v_add_f32_e64 v79, v123, -v0
	v_add_f32_e32 v78, 0, v173
	v_exp_f32_e32 v123, v79
	v_add_f32_e64 v79, v122, -v0
	v_add_f32_e32 v78, v188, v78
	v_exp_f32_e32 v122, v79
	v_add_f32_e64 v79, v117, -v0
	v_add_f32_e32 v78, v121, v78
	v_exp_f32_e32 v117, v79
	v_add_f32_e64 v79, v116, -v0
	v_add_f32_e32 v78, v120, v78
	v_exp_f32_e32 v116, v79
	v_add_f32_e64 v79, v119, -v0
	v_add_f32_e32 v78, v123, v78
	v_exp_f32_e32 v119, v79
	v_add_f32_e64 v79, v118, -v0
	v_add_f32_e32 v78, v122, v78
	v_exp_f32_e32 v118, v79
	v_add_f32_e64 v79, v113, -v0
	v_add_f32_e32 v78, v117, v78
	v_exp_f32_e32 v113, v79
	v_add_f32_e64 v79, v112, -v0
	v_add_f32_e32 v78, v116, v78
	v_exp_f32_e32 v112, v79
	v_add_f32_e64 v79, v115, -v0
	v_add_f32_e32 v78, v119, v78
	v_exp_f32_e32 v115, v79
	v_add_f32_e64 v79, v114, -v0
	v_add_f32_e32 v78, v118, v78
	v_exp_f32_e32 v114, v79
	v_add_f32_e64 v79, v109, -v0
	v_add_f32_e32 v78, v113, v78
	v_exp_f32_e32 v109, v79
	v_add_f32_e64 v79, v108, -v0
	v_add_f32_e32 v78, v112, v78
	v_exp_f32_e32 v108, v79
	v_add_f32_e64 v79, v111, -v0
	v_add_f32_e32 v78, v115, v78
	v_exp_f32_e32 v111, v79
	v_add_f32_e64 v79, v110, -v0
	v_add_f32_e32 v78, v114, v78
	v_exp_f32_e32 v110, v79
	v_add_f32_e64 v79, v89, -v0
	v_add_f32_e32 v78, v109, v78
	v_exp_f32_e32 v189, v79
	v_add_f32_e64 v79, v88, -v0
	v_add_f32_e32 v78, v108, v78
	v_exp_f32_e32 v243, v79
	v_add_f32_e64 v79, v91, -v0
	v_add_f32_e32 v78, v111, v78
	v_exp_f32_e32 v244, v79
	v_add_f32_e64 v79, v90, -v0
	v_add_f32_e32 v78, v110, v78
	v_exp_f32_e32 v245, v79
	v_add_f32_e64 v79, v85, -v0
	v_add_f32_e32 v78, v189, v78
	v_exp_f32_e32 v246, v79
	v_add_f32_e64 v79, v84, -v0
	v_add_f32_e32 v78, v243, v78
	v_exp_f32_e32 v247, v79
	v_add_f32_e64 v79, v87, -v0
	v_add_f32_e32 v78, v244, v78
	v_exp_f32_e32 v248, v79
	v_add_f32_e64 v79, v86, -v0
	v_add_f32_e32 v78, v245, v78
	v_exp_f32_e32 v249, v79
	v_add_f32_e64 v79, v81, -v0
	v_add_f32_e32 v78, v246, v78
	v_exp_f32_e32 v250, v79
	v_add_f32_e64 v79, v80, -v0
	v_add_f32_e32 v78, v247, v78
	v_exp_f32_e32 v251, v79
	v_add_f32_e64 v79, v83, -v0
	v_add_f32_e32 v78, v248, v78
	v_exp_f32_e32 v252, v79
	v_add_f32_e64 v79, v82, -v0
	v_add_f32_e32 v78, v249, v78
	v_exp_f32_e32 v253, v79
	v_add_f32_e64 v77, v77, -v0
	v_add_f32_e32 v78, v250, v78
	v_exp_f32_e32 v195, v77
	v_add_f32_e64 v0, v76, -v0
	v_sub_f32_e32 v2, v2, v126
	v_add_f32_e32 v78, v251, v78
	v_exp_f32_e32 v200, v0
	v_add_f32_e32 v78, v252, v78
	v_exp_f32_e32 v0, v2
	v_add_f32_e32 v2, v253, v78
	v_add_f32_e32 v2, v195, v2
	v_add_f32_e32 v127, v200, v2
	v_fmac_f32_e32 v127, v3, v0
	v_pk_mul_f32 v[78:79], v[94:95], v[0:1] op_sel_hi:[1,0]
	v_pk_mul_f32 v[76:77], v[92:93], v[0:1] op_sel_hi:[1,0]
	v_pk_mul_f32 v[82:83], v[98:99], v[0:1] op_sel_hi:[1,0]
	v_pk_mul_f32 v[80:81], v[96:97], v[0:1] op_sel_hi:[1,0]
	v_pk_mul_f32 v[86:87], v[102:103], v[0:1] op_sel_hi:[1,0]
	v_pk_mul_f32 v[84:85], v[100:101], v[0:1] op_sel_hi:[1,0]
	v_pk_mul_f32 v[90:91], v[106:107], v[0:1] op_sel_hi:[1,0]
	v_pk_mul_f32 v[88:89], v[104:105], v[0:1] op_sel_hi:[1,0]
	s_setprio 1
	ds_read_b64_tr_b16 v[98:99], v206 offset:2560
	ds_read_b64_tr_b16 v[102:103], v206 offset:2592
	ds_read_b64_tr_b16 v[96:97], v205 offset:64000
	ds_read_b64_tr_b16 v[100:101], v205 offset:64032
	v_cvt_pk_f16_f32 v95, v117, v116
	v_cvt_pk_f16_f32 v94, v123, v122
	v_cvt_pk_f16_f32 v93, v121, v120
	v_cvt_pk_f16_f32 v92, v173, v188
	s_waitcnt lgkmcnt(1)
; #define LAS __attribute__((address_space(3)))
; template <int MODE, int TM> ...
;     ...
;   __builtin_amdgcn_s_setprio(1);
; #pragma unroll
;   for (int t = 0; t < 2; ++t) {
;     if (!(TM & (1 << t))) continue;
;     const h16* Vt = t ? Vt1 : Vt0;
; #pragma unroll
;     for (int ks = 0; ks < 2; ++ks) {
;       h16x8 Pf;
; #pragma unroll
;       for (int i = 0; i < 4; ++i) { Pf[i] = (h16)S[t][2 * ks][i]; Pf[4 + i] = (h16)S[t][2 * ks + 1][i]; }
; #pragma unroll
;       for (int nt = 0; nt < 4; ++nt) {
;         const h16* vp = Vt + (ks * 32 + q4 * 4 + (col >> 2)) * KP + nt * 16 + 4 * (col & 3);
;         const s16x4v r0 = __builtin_amdgcn_ds_read_tr16_b64_v4i16((LAS s16x4v*)vp);
;         const s16x4v r1 = __builtin_amdgcn_ds_read_tr16_b64_v4i16((LAS s16x4v*)(vp + 16 * KP));
;         const h16x4 v0 = __builtin_bit_cast(h16x4, r0), v1 = __builtin_bit_cast(h16x4, r1);
;         const h16x8 Vf = {v0[0], v0[1], v0[2], v0[3], v1[0], v1[1], v1[2], v1[3]};
;         O[nt] = __builtin_amdgcn_mfma_f32_16x16x32_f16(Vf, Pf, O[nt], 0, 0, 0);
;       }
;     }
;   }
;   __builtin_amdgcn_s_setprio(0);
	s_nop 0
	v_mfma_f32_16x16x32_f16 v[76:79], v[96:99], v[92:95], v[76:79]
	ds_read_b64_tr_b16 v[96:97], v205 offset:64064
	ds_read_b64_tr_b16 v[98:99], v206 offset:2624
	s_waitcnt lgkmcnt(0)
	v_mfma_f32_16x16x32_f16 v[84:87], v[96:99], v[92:95], v[84:87]
	ds_read_b64_tr_b16 v[96:97], v205 offset:64096
	ds_read_b64_tr_b16 v[98:99], v206 offset:2656
	v_mfma_f32_16x16x32_f16 v[80:83], v[100:103], v[92:95], v[80:83]
	s_waitcnt lgkmcnt(0)
	v_mfma_f32_16x16x32_f16 v[88:91], v[96:99], v[92:95], v[88:91]
	ds_read_b64_tr_b16 v[98:99], v207 offset:2560
	ds_read_b64_tr_b16 v[96:97], v207
	ds_read_b64_tr_b16 v[100:101], v207 offset:32
	v_cvt_pk_f16_f32 v95, v109, v108
	v_cvt_pk_f16_f32 v94, v115, v114
	v_cvt_pk_f16_f32 v93, v113, v112
	v_cvt_pk_f16_f32 v92, v119, v118
	ds_read_b64_tr_b16 v[102:103], v207 offset:2592
	s_waitcnt lgkmcnt(2)
	v_mfma_f32_16x16x32_f16 v[76:79], v[96:99], v[92:95], v[76:79]
	ds_read_b64_tr_b16 v[96:97], v207 offset:64
	ds_read_b64_tr_b16 v[98:99], v207 offset:2624
	s_waitcnt lgkmcnt(0)
	v_mfma_f32_16x16x32_f16 v[84:87], v[96:99], v[92:95], v[84:87]
	ds_read_b64_tr_b16 v[96:97], v207 offset:96
	ds_read_b64_tr_b16 v[98:99], v207 offset:2656
	v_mfma_f32_16x16x32_f16 v[80:83], v[100:103], v[92:95], v[80:83]
	s_waitcnt lgkmcnt(0)
	v_mfma_f32_16x16x32_f16 v[88:91], v[96:99], v[92:95], v[88:91]
	ds_read_b64_tr_b16 v[98:99], v208 offset:2560
	ds_read_b64_tr_b16 v[96:97], v208
	ds_read_b64_tr_b16 v[100:101], v208 offset:32
	v_cvt_pk_f16_f32 v95, v246, v247
	v_cvt_pk_f16_f32 v94, v244, v245
	v_cvt_pk_f16_f32 v93, v189, v243
	v_cvt_pk_f16_f32 v92, v111, v110
	ds_read_b64_tr_b16 v[102:103], v208 offset:2592
	s_waitcnt lgkmcnt(2)
	v_mfma_f32_16x16x32_f16 v[76:79], v[96:99], v[92:95], v[76:79]
	ds_read_b64_tr_b16 v[96:97], v208 offset:64
	ds_read_b64_tr_b16 v[98:99], v208 offset:2624
	s_waitcnt lgkmcnt(0)
	v_mfma_f32_16x16x32_f16 v[84:87], v[96:99], v[92:95], v[84:87]
	ds_read_b64_tr_b16 v[96:97], v208 offset:96
	ds_read_b64_tr_b16 v[98:99], v208 offset:2656
	s_waitcnt lgkmcnt(0)
	v_mfma_f32_16x16x32_f16 v[88:91], v[96:99], v[92:95], v[88:91]
	ds_read_b64_tr_b16 v[96:97], v208 offset:5120
	ds_read_b64_tr_b16 v[98:99], v208 offset:7680
	v_mfma_f32_16x16x32_f16 v[80:83], v[100:103], v[92:95], v[80:83]
	v_cvt_pk_f16_f32 v95, v195, v200
	v_cvt_pk_f16_f32 v94, v252, v253
	v_cvt_pk_f16_f32 v93, v250, v251
	v_cvt_pk_f16_f32 v92, v248, v249
	s_waitcnt lgkmcnt(0)
	s_nop 0
	v_mfma_f32_16x16x32_f16 v[76:79], v[96:99], v[92:95], v[76:79]
	ds_read_b64_tr_b16 v[96:97], v208 offset:5152
	ds_read_b64_tr_b16 v[98:99], v208 offset:7712
	s_waitcnt lgkmcnt(0)
	v_mfma_f32_16x16x32_f16 v[80:83], v[96:99], v[92:95], v[80:83]
	ds_read_b64_tr_b16 v[96:97], v208 offset:5184
	ds_read_b64_tr_b16 v[98:99], v208 offset:7744
	s_waitcnt lgkmcnt(0)
	v_mfma_f32_16x16x32_f16 v[84:87], v[96:99], v[92:95], v[84:87]
	ds_read_b64_tr_b16 v[96:97], v208 offset:5216
	ds_read_b64_tr_b16 v[98:99], v208 offset:7776
	s_waitcnt lgkmcnt(0)
	v_mfma_f32_16x16x32_f16 v[88:91], v[96:99], v[92:95], v[88:91]

; #define LAS __attribute__((address_space(3)))
; template <int MODE, int TM> ...
;     ...
;     float mx = -1e30f;
; #pragma unroll
;     for (int t = 0; t < 2; ++t) {
;       if (!(TM & (1 << t))) continue;
;       float mt = -1e30f;
; #pragma unroll
;       for (int kt = 0; kt < 4; ++kt)
; #pragma unroll
;         for (int j = 0; j < 4; ++j) mt = fmaxf(mt, S[t][kt][j]);
;       mx = fmaxf(mx, mt * sclc[t] + addc[t]);
;     }
;     mx = max4q(mx);
;     const float mn = fmaxf(st.m, mx);
;     const float corr = __builtin_amdgcn_exp2f(st.m - mn);
;     st.m = mn;
;     const float mm = fmaxf(mn, -1e20f);
;     float ls = 0.f;
; #pragma unroll
;     for (int t = 0; t < 2; ++t) {
;       if (!(TM & (1 << t))) continue;
;       const float am = addc[t] - mm;
; #pragma unroll
;       for (int kt = 0; kt < 4; ++kt) {
;         const f32x4 e = S[t][kt] * sclc[t] + am;
; #pragma unroll
;         for (int j = 0; j < 4; ++j) {
;           float pv = __builtin_amdgcn_exp2f(e[j]);
;           S[t][kt][j] = pv;
;           ls += pv;
;         }
;       }
;     }
;     st.l = st.l * corr + ls;
;     if (MODE != M_CMPA) {
; #pragma unroll
;       for (int nt = 0; nt < 4; ++nt) O[nt] *= corr;
;     }
;   }
;   if (MODE == M_CMPA) return;
;   __builtin_amdgcn_s_setprio(1);
; #pragma unroll
;   for (int t = 0; t < 2; ++t) {
;     if (!(TM & (1 << t))) continue;
;     const h16* Vt = t ? Vt1 : Vt0;
; #pragma unroll
;     for (int ks = 0; ks < 2; ++ks) {
;       h16x8 Pf;
; #pragma unroll
;       for (int i = 0; i < 4; ++i) { Pf[i] = (h16)S[t][2 * ks][i]; Pf[4 + i] = (h16)S[t][2 * ks + 1][i]; }
; #pragma unroll
;       for (int nt = 0; nt < 4; ++nt) {
;         const h16* vp = Vt + (ks * 32 + q4 * 4 + (col >> 2)) * KP + nt * 16 + 4 * (col & 3);
;         const s16x4v r0 = __builtin_amdgcn_ds_read_tr16_b64_v4i16((LAS s16x4v*)vp);
;         const s16x4v r1 = __builtin_amdgcn_ds_read_tr16_b64_v4i16((LAS s16x4v*)(vp + 16 * KP));
;         const h16x4 v0 = __builtin_bit_cast(h16x4, r0), v1 = __builtin_bit_cast(h16x4, r1);
;         const h16x8 Vf = {v0[0], v0[1], v0[2], v0[3], v1[0], v1[1], v1[2], v1[3]};
;         O[nt] = __builtin_amdgcn_mfma_f32_16x16x32_f16(Vf, Pf, O[nt], 0, 0, 0);
;       }
.LBB0_1866:
	s_or_b64 exec, exec, s[0:1]
	s_waitcnt lgkmcnt(0)
	v_fmac_f32_e32 v93, 0x3e38aa3b, v94
	v_max3_f32 v2, v116, s67, v3
	v_max3_f32 v2, v2, v105, v104
	v_max3_f32 v2, v2, v107, v106
	v_max3_f32 v2, v2, v101, v100
	v_max3_f32 v2, v2, v103, v102
	v_max3_f32 v2, v2, v97, v96
	v_max3_f32 v2, v2, v99, v98
	v_max3_f32 v2, v2, v93, v92
	v_add_f32_e32 v2, 0, v2
	v_max_f32_e32 v2, 0xf149f2ca, v2
	v_mov_b32_e32 v94, v2
	s_nop 1
	v_permlane16_swap_b32_e32 v94, v2
	s_waitcnt lgkmcnt(0)
	v_max_f32_e32 v94, v94, v94
	v_max_f32_e32 v2, v2, v94
	v_mov_b32_e32 v94, v2
	s_nop 1
	v_permlane32_swap_b32_e32 v2, v94
	v_max3_f32 v2, v126, v2, v94
	v_max_f32_e32 v95, 0xe0ad78ec, v2
	v_add_f32_e64 v116, v116, -v95
	v_add_f32_e64 v3, v3, -v95
	v_exp_f32_e32 v116, v116
	v_add_f32_e64 v105, v105, -v95
	v_exp_f32_e32 v120, v3
	v_add_f32_e64 v104, v104, -v95
	v_exp_f32_e32 v117, v105
	v_exp_f32_e32 v121, v104
	v_add_f32_e64 v104, v107, -v95
	v_add_f32_e32 v3, 0, v116
	v_exp_f32_e32 v118, v104
	v_add_f32_e64 v104, v106, -v95
	v_add_f32_e32 v3, v120, v3
	v_exp_f32_e32 v122, v104
	v_add_f32_e64 v101, v101, -v95
	v_add_f32_e32 v3, v117, v3
	v_exp_f32_e32 v119, v101
	v_add_f32_e64 v100, v100, -v95
	v_add_f32_e32 v3, v121, v3
	v_exp_f32_e32 v123, v100
	v_add_f32_e64 v100, v103, -v95
	v_add_f32_e32 v3, v118, v3
	v_exp_f32_e32 v173, v100
	v_add_f32_e64 v100, v102, -v95
	v_add_f32_e32 v3, v122, v3
	v_exp_f32_e32 v188, v100
	v_add_f32_e64 v97, v97, -v95
	v_add_f32_e32 v3, v119, v3
	v_exp_f32_e32 v189, v97
	v_add_f32_e64 v96, v96, -v95
	v_add_f32_e32 v3, v123, v3
	v_exp_f32_e32 v243, v96
	v_add_f32_e64 v96, v99, -v95
	v_add_f32_e32 v3, v173, v3
	v_exp_f32_e32 v248, v96
	v_add_f32_e64 v96, v98, -v95
	v_add_f32_e32 v3, v188, v3
	v_exp_f32_e32 v249, v96
	v_add_f32_e64 v93, v93, -v95
	v_add_f32_e32 v3, v189, v3
	v_exp_f32_e32 v250, v93
	v_add_f32_e64 v92, v92, -v95
	v_sub_f32_e32 v94, v126, v2
	v_add_f32_e32 v3, v243, v3
	v_exp_f32_e32 v251, v92
	v_add_f32_e32 v3, v248, v3
	v_exp_f32_e32 v104, v94
	v_add_f32_e32 v3, v249, v3
	v_add_f32_e32 v3, v250, v3
	v_add_f32_e32 v3, v251, v3
	v_fmac_f32_e32 v3, v127, v104
	v_pk_mul_f32 v[94:95], v[78:79], v[104:105] op_sel_hi:[1,0]
	v_pk_mul_f32 v[92:93], v[76:77], v[104:105] op_sel_hi:[1,0]
	v_pk_mul_f32 v[98:99], v[82:83], v[104:105] op_sel_hi:[1,0]
	v_pk_mul_f32 v[96:97], v[80:81], v[104:105] op_sel_hi:[1,0]
	v_pk_mul_f32 v[102:103], v[86:87], v[104:105] op_sel_hi:[1,0]
	v_pk_mul_f32 v[100:101], v[84:85], v[104:105] op_sel_hi:[1,0]
	v_pk_mul_f32 v[106:107], v[90:91], v[104:105] op_sel_hi:[1,0]
	v_pk_mul_f32 v[104:105], v[88:89], v[104:105] op_sel_hi:[1,0]
	s_setprio 1
	v_cvt_pk_f16_f32 v119, v119, v123
	v_cvt_pk_f16_f32 v118, v118, v122
	v_cvt_pk_f16_f32 v117, v117, v121
	v_cvt_pk_f16_f32 v116, v116, v120
	ds_read_b64_tr_b16 v[122:123], v205 offset:25600
	ds_read_b64_tr_b16 v[120:121], v205 offset:23040
	ds_read_b64_tr_b16 v[244:245], v205 offset:23072
	s_waitcnt lgkmcnt(1)
	v_mfma_f32_16x16x32_f16 v[92:95], v[120:123], v[116:119], v[92:95]
	ds_read_b64_tr_b16 v[246:247], v205 offset:25632
	ds_read_b64_tr_b16 v[120:121], v205 offset:23104
	ds_read_b64_tr_b16 v[122:123], v205 offset:25664
	s_mov_b64 s[0:1], 0
	s_waitcnt lgkmcnt(0)
	v_mfma_f32_16x16x32_f16 v[100:103], v[120:123], v[116:119], v[100:103]
	ds_read_b64_tr_b16 v[120:121], v205 offset:23136
	ds_read_b64_tr_b16 v[122:123], v205 offset:25696
	s_waitcnt lgkmcnt(0)
	v_mfma_f32_16x16x32_f16 v[104:107], v[120:123], v[116:119], v[104:107]
	ds_read_b64_tr_b16 v[120:121], v205 offset:28160
	ds_read_b64_tr_b16 v[122:123], v205 offset:30720
	v_mfma_f32_16x16x32_f16 v[96:99], v[244:247], v[116:119], v[96:99]
	v_cvt_pk_f16_f32 v119, v250, v251
	v_cvt_pk_f16_f32 v118, v248, v249
	v_cvt_pk_f16_f32 v117, v189, v243
	v_cvt_pk_f16_f32 v116, v173, v188
	s_waitcnt lgkmcnt(0)
	s_nop 0
	v_mfma_f32_16x16x32_f16 v[92:95], v[120:123], v[116:119], v[92:95]
	ds_read_b64_tr_b16 v[120:121], v205 offset:28192
	ds_read_b64_tr_b16 v[122:123], v205 offset:30752
	s_waitcnt lgkmcnt(0)
	v_mfma_f32_16x16x32_f16 v[96:99], v[120:123], v[116:119], v[96:99]
	ds_read_b64_tr_b16 v[120:121], v205 offset:28224
	ds_read_b64_tr_b16 v[122:123], v205 offset:30784
	s_waitcnt lgkmcnt(0)
	v_mfma_f32_16x16x32_f16 v[100:103], v[120:123], v[116:119], v[100:103]
	ds_read_b64_tr_b16 v[120:121], v205 offset:28256
	ds_read_b64_tr_b16 v[122:123], v205 offset:30816
	s_waitcnt lgkmcnt(0)
	v_mfma_f32_16x16x32_f16 v[104:107], v[120:123], v[116:119], v[104:107]

; #define LAS __attribute__((address_space(3)))
; template <int MODE, int TM> ...
;     ...
;     float mx = -1e30f;
; #pragma unroll
;     for (int t = 0; t < 2; ++t) {
;       if (!(TM & (1 << t))) continue;
;       float mt = -1e30f;
; #pragma unroll
;       for (int kt = 0; kt < 4; ++kt)
; #pragma unroll
;         for (int j = 0; j < 4; ++j) mt = fmaxf(mt, S[t][kt][j]);
;       mx = fmaxf(mx, mt * sclc[t] + addc[t]);
;     }
;     mx = max4q(mx);
;     const float mn = fmaxf(st.m, mx);
;     const float corr = __builtin_amdgcn_exp2f(st.m - mn);
;     st.m = mn;
;     const float mm = fmaxf(mn, -1e20f);
;     float ls = 0.f;
; #pragma unroll
;     for (int t = 0; t < 2; ++t) {
;       if (!(TM & (1 << t))) continue;
;       const float am = addc[t] - mm;
; #pragma unroll
;       for (int kt = 0; kt < 4; ++kt) {
;         const f32x4 e = S[t][kt] * sclc[t] + am;
; #pragma unroll
;         for (int j = 0; j < 4; ++j) {
;           float pv = __builtin_amdgcn_exp2f(e[j]);
;           S[t][kt][j] = pv;
;           ls += pv;
;         }
;       }
;     }
;     st.l = st.l * corr + ls;
;     if (MODE != M_CMPA) {
; #pragma unroll
;       for (int nt = 0; nt < 4; ++nt) O[nt] *= corr;
;     }
;   }
;   if (MODE == M_CMPA) return;
;   __builtin_amdgcn_s_setprio(1);
; #pragma unroll
;   for (int t = 0; t < 2; ++t) {
;     if (!(TM & (1 << t))) continue;
;     const h16* Vt = t ? Vt1 : Vt0;
; #pragma unroll
;     for (int ks = 0; ks < 2; ++ks) {
;       h16x8 Pf;
; #pragma unroll
;       for (int i = 0; i < 4; ++i) { Pf[i] = (h16)S[t][2 * ks][i]; Pf[4 + i] = (h16)S[t][2 * ks + 1][i]; }
; #pragma unroll
;       for (int nt = 0; nt < 4; ++nt) {
;         const h16* vp = Vt + (ks * 32 + q4 * 4 + (col >> 2)) * KP + nt * 16 + 4 * (col & 3);
;         const s16x4v r0 = __builtin_amdgcn_ds_read_tr16_b64_v4i16((LAS s16x4v*)vp);
;         const s16x4v r1 = __builtin_amdgcn_ds_read_tr16_b64_v4i16((LAS s16x4v*)(vp + 16 * KP));
;         const h16x4 v0 = __builtin_bit_cast(h16x4, r0), v1 = __builtin_bit_cast(h16x4, r1);
;         const h16x8 Vf = {v0[0], v0[1], v0[2], v0[3], v1[0], v1[1], v1[2], v1[3]};
;         O[nt] = __builtin_amdgcn_mfma_f32_16x16x32_f16(Vf, Pf, O[nt], 0, 0, 0);
;       }
.LBB0_1932:
	s_or_b64 exec, exec, s[0:1]
	s_waitcnt lgkmcnt(0)
	v_fmac_f32_e32 v93, 0x3e38aa3b, v94
	v_max3_f32 v0, v173, s67, v3
	v_max3_f32 v2, v111, s67, v110
	v_max3_f32 v0, v0, v121, v120
	v_max3_f32 v2, v2, v105, v104
	v_max3_f32 v0, v0, v123, v122
	v_max3_f32 v2, v2, v107, v106
	v_max3_f32 v0, v0, v117, v116
	v_max3_f32 v2, v2, v101, v100
	v_max3_f32 v0, v0, v119, v118
	v_max3_f32 v2, v2, v103, v102
	v_max3_f32 v0, v0, v113, v112
	v_max3_f32 v2, v2, v97, v96
	v_max3_f32 v0, v0, v115, v114
	v_max3_f32 v2, v2, v99, v98
	v_max3_f32 v0, v0, v109, v108
	v_max3_f32 v2, v2, v93, v92
	v_add_f32_e32 v0, 0, v0
	v_add_f32_e32 v2, 0, v2
	v_max3_f32 v0, v0, s67, v2
	v_mov_b32_e32 v2, v0
	s_nop 1
	v_permlane16_swap_b32_e32 v2, v0
	s_waitcnt lgkmcnt(0)
	v_max_f32_e32 v2, v2, v2
	v_max_f32_e32 v0, v0, v2
	v_mov_b32_e32 v2, v0
	s_nop 1
	v_permlane32_swap_b32_e32 v0, v2
	v_max3_f32 v2, v126, v0, v2
	v_max_f32_e32 v0, 0xe0ad78ec, v2
	v_add_f32_e64 v94, v173, -v0
	v_exp_f32_e32 v173, v94
	v_add_f32_e64 v3, v3, -v0
	v_sub_f32_e32 v94, v126, v2
	v_exp_f32_e32 v126, v3
	v_add_f32_e64 v3, v121, -v0
	v_exp_f32_e32 v121, v3
	v_add_f32_e64 v3, v120, -v0
	v_add_f32_e32 v95, 0, v173
	v_exp_f32_e32 v120, v3
	v_add_f32_e64 v3, v123, -v0
	v_exp_f32_e32 v123, v3
	v_add_f32_e32 v3, v126, v95
	v_add_f32_e64 v95, v122, -v0
	v_exp_f32_e32 v122, v95
	v_add_f32_e64 v95, v117, -v0
	v_add_f32_e32 v3, v121, v3
	v_exp_f32_e32 v95, v95
	v_add_f32_e64 v116, v116, -v0
	v_add_f32_e32 v3, v120, v3
	v_exp_f32_e32 v116, v116
	v_add_f32_e64 v117, v119, -v0
	v_add_f32_e32 v3, v123, v3
	v_exp_f32_e32 v117, v117
	v_add_f32_e64 v118, v118, -v0
	v_add_f32_e32 v3, v122, v3
	v_exp_f32_e32 v118, v118
	v_add_f32_e64 v113, v113, -v0
	v_add_f32_e32 v3, v95, v3
	v_exp_f32_e32 v113, v113
	v_add_f32_e64 v112, v112, -v0
	v_add_f32_e32 v3, v116, v3
	v_exp_f32_e32 v112, v112
	v_add_f32_e64 v115, v115, -v0
	v_add_f32_e32 v3, v117, v3
	v_exp_f32_e32 v115, v115
	v_add_f32_e64 v114, v114, -v0
	v_add_f32_e32 v3, v118, v3
	v_exp_f32_e32 v114, v114
	v_add_f32_e64 v109, v109, -v0
	v_add_f32_e32 v3, v113, v3
	v_exp_f32_e32 v109, v109
	v_add_f32_e64 v108, v108, -v0
	v_add_f32_e32 v3, v112, v3
	v_exp_f32_e32 v108, v108
	v_add_f32_e64 v111, v111, -v0
	v_add_f32_e32 v3, v115, v3
	v_exp_f32_e32 v111, v111
	v_add_f32_e64 v110, v110, -v0
	v_add_f32_e32 v3, v114, v3
	v_exp_f32_e32 v110, v110
	v_add_f32_e64 v105, v105, -v0
	v_add_f32_e32 v3, v109, v3
	v_exp_f32_e32 v105, v105
	v_add_f32_e64 v104, v104, -v0
	v_add_f32_e32 v3, v108, v3
	v_exp_f32_e32 v104, v104
	v_add_f32_e64 v107, v107, -v0
	v_add_f32_e32 v3, v111, v3
	v_exp_f32_e32 v107, v107
	v_add_f32_e64 v106, v106, -v0
	v_add_f32_e32 v3, v110, v3
	v_exp_f32_e32 v106, v106
	v_add_f32_e64 v101, v101, -v0
	v_add_f32_e32 v3, v105, v3
	v_exp_f32_e32 v119, v101
	v_add_f32_e64 v100, v100, -v0
	v_add_f32_e32 v3, v104, v3
	v_exp_f32_e32 v188, v100
	v_add_f32_e64 v100, v103, -v0
	v_add_f32_e32 v3, v107, v3
	v_exp_f32_e32 v189, v100
	v_add_f32_e64 v100, v102, -v0
	v_add_f32_e32 v3, v106, v3
	v_exp_f32_e32 v243, v100
	v_add_f32_e64 v97, v97, -v0
	v_add_f32_e32 v3, v119, v3
	v_exp_f32_e32 v244, v97
	v_add_f32_e64 v96, v96, -v0
	v_add_f32_e32 v3, v188, v3
	v_exp_f32_e32 v245, v96
	v_add_f32_e64 v96, v99, -v0
	v_add_f32_e32 v3, v189, v3
	v_exp_f32_e32 v246, v96
	v_add_f32_e64 v96, v98, -v0
	v_add_f32_e32 v3, v243, v3
	v_exp_f32_e32 v247, v96
	v_add_f32_e64 v93, v93, -v0
	v_add_f32_e32 v3, v244, v3
	v_exp_f32_e32 v248, v93
	v_add_f32_e64 v0, v92, -v0
	v_add_f32_e32 v3, v245, v3
	v_exp_f32_e32 v249, v0
	v_add_f32_e32 v3, v246, v3
	v_exp_f32_e32 v0, v94
	v_add_f32_e32 v3, v247, v3
	v_add_f32_e32 v3, v248, v3
	v_add_f32_e32 v3, v249, v3
	v_fmac_f32_e32 v3, v127, v0
	v_pk_mul_f32 v[78:79], v[78:79], v[0:1] op_sel_hi:[1,0]
	v_pk_mul_f32 v[76:77], v[76:77], v[0:1] op_sel_hi:[1,0]
	v_pk_mul_f32 v[82:83], v[82:83], v[0:1] op_sel_hi:[1,0]
	v_pk_mul_f32 v[80:81], v[80:81], v[0:1] op_sel_hi:[1,0]
	v_pk_mul_f32 v[86:87], v[86:87], v[0:1] op_sel_hi:[1,0]
	v_pk_mul_f32 v[84:85], v[84:85], v[0:1] op_sel_hi:[1,0]
	v_pk_mul_f32 v[90:91], v[90:91], v[0:1] op_sel_hi:[1,0]
	v_pk_mul_f32 v[88:89], v[88:89], v[0:1] op_sel_hi:[1,0]
	s_setprio 1
	ds_read_b64_tr_b16 v[98:99], v205 offset:25600
	ds_read_b64_tr_b16 v[96:97], v205 offset:23040
	ds_read_b64_tr_b16 v[100:101], v205 offset:23072
	v_cvt_pk_f16_f32 v95, v95, v116
	v_cvt_pk_f16_f32 v94, v123, v122
	v_cvt_pk_f16_f32 v93, v121, v120
	v_cvt_pk_f16_f32 v92, v173, v126
	ds_read_b64_tr_b16 v[102:103], v205 offset:25632
	s_waitcnt lgkmcnt(2)
; #define LAS __attribute__((address_space(3)))
; template <int MODE, int TM> ...
;     ...
;   __builtin_amdgcn_s_setprio(1);
; #pragma unroll
;   for (int t = 0; t < 2; ++t) {
;     if (!(TM & (1 << t))) continue;
;     const h16* Vt = t ? Vt1 : Vt0;
; #pragma unroll
;     for (int ks = 0; ks < 2; ++ks) {
;       h16x8 Pf;
; #pragma unroll
;       for (int i = 0; i < 4; ++i) { Pf[i] = (h16)S[t][2 * ks][i]; Pf[4 + i] = (h16)S[t][2 * ks + 1][i]; }
; #pragma unroll
;       for (int nt = 0; nt < 4; ++nt) {
;         const h16* vp = Vt + (ks * 32 + q4 * 4 + (col >> 2)) * KP + nt * 16 + 4 * (col & 3);
;         const s16x4v r0 = __builtin_amdgcn_ds_read_tr16_b64_v4i16((LAS s16x4v*)vp);
;         const s16x4v r1 = __builtin_amdgcn_ds_read_tr16_b64_v4i16((LAS s16x4v*)(vp + 16 * KP));
;         const h16x4 v0 = __builtin_bit_cast(h16x4, r0), v1 = __builtin_bit_cast(h16x4, r1);
;         const h16x8 Vf = {v0[0], v0[1], v0[2], v0[3], v1[0], v1[1], v1[2], v1[3]};
;         O[nt] = __builtin_amdgcn_mfma_f32_16x16x32_f16(Vf, Pf, O[nt], 0, 0, 0);
;       }
;     }
;   }
;   __builtin_amdgcn_s_setprio(0);
	v_mfma_f32_16x16x32_f16 v[76:79], v[96:99], v[92:95], v[76:79]
	ds_read_b64_tr_b16 v[96:97], v205 offset:23104
	ds_read_b64_tr_b16 v[98:99], v205 offset:25664
	s_waitcnt lgkmcnt(0)
	v_mfma_f32_16x16x32_f16 v[84:87], v[96:99], v[92:95], v[84:87]
	ds_read_b64_tr_b16 v[96:97], v205 offset:23136
	ds_read_b64_tr_b16 v[98:99], v205 offset:25696
	s_waitcnt lgkmcnt(0)
	v_mfma_f32_16x16x32_f16 v[88:91], v[96:99], v[92:95], v[88:91]
	ds_read_b64_tr_b16 v[96:97], v205 offset:28160
	ds_read_b64_tr_b16 v[98:99], v205 offset:30720
	v_mfma_f32_16x16x32_f16 v[80:83], v[100:103], v[92:95], v[80:83]
	v_cvt_pk_f16_f32 v95, v109, v108
	v_cvt_pk_f16_f32 v94, v115, v114
	v_cvt_pk_f16_f32 v93, v113, v112
	v_cvt_pk_f16_f32 v92, v117, v118
	s_waitcnt lgkmcnt(0)
	s_nop 0
	v_mfma_f32_16x16x32_f16 v[76:79], v[96:99], v[92:95], v[76:79]
	ds_read_b64_tr_b16 v[96:97], v205 offset:28192
	ds_read_b64_tr_b16 v[98:99], v205 offset:30752
	s_waitcnt lgkmcnt(0)
	v_mfma_f32_16x16x32_f16 v[80:83], v[96:99], v[92:95], v[80:83]
	ds_read_b64_tr_b16 v[96:97], v205 offset:28224
	ds_read_b64_tr_b16 v[98:99], v205 offset:30784
	s_waitcnt lgkmcnt(0)
	v_mfma_f32_16x16x32_f16 v[84:87], v[96:99], v[92:95], v[84:87]
	ds_read_b64_tr_b16 v[96:97], v205 offset:28256
	ds_read_b64_tr_b16 v[98:99], v205 offset:30816
	s_waitcnt lgkmcnt(0)
	v_mfma_f32_16x16x32_f16 v[88:91], v[96:99], v[92:95], v[88:91]
	ds_read_b64_tr_b16 v[96:97], v205 offset:43520
	ds_read_b64_tr_b16 v[98:99], v205 offset:46080
	v_cvt_pk_f16_f32 v95, v119, v188
	v_cvt_pk_f16_f32 v94, v107, v106
	v_cvt_pk_f16_f32 v93, v105, v104
	v_cvt_pk_f16_f32 v92, v111, v110
	v_cvt_pk_f16_f32 v107, v248, v249
	v_cvt_pk_f16_f32 v106, v246, v247
	s_waitcnt lgkmcnt(0)
	v_mfma_f32_16x16x32_f16 v[76:79], v[96:99], v[92:95], v[76:79]
	ds_read_b64_tr_b16 v[96:97], v205 offset:43552
	ds_read_b64_tr_b16 v[98:99], v205 offset:46112
	v_cvt_pk_f16_f32 v105, v244, v245
	v_cvt_pk_f16_f32 v104, v189, v243
	s_waitcnt lgkmcnt(0)
	v_mfma_f32_16x16x32_f16 v[80:83], v[96:99], v[92:95], v[80:83]
	ds_read_b64_tr_b16 v[96:97], v205 offset:43584
	ds_read_b64_tr_b16 v[98:99], v205 offset:46144
	s_waitcnt lgkmcnt(0)
	v_mfma_f32_16x16x32_f16 v[84:87], v[96:99], v[92:95], v[84:87]
	ds_read_b64_tr_b16 v[96:97], v205 offset:43616
	ds_read_b64_tr_b16 v[98:99], v205 offset:46176
	s_waitcnt lgkmcnt(0)
	v_mfma_f32_16x16x32_f16 v[88:91], v[96:99], v[92:95], v[88:91]
	ds_read_b64_tr_b16 v[92:93], v205 offset:48640
	ds_read_b64_tr_b16 v[94:95], v205 offset:51200
	s_waitcnt lgkmcnt(0)
	v_mfma_f32_16x16x32_f16 v[92:95], v[92:95], v[104:107], v[76:79]
	s_nop 2
	ds_read_b64_tr_b16 v[76:77], v205 offset:48672
	ds_read_b64_tr_b16 v[78:79], v205 offset:51232
	s_waitcnt lgkmcnt(0)
	v_mfma_f32_16x16x32_f16 v[96:99], v[76:79], v[104:107], v[80:83]
	ds_read_b64_tr_b16 v[76:77], v205 offset:48704
	ds_read_b64_tr_b16 v[78:79], v205 offset:51264
	s_waitcnt lgkmcnt(0)
	v_mfma_f32_16x16x32_f16 v[100:103], v[76:79], v[104:107], v[84:87]
	ds_read_b64_tr_b16 v[76:77], v205 offset:48736
	ds_read_b64_tr_b16 v[78:79], v205 offset:51296
	s_waitcnt lgkmcnt(0)
	v_mfma_f32_16x16x32_f16 v[104:107], v[76:79], v[104:107], v[88:91]

; #define LAS __attribute__((address_space(3)))
; template <int MODE, int TM> ...
;     ...
;     float mx = -1e30f;
; #pragma unroll
;     for (int t = 0; t < 2; ++t) {
;       if (!(TM & (1 << t))) continue;
;       float mt = -1e30f;
; #pragma unroll
;       for (int kt = 0; kt < 4; ++kt)
; #pragma unroll
;         for (int j = 0; j < 4; ++j) mt = fmaxf(mt, S[t][kt][j]);
;       mx = fmaxf(mx, mt * sclc[t] + addc[t]);
;     }
;     mx = max4q(mx);
;     const float mn = fmaxf(st.m, mx);
;     const float corr = __builtin_amdgcn_exp2f(st.m - mn);
;     st.m = mn;
;     const float mm = fmaxf(mn, -1e20f);
;     float ls = 0.f;
; #pragma unroll
;     for (int t = 0; t < 2; ++t) {
;       if (!(TM & (1 << t))) continue;
;       const float am = addc[t] - mm;
; #pragma unroll
;       for (int kt = 0; kt < 4; ++kt) {
;         const f32x4 e = S[t][kt] * sclc[t] + am;
; #pragma unroll
;         for (int j = 0; j < 4; ++j) {
;           float pv = __builtin_amdgcn_exp2f(e[j]);
;           S[t][kt][j] = pv;
;           ls += pv;
;         }
;       }
;     }
;     st.l = st.l * corr + ls;
;     if (MODE != M_CMPA) {
; #pragma unroll
;       for (int nt = 0; nt < 4; ++nt) O[nt] *= corr;
;     }
;   }
;   if (MODE == M_CMPA) return;
;   __builtin_amdgcn_s_setprio(1);
; #pragma unroll
;   for (int t = 0; t < 2; ++t) {
;     if (!(TM & (1 << t))) continue;
;     const h16* Vt = t ? Vt1 : Vt0;
; #pragma unroll
;     for (int ks = 0; ks < 2; ++ks) {
;       h16x8 Pf;
; #pragma unroll
;       for (int i = 0; i < 4; ++i) { Pf[i] = (h16)S[t][2 * ks][i]; Pf[4 + i] = (h16)S[t][2 * ks + 1][i]; }
; #pragma unroll
;       for (int nt = 0; nt < 4; ++nt) {
;         const h16* vp = Vt + (ks * 32 + q4 * 4 + (col >> 2)) * KP + nt * 16 + 4 * (col & 3);
;         const s16x4v r0 = __builtin_amdgcn_ds_read_tr16_b64_v4i16((LAS s16x4v*)vp);
;         const s16x4v r1 = __builtin_amdgcn_ds_read_tr16_b64_v4i16((LAS s16x4v*)(vp + 16 * KP));
;         const h16x4 v0 = __builtin_bit_cast(h16x4, r0), v1 = __builtin_bit_cast(h16x4, r1);
;         const h16x8 Vf = {v0[0], v0[1], v0[2], v0[3], v1[0], v1[1], v1[2], v1[3]};
;         O[nt] = __builtin_amdgcn_mfma_f32_16x16x32_f16(Vf, Pf, O[nt], 0, 0, 0);
;       }
.LBB0_1979:
	s_or_b64 exec, exec, s[0:1]
	v_max3_f32 v78, v117, s67, v116
	v_max3_f32 v78, v78, v89, v88
	v_max3_f32 v78, v78, v91, v90
	v_max3_f32 v78, v78, v85, v84
	v_max3_f32 v78, v78, v87, v86
	v_max3_f32 v78, v78, v81, v80
	v_max3_f32 v78, v78, v83, v82
	v_max3_f32 v78, v78, v77, v76
	v_add_f32_e32 v78, 0, v78
	v_max_f32_e32 v78, 0xf149f2ca, v78
	v_mov_b32_e32 v79, v78
	s_nop 1
	v_permlane16_swap_b32_e32 v79, v78
	s_waitcnt lgkmcnt(0)
	v_max_f32_e32 v79, v79, v79
	v_max_f32_e32 v78, v78, v79
	v_mov_b32_e32 v79, v78
	s_nop 1
	v_permlane32_swap_b32_e32 v78, v79
	v_max3_f32 v126, v2, v78, v79
	v_max_f32_e32 v79, 0xe0ad78ec, v126
	v_add_f32_e64 v117, v117, -v79
	v_add_f32_e64 v116, v116, -v79
	v_exp_f32_e32 v120, v117
	v_exp_f32_e32 v116, v116
	v_add_f32_e64 v89, v89, -v79
	v_add_f32_e64 v88, v88, -v79
	v_exp_f32_e32 v117, v89
	v_add_f32_e32 v89, 0, v120
	v_exp_f32_e32 v121, v88
	v_add_f32_e64 v88, v91, -v79
	v_exp_f32_e32 v118, v88
	v_add_f32_e32 v88, v116, v89
	v_add_f32_e64 v89, v90, -v79
	v_exp_f32_e32 v122, v89
	v_add_f32_e64 v85, v85, -v79
	v_add_f32_e32 v88, v117, v88
	v_exp_f32_e32 v119, v85
	v_add_f32_e64 v84, v84, -v79
	v_add_f32_e32 v88, v121, v88
	v_exp_f32_e32 v123, v84
	v_add_f32_e64 v84, v87, -v79
	v_add_f32_e32 v88, v118, v88
	v_exp_f32_e32 v173, v84
	v_add_f32_e64 v85, v86, -v79
	v_add_f32_e32 v84, v122, v88
	v_exp_f32_e32 v188, v85
	v_add_f32_e64 v81, v81, -v79
	v_add_f32_e32 v84, v119, v84
	v_exp_f32_e32 v189, v81
	v_add_f32_e64 v80, v80, -v79
	v_add_f32_e32 v84, v123, v84
	v_exp_f32_e32 v243, v80
	v_add_f32_e64 v80, v83, -v79
	v_add_f32_e32 v84, v173, v84
	v_exp_f32_e32 v248, v80
	v_add_f32_e64 v81, v82, -v79
	v_add_f32_e32 v80, v188, v84
	v_exp_f32_e32 v249, v81
	v_add_f32_e64 v77, v77, -v79
	v_add_f32_e32 v80, v189, v80
	v_exp_f32_e32 v250, v77
	v_add_f32_e64 v76, v76, -v79
	v_sub_f32_e32 v78, v2, v126
	v_add_f32_e32 v80, v243, v80
	v_exp_f32_e32 v251, v76
	v_add_f32_e32 v80, v248, v80
	v_exp_f32_e32 v88, v78
	v_add_f32_e32 v76, v249, v80
	v_add_f32_e32 v76, v250, v76
	v_add_f32_e32 v127, v251, v76
	v_fmac_f32_e32 v127, v3, v88
	v_pk_mul_f32 v[78:79], v[94:95], v[88:89] op_sel_hi:[1,0]
	v_pk_mul_f32 v[76:77], v[92:93], v[88:89] op_sel_hi:[1,0]
	v_pk_mul_f32 v[82:83], v[98:99], v[88:89] op_sel_hi:[1,0]
	v_pk_mul_f32 v[80:81], v[96:97], v[88:89] op_sel_hi:[1,0]
	v_pk_mul_f32 v[86:87], v[102:103], v[88:89] op_sel_hi:[1,0]
	v_pk_mul_f32 v[84:85], v[100:101], v[88:89] op_sel_hi:[1,0]
	v_pk_mul_f32 v[90:91], v[106:107], v[88:89] op_sel_hi:[1,0]
	v_pk_mul_f32 v[88:89], v[104:105], v[88:89] op_sel_hi:[1,0]
	s_setprio 1
	v_cvt_pk_f16_f32 v119, v119, v123
	v_cvt_pk_f16_f32 v118, v118, v122
	v_cvt_pk_f16_f32 v117, v117, v121
	v_cvt_pk_f16_f32 v116, v120, v116
	ds_read_b64_tr_b16 v[122:123], v206 offset:2560
	ds_read_b64_tr_b16 v[246:247], v206 offset:2592
	ds_read_b64_tr_b16 v[120:121], v205 offset:64000
	ds_read_b64_tr_b16 v[244:245], v205 offset:64032
	s_waitcnt lgkmcnt(1)
	v_mfma_f32_16x16x32_f16 v[76:79], v[120:123], v[116:119], v[76:79]
	ds_read_b64_tr_b16 v[120:121], v205 offset:64064
	ds_read_b64_tr_b16 v[122:123], v206 offset:2624
	s_mov_b64 s[0:1], 0
	s_waitcnt lgkmcnt(0)
	v_mfma_f32_16x16x32_f16 v[84:87], v[120:123], v[116:119], v[84:87]
	ds_read_b64_tr_b16 v[120:121], v205 offset:64096
	ds_read_b64_tr_b16 v[122:123], v206 offset:2656
	s_waitcnt lgkmcnt(0)
	v_mfma_f32_16x16x32_f16 v[88:91], v[120:123], v[116:119], v[88:91]
	ds_read_b64_tr_b16 v[120:121], v206 offset:5120
	ds_read_b64_tr_b16 v[122:123], v206 offset:7680
	v_mfma_f32_16x16x32_f16 v[80:83], v[244:247], v[116:119], v[80:83]
	v_cvt_pk_f16_f32 v119, v250, v251
	v_cvt_pk_f16_f32 v118, v248, v249
	v_cvt_pk_f16_f32 v117, v189, v243
	v_cvt_pk_f16_f32 v116, v173, v188
	s_waitcnt lgkmcnt(0)
	s_nop 0
	v_mfma_f32_16x16x32_f16 v[76:79], v[120:123], v[116:119], v[76:79]
	ds_read_b64_tr_b16 v[120:121], v206 offset:5152
	ds_read_b64_tr_b16 v[122:123], v206 offset:7712
	s_waitcnt lgkmcnt(0)
	v_mfma_f32_16x16x32_f16 v[80:83], v[120:123], v[116:119], v[80:83]
	ds_read_b64_tr_b16 v[120:121], v206 offset:5184
	ds_read_b64_tr_b16 v[122:123], v206 offset:7744
	s_waitcnt lgkmcnt(0)
	v_mfma_f32_16x16x32_f16 v[84:87], v[120:123], v[116:119], v[84:87]
	ds_read_b64_tr_b16 v[120:121], v206 offset:5216
	ds_read_b64_tr_b16 v[122:123], v206 offset:7776
	s_waitcnt lgkmcnt(0)
	v_mfma_f32_16x16x32_f16 v[88:91], v[120:123], v[116:119], v[88:91]

; __device__ __forceinline__ float quadsum(float v) { v += dppf<0xB1>(v); v += dppf<0x4E>(v); return v; }
; __device__ __forceinline__ int fetch_unit(unsigned* ctr, int* slot) {
;   __syncthreads();
;   if (threadIdx.x == 0) *slot = (int)atomicAdd(ctr, 1u);
;   __syncthreads();
;     ...
;     {
;       const float ls = sum4q(st.l);
;       const float f = ls > 0.f ? (float)gp[2] / ls : 0.f;
;       float ss = 0.f;
; #pragma unroll
;       for (int nt = 0; nt < 4; ++nt) {
;         Oc[nt] += O[nt] * f;
; #pragma unroll
;         for (int j = 0; j < 4; ++j) ss += Oc[nt][j] * Oc[nt][j];
;       }
;       ss = quadsum(sum4q(ss));
;       const float sc = rsqrtf(ss * (1.f / 256.f) + EPS);
; #pragma unroll
;       for (int nt = 0; nt < 4; ++nt)
;         *(h16x4*)(OAC + ((size_t)b * SEQ + tq) * 1024 + 256 + hd * 64 + nt * 16 + q4 * 4) =
;             pack4(Oc[nt][0] * sc, Oc[nt][1] * sc, Oc[nt][2] * sc, Oc[nt][3] * sc);
;     }
.LBB0_2049:
	s_or_b64 exec, exec, s[0:1]
	v_cvt_f32_f16_e32 v2, v171
	v_pk_mul_f32 v[6:7], v[28:29], v[124:125] op_sel_hi:[1,0]
	v_pk_mul_f32 v[4:5], v[30:31], v[124:125] op_sel_hi:[1,0]
	v_pk_mul_f32 v[10:11], v[32:33], v[124:125] op_sel_hi:[1,0]
	v_pk_fma_f32 v[6:7], v[12:13], v[2:3], v[6:7] op_sel_hi:[1,0,1]
	v_pk_fma_f32 v[4:5], v[14:15], v[2:3], v[4:5] op_sel_hi:[1,0,1]
	v_pk_mul_f32 v[14:15], v[36:37], v[124:125] op_sel_hi:[1,0]
	v_pk_fma_f32 v[6:7], v[76:77], v[0:1], v[6:7] op_sel_hi:[1,0,1]
	v_pk_fma_f32 v[14:15], v[20:21], v[2:3], v[14:15] op_sel_hi:[1,0,1]
	v_mul_f32_e32 v20, v7, v7
	v_pk_fma_f32 v[4:5], v[78:79], v[0:1], v[4:5] op_sel_hi:[1,0,1]
	v_fmac_f32_e32 v20, v6, v6
	v_pk_fma_f32 v[10:11], v[16:17], v[2:3], v[10:11] op_sel_hi:[1,0,1]
	v_fmac_f32_e32 v20, v4, v4
	v_pk_mul_f32 v[8:9], v[34:35], v[124:125] op_sel_hi:[1,0]
	v_fmac_f32_e32 v20, v5, v5
	v_pk_fma_f32 v[10:11], v[80:81], v[0:1], v[10:11] op_sel_hi:[1,0,1]
	v_pk_fma_f32 v[8:9], v[18:19], v[2:3], v[8:9] op_sel_hi:[1,0,1]
	v_fmac_f32_e32 v20, v10, v10
	v_pk_fma_f32 v[8:9], v[82:83], v[0:1], v[8:9] op_sel_hi:[1,0,1]
	v_fmac_f32_e32 v20, v11, v11
	v_fmac_f32_e32 v20, v8, v8
	v_pk_mul_f32 v[12:13], v[38:39], v[124:125] op_sel_hi:[1,0]
	v_fmac_f32_e32 v20, v9, v9
	v_pk_fma_f32 v[14:15], v[84:85], v[0:1], v[14:15] op_sel_hi:[1,0,1]
	v_pk_fma_f32 v[12:13], v[22:23], v[2:3], v[12:13] op_sel_hi:[1,0,1]
	v_fmac_f32_e32 v20, v14, v14
	v_pk_mul_f32 v[18:19], v[40:41], v[124:125] op_sel_hi:[1,0]
	v_pk_fma_f32 v[12:13], v[86:87], v[0:1], v[12:13] op_sel_hi:[1,0,1]
	v_fmac_f32_e32 v20, v15, v15
	v_pk_mul_f32 v[16:17], v[42:43], v[124:125] op_sel_hi:[1,0]
	v_pk_fma_f32 v[18:19], v[24:25], v[2:3], v[18:19] op_sel_hi:[1,0,1]
	v_fmac_f32_e32 v20, v12, v12
	v_pk_fma_f32 v[2:3], v[26:27], v[2:3], v[16:17] op_sel_hi:[1,0,1]
	v_fmac_f32_e32 v20, v13, v13
	v_pk_fma_f32 v[16:17], v[88:89], v[0:1], v[18:19] op_sel_hi:[1,0,1]
	v_pk_fma_f32 v[2:3], v[90:91], v[0:1], v[2:3] op_sel_hi:[1,0,1]
	v_fmac_f32_e32 v20, v16, v16
	v_fmac_f32_e32 v20, v17, v17
	v_pk_mul_f32 v[18:19], v[2:3], v[2:3]
	s_lshl_b32 s0, s92, 24
	v_add_f32_e32 v0, v18, v20
	v_add_f32_e32 v0, v19, v0
	v_mov_b32_e32 v18, v0
	s_nop 1
	v_permlane16_swap_b32_e32 v18, v0
	v_readlane_b32 s1, v255, 34
	s_add_u32 s0, s1, s0
	v_readlane_b32 s1, v255, 35
	s_addc_u32 s1, s1, 0
	s_waitcnt lgkmcnt(0)
	v_add_f32_e32 v0, v0, v18
	v_mov_b32_e32 v18, v0
	s_nop 1
	v_permlane32_swap_b32_e32 v0, v18
	v_add_f32_e32 v0, v0, v18
	v_lshlrev_b64 v[20:21], 11, v[182:183]
	v_lshl_add_u64 v[20:21], s[0:1], 0, v[20:21]
	v_add_f32_dpp v0, v0, v0 quad_perm:[1,0,3,2] row_mask:0xf bank_mask:0xf bound_ctrl:1
	v_mov_b32_e32 v181, v1
	v_lshl_add_u64 v[20:21], v[20:21], 0, v[180:181]
	v_add_f32_dpp v0, v0, v0 quad_perm:[2,3,0,1] row_mask:0xf bank_mask:0xf bound_ctrl:1
	v_fmamk_f32 v0, v0, 0x3b800000, v144
	v_mul_f32_e32 v18, 0x4b800000, v0
	v_cmp_gt_f32_e32 vcc, s75, v0
	s_mov_b64 s[0:1], 0x1787dc00
	s_nop 0
	v_cndmask_b32_e32 v0, v0, v18, vcc
	v_rsq_f32_e32 v0, v0
	s_nop 0
	v_mul_f32_e32 v18, 0x45800000, v0
	v_cndmask_b32_e32 v18, v0, v18, vcc
	v_lshlrev_b32_e32 v0, 1, v154
	v_lshl_add_u64 v[20:21], v[20:21], 0, v[0:1]
	v_fma_mixlo_f16 v0, v6, v18, 0
	v_pk_mov_b32 v[6:7], v[6:7], v[4:5] op_sel:[1,0]
	v_lshl_add_u64 v[22:23], v[20:21], 0, s[0:1]
	v_pk_mul_f32 v[6:7], v[6:7], v[18:19] op_sel_hi:[1,0]
	s_mov_b32 s0, 0x1787d000
	v_cvt_pk_f16_f32 v6, v6, v7
	v_pack_b32_f16 v4, v0, v6
	v_fma_mixlo_f16 v0, v5, v18, 0
	v_alignbit_b32 v5, v0, v6, 16
	v_add_co_u32_e32 v6, vcc, s0, v20
	v_fma_mixlo_f16 v0, v10, v18, 0
	s_nop 0
	v_addc_co_u32_e32 v7, vcc, 0, v21, vcc
	global_store_dwordx2 v[6:7], v[4:5], off offset:3072
	v_pk_mov_b32 v[4:5], v[10:11], v[8:9] op_sel:[1,0]
	s_nop 0
	v_pk_mul_f32 v[4:5], v[4:5], v[18:19] op_sel_hi:[1,0]
	s_nop 0
	v_cvt_pk_f16_f32 v5, v4, v5
	v_pack_b32_f16 v4, v0, v5
	v_fma_mixlo_f16 v0, v9, v18, 0
	v_alignbit_b32 v5, v0, v5, 16
	global_store_dwordx2 v[22:23], v[4:5], off offset:32
	v_pk_mov_b32 v[4:5], v[14:15], v[12:13] op_sel:[1,0]
	v_fma_mixlo_f16 v0, v14, v18, 0
	v_pk_mul_f32 v[4:5], v[4:5], v[18:19] op_sel_hi:[1,0]
	s_nop 0
	v_cvt_pk_f16_f32 v5, v4, v5
	v_pack_b32_f16 v4, v0, v5
	v_fma_mixlo_f16 v0, v13, v18, 0
	v_alignbit_b32 v5, v0, v5, 16
	global_store_dwordx2 v[22:23], v[4:5], off offset:64
	v_pk_mov_b32 v[4:5], v[16:17], v[2:3] op_sel:[1,0]
	v_fma_mixlo_f16 v0, v16, v18, 0
	v_pk_mul_f32 v[4:5], v[4:5], v[18:19] op_sel_hi:[1,0]
	s_nop 0
	v_cvt_pk_f16_f32 v4, v4, v5
	v_pack_b32_f16 v2, v0, v4
	v_fma_mixlo_f16 v0, v3, v18, 0
	v_alignbit_b32 v3, v0, v4, 16
	global_store_dwordx2 v[22:23], v[2:3], off offset:96
	s_barrier
	s_mov_b64 s[0:1], exec
	v_readlane_b32 s2, v254, 0
	v_readlane_b32 s3, v254, 1
	s_and_b64 s[2:3], s[0:1], s[2:3]
	s_mov_b64 exec, s[2:3]
	s_cbranch_execz .LBB0_738
	s_mov_b64 s[44:45], exec
	v_mbcnt_lo_u32_b32 v0, s44, 0
	v_mbcnt_hi_u32_b32 v0, s45, v0
	v_cmp_eq_u32_e32 vcc, 0, v0
	s_and_saveexec_b64 s[42:43], vcc
	s_cbranch_execz .LBB0_737
	s_bcnt1_i32_b64 s2, s[44:45]
	v_mov_b32_e32 v2, s2
	v_readlane_b32 s2, v255, 32
	v_readlane_b32 s3, v255, 33
	s_nop 4
	global_atomic_add v2, v1, v2, s[2:3] sc0
	s_branch .LBB0_737

; template <int MODE, int RGM> ...
;     ...
;       for (int kt = 0; kt < 4; ++kt)
; #pragma unroll
;         for (int j = 0; j < 4; ++j) {
;           const int dist = d0 - DK * (kt * 16 + j);
;           const int kx = kx0 + kt * 16 + j;
;           bool valid = dist >= 0;
;           if (MODE == M_SWA) valid = valid && dist < 128 && kx >= 0;
;           if (MODE == M_WIN) valid = valid && dist < 512 && kx >= 0;
;           if (MODE == M_SEL) valid = valid && selbit[rg];
;           if (DK == 16) valid = valid && kx < NCMP;
;           const int dc = dist < 0 ? 0 : (dist > 799 ? 799 : dist);
;           S[rg][kt][j] = valid ? S[rg][kt][j] * SCL2 + bt[dc] : -1e30f;
;         }
;     }
;     if (MODE == M_CMPB) {
; #pragma unroll
;       for (int kt = 0; kt < 4; ++kt) {
;         float h = 0.f;
; #pragma unroll
;         for (int j = 0; j < 4; ++j) {
;           float pv = __builtin_amdgcn_exp2f(S[rg][kt][j] - st[rg].m) * st[rg].l;
;           S[rg][kt][j] = pv;
;           h += pv;
;         }
;         hq[rg][kt] = h;
;         h3[rg][kt] = S[rg][kt][3];
;       }
;     } else {
;       float mx = -1e30f;
; #pragma unroll
;       for (int kt = 0; kt < 4; ++kt)
; #pragma unroll
;         for (int j = 0; j < 4; ++j) mx = fmaxf(mx, S[rg][kt][j]);
;       mx = max4q(mx);
;       const float mn = fmaxf(st[rg].m, mx);
;       const float corr = __builtin_amdgcn_exp2f(st[rg].m - mn);
;       st[rg].m = mn;
;       const float mm = fmaxf(mn, -1e20f);
.LBB0_2178:
	s_or_b64 exec, exec, s[0:1]
	v_mov_b32_e32 v82, 0xf149f2ca
	v_max3_f32 v83, v130, v82, v129
	v_max3_f32 v83, v83, v95, v94
	v_max3_f32 v83, v83, v97, v96
	v_max3_f32 v83, v83, v91, v90
	v_max3_f32 v83, v83, v93, v92
	v_max3_f32 v83, v83, v87, v86
	v_max3_f32 v83, v83, v89, v88
	v_max3_f32 v83, v83, v135, v134
	v_mov_b32_e32 v84, v83
	s_nop 1
	v_permlane16_swap_b32_e32 v84, v83
	v_add_u32_e32 v85, 0x90, v132
	v_cmp_gt_u32_e64 s[0:1], s77, v85
	s_and_b64 s[74:75], s[86:87], s[0:1]
	s_waitcnt lgkmcnt(0)
	v_max_f32_e32 v84, v84, v84
	v_max_f32_e32 v141, v83, v84
	v_mov_b32_e32 v152, v141
	s_nop 1
	v_permlane32_swap_b32_e32 v141, v152
	v_mov_b32_e32 v83, 0xf149f2ca
	s_and_saveexec_b64 s[0:1], s[74:75]
	s_cbranch_execz .LBB0_2180
	ds_read_b32 v83, v131 offset:576
	s_waitcnt lgkmcnt(0)
	v_fmac_f32_e32 v83, 0x3e38aa3b, v78

; #define LAS __attribute__((address_space(3)))
; template <int MODE, int RGM> ...
;     ...
;       const float mn = fmaxf(st[rg].m, mx);
;       const float corr = __builtin_amdgcn_exp2f(st[rg].m - mn);
;       st[rg].m = mn;
;       const float mm = fmaxf(mn, -1e20f);
;       float ls = 0.f;
; #pragma unroll
;       for (int kt = 0; kt < 4; ++kt)
; #pragma unroll
;         for (int j = 0; j < 4; ++j) {
;           float pv = __builtin_amdgcn_exp2f(S[rg][kt][j] - mm);
;           S[rg][kt][j] = pv;
;           ls += pv;
;         }
;       st[rg].l = st[rg].l * corr + ls;
;       if (MODE != M_CMPA) {
; #pragma unroll
;         for (int nt = 0; nt < 4; ++nt) O[rg][nt] *= corr;
;       }
;     }
;     if (MODE != M_CMPA) {
; #pragma unroll
;       for (int ks = 0; ks < 2; ++ks)
; #pragma unroll
;         for (int i = 0; i < 4; ++i) {
;           Pf[rg][ks][i] = (h16)S[rg][2 * ks][i];
;           Pf[rg][ks][4 + i] = (h16)S[rg][2 * ks + 1][i];
;         }
;     }
;   }
;   if (MODE == M_CMPA) return;
; #pragma unroll
;   for (int ks = 0; ks < 2; ++ks)
; #pragma unroll
;     for (int nt = 0; nt < 4; ++nt) {
;       const h16* vp = Vt + (ks * 32 + q4 * 4 + (col >> 2)) * KP + nt * 16 + 4 * (col & 3);
;       const s16x4v r0 = __builtin_amdgcn_ds_read_tr16_b64_v4i16((LAS s16x4v*)vp);
;       const s16x4v r1 = __builtin_amdgcn_ds_read_tr16_b64_v4i16((LAS s16x4v*)(vp + 16 * KP));
;       const h16x4 v0 = __builtin_bit_cast(h16x4, r0), v1 = __builtin_bit_cast(h16x4, r1);
;       const h16x8 Vf = {v0[0], v0[1], v0[2], v0[3], v1[0], v1[1], v1[2], v1[3]};
; #pragma unroll
;       for (int rg = 0; rg < 2; ++rg)
;         if (RGM & (1 << rg)) O[rg][nt] = __builtin_amdgcn_mfma_f32_16x16x32_f16(Vf, Pf[rg][ks], O[rg][nt], 0, 0, 0);
.LBB0_2210:
	s_or_b64 exec, exec, s[0:1]
	v_max3_f32 v75, v128, v141, v152
	v_max_f32_e32 v66, 0xe0ad78ec, v75
	v_sub_f32_e32 v67, v130, v66
	v_exp_f32_e32 v130, v67
	v_sub_f32_e32 v68, v129, v66
	v_sub_f32_e32 v67, v128, v75
	v_exp_f32_e32 v128, v68
	v_sub_f32_e32 v69, v95, v66
	v_exp_f32_e32 v95, v69
	v_sub_f32_e32 v69, v94, v66
	v_exp_f32_e32 v94, v69
	v_sub_f32_e32 v69, v97, v66
	v_add_f32_e32 v68, 0, v130
	v_exp_f32_e32 v97, v69
	v_sub_f32_e32 v69, v96, v66
	v_add_f32_e32 v68, v128, v68
	v_exp_f32_e32 v96, v69
	v_sub_f32_e32 v69, v91, v66
	v_add_f32_e32 v68, v95, v68
	v_exp_f32_e32 v91, v69
	v_sub_f32_e32 v69, v90, v66
	v_add_f32_e32 v68, v94, v68
	v_exp_f32_e32 v90, v69
	v_sub_f32_e32 v69, v93, v66
	v_add_f32_e32 v68, v97, v68
	v_exp_f32_e32 v93, v69
	v_sub_f32_e32 v69, v92, v66
	v_add_f32_e32 v68, v96, v68
	v_exp_f32_e32 v92, v69
	v_sub_f32_e32 v69, v87, v66
	v_add_f32_e32 v68, v91, v68
	v_exp_f32_e32 v87, v69
	v_sub_f32_e32 v69, v86, v66
	v_add_f32_e32 v68, v90, v68
	v_exp_f32_e32 v86, v69
	v_sub_f32_e32 v69, v89, v66
	v_add_f32_e32 v68, v93, v68
	v_exp_f32_e32 v89, v69
	v_sub_f32_e32 v69, v88, v66
	v_add_f32_e32 v68, v92, v68
	v_exp_f32_e32 v88, v69
	v_sub_f32_e32 v69, v135, v66
	v_add_f32_e32 v68, v87, v68
	v_exp_f32_e32 v129, v69
	v_sub_f32_e32 v66, v134, v66
	v_add_f32_e32 v68, v86, v68
	v_exp_f32_e32 v131, v66
	v_add_f32_e32 v68, v89, v68
	v_exp_f32_e32 v76, v67
	v_add_f32_e32 v66, v88, v68
	v_add_f32_e32 v66, v129, v66
	v_add_f32_e32 v77, v131, v66
	v_fmac_f32_e32 v77, v127, v76
	v_pk_mul_f32 v[66:67], v[54:55], v[76:77] op_sel_hi:[1,0]
	v_pk_mul_f32 v[54:55], v[58:59], v[76:77] op_sel_hi:[1,0]
	v_max3_f32 v58, v83, s67, v82
	v_max3_f32 v58, v58, v85, v84
	v_max3_f32 v58, v58, v133, v132
	v_max3_f32 v58, v58, v136, v74
	v_max3_f32 v58, v58, v138, v137
	v_max3_f32 v58, v58, v140, v139
	v_max3_f32 v58, v58, v81, v80
	v_pk_mul_f32 v[72:73], v[52:53], v[76:77] op_sel_hi:[1,0]
	v_pk_mul_f32 v[70:71], v[50:51], v[76:77] op_sel_hi:[1,0]
	v_pk_mul_f32 v[68:69], v[56:57], v[76:77] op_sel_hi:[1,0]
	v_pk_mul_f32 v[56:57], v[60:61], v[76:77] op_sel_hi:[1,0]
	v_pk_mul_f32 v[52:53], v[64:65], v[76:77] op_sel_hi:[1,0]
	v_pk_mul_f32 v[50:51], v[62:63], v[76:77] op_sel_hi:[1,0]
	v_max3_f32 v76, v58, v79, v78
	v_cvt_pk_f16_f32 v63, v87, v86
	v_mov_b32_e32 v86, v76
	s_nop 1
	v_permlane16_swap_b32_e32 v86, v76
	v_cvt_pk_f16_f32 v59, v95, v94
	v_cvt_pk_f16_f32 v58, v130, v128
	v_cvt_pk_f16_f32 v65, v129, v131
	v_cvt_pk_f16_f32 v62, v93, v92
	s_waitcnt lgkmcnt(0)
	v_max_f32_e32 v86, v86, v86
	v_max_f32_e32 v76, v76, v86
	v_mov_b32_e32 v86, v76
	s_nop 1
	v_permlane32_swap_b32_e32 v76, v86
	v_max3_f32 v76, v126, v76, v86
	v_max_f32_e32 v127, 0xe0ad78ec, v76
	v_sub_f32_e32 v83, v83, v127
	v_exp_f32_e32 v86, v83
	v_sub_f32_e32 v82, v82, v127
	v_exp_f32_e32 v94, v82
	v_sub_f32_e32 v82, v85, v127
	v_exp_f32_e32 v87, v82
	v_add_f32_e32 v83, 0, v86
	v_add_f32_e32 v83, v94, v83
	v_sub_f32_e32 v82, v126, v76
	v_add_f32_e32 v126, v87, v83
	v_sub_f32_e32 v83, v84, v127
	v_exp_f32_e32 v128, v83
	v_sub_f32_e32 v83, v133, v127
	v_sub_f32_e32 v74, v74, v127
	v_exp_f32_e32 v129, v83
	v_sub_f32_e32 v83, v132, v127
	v_exp_f32_e32 v132, v74
	v_sub_f32_e32 v74, v138, v127
	v_exp_f32_e32 v133, v74
	v_sub_f32_e32 v74, v137, v127
	v_exp_f32_e32 v130, v83
	v_sub_f32_e32 v83, v136, v127
	v_exp_f32_e32 v134, v74
	v_sub_f32_e32 v74, v140, v127
	v_exp_f32_e32 v131, v83
	v_exp_f32_e32 v135, v74
	v_exp_f32_e32 v74, v82
	ds_read_b64_tr_b16 v[84:85], v122 offset:35840
	ds_read_b64_tr_b16 v[82:83], v122 offset:33280
	v_cvt_pk_f16_f32 v61, v91, v90
	ds_read_b64_tr_b16 v[90:91], v122 offset:33312
	ds_read_b64_tr_b16 v[92:93], v122 offset:35872
	v_cvt_pk_f16_f32 v64, v89, v88
	v_sub_f32_e32 v88, v139, v127
	v_cvt_pk_f16_f32 v60, v97, v96
	v_exp_f32_e32 v136, v88
	v_sub_f32_e32 v81, v81, v127
	v_pk_mul_f32 v[48:49], v[48:49], v[74:75] op_sel_hi:[1,0]
	v_pk_mul_f32 v[46:47], v[46:47], v[74:75] op_sel_hi:[1,0]
	v_cvt_pk_f16_f32 v89, v131, v132
	v_cvt_pk_f16_f32 v88, v129, v130
	v_cvt_pk_f16_f32 v87, v87, v128
	v_cvt_pk_f16_f32 v86, v86, v94
	v_exp_f32_e32 v137, v81
	s_waitcnt lgkmcnt(2)
	v_mfma_f32_16x16x32_f16 v[70:73], v[82:85], v[58:61], v[70:73]
	v_mul_f32_e64 v44, v44, v74
	v_mul_f32_e64 v45, v45, v74
	v_pk_mul_f32 v[42:43], v[42:43], v[74:75] op_sel_hi:[1,0]
	v_pk_mul_f32 v[40:41], v[40:41], v[74:75] op_sel_hi:[1,0]
	v_mfma_f32_16x16x32_f16 v[46:49], v[82:85], v[86:89], v[46:49]
	v_sub_f32_e32 v84, v80, v127
	ds_read_b64_tr_b16 v[80:81], v122 offset:33344
	ds_read_b64_tr_b16 v[82:83], v122 offset:35904
	v_pk_mul_f32 v[38:39], v[38:39], v[74:75] op_sel_hi:[1,0]
	s_waitcnt lgkmcnt(2)
	v_mfma_f32_16x16x32_f16 v[66:69], v[90:93], v[58:61], v[66:69]
	v_sub_f32_e32 v79, v79, v127
	v_exp_f32_e32 v138, v84
	v_exp_f32_e32 v139, v79
	v_mfma_f32_16x16x32_f16 v[42:45], v[90:93], v[86:89], v[42:45]
	ds_read_b64_tr_b16 v[90:91], v122 offset:33376
	ds_read_b64_tr_b16 v[92:93], v122 offset:35936
	v_pk_mul_f32 v[36:37], v[36:37], v[74:75] op_sel_hi:[1,0]
	v_pk_mul_f32 v[34:35], v[34:35], v[74:75] op_sel_hi:[1,0]
	s_waitcnt lgkmcnt(2)
	v_mfma_f32_16x16x32_f16 v[94:97], v[80:83], v[58:61], v[54:57]
	s_nop 2
	ds_read_b64_tr_b16 v[54:55], v122 offset:38400
	ds_read_b64_tr_b16 v[56:57], v122 offset:40960
	v_cvt_pk_f16_f32 v84, v137, v138
	s_add_i32 s71, s71, 1
	v_mfma_f32_16x16x32_f16 v[38:41], v[80:83], v[86:89], v[38:41]
	v_sub_f32_e32 v82, v78, v127
	v_exp_f32_e32 v127, v82
	v_cvt_pk_f16_f32 v83, v135, v136
	s_waitcnt lgkmcnt(2)
; #define LAS __attribute__((address_space(3)))
; template <int MODE, int RGM> ...
;     ...
; #pragma unroll
;   for (int ks = 0; ks < 2; ++ks)
; #pragma unroll
;     for (int nt = 0; nt < 4; ++nt) {
;       const h16* vp = Vt + (ks * 32 + q4 * 4 + (col >> 2)) * KP + nt * 16 + 4 * (col & 3);
;       const s16x4v r0 = __builtin_amdgcn_ds_read_tr16_b64_v4i16((LAS s16x4v*)vp);
;       const s16x4v r1 = __builtin_amdgcn_ds_read_tr16_b64_v4i16((LAS s16x4v*)(vp + 16 * KP));
;       const h16x4 v0 = __builtin_bit_cast(h16x4, r0), v1 = __builtin_bit_cast(h16x4, r1);
;       const h16x8 Vf = {v0[0], v0[1], v0[2], v0[3], v1[0], v1[1], v1[2], v1[3]};
; #pragma unroll
;       for (int rg = 0; rg < 2; ++rg)
;         if (RGM & (1 << rg)) O[rg][nt] = __builtin_amdgcn_mfma_f32_16x16x32_f16(Vf, Pf[rg][ks], O[rg][nt], 0, 0, 0);
;     }
; __device__ __forceinline__ void phase_swa(const Params& p, int l, char* lds, unsigned* ctr, int* slot) {
;     ...
;     __syncthreads();
; #pragma unroll
;     for (int rg = 0; rg < 2; ++rg) {
;       const int qb = (w & 1) * 32 + rg * 16;
;       const float lsum = sum4q(st[rg].l);
;       const float mn = fmaxf(st[rg].m, sink);
;       const float corr = __builtin_amdgcn_exp2f(st[rg].m - mn);
;       const float inv = corr / (lsum * corr + __builtin_amdgcn_exp2f(sink - mn));
;       float ss = 0.f;
; #pragma unroll
;       for (int nt = 0; nt < 4; ++nt) {
;         O[rg][nt] *= inv;
; #pragma unroll
;         for (int j = 0; j < 4; ++j) ss += O[rg][nt][j] * O[rg][nt][j];
;       }
;       ss = sum4q(ss);
;       if (q4 == 0) nrm[head * 64 + qb + col] = ss;
;     }
	v_mfma_f32_16x16x32_f16 v[78:81], v[90:93], v[58:61], v[50:53]
	ds_read_b64_tr_b16 v[58:59], v122 offset:38432
	ds_read_b64_tr_b16 v[60:61], v122 offset:40992
	v_cvt_pk_f16_f32 v85, v139, v127
	v_cvt_pk_f16_f32 v82, v133, v134
	v_mfma_f32_16x16x32_f16 v[34:37], v[90:93], v[86:89], v[34:37]
	v_add_f32_e32 v86, v128, v126
	s_add_i32 s91, s91, 64
	s_sub_i32 s70, s70, 64
	s_waitcnt lgkmcnt(2)
	v_mfma_f32_16x16x32_f16 v[50:53], v[54:57], v[62:65], v[70:73]
	s_nop 2
	ds_read_b64_tr_b16 v[70:71], v122 offset:38464
	ds_read_b64_tr_b16 v[72:73], v122 offset:41024
	v_add_u32_e32 v107, 0xffffff00, v107
	v_add_u32_e32 v123, 64, v123
	v_mfma_f32_16x16x32_f16 v[46:49], v[54:57], v[82:85], v[46:49]
	v_add_u32_e32 v0, 0x1c000, v0
	s_cmp_gt_u32 s71, 1
	v_add_u32_e32 v124, 64, v124
	s_waitcnt lgkmcnt(2)
	v_mfma_f32_16x16x32_f16 v[54:57], v[58:61], v[62:65], v[66:69]
	s_nop 2
	v_add_f32_e32 v66, v129, v86
	v_add_f32_e32 v66, v130, v66
	v_add_f32_e32 v66, v131, v66
	v_add_f32_e32 v66, v132, v66
	ds_read_b64_tr_b16 v[86:87], v122 offset:38496
	ds_read_b64_tr_b16 v[88:89], v122 offset:41056
	v_add_f32_e32 v66, v133, v66
	v_add_f32_e32 v66, v134, v66
	v_add_f32_e32 v66, v135, v66
	v_add_f32_e32 v66, v136, v66
	v_add_f32_e32 v66, v137, v66
	v_mfma_f32_16x16x32_f16 v[42:45], v[58:61], v[82:85], v[42:45]
	v_add_f32_e32 v66, v138, v66
	v_add_f32_e32 v66, v139, v66
	v_add_f32_e32 v66, v127, v66
	s_waitcnt lgkmcnt(2)
	v_mfma_f32_16x16x32_f16 v[58:61], v[70:73], v[62:65], v[94:97]
	v_fmac_f32_e32 v66, v125, v74
	v_mfma_f32_16x16x32_f16 v[38:41], v[70:73], v[82:85], v[38:41]
	s_waitcnt lgkmcnt(0)
	v_mfma_f32_16x16x32_f16 v[62:65], v[86:89], v[62:65], v[78:81]
	v_mfma_f32_16x16x32_f16 v[34:37], v[86:89], v[82:85], v[34:37]
	s_cbranch_scc1 .LBB0_2212
	v_mov_b32_e32 v125, v66
	v_mov_b32_e32 v126, v76
	v_mov_b32_e32 v127, v77
	v_mov_b32_e32 v128, v75
	s_branch .LBB0_2136
.LBB0_2212:
	ds_swizzle_b32 v2, v77 offset:swizzle(SWAP,16)
	v_max_f32_e32 v0, v99, v99
	v_max_f32_e32 v3, v75, v75
	v_max_f32_e32 v3, v3, v0
	v_sub_f32_e32 v4, v75, v3
	v_sub_f32_e32 v3, v99, v3
	s_waitcnt lgkmcnt(0)
	v_add_f32_e32 v2, v77, v2
	v_exp_f32_e32 v4, v4
	v_exp_f32_e32 v3, v3
	v_mov_b32_e32 v5, v2
	s_nop 1
	v_permlane32_swap_b32_e32 v2, v5
	v_add_f32_e32 v2, v2, v5
	v_fmac_f32_e32 v3, v4, v2
	v_div_scale_f32 v2, s[0:1], v3, v3, v4
	v_rcp_f32_e32 v5, v2
	s_barrier
	v_fma_f32 v6, -v2, v5, 1.0
	v_fmac_f32_e32 v5, v6, v5
	v_div_scale_f32 v6, vcc, v4, v3, v4
	v_mul_f32_e32 v7, v6, v5
	v_fma_f32 v8, -v2, v7, v6
	v_fmac_f32_e32 v7, v8, v5
	v_fma_f32 v2, -v2, v7, v6
	v_div_fmas_f32 v2, v2, v5, v7
	v_div_fixup_f32 v16, v2, v3, v4
	v_pk_mul_f32 v[10:11], v[50:51], v[16:17] op_sel_hi:[1,0]
	v_pk_mul_f32 v[4:5], v[52:53], v[16:17] op_sel_hi:[1,0]
	s_waitcnt vmcnt(0)
	v_mul_f32_e32 v18, v11, v11
	v_fmac_f32_e32 v18, v10, v10
	v_fmac_f32_e32 v18, v4, v4
	v_fmac_f32_e32 v18, v5, v5
	v_pk_mul_f32 v[12:13], v[54:55], v[16:17] op_sel_hi:[1,0]
	v_pk_mul_f32 v[6:7], v[56:57], v[16:17] op_sel_hi:[1,0]
	v_fmac_f32_e32 v18, v12, v12
	v_fmac_f32_e32 v18, v13, v13
	v_fmac_f32_e32 v18, v6, v6
	v_fmac_f32_e32 v18, v7, v7
	v_pk_mul_f32 v[14:15], v[58:59], v[16:17] op_sel_hi:[1,0]
	v_pk_mul_f32 v[8:9], v[60:61], v[16:17] op_sel_hi:[1,0]
	v_fmac_f32_e32 v18, v14, v14
	v_fmac_f32_e32 v18, v15, v15
	v_fmac_f32_e32 v18, v8, v8
	v_fmac_f32_e32 v18, v9, v9
	v_pk_mul_f32 v[2:3], v[64:65], v[16:17] op_sel_hi:[1,0]
	v_pk_mul_f32 v[16:17], v[62:63], v[16:17] op_sel_hi:[1,0]
	s_nop 0
	v_fmac_f32_e32 v18, v16, v16
	v_fmac_f32_e32 v18, v17, v17
	v_fmac_f32_e32 v18, v2, v2
	v_fmac_f32_e32 v18, v3, v3
	v_mov_b32_e32 v19, v18
	s_nop 1
	v_permlane16_swap_b32_e32 v19, v18
	s_waitcnt lgkmcnt(0)
	v_add_f32_e32 v18, v18, v19
	v_mov_b32_e32 v19, v18
	s_nop 1
	v_permlane32_swap_b32_e32 v18, v19
	s_and_saveexec_b64 s[0:1], s[4:5]
	v_add_f32_e32 v18, v18, v19
	ds_write_b32 v112, v18 offset:53760
	s_or_b64 exec, exec, s[0:1]
	ds_swizzle_b32 v18, v66 offset:swizzle(SWAP,16)
	v_max_f32_e32 v19, v76, v76
	v_max_f32_e32 v0, v19, v0
	v_sub_f32_e32 v19, v76, v0
	v_sub_f32_e32 v0, v99, v0
	v_exp_f32_e32 v19, v19
	s_waitcnt lgkmcnt(0)
	v_add_f32_e32 v18, v66, v18
	v_exp_f32_e32 v0, v0
	v_mov_b32_e32 v20, v18
	s_nop 1
	v_permlane32_swap_b32_e32 v18, v20
	v_add_f32_e32 v18, v18, v20
	v_fmac_f32_e32 v0, v19, v18
	v_div_scale_f32 v18, s[0:1], v0, v0, v19
	v_rcp_f32_e32 v20, v18
	s_nop 0
	v_fma_f32 v21, -v18, v20, 1.0
	v_fmac_f32_e32 v20, v21, v20
	v_div_scale_f32 v21, vcc, v19, v0, v19
	v_mul_f32_e32 v22, v21, v20
	v_fma_f32 v23, -v18, v22, v21
	v_fmac_f32_e32 v22, v23, v20
	v_fma_f32 v18, -v18, v22, v21
	v_div_fmas_f32 v18, v18, v20, v22
	v_div_fixup_f32 v0, v18, v0, v19
	v_pk_mul_f32 v[32:33], v[46:47], v[0:1] op_sel_hi:[1,0]
	v_pk_mul_f32 v[24:25], v[48:49], v[0:1] op_sel_hi:[1,0]
	v_mul_f32_e32 v46, v33, v33
	v_fmac_f32_e32 v46, v32, v32
	v_fmac_f32_e32 v46, v24, v24
	v_fmac_f32_e32 v46, v25, v25
	v_pk_mul_f32 v[30:31], v[42:43], v[0:1] op_sel_hi:[1,0]
	v_pk_mul_f32 v[22:23], v[44:45], v[0:1] op_sel_hi:[1,0]
	v_fmac_f32_e32 v46, v30, v30
	v_fmac_f32_e32 v46, v31, v31
	v_fmac_f32_e32 v46, v22, v22
	v_fmac_f32_e32 v46, v23, v23
	v_pk_mul_f32 v[28:29], v[38:39], v[0:1] op_sel_hi:[1,0]
	v_pk_mul_f32 v[20:21], v[40:41], v[0:1] op_sel_hi:[1,0]
	v_fmac_f32_e32 v46, v28, v28
	v_fmac_f32_e32 v46, v29, v29
	v_fmac_f32_e32 v46, v20, v20
	v_fmac_f32_e32 v46, v21, v21
	v_pk_mul_f32 v[26:27], v[34:35], v[0:1] op_sel_hi:[1,0]
	v_pk_mul_f32 v[18:19], v[36:37], v[0:1] op_sel_hi:[1,0]
	v_fmac_f32_e32 v46, v26, v26
	v_fmac_f32_e32 v46, v27, v27
	v_fmac_f32_e32 v46, v18, v18
	v_fmac_f32_e32 v46, v19, v19
	v_mov_b32_e32 v0, v46
	s_nop 1
	v_permlane16_swap_b32_e32 v0, v46
	s_waitcnt lgkmcnt(0)
	v_add_f32_e32 v0, v46, v0
	v_mov_b32_e32 v34, v0
	s_nop 1
	v_permlane32_swap_b32_e32 v0, v34
	s_and_saveexec_b64 s[0:1], s[4:5]
	v_add_f32_e32 v0, v0, v34
	ds_write_b32 v112, v0 offset:53824
	s_or_b64 exec, exec, s[0:1]
	v_add_u32_e32 v0, 0xd000, v114
	s_waitcnt lgkmcnt(0)
	s_barrier
; __device__ __forceinline__ int fetch_unit(unsigned* ctr, int* slot) {
;   __syncthreads();
;   if (threadIdx.x == 0) *slot = (int)atomicAdd(ctr, 1u);
;   __syncthreads();
;   return *slot;
; __device__ __forceinline__ void phase_swa(const Params& p, int l, char* lds, unsigned* ctr, int* slot) {
;     ...
; #pragma unroll
;     for (int rg = 0; rg < 2; ++rg) {
;       const int qi = (w & 1) * 32 + rg * 16 + col;
;       const float tot = nrm[qi] + nrm[64 + qi] + nrm[128 + qi] + nrm[192 + qi];
;       const float sc = rsqrtf(tot * (1.f / 256.f) + EPS);
; #pragma unroll
;       for (int nt = 0; nt < 4; ++nt)
;         *(h16x4*)(OAC + ((size_t)b * SEQ + t0 + qi) * 1024 + head * 64 + nt * 16 + q4 * 4) =
;             pack4(O[rg][nt][0] * sc, O[rg][nt][1] * sc, O[rg][nt][2] * sc, O[rg][nt][3] * sc);
;     }
	ds_read2_b32 v[34:35], v0 offset0:128 offset1:144
	ds_read2_b32 v[36:37], v0 offset0:192 offset1:208
	v_add_u32_e32 v0, 0xd400, v114
	ds_read2_b32 v[38:39], v0 offset1:16
	ds_read2_b32 v[40:41], v0 offset0:64 offset1:80
	s_lshl_b64 s[0:1], s[68:69], 13
	s_waitcnt lgkmcnt(3)
	v_mov_b32_e32 v50, v35
	v_mov_b32_e32 v51, v34
	s_waitcnt lgkmcnt(2)
	v_mov_b32_e32 v34, v37
	v_mov_b32_e32 v35, v36
	v_pk_add_f32 v[34:35], v[50:51], v[34:35]
	s_waitcnt lgkmcnt(1)
	v_mov_b32_e32 v36, v39
	v_mov_b32_e32 v37, v38
	v_pk_add_f32 v[34:35], v[34:35], v[36:37]
	s_waitcnt lgkmcnt(0)
	v_mov_b32_e32 v36, v41
	v_mov_b32_e32 v37, v40
	s_or_b32 s2, s0, s2
	v_pk_add_f32 v[34:35], v[34:35], v[36:37]
	s_mov_b32 s0, 0x3b800000
	v_pk_fma_f32 v[34:35], v[34:35], s[0:1], v[144:145] op_sel_hi:[1,0,0]
	s_mov_b32 s0, 0x800000
	v_mul_f32_e32 v0, 0x4b800000, v35
	v_cmp_gt_f32_e32 vcc, s0, v35
	v_mov_b32_e32 v37, v2
	v_mov_b32_e32 v44, v11
	v_cndmask_b32_e32 v0, v35, v0, vcc
	v_rsq_f32_e32 v0, v0
	v_mov_b32_e32 v45, v4
	v_mov_b32_e32 v43, s1
	v_or_b32_e32 v42, s2, v98
	v_mul_f32_e32 v2, 0x45800000, v0
	v_cndmask_b32_e32 v0, v0, v2, vcc
	v_fma_mixlo_f16 v2, v10, v0, 0
	v_pk_mul_f32 v[10:11], v[44:45], v[0:1] op_sel_hi:[1,0]
	v_mov_b32_e32 v47, v6
	v_cvt_pk_f16_f32 v6, v10, v11
	v_lshlrev_b64 v[42:43], 11, v[42:43]
	v_pack_b32_f16 v4, v2, v6
	v_fma_mixlo_f16 v2, v5, v0, 0
	v_lshl_add_u64 v[42:43], v[102:103], 0, v[42:43]
	v_mov_b32_e32 v46, v13
	v_alignbit_b32 v5, v2, v6, 16
	global_store_dwordx2 v[42:43], v[4:5], off
	v_pk_mul_f32 v[4:5], v[46:47], v[0:1] op_sel_hi:[1,0]
	v_fma_mixlo_f16 v2, v12, v0, 0
	v_cvt_pk_f16_f32 v5, v4, v5
	v_pack_b32_f16 v4, v2, v5
	v_fma_mixlo_f16 v2, v7, v0, 0
	v_mov_b32_e32 v48, v15
	v_mov_b32_e32 v49, v8
	v_alignbit_b32 v5, v2, v5, 16
	global_store_dwordx2 v[42:43], v[4:5], off offset:32
	v_pk_mul_f32 v[4:5], v[48:49], v[0:1] op_sel_hi:[1,0]
	v_fma_mixlo_f16 v2, v14, v0, 0
	v_cvt_pk_f16_f32 v5, v4, v5
	v_pack_b32_f16 v4, v2, v5
	v_fma_mixlo_f16 v2, v9, v0, 0
	v_mov_b32_e32 v36, v17
	v_alignbit_b32 v5, v2, v5, 16
	global_store_dwordx2 v[42:43], v[4:5], off offset:64
	v_pk_mul_f32 v[4:5], v[36:37], v[0:1] op_sel_hi:[1,0]
	v_cmp_gt_f32_e32 vcc, s0, v34
	v_cvt_pk_f16_f32 v4, v4, v5
	v_mul_f32_e32 v5, 0x4b800000, v34
	v_cndmask_b32_e32 v5, v34, v5, vcc
	v_rsq_f32_e32 v5, v5
	v_fma_mixlo_f16 v2, v16, v0, 0
	v_fma_mixlo_f16 v0, v3, v0, 0
	v_alignbit_b32 v3, v0, v4, 16
	v_mul_f32_e32 v0, 0x45800000, v5
	v_pack_b32_f16 v2, v2, v4
	v_cndmask_b32_e32 v0, v5, v0, vcc
	v_mov_b32_e32 v4, v33
	v_mov_b32_e32 v5, v24
	v_pk_mul_f32 v[4:5], v[4:5], v[0:1] op_sel_hi:[1,0]
	global_store_dwordx2 v[42:43], v[2:3], off offset:96
	v_mov_b32_e32 v3, s1
	v_or_b32_e32 v2, s2, v104
	v_fma_mixlo_f16 v6, v32, v0, 0
	v_cvt_pk_f16_f32 v5, v4, v5
	v_lshlrev_b64 v[2:3], 11, v[2:3]
	v_pack_b32_f16 v4, v6, v5
	v_fma_mixlo_f16 v6, v25, v0, 0
	v_lshl_add_u64 v[2:3], v[102:103], 0, v[2:3]
	v_alignbit_b32 v5, v6, v5, 16
	global_store_dwordx2 v[2:3], v[4:5], off
	v_mov_b32_e32 v4, v31
	v_mov_b32_e32 v5, v22
	v_pk_mul_f32 v[4:5], v[4:5], v[0:1] op_sel_hi:[1,0]
	v_fma_mixlo_f16 v6, v30, v0, 0
	v_cvt_pk_f16_f32 v5, v4, v5
	v_pack_b32_f16 v4, v6, v5
	v_fma_mixlo_f16 v6, v23, v0, 0
	v_alignbit_b32 v5, v6, v5, 16
	global_store_dwordx2 v[2:3], v[4:5], off offset:32
	v_mov_b32_e32 v4, v29
	v_mov_b32_e32 v5, v20
	v_pk_mul_f32 v[4:5], v[4:5], v[0:1] op_sel_hi:[1,0]
	v_fma_mixlo_f16 v6, v28, v0, 0
	v_cvt_pk_f16_f32 v5, v4, v5
	v_pack_b32_f16 v4, v6, v5
	v_fma_mixlo_f16 v6, v21, v0, 0
	v_alignbit_b32 v5, v6, v5, 16
	global_store_dwordx2 v[2:3], v[4:5], off offset:64
	v_mov_b32_e32 v4, v27
	v_mov_b32_e32 v5, v18
	v_pk_mul_f32 v[4:5], v[4:5], v[0:1] op_sel_hi:[1,0]
	v_fma_mixlo_f16 v6, v26, v0, 0
	v_cvt_pk_f16_f32 v5, v4, v5
	v_fma_mixlo_f16 v0, v19, v0, 0
	s_mov_b32 s75, 0x800000
	v_pack_b32_f16 v4, v6, v5
	v_alignbit_b32 v5, v0, v5, 16
	global_store_dwordx2 v[2:3], v[4:5], off offset:96
	s_barrier
	s_mov_b64 s[0:1], exec
	v_readlane_b32 s6, v254, 0
	v_readlane_b32 s7, v254, 1
	s_and_b64 s[6:7], s[0:1], s[6:7]
	s_mov_b64 exec, s[6:7]
	s_cbranch_execz .LBB0_2126
	s_mov_b64 s[8:9], exec
	v_mbcnt_lo_u32_b32 v0, s8, 0
	v_mbcnt_hi_u32_b32 v0, s9, v0
	v_cmp_eq_u32_e32 vcc, 0, v0
	s_and_saveexec_b64 s[6:7], vcc
	s_cbranch_execz .LBB0_2125
	s_bcnt1_i32_b64 s2, s[8:9]
	v_readlane_b32 s8, v255, 32
	v_mov_b32_e32 v2, s2
	v_readlane_b32 s9, v255, 33
	s_nop 4
	global_atomic_add v2, v1, v2, s[8:9] offset:512 sc0
	s_branch .LBB0_2125

; #define G8_STAGE(bufoff, gbase) do { _Pragma("unroll") for (int _i = 0; _i < 2; ++_i) \
;     __builtin_amdgcn_global_load_lds((const unsigned*)((const char*)(gbase) + voffA[_i]), (LAS unsigned*)(lds + (bufoff) + ldsw + _i * 8192), 16, 0, 0); } while (0)
; #define G8_LDA(dst, b, h) do { _Pragma("unroll") for (int m = 0; m < 4; ++m) _Pragma("unroll") for (int k = 0; k < 2; ++k) dst[m][k] = *(const LAS h16x8*)(lds + G8_SA(b, h) + aoff + m * 2048 + k * 1024); } while (0)
; #define G8_LDB(dst, b, h) do { _Pragma("unroll") for (int n = 0; n < 2; ++n) _Pragma("unroll") for (int k = 0; k < 2; ++k) dst[n][k] = *(const LAS h16x8*)(lds + G8_SB(b, h) + boff + n * 2048 + k * 1024); } while (0)
; #define G8_MMA(ai, bj, At, Bt_) do { __builtin_amdgcn_s_setprio(1); _Pragma("unroll") for (int m = 0; m < 4; ++m) _Pragma("unroll") for (int n = 0; n < 2; ++n) _Pragma("unroll") for (int k = 0; k < 2; ++k) \
;     acc[ai][bj][m][n] = __builtin_amdgcn_mfma_f32_16x16x32_f16(Bt_[n][k], At[m][k], acc[ai][bj][m][n], 0, 0, 0); __builtin_amdgcn_s_setprio(0); } while (0)
; #define G8_WAIT_V(n) asm volatile("s_waitcnt vmcnt(" #n ")" ::: "memory")
; #define G8_WAIT_L(n) asm volatile("s_waitcnt lgkmcnt(" #n ")" ::: "memory")
; #define G8_BAR __builtin_amdgcn_s_barrier()
; #define G8_SCHED __builtin_amdgcn_sched_barrier(0)
; template <class Epi>
; __device__ __forceinline__ void gemm_phase(LAS unsigned char* lds, const h16* A, const h16* Bt, int K, const Order& S, const Epi& E) {
;     ...
;       G8_LDB(B0, 0, 0); G8_SCHED; G8_LDA(At, 0, 0); G8_STAGE(G8_SA(1, 1), a1 + hstep);
;       G8_WAIT_L(8); G8_BAR; G8_WAIT_L(0); G8_MMA(0, 0, At, B0); G8_BAR; G8_SCHED;
;       G8_LDB(B1, 0, 1); G8_STAGE(G8_SB(0, 0), b2);
;       G8_BAR; G8_WAIT_L(0); G8_MMA(0, 1, At, B1); G8_BAR;
;       G8_LDA(At, 0, 1); G8_STAGE(G8_SA(0, 0), a2);
;       G8_BAR; G8_WAIT_L(0); G8_MMA(1, 0, At, B0); G8_BAR; G8_SCHED;
;       G8_STAGE(G8_SB(0, 1), b2 + hstep);
;       G8_WAIT_V(6); G8_BAR; G8_MMA(1, 1, At, B1); G8_BAR;
.LBB0_2284:
	v_or_b32_e32 v34, 0x10000, v171
	v_add_u32_e32 v46, 0x10400, v171
	v_add_u32_e32 v50, 0x10800, v171
	v_add_u32_e32 v160, 0x10c00, v171
	ds_read_b128 v[34:37], v34
	ds_read_b128 v[46:49], v46
	ds_read_b128 v[50:53], v50
	ds_read_b128 v[160:163], v160
	s_add_u32 s26, s24, 0xfffe0080
	s_addc_u32 s27, s25, -1
	s_cmp_eq_u32 s55, 4
	s_cselect_b32 s29, s3, s27
	s_cselect_b32 s28, s17, s26
	s_cselect_b32 s27, s15, s54
	s_cselect_b32 s26, s23, s53
	v_lshl_add_u64 v[168:169], s[24:25], 0, v[156:157]
	s_add_i32 m0, s37, 0xc000
	ds_read_b128 v[164:167], v170
	ds_read_b128 v[174:177], v170 offset:1024
	ds_read_b128 v[178:181], v170 offset:2048
	ds_read_b128 v[182:185], v170 offset:3072
	ds_read_b128 v[186:189], v170 offset:4096
	ds_read_b128 v[202:205], v170 offset:5120
	ds_read_b128 v[206:209], v170 offset:6144
	ds_read_b128 v[210:213], v170 offset:7168
	global_load_lds_dwordx4 v[168:169], off
	v_lshl_add_u64 v[168:169], s[24:25], 0, v[158:159]
	s_add_i32 m0, s37, 0xe000
	s_nop 0
	global_load_lds_dwordx4 v[168:169], off
	s_waitcnt lgkmcnt(8)
	s_barrier
	s_waitcnt lgkmcnt(0)
	s_setprio 1
	s_waitcnt lgkmcnt(0)
	v_mfma_f32_16x16x32_f16 v[62:65], v[34:37], v[164:167], v[62:65]
	v_mfma_f32_16x16x32_f16 v[138:141], v[50:53], v[164:167], v[138:141]
	v_mfma_f32_16x16x32_f16 v[122:125], v[34:37], v[178:181], v[122:125]
	v_mfma_f32_16x16x32_f16 v[126:129], v[50:53], v[178:181], v[126:129]
	v_mfma_f32_16x16x32_f16 v[106:109], v[34:37], v[186:189], v[106:109]
	v_mfma_f32_16x16x32_f16 v[110:113], v[50:53], v[186:189], v[110:113]
	v_mfma_f32_16x16x32_f16 v[90:93], v[34:37], v[206:209], v[90:93]
	v_mfma_f32_16x16x32_f16 v[94:97], v[50:53], v[206:209], v[94:97]
	v_mfma_f32_16x16x32_f16 v[62:65], v[46:49], v[174:177], v[62:65]
	v_mfma_f32_16x16x32_f16 v[138:141], v[160:163], v[174:177], v[138:141]
	v_mfma_f32_16x16x32_f16 v[122:125], v[46:49], v[182:185], v[122:125]
	v_mfma_f32_16x16x32_f16 v[126:129], v[160:163], v[182:185], v[126:129]
	v_mfma_f32_16x16x32_f16 v[106:109], v[46:49], v[202:205], v[106:109]
	v_mfma_f32_16x16x32_f16 v[110:113], v[160:163], v[202:205], v[110:113]
	v_mfma_f32_16x16x32_f16 v[90:93], v[46:49], v[210:213], v[90:93]
	v_mfma_f32_16x16x32_f16 v[94:97], v[160:163], v[210:213], v[94:97]
	s_setprio 0
	s_barrier
	v_or_b32_e32 v168, 0x14000, v171
	v_add_u32_e32 v169, 0x14400, v171
	ds_read_b128 v[214:217], v168
	ds_read_b128 v[218:221], v169
	v_add_u32_e32 v168, 0x14800, v171
	v_add_u32_e32 v169, 0x14c00, v171
	s_mov_b32 m0, s38
	ds_read_b128 v[222:225], v168
	ds_read_b128 v[226:229], v169
	v_lshl_add_u64 v[168:169], s[26:27], 0, v[0:1]
	global_load_lds_dwordx4 v[168:169], off
	v_lshl_add_u64 v[230:231], s[26:27], 0, v[152:153]
	s_mov_b32 m0, s39
	s_nop 0
	global_load_lds_dwordx4 v[230:231], off
	s_barrier
	s_waitcnt lgkmcnt(0)
	s_setprio 1
	s_waitcnt lgkmcnt(0)
	v_mfma_f32_16x16x32_f16 v[130:133], v[214:217], v[164:167], v[130:133]
	v_mfma_f32_16x16x32_f16 v[134:137], v[222:225], v[164:167], v[134:137]
	v_mfma_f32_16x16x32_f16 v[114:117], v[214:217], v[178:181], v[114:117]
	v_mfma_f32_16x16x32_f16 v[118:121], v[222:225], v[178:181], v[118:121]
	v_mfma_f32_16x16x32_f16 v[98:101], v[214:217], v[186:189], v[98:101]
	v_mfma_f32_16x16x32_f16 v[102:105], v[222:225], v[186:189], v[102:105]
	v_mfma_f32_16x16x32_f16 v[82:85], v[214:217], v[206:209], v[82:85]
	v_mfma_f32_16x16x32_f16 v[86:89], v[222:225], v[206:209], v[86:89]
	v_mfma_f32_16x16x32_f16 v[130:133], v[218:221], v[174:177], v[130:133]
	v_mfma_f32_16x16x32_f16 v[134:137], v[226:229], v[174:177], v[134:137]
	v_mfma_f32_16x16x32_f16 v[114:117], v[218:221], v[182:185], v[114:117]
	v_mfma_f32_16x16x32_f16 v[118:121], v[226:229], v[182:185], v[118:121]
	v_mfma_f32_16x16x32_f16 v[98:101], v[218:221], v[202:205], v[98:101]
	v_mfma_f32_16x16x32_f16 v[102:105], v[226:229], v[202:205], v[102:105]
	v_mfma_f32_16x16x32_f16 v[82:85], v[218:221], v[210:213], v[82:85]
	v_mfma_f32_16x16x32_f16 v[86:89], v[226:229], v[210:213], v[86:89]
	s_setprio 0
	s_mov_b32 m0, s37
	v_lshl_add_u64 v[232:233], s[28:29], 0, v[0:1]
	s_barrier
	ds_read_b128 v[164:167], v170 offset:16384
	ds_read_b128 v[174:177], v170 offset:17408
	ds_read_b128 v[178:181], v170 offset:18432
	ds_read_b128 v[182:185], v170 offset:19456
	ds_read_b128 v[186:189], v170 offset:20480
	ds_read_b128 v[202:205], v170 offset:21504
	ds_read_b128 v[206:209], v170 offset:22528
	ds_read_b128 v[210:213], v170 offset:23552
	global_load_lds_dwordx4 v[232:233], off
	v_lshl_add_u64 v[234:235], s[28:29], 0, v[152:153]
	s_mov_b32 m0, s40
	s_nop 0
	global_load_lds_dwordx4 v[234:235], off
	s_barrier
	s_waitcnt lgkmcnt(0)
	s_setprio 1
	s_waitcnt lgkmcnt(0)
	v_mfma_f32_16x16x32_f16 v[74:77], v[34:37], v[164:167], v[74:77]
	v_mfma_f32_16x16x32_f16 v[78:81], v[50:53], v[164:167], v[78:81]
	v_mfma_f32_16x16x32_f16 v[54:57], v[34:37], v[178:181], v[54:57]
	v_mfma_f32_16x16x32_f16 v[58:61], v[50:53], v[178:181], v[58:61]
	v_mfma_f32_16x16x32_f16 v[26:29], v[34:37], v[186:189], v[26:29]
	v_mfma_f32_16x16x32_f16 v[30:33], v[50:53], v[186:189], v[30:33]
	v_mfma_f32_16x16x32_f16 v[10:13], v[34:37], v[206:209], v[10:13]
	v_mfma_f32_16x16x32_f16 v[14:17], v[50:53], v[206:209], v[14:17]
	v_mfma_f32_16x16x32_f16 v[74:77], v[46:49], v[174:177], v[74:77]
	v_mfma_f32_16x16x32_f16 v[78:81], v[160:163], v[174:177], v[78:81]
	v_mfma_f32_16x16x32_f16 v[54:57], v[46:49], v[182:185], v[54:57]
	v_mfma_f32_16x16x32_f16 v[58:61], v[160:163], v[182:185], v[58:61]
	v_mfma_f32_16x16x32_f16 v[26:29], v[46:49], v[202:205], v[26:29]
	v_mfma_f32_16x16x32_f16 v[30:33], v[160:163], v[202:205], v[30:33]
	v_mfma_f32_16x16x32_f16 v[10:13], v[46:49], v[210:213], v[10:13]
	v_mfma_f32_16x16x32_f16 v[14:17], v[160:163], v[210:213], v[14:17]
	s_setprio 0
	s_barrier
; #define G8_STAGE(bufoff, gbase) do { _Pragma("unroll") for (int _i = 0; _i < 2; ++_i) \
;     __builtin_amdgcn_global_load_lds((const unsigned*)((const char*)(gbase) + voffA[_i]), (LAS unsigned*)(lds + (bufoff) + ldsw + _i * 8192), 16, 0, 0); } while (0)
; #define G8_LDA(dst, b, h) do { _Pragma("unroll") for (int m = 0; m < 4; ++m) _Pragma("unroll") for (int k = 0; k < 2; ++k) dst[m][k] = *(const LAS h16x8*)(lds + G8_SA(b, h) + aoff + m * 2048 + k * 1024); } while (0)
; #define G8_LDB(dst, b, h) do { _Pragma("unroll") for (int n = 0; n < 2; ++n) _Pragma("unroll") for (int k = 0; k < 2; ++k) dst[n][k] = *(const LAS h16x8*)(lds + G8_SB(b, h) + boff + n * 2048 + k * 1024); } while (0)
; #define G8_MMA(ai, bj, At, Bt_) do { __builtin_amdgcn_s_setprio(1); _Pragma("unroll") for (int m = 0; m < 4; ++m) _Pragma("unroll") for (int n = 0; n < 2; ++n) _Pragma("unroll") for (int k = 0; k < 2; ++k) \
;     acc[ai][bj][m][n] = __builtin_amdgcn_mfma_f32_16x16x32_f16(Bt_[n][k], At[m][k], acc[ai][bj][m][n], 0, 0, 0); __builtin_amdgcn_s_setprio(0); } while (0)
; #define G8_WAIT_V(n) asm volatile("s_waitcnt vmcnt(" #n ")" ::: "memory")
; #define G8_WAIT_L(n) asm volatile("s_waitcnt lgkmcnt(" #n ")" ::: "memory")
; #define G8_BAR __builtin_amdgcn_s_barrier()
; #define G8_SCHED __builtin_amdgcn_sched_barrier(0)
; template <class Epi>
; __device__ __forceinline__ void gemm_phase(LAS unsigned char* lds, const h16* A, const h16* Bt, int K, const Order& S, const Epi& E) {
;     ...
;       G8_WAIT_V(6); G8_BAR; G8_MMA(1, 1, At, B1); G8_BAR;
;       G8_LDB(B0, 1, 0); G8_SCHED; G8_LDA(At, 1, 0); G8_STAGE(G8_SA(0, 1), a2 + hstep);
;       G8_WAIT_L(8); G8_BAR; G8_WAIT_L(0); G8_MMA(0, 0, At, B0); G8_BAR; G8_SCHED;
;       G8_LDB(B1, 1, 1); G8_STAGE(G8_SB(1, 0), b3);
;       G8_BAR; G8_WAIT_L(0); G8_MMA(0, 1, At, B1); G8_BAR;
;       G8_LDA(At, 1, 1); G8_STAGE(G8_SA(1, 0), a3);
;       G8_BAR; G8_WAIT_L(0); G8_MMA(1, 0, At, B0); G8_BAR; G8_SCHED;
	s_add_u32 s56, s26, 0x20000
	s_addc_u32 s57, s27, 0
	s_mov_b32 m0, s41
	v_lshl_add_u64 v[34:35], s[56:57], 0, v[0:1]
	global_load_lds_dwordx4 v[34:35], off
	v_lshl_add_u64 v[34:35], s[56:57], 0, v[152:153]
	s_mov_b32 m0, s42
	s_nop 0
	global_load_lds_dwordx4 v[34:35], off
	s_waitcnt vmcnt(6)
	s_barrier
	s_setprio 1
	v_mfma_f32_16x16x32_f16 v[38:41], v[214:217], v[178:181], v[38:41]
	v_mfma_f32_16x16x32_f16 v[42:45], v[222:225], v[178:181], v[42:45]
	v_mfma_f32_16x16x32_f16 v[18:21], v[214:217], v[186:189], v[18:21]
	v_mfma_f32_16x16x32_f16 v[22:25], v[222:225], v[186:189], v[22:25]
	v_mfma_f32_16x16x32_f16 v[2:5], v[214:217], v[206:209], v[2:5]
	v_mfma_f32_16x16x32_f16 v[6:9], v[222:225], v[206:209], v[6:9]
	v_mfma_f32_16x16x32_f16 v[34:37], v[214:217], v[164:167], v[66:69]
	v_mfma_f32_16x16x32_f16 v[46:49], v[222:225], v[164:167], v[70:73]
	v_mfma_f32_16x16x32_f16 v[38:41], v[218:221], v[182:185], v[38:41]
	v_mfma_f32_16x16x32_f16 v[42:45], v[226:229], v[182:185], v[42:45]
	v_mfma_f32_16x16x32_f16 v[18:21], v[218:221], v[202:205], v[18:21]
	v_mfma_f32_16x16x32_f16 v[22:25], v[226:229], v[202:205], v[22:25]
	v_mfma_f32_16x16x32_f16 v[2:5], v[218:221], v[210:213], v[2:5]
	v_mfma_f32_16x16x32_f16 v[6:9], v[226:229], v[210:213], v[6:9]
	v_mfma_f32_16x16x32_f16 v[34:37], v[218:221], v[174:177], v[34:37]
	v_mfma_f32_16x16x32_f16 v[46:49], v[226:229], v[174:177], v[46:49]
	s_setprio 0
	v_or_b32_e32 v50, 0x18000, v171
	v_add_u32_e32 v66, 0x18400, v171
	v_add_u32_e32 v70, 0x18800, v171
	v_add_u32_e32 v160, 0x18c00, v171
	s_barrier
	ds_read_b128 v[50:53], v50
	ds_read_b128 v[66:69], v66
	ds_read_b128 v[70:73], v70
	ds_read_b128 v[160:163], v160
	s_add_u32 s28, s28, 0x20000
	s_addc_u32 s29, s29, 0
	s_mov_b32 m0, s43
	v_lshl_add_u64 v[214:215], s[28:29], 0, v[0:1]
	ds_read_b128 v[164:167], v170 offset:32768
	ds_read_b128 v[174:177], v170 offset:33792
	ds_read_b128 v[178:181], v170 offset:34816
	ds_read_b128 v[182:185], v170 offset:35840
	ds_read_b128 v[186:189], v170 offset:36864
	ds_read_b128 v[202:205], v170 offset:37888
	ds_read_b128 v[206:209], v170 offset:38912
	ds_read_b128 v[210:213], v170 offset:39936
	global_load_lds_dwordx4 v[214:215], off
	v_lshl_add_u64 v[214:215], s[28:29], 0, v[152:153]
	s_mov_b32 m0, s44
	s_nop 0
	global_load_lds_dwordx4 v[214:215], off
	s_waitcnt lgkmcnt(8)
	s_barrier
	s_waitcnt lgkmcnt(0)
	s_setprio 1
	s_waitcnt lgkmcnt(0)
	v_mfma_f32_16x16x32_f16 v[62:65], v[50:53], v[164:167], v[62:65]
	v_mfma_f32_16x16x32_f16 v[138:141], v[70:73], v[164:167], v[138:141]
	v_mfma_f32_16x16x32_f16 v[122:125], v[50:53], v[178:181], v[122:125]
	v_mfma_f32_16x16x32_f16 v[126:129], v[70:73], v[178:181], v[126:129]
	v_mfma_f32_16x16x32_f16 v[106:109], v[50:53], v[186:189], v[106:109]
	v_mfma_f32_16x16x32_f16 v[110:113], v[70:73], v[186:189], v[110:113]
	v_mfma_f32_16x16x32_f16 v[90:93], v[50:53], v[206:209], v[90:93]
	v_mfma_f32_16x16x32_f16 v[94:97], v[70:73], v[206:209], v[94:97]
	v_mfma_f32_16x16x32_f16 v[62:65], v[66:69], v[174:177], v[62:65]
	v_mfma_f32_16x16x32_f16 v[138:141], v[160:163], v[174:177], v[138:141]
	v_mfma_f32_16x16x32_f16 v[122:125], v[66:69], v[182:185], v[122:125]
	v_mfma_f32_16x16x32_f16 v[126:129], v[160:163], v[182:185], v[126:129]
	v_mfma_f32_16x16x32_f16 v[106:109], v[66:69], v[202:205], v[106:109]
	v_mfma_f32_16x16x32_f16 v[110:113], v[160:163], v[202:205], v[110:113]
	v_mfma_f32_16x16x32_f16 v[90:93], v[66:69], v[210:213], v[90:93]
	v_mfma_f32_16x16x32_f16 v[94:97], v[160:163], v[210:213], v[94:97]
	s_setprio 0
	s_barrier
	v_or_b32_e32 v173, 0x1c000, v171
	s_mov_b32 m0, s46
	v_add_u32_e32 v195, 0x1c400, v171
	ds_read_b128 v[214:217], v173
	ds_read_b128 v[218:221], v195
	v_add_u32_e32 v173, 0x1c800, v171
	v_lshl_add_u64 v[168:169], v[168:169], 0, s[94:95]
	v_add_u32_e32 v195, 0x1cc00, v171
	ds_read_b128 v[222:225], v173
	ds_read_b128 v[226:229], v195
	global_load_lds_dwordx4 v[168:169], off
	v_lshl_add_u64 v[168:169], v[230:231], 0, s[94:95]
	s_mov_b32 m0, s47
	s_nop 0
	global_load_lds_dwordx4 v[168:169], off
	s_barrier
	s_waitcnt lgkmcnt(0)
	s_setprio 1
	s_waitcnt lgkmcnt(0)
	v_mfma_f32_16x16x32_f16 v[130:133], v[214:217], v[164:167], v[130:133]
	v_mfma_f32_16x16x32_f16 v[134:137], v[222:225], v[164:167], v[134:137]
	v_mfma_f32_16x16x32_f16 v[114:117], v[214:217], v[178:181], v[114:117]
	v_mfma_f32_16x16x32_f16 v[118:121], v[222:225], v[178:181], v[118:121]
	v_mfma_f32_16x16x32_f16 v[98:101], v[214:217], v[186:189], v[98:101]
	v_mfma_f32_16x16x32_f16 v[102:105], v[222:225], v[186:189], v[102:105]
	v_mfma_f32_16x16x32_f16 v[82:85], v[214:217], v[206:209], v[82:85]
	v_mfma_f32_16x16x32_f16 v[86:89], v[222:225], v[206:209], v[86:89]
	v_mfma_f32_16x16x32_f16 v[130:133], v[218:221], v[174:177], v[130:133]
	v_mfma_f32_16x16x32_f16 v[134:137], v[226:229], v[174:177], v[134:137]
	v_mfma_f32_16x16x32_f16 v[114:117], v[218:221], v[182:185], v[114:117]
	v_mfma_f32_16x16x32_f16 v[118:121], v[226:229], v[182:185], v[118:121]
	v_mfma_f32_16x16x32_f16 v[98:101], v[218:221], v[202:205], v[98:101]
	v_mfma_f32_16x16x32_f16 v[102:105], v[226:229], v[202:205], v[102:105]
	v_mfma_f32_16x16x32_f16 v[82:85], v[218:221], v[210:213], v[82:85]
	v_mfma_f32_16x16x32_f16 v[86:89], v[226:229], v[210:213], v[86:89]
	s_setprio 0
	s_mov_b32 m0, s48
	v_lshl_add_u64 v[168:169], v[232:233], 0, s[94:95]
	s_barrier
	ds_read_b128 v[164:167], v170 offset:49152
	ds_read_b128 v[174:177], v170 offset:50176
	ds_read_b128 v[178:181], v170 offset:51200
	ds_read_b128 v[182:185], v170 offset:52224
	ds_read_b128 v[186:189], v170 offset:53248
	ds_read_b128 v[202:205], v170 offset:54272
	ds_read_b128 v[206:209], v170 offset:55296
	ds_read_b128 v[210:213], v170 offset:56320
	global_load_lds_dwordx4 v[168:169], off
	v_lshl_add_u64 v[168:169], v[234:235], 0, s[94:95]
	s_mov_b32 m0, s49
	s_nop 0
	global_load_lds_dwordx4 v[168:169], off
	s_barrier
; __device__ __forceinline__ float sigmoidf(float x) { return 1.f / (1.f + __expf(-x)); }
; #define G8_STAGE(bufoff, gbase) do { _Pragma("unroll") for (int _i = 0; _i < 2; ++_i) \
;     __builtin_amdgcn_global_load_lds((const unsigned*)((const char*)(gbase) + voffA[_i]), (LAS unsigned*)(lds + (bufoff) + ldsw + _i * 8192), 16, 0, 0); } while (0)
; #define G8_MMA(ai, bj, At, Bt_) do { __builtin_amdgcn_s_setprio(1); _Pragma("unroll") for (int m = 0; m < 4; ++m) _Pragma("unroll") for (int n = 0; n < 2; ++n) _Pragma("unroll") for (int k = 0; k < 2; ++k) \
;     acc[ai][bj][m][n] = __builtin_amdgcn_mfma_f32_16x16x32_f16(Bt_[n][k], At[m][k], acc[ai][bj][m][n], 0, 0, 0); __builtin_amdgcn_s_setprio(0); } while (0)
; #define G8_WAIT_V(n) asm volatile("s_waitcnt vmcnt(" #n ")" ::: "memory")
; #define G8_WAIT_L(n) asm volatile("s_waitcnt lgkmcnt(" #n ")" ::: "memory")
; #define G8_BAR __builtin_amdgcn_s_barrier()
; #define G8_SCHED __builtin_amdgcn_sched_barrier(0)
; template <class Epi>
; __device__ __forceinline__ void gemm_phase(LAS unsigned char* lds, const h16* A, const h16* Bt, int K, const Order& S, const Epi& E) {
;     ...
;       G8_BAR; G8_WAIT_L(0); G8_MMA(1, 0, At, B0); G8_BAR; G8_SCHED;
;       G8_STAGE(G8_SB(1, 1), b3 + hstep);
;       G8_WAIT_V(6); G8_BAR; G8_MMA(1, 1, At, B1); G8_BAR;
;   __device__ __forceinline__ void operator()(const f32x4 (&acc)[2][2][4][2], const g8::Unit& u, int ui, int wr, int wc, int fr, int fq) const {
;     const int ocb = 128 * u.pn + 16 * wc + 4 * fq;
;     float4 ba[2], bb[2];
; #pragma unroll
;     for (int bj = 0; bj < 2; ++bj) { ba[bj] = *(const float4*)(gb + ocb + 64 * bj); bb[bj] = *(const float4*)(gb + 512 + ocb + 64 * bj); }
; #pragma unroll
;     for (int ai = 0; ai < 2; ++ai)
; #pragma unroll
;       for (int m = 0; m < 4; ++m) {
;         const size_t row = (size_t)u.pm * 256 + 128 * ai + 64 * wr + 16 * m + fr;
;         float ss = 0.f;
; #pragma unroll
;         for (int bj = 0; bj < 2; ++bj) {
;           const f32x4 a = acc[ai][bj][m][0], b = acc[ai][bj][m][1];
;           float o0 = (a[0] + ba[bj].x) * sigmoidf(b[0] + bb[bj].x);
;           float o1 = (a[1] + ba[bj].y) * sigmoidf(b[1] + bb[bj].y);
;           float o2 = (a[2] + ba[bj].z) * sigmoidf(b[2] + bb[bj].z);
;           float o3 = (a[3] + ba[bj].w) * sigmoidf(b[3] + bb[bj].w);
	s_waitcnt lgkmcnt(0)
	s_setprio 1
	s_waitcnt lgkmcnt(0)
	v_mfma_f32_16x16x32_f16 v[74:77], v[50:53], v[164:167], v[74:77]
	v_mfma_f32_16x16x32_f16 v[78:81], v[70:73], v[164:167], v[78:81]
	v_mfma_f32_16x16x32_f16 v[54:57], v[50:53], v[178:181], v[54:57]
	v_mfma_f32_16x16x32_f16 v[58:61], v[70:73], v[178:181], v[58:61]
	v_mfma_f32_16x16x32_f16 v[26:29], v[50:53], v[186:189], v[26:29]
	v_mfma_f32_16x16x32_f16 v[30:33], v[70:73], v[186:189], v[30:33]
	v_mfma_f32_16x16x32_f16 v[10:13], v[50:53], v[206:209], v[10:13]
	v_mfma_f32_16x16x32_f16 v[14:17], v[70:73], v[206:209], v[14:17]
	v_mfma_f32_16x16x32_f16 v[74:77], v[66:69], v[174:177], v[74:77]
	v_mfma_f32_16x16x32_f16 v[78:81], v[160:163], v[174:177], v[78:81]
	v_mfma_f32_16x16x32_f16 v[54:57], v[66:69], v[182:185], v[54:57]
	v_mfma_f32_16x16x32_f16 v[58:61], v[160:163], v[182:185], v[58:61]
	v_mfma_f32_16x16x32_f16 v[26:29], v[66:69], v[202:205], v[26:29]
	v_mfma_f32_16x16x32_f16 v[30:33], v[160:163], v[202:205], v[30:33]
	v_mfma_f32_16x16x32_f16 v[10:13], v[66:69], v[210:213], v[10:13]
	v_mfma_f32_16x16x32_f16 v[14:17], v[160:163], v[210:213], v[14:17]
	s_setprio 0
	s_barrier
	s_add_u32 s26, s26, 0x20080
	s_addc_u32 s27, s27, 0
	s_mov_b32 m0, s50
	v_lshl_add_u64 v[50:51], s[26:27], 0, v[0:1]
	global_load_lds_dwordx4 v[50:51], off
	v_lshl_add_u64 v[50:51], s[26:27], 0, v[152:153]
	s_mov_b32 m0, s51
	s_nop 0
	global_load_lds_dwordx4 v[50:51], off
	s_waitcnt vmcnt(6)
	s_barrier
	s_setprio 1
	v_mfma_f32_16x16x32_f16 v[34:37], v[214:217], v[164:167], v[34:37]
	v_mfma_f32_16x16x32_f16 v[66:69], v[218:221], v[174:177], v[34:37]
	v_mfma_f32_16x16x32_f16 v[34:37], v[222:225], v[164:167], v[46:49]
	v_mfma_f32_16x16x32_f16 v[70:73], v[226:229], v[174:177], v[34:37]
	v_mfma_f32_16x16x32_f16 v[34:37], v[214:217], v[178:181], v[38:41]
	v_mfma_f32_16x16x32_f16 v[38:41], v[218:221], v[182:185], v[34:37]
	v_mfma_f32_16x16x32_f16 v[34:37], v[222:225], v[178:181], v[42:45]
	v_mfma_f32_16x16x32_f16 v[18:21], v[214:217], v[186:189], v[18:21]
	v_mfma_f32_16x16x32_f16 v[22:25], v[222:225], v[186:189], v[22:25]
	v_mfma_f32_16x16x32_f16 v[2:5], v[214:217], v[206:209], v[2:5]
	v_mfma_f32_16x16x32_f16 v[6:9], v[222:225], v[206:209], v[6:9]
	v_mfma_f32_16x16x32_f16 v[42:45], v[226:229], v[182:185], v[34:37]
	v_mfma_f32_16x16x32_f16 v[18:21], v[218:221], v[202:205], v[18:21]
	v_mfma_f32_16x16x32_f16 v[22:25], v[226:229], v[202:205], v[22:25]
	v_mfma_f32_16x16x32_f16 v[2:5], v[218:221], v[210:213], v[2:5]
	v_mfma_f32_16x16x32_f16 v[6:9], v[226:229], v[210:213], v[6:9]
	s_setprio 0
	s_add_i32 s55, s55, 2
	s_add_u32 s24, s24, 0x100
	s_addc_u32 s25, s25, 0
	s_add_u32 s53, s53, 0x100
	s_addc_u32 s54, s54, 0
	s_cmp_gt_u32 s55, 5
	s_barrier
	s_cbranch_scc0 .LBB0_2284
	v_lshl_or_b32 v160, s2, 7, v172
	v_ashrrev_i32_e32 v161, 31, v160
	v_lshl_add_u64 v[166:167], v[160:161], 2, s[12:13]
	global_load_dwordx4 v[46:49], v[166:167], off offset:2048
	global_load_dwordx4 v[34:37], v[166:167], off offset:2304
	v_and_b32_e32 v51, 64, v199
	v_xor_b32_e32 v50, 32, v199
	v_add_u32_e32 v51, 64, v51
	v_cmp_lt_i32_e32 vcc, v50, v51
	s_ashr_i32 s23, s22, 31
	s_lshl_b64 s[22:23], s[22:23], 8
	v_cndmask_b32_e32 v50, v199, v50, vcc
	v_lshlrev_b32_e32 v173, 2, v50
	v_lshl_add_u64 v[162:163], s[22:23], 0, v[154:155]
	s_lshl_b32 s22, s2, 2
	v_lshlrev_b64 v[164:165], 11, v[162:163]
	s_ashr_i32 s23, s22, 31
	s_waitcnt vmcnt(0)
	v_add_f32_e32 v50, v138, v46
	v_mul_f32_e32 v50, 0xbfb8aa3b, v50
	v_exp_f32_e32 v138, v50
	global_load_dwordx4 v[50:53], v[166:167], off
	v_add_f32_e32 v139, v139, v47
	v_mul_f32_e32 v139, 0xbfb8aa3b, v139
	v_exp_f32_e32 v139, v139
	v_add_f32_e32 v140, v140, v48
	v_add_f32_e32 v141, v141, v49
	v_mul_f32_e32 v140, 0xbfb8aa3b, v140
	v_pk_add_f32 v[138:139], v[138:139], 1.0 op_sel_hi:[1,0]
	v_mul_f32_e32 v141, 0xbfb8aa3b, v141
	v_div_scale_f32 v168, s[2:3], v139, v139, 1.0
	v_rcp_f32_e32 v169, v168
	v_exp_f32_e32 v140, v140
	v_exp_f32_e32 v141, v141
	v_add_f32_e32 v135, v135, v35
	v_fma_f32 v174, -v168, v169, 1.0
	v_fmac_f32_e32 v169, v174, v169
	v_div_scale_f32 v174, vcc, 1.0, v139, 1.0
	v_mul_f32_e32 v175, v174, v169
	v_fma_f32 v176, -v168, v175, v174
	v_fmac_f32_e32 v175, v176, v169
	v_fma_f32 v168, -v168, v175, v174
	v_div_fmas_f32 v168, v168, v169, v175
	v_div_fixup_f32 v139, v168, v139, 1.0
	v_div_scale_f32 v168, s[2:3], v138, v138, 1.0
	v_rcp_f32_e32 v169, v168
	v_mul_f32_e32 v135, 0xbfb8aa3b, v135
	v_exp_f32_e32 v135, v135
	v_add_f32_e32 v136, v136, v36
	v_fma_f32 v174, -v168, v169, 1.0
	v_fmac_f32_e32 v169, v174, v169
	v_div_scale_f32 v174, vcc, 1.0, v138, 1.0
	v_mul_f32_e32 v175, v174, v169
	v_fma_f32 v176, -v168, v175, v174
	v_fmac_f32_e32 v175, v176, v169
	v_fma_f32 v168, -v168, v175, v174
	v_div_fmas_f32 v168, v168, v169, v175
	v_div_fixup_f32 v138, v168, v138, 1.0
	v_add_f32_e32 v137, v137, v37
	v_mul_f32_e32 v136, 0xbfb8aa3b, v136
	v_mul_f32_e32 v137, 0xbfb8aa3b, v137
	v_exp_f32_e32 v136, v136
	v_exp_f32_e32 v137, v137
	s_waitcnt vmcnt(0)
; __device__ __forceinline__ float xor16(float v) { return __int_as_float(__builtin_amdgcn_ds_swizzle(__float_as_int(v), 0x401F)); }
; __device__ __forceinline__ float sigmoidf(float x) { return 1.f / (1.f + __expf(-x)); }
;   __device__ __forceinline__ void operator()(const f32x4 (&acc)[2][2][4][2], const g8::Unit& u, int ui, int wr, int wc, int fr, int fq) const {
;     ...
;       for (int m = 0; m < 4; ++m) {
;         const size_t row = (size_t)u.pm * 256 + 128 * ai + 64 * wr + 16 * m + fr;
;         float ss = 0.f;
; #pragma unroll
;         for (int bj = 0; bj < 2; ++bj) {
;           const f32x4 a = acc[ai][bj][m][0], b = acc[ai][bj][m][1];
;           float o0 = (a[0] + ba[bj].x) * sigmoidf(b[0] + bb[bj].x);
;           float o1 = (a[1] + ba[bj].y) * sigmoidf(b[1] + bb[bj].y);
;           float o2 = (a[2] + ba[bj].z) * sigmoidf(b[2] + bb[bj].z);
;           float o3 = (a[3] + ba[bj].w) * sigmoidf(b[3] + bb[bj].w);
;           *(h16x4*)(OB + row * 1024 + ocb + 64 * bj) = pack4(o0, o1, o2, o3);
;           ss += o0 * o0 + o1 * o1 + o2 * o2 + o3 * o3;
;         }
;         ss += xor16(ss);
;         ss += __shfl_xor(ss, 32);
;         if (fq == 0) ssqb[row * 16 + u.pn * 4 + wc] = ss;
;       }
	v_pk_add_f32 v[62:63], v[62:63], v[50:51]
	s_nop 0
	v_pk_mul_f32 v[62:63], v[62:63], v[138:139]
	v_pk_add_f32 v[138:139], v[140:141], 1.0 op_sel_hi:[1,0]
	v_cvt_pk_f16_f32 v168, v62, v63
	v_div_scale_f32 v140, s[2:3], v139, v139, 1.0
	v_rcp_f32_e32 v141, v140
	v_pk_add_f32 v[64:65], v[64:65], v[52:53]
	v_pk_add_f32 v[136:137], v[136:137], 1.0 op_sel_hi:[1,0]
	v_fma_f32 v169, -v140, v141, 1.0
	v_fmac_f32_e32 v141, v169, v141
	v_div_scale_f32 v169, vcc, 1.0, v139, 1.0
	v_mul_f32_e32 v174, v169, v141
	v_fma_f32 v175, -v140, v174, v169
	v_fmac_f32_e32 v174, v175, v141
	v_fma_f32 v140, -v140, v174, v169
	v_div_fmas_f32 v140, v140, v141, v174
	v_div_fixup_f32 v139, v140, v139, 1.0
	v_div_scale_f32 v140, s[2:3], v138, v138, 1.0
	v_rcp_f32_e32 v141, v140
	s_nop 0
	v_fma_f32 v169, -v140, v141, 1.0
	v_fmac_f32_e32 v141, v169, v141
	v_div_scale_f32 v169, vcc, 1.0, v138, 1.0
	v_mul_f32_e32 v174, v169, v141
	v_fma_f32 v175, -v140, v174, v169
	v_fmac_f32_e32 v174, v175, v141
	v_fma_f32 v140, -v140, v174, v169
	v_div_fmas_f32 v140, v140, v141, v174
	v_div_fixup_f32 v138, v140, v138, 1.0
	v_pk_mul_f32 v[140:141], v[62:63], v[62:63]
	v_add_f32_e32 v62, v134, v34
	v_pk_mul_f32 v[64:65], v[64:65], v[138:139]
	v_lshl_add_u64 v[138:139], s[0:1], 0, v[164:165]
	v_mul_f32_e32 v62, 0xbfb8aa3b, v62
	v_cvt_pk_f16_f32 v169, v64, v65
	v_lshl_add_u64 v[164:165], v[160:161], 1, v[138:139]
	v_pk_mul_f32 v[138:139], v[64:65], v[64:65]
	v_exp_f32_e32 v134, v62
	global_load_dwordx4 v[62:65], v[166:167], off offset:256
	v_pk_add_f32 v[134:135], v[134:135], 1.0 op_sel_hi:[1,0]
	s_nop 0
	v_div_scale_f32 v166, s[2:3], v135, v135, 1.0
	v_rcp_f32_e32 v167, v166
	global_store_dwordx2 v[164:165], v[168:169], off
	v_fma_f32 v168, -v166, v167, 1.0
	v_fmac_f32_e32 v167, v168, v167
	v_div_scale_f32 v168, vcc, 1.0, v135, 1.0
	v_mul_f32_e32 v169, v168, v167
	v_fma_f32 v174, -v166, v169, v168
	v_fmac_f32_e32 v169, v174, v167
	v_fma_f32 v166, -v166, v169, v168
	v_div_fmas_f32 v166, v166, v167, v169
	v_div_fixup_f32 v135, v166, v135, 1.0
	v_div_scale_f32 v166, s[2:3], v134, v134, 1.0
	v_rcp_f32_e32 v167, v166
	s_waitcnt vmcnt(0)
	v_pk_add_f32 v[130:131], v[130:131], v[62:63]
	v_fma_f32 v168, -v166, v167, 1.0
	v_fmac_f32_e32 v167, v168, v167
	v_div_scale_f32 v168, vcc, 1.0, v134, 1.0
	v_mul_f32_e32 v169, v168, v167
	v_fma_f32 v174, -v166, v169, v168
	v_fmac_f32_e32 v169, v174, v167
	v_fma_f32 v166, -v166, v169, v168
	v_div_fmas_f32 v166, v166, v167, v169
	v_div_fixup_f32 v134, v166, v134, 1.0
	v_pk_mul_f32 v[130:131], v[130:131], v[134:135]
	v_div_scale_f32 v135, s[2:3], v137, v137, 1.0
	v_rcp_f32_e32 v166, v135
	v_pk_add_f32 v[132:133], v[132:133], v[64:65]
	v_cvt_pk_f16_f32 v134, v130, v131
	v_pk_mul_f32 v[130:131], v[130:131], v[130:131]
	v_fma_f32 v167, -v135, v166, 1.0
	v_fmac_f32_e32 v166, v167, v166
	v_div_scale_f32 v167, vcc, 1.0, v137, 1.0
	v_mul_f32_e32 v168, v167, v166
	v_fma_f32 v169, -v135, v168, v167
	v_fmac_f32_e32 v168, v169, v166
	v_fma_f32 v135, -v135, v168, v167
	v_div_fmas_f32 v135, v135, v166, v168
	v_div_fixup_f32 v137, v135, v137, 1.0
	v_div_scale_f32 v135, s[2:3], v136, v136, 1.0
	v_rcp_f32_e32 v166, v135
	v_add_f32_e32 v130, v130, v131
	v_add_f32_e32 v131, v140, v141
	v_add_f32_e32 v131, v138, v131
	v_fma_f32 v167, -v135, v166, 1.0
	v_fmac_f32_e32 v166, v167, v166
	v_div_scale_f32 v167, vcc, 1.0, v136, 1.0
	v_mul_f32_e32 v168, v167, v166
	v_fma_f32 v169, -v135, v168, v167
	v_fmac_f32_e32 v168, v169, v166
	v_fma_f32 v135, -v135, v168, v167
	v_div_fmas_f32 v135, v135, v166, v168
	v_div_fixup_f32 v136, v135, v136, 1.0
	v_pk_mul_f32 v[132:133], v[132:133], v[136:137]
	v_add_f32_e32 v131, v139, v131
	v_cvt_pk_f16_f32 v135, v132, v133
	v_pk_mul_f32 v[132:133], v[132:133], v[132:133]
	global_store_dwordx2 v[164:165], v[134:135], off offset:128
	v_add_f32_e32 v130, v132, v130
	v_add_f32_e32 v130, v133, v130
	v_add_f32_e32 v130, v131, v130
	v_mov_b32_e32 v131, v130
	s_nop 1
	v_permlane16_swap_b32_e32 v131, v130
	s_waitcnt lgkmcnt(0)
	v_add_f32_e32 v130, v130, v131
	ds_bpermute_b32 v131, v173, v130
	s_and_saveexec_b64 s[24:25], s[6:7]
	s_cbranch_execz .LBB0_2287
	s_waitcnt lgkmcnt(0)
	v_add_f32_e32 v132, v130, v131
	v_lshlrev_b64 v[130:131], 6, v[162:163]
	v_lshl_add_u64 v[130:131], s[10:11], 0, v[130:131]
	v_lshl_add_u64 v[130:131], s[22:23], 2, v[130:131]
	s_lshl_b32 s92, s45, 2
	v_lshl_add_u64 v[130:131], v[130:131], 0, s[92:93]
	global_store_dword v[130:131], v132, off
; __device__ __forceinline__ float xor16(float v) { return __int_as_float(__builtin_amdgcn_ds_swizzle(__float_as_int(v), 0x401F)); }
; __device__ __forceinline__ float sigmoidf(float x) { return 1.f / (1.f + __expf(-x)); }
;   __device__ __forceinline__ void operator()(const f32x4 (&acc)[2][2][4][2], const g8::Unit& u, int ui, int wr, int wc, int fr, int fq) const {
;     ...
;       for (int m = 0; m < 4; ++m) {
;         const size_t row = (size_t)u.pm * 256 + 128 * ai + 64 * wr + 16 * m + fr;
;         float ss = 0.f;
; #pragma unroll
;         for (int bj = 0; bj < 2; ++bj) {
;           const f32x4 a = acc[ai][bj][m][0], b = acc[ai][bj][m][1];
;           float o0 = (a[0] + ba[bj].x) * sigmoidf(b[0] + bb[bj].x);
;           float o1 = (a[1] + ba[bj].y) * sigmoidf(b[1] + bb[bj].y);
;           float o2 = (a[2] + ba[bj].z) * sigmoidf(b[2] + bb[bj].z);
;           float o3 = (a[3] + ba[bj].w) * sigmoidf(b[3] + bb[bj].w);
;           *(h16x4*)(OB + row * 1024 + ocb + 64 * bj) = pack4(o0, o1, o2, o3);
;           ss += o0 * o0 + o1 * o1 + o2 * o2 + o3 * o3;
;         }
;         ss += xor16(ss);
;         ss += __shfl_xor(ss, 32);
;         if (fq == 0) ssqb[row * 16 + u.pn * 4 + wc] = ss;
;       }
.LBB0_2287:
	s_or_b64 exec, exec, s[24:25]
	v_add_f32_e32 v126, v126, v46
	v_add_f32_e32 v127, v127, v47
	v_mul_f32_e32 v126, 0xbfb8aa3b, v126
	v_mul_f32_e32 v127, 0xbfb8aa3b, v127
	v_exp_f32_e32 v126, v126
	v_exp_f32_e32 v127, v127
	v_add_f32_e32 v128, v128, v48
	v_add_f32_e32 v129, v129, v49
	v_mul_f32_e32 v128, 0xbfb8aa3b, v128
	v_pk_add_f32 v[126:127], v[126:127], 1.0 op_sel_hi:[1,0]
	v_mul_f32_e32 v129, 0xbfb8aa3b, v129
	v_div_scale_f32 v134, s[2:3], v127, v127, 1.0
	v_rcp_f32_e32 v135, v134
	v_exp_f32_e32 v128, v128
	v_exp_f32_e32 v129, v129
	v_pk_add_f32 v[122:123], v[122:123], v[50:51]
	v_fma_f32 v136, -v134, v135, 1.0
	v_fmac_f32_e32 v135, v136, v135
	v_div_scale_f32 v136, vcc, 1.0, v127, 1.0
	v_mul_f32_e32 v137, v136, v135
	v_fma_f32 v138, -v134, v137, v136
	v_fmac_f32_e32 v137, v138, v135
	v_fma_f32 v134, -v134, v137, v136
	v_div_fmas_f32 v134, v134, v135, v137
	v_div_fixup_f32 v127, v134, v127, 1.0
	v_div_scale_f32 v134, s[2:3], v126, v126, 1.0
	v_rcp_f32_e32 v135, v134
	v_pk_add_f32 v[128:129], v[128:129], 1.0 op_sel_hi:[1,0]
	v_add_f32_e32 v118, v118, v34
	v_add_f32_e32 v119, v119, v35
	v_fma_f32 v136, -v134, v135, 1.0
	v_fmac_f32_e32 v135, v136, v135
	v_div_scale_f32 v136, vcc, 1.0, v126, 1.0
	v_mul_f32_e32 v137, v136, v135
	v_fma_f32 v138, -v134, v137, v136
	v_fmac_f32_e32 v137, v138, v135
	v_fma_f32 v134, -v134, v137, v136
	v_div_fmas_f32 v134, v134, v135, v137
	v_div_fixup_f32 v126, v134, v126, 1.0
	v_pk_mul_f32 v[122:123], v[122:123], v[126:127]
	v_div_scale_f32 v127, s[2:3], v129, v129, 1.0
	v_rcp_f32_e32 v134, v127
	v_mul_f32_e32 v118, 0xbfb8aa3b, v118
	v_mul_f32_e32 v119, 0xbfb8aa3b, v119
	v_exp_f32_e32 v118, v118
	v_fma_f32 v135, -v127, v134, 1.0
	v_fmac_f32_e32 v134, v135, v134
	v_div_scale_f32 v135, vcc, 1.0, v129, 1.0
	v_mul_f32_e32 v136, v135, v134
	v_fma_f32 v137, -v127, v136, v135
	v_fmac_f32_e32 v136, v137, v134
	v_fma_f32 v127, -v127, v136, v135
	v_div_fmas_f32 v127, v127, v134, v136
	v_div_fixup_f32 v129, v127, v129, 1.0
	v_div_scale_f32 v127, s[2:3], v128, v128, 1.0
	v_rcp_f32_e32 v134, v127
	v_exp_f32_e32 v119, v119
	v_or_b32_e32 v130, 16, v162
	s_waitcnt lgkmcnt(0)
	v_mov_b32_e32 v131, v163
	v_fma_f32 v135, -v127, v134, 1.0
	v_fmac_f32_e32 v134, v135, v134
	v_div_scale_f32 v135, vcc, 1.0, v128, 1.0
	v_mul_f32_e32 v136, v135, v134
	v_fma_f32 v137, -v127, v136, v135
	v_fmac_f32_e32 v136, v137, v134
	v_fma_f32 v127, -v127, v136, v135
	v_div_fmas_f32 v127, v127, v134, v136
	v_lshlrev_b64 v[132:133], 11, v[130:131]
	v_pk_add_f32 v[124:125], v[124:125], v[52:53]
	v_div_fixup_f32 v128, v127, v128, 1.0
	v_pk_mul_f32 v[124:125], v[124:125], v[128:129]
	v_lshl_add_u64 v[128:129], s[0:1], 0, v[132:133]
	v_cvt_pk_f16_f32 v126, v122, v123
	v_cvt_pk_f16_f32 v127, v124, v125
	v_lshl_add_u64 v[128:129], v[160:161], 1, v[128:129]
	v_pk_add_f32 v[118:119], v[118:119], 1.0 op_sel_hi:[1,0]
	global_store_dwordx2 v[128:129], v[126:127], off
	v_div_scale_f32 v126, s[2:3], v119, v119, 1.0
	v_rcp_f32_e32 v127, v126
	v_add_f32_e32 v120, v120, v36
	v_add_f32_e32 v121, v121, v37
	v_mul_f32_e32 v120, 0xbfb8aa3b, v120
	v_fma_f32 v132, -v126, v127, 1.0
	v_fmac_f32_e32 v127, v132, v127
	v_div_scale_f32 v132, vcc, 1.0, v119, 1.0
	v_mul_f32_e32 v133, v132, v127
	v_fma_f32 v134, -v126, v133, v132
	v_fmac_f32_e32 v133, v134, v127
	v_fma_f32 v126, -v126, v133, v132
	v_div_fmas_f32 v126, v126, v127, v133
	v_div_fixup_f32 v119, v126, v119, 1.0
	v_div_scale_f32 v126, s[2:3], v118, v118, 1.0
	v_rcp_f32_e32 v127, v126
	v_mul_f32_e32 v121, 0xbfb8aa3b, v121
	v_exp_f32_e32 v120, v120
	v_exp_f32_e32 v121, v121
	v_fma_f32 v132, -v126, v127, 1.0
	v_fmac_f32_e32 v127, v132, v127
	v_div_scale_f32 v132, vcc, 1.0, v118, 1.0
	v_mul_f32_e32 v133, v132, v127
	v_fma_f32 v134, -v126, v133, v132
	v_fmac_f32_e32 v133, v134, v127
	v_fma_f32 v126, -v126, v133, v132
	v_div_fmas_f32 v126, v126, v127, v133
	v_pk_add_f32 v[114:115], v[114:115], v[62:63]
	v_div_fixup_f32 v118, v126, v118, 1.0
	v_pk_add_f32 v[120:121], v[120:121], 1.0 op_sel_hi:[1,0]
	v_pk_mul_f32 v[114:115], v[114:115], v[118:119]
	v_div_scale_f32 v119, s[2:3], v121, v121, 1.0
	v_rcp_f32_e32 v126, v119
	v_pk_add_f32 v[116:117], v[116:117], v[64:65]
	v_pk_mul_f32 v[122:123], v[122:123], v[122:123]
	v_cvt_pk_f16_f32 v118, v114, v115
	v_fma_f32 v127, -v119, v126, 1.0
	v_fmac_f32_e32 v126, v127, v126
	v_div_scale_f32 v127, vcc, 1.0, v121, 1.0
	v_mul_f32_e32 v132, v127, v126
	v_fma_f32 v133, -v119, v132, v127
	v_fmac_f32_e32 v132, v133, v126
	v_fma_f32 v119, -v119, v132, v127
	v_div_fmas_f32 v119, v119, v126, v132
	v_div_fixup_f32 v121, v119, v121, 1.0
	v_div_scale_f32 v119, s[2:3], v120, v120, 1.0
	v_rcp_f32_e32 v126, v119
	v_pk_mul_f32 v[114:115], v[114:115], v[114:115]
	v_pk_mul_f32 v[124:125], v[124:125], v[124:125]
	v_add_f32_e32 v114, v114, v115
	v_fma_f32 v127, -v119, v126, 1.0
	v_fmac_f32_e32 v126, v127, v126
	v_div_scale_f32 v127, vcc, 1.0, v120, 1.0
	v_mul_f32_e32 v132, v127, v126
	v_fma_f32 v133, -v119, v132, v127
	v_fmac_f32_e32 v132, v133, v126
	v_fma_f32 v119, -v119, v132, v127
	v_div_fmas_f32 v119, v119, v126, v132
	v_div_fixup_f32 v120, v119, v120, 1.0
	v_pk_mul_f32 v[116:117], v[116:117], v[120:121]
	v_add_f32_e32 v115, v122, v123
	v_cvt_pk_f16_f32 v119, v116, v117
	v_pk_mul_f32 v[116:117], v[116:117], v[116:117]
	v_add_f32_e32 v115, v124, v115
	v_add_f32_e32 v114, v116, v114
	v_add_f32_e32 v114, v117, v114
	v_add_f32_e32 v115, v125, v115
	v_add_f32_e32 v114, v115, v114
	v_mov_b32_e32 v115, v114
	s_nop 1
	v_permlane16_swap_b32_e32 v115, v114
	global_store_dwordx2 v[128:129], v[118:119], off offset:128
	s_waitcnt lgkmcnt(0)
	v_add_f32_e32 v114, v114, v115
	ds_bpermute_b32 v115, v173, v114
	s_and_saveexec_b64 s[24:25], s[6:7]
	s_cbranch_execz .LBB0_2289
	s_waitcnt lgkmcnt(0)
	v_add_f32_e32 v116, v114, v115
	v_lshlrev_b64 v[114:115], 6, v[130:131]
	v_lshl_add_u64 v[114:115], s[10:11], 0, v[114:115]
	v_lshl_add_u64 v[114:115], s[22:23], 2, v[114:115]
	s_lshl_b32 s92, s45, 2
	v_lshl_add_u64 v[114:115], v[114:115], 0, s[92:93]
	global_store_dword v[114:115], v116, off
; __device__ __forceinline__ float xor16(float v) { return __int_as_float(__builtin_amdgcn_ds_swizzle(__float_as_int(v), 0x401F)); }
; __device__ __forceinline__ float sigmoidf(float x) { return 1.f / (1.f + __expf(-x)); }
;   __device__ __forceinline__ void operator()(const f32x4 (&acc)[2][2][4][2], const g8::Unit& u, int ui, int wr, int wc, int fr, int fq) const {
;     ...
;       for (int m = 0; m < 4; ++m) {
;         const size_t row = (size_t)u.pm * 256 + 128 * ai + 64 * wr + 16 * m + fr;
;         float ss = 0.f;
; #pragma unroll
;         for (int bj = 0; bj < 2; ++bj) {
;           const f32x4 a = acc[ai][bj][m][0], b = acc[ai][bj][m][1];
;           float o0 = (a[0] + ba[bj].x) * sigmoidf(b[0] + bb[bj].x);
;           float o1 = (a[1] + ba[bj].y) * sigmoidf(b[1] + bb[bj].y);
;           float o2 = (a[2] + ba[bj].z) * sigmoidf(b[2] + bb[bj].z);
;           float o3 = (a[3] + ba[bj].w) * sigmoidf(b[3] + bb[bj].w);
;           *(h16x4*)(OB + row * 1024 + ocb + 64 * bj) = pack4(o0, o1, o2, o3);
;           ss += o0 * o0 + o1 * o1 + o2 * o2 + o3 * o3;
;         }
;         ss += xor16(ss);
;         ss += __shfl_xor(ss, 32);
;         if (fq == 0) ssqb[row * 16 + u.pn * 4 + wc] = ss;
;       }
.LBB0_2289:
	s_or_b64 exec, exec, s[24:25]
	v_add_f32_e32 v110, v110, v46
	v_add_f32_e32 v111, v111, v47
	v_mul_f32_e32 v110, 0xbfb8aa3b, v110
	v_mul_f32_e32 v111, 0xbfb8aa3b, v111
	v_exp_f32_e32 v110, v110
	v_exp_f32_e32 v111, v111
	v_add_f32_e32 v112, v112, v48
	v_add_f32_e32 v113, v113, v49
	v_mul_f32_e32 v112, 0xbfb8aa3b, v112
	v_pk_add_f32 v[110:111], v[110:111], 1.0 op_sel_hi:[1,0]
	v_mul_f32_e32 v113, 0xbfb8aa3b, v113
	v_div_scale_f32 v118, s[2:3], v111, v111, 1.0
	v_rcp_f32_e32 v119, v118
	v_exp_f32_e32 v112, v112
	v_exp_f32_e32 v113, v113
	v_pk_add_f32 v[106:107], v[106:107], v[50:51]
	v_fma_f32 v120, -v118, v119, 1.0
	v_fmac_f32_e32 v119, v120, v119
	v_div_scale_f32 v120, vcc, 1.0, v111, 1.0
	v_mul_f32_e32 v121, v120, v119
	v_fma_f32 v122, -v118, v121, v120
	v_fmac_f32_e32 v121, v122, v119
	v_fma_f32 v118, -v118, v121, v120
	v_div_fmas_f32 v118, v118, v119, v121
	v_div_fixup_f32 v111, v118, v111, 1.0
	v_div_scale_f32 v118, s[2:3], v110, v110, 1.0
	v_rcp_f32_e32 v119, v118
	v_pk_add_f32 v[112:113], v[112:113], 1.0 op_sel_hi:[1,0]
	v_add_f32_e32 v102, v102, v34
	v_add_f32_e32 v103, v103, v35
	v_fma_f32 v120, -v118, v119, 1.0
	v_fmac_f32_e32 v119, v120, v119
	v_div_scale_f32 v120, vcc, 1.0, v110, 1.0
	v_mul_f32_e32 v121, v120, v119
	v_fma_f32 v122, -v118, v121, v120
	v_fmac_f32_e32 v121, v122, v119
	v_fma_f32 v118, -v118, v121, v120
	v_div_fmas_f32 v118, v118, v119, v121
	v_div_fixup_f32 v110, v118, v110, 1.0
	v_pk_mul_f32 v[106:107], v[106:107], v[110:111]
	v_div_scale_f32 v111, s[2:3], v113, v113, 1.0
	v_rcp_f32_e32 v118, v111
	v_mul_f32_e32 v102, 0xbfb8aa3b, v102
	v_mul_f32_e32 v103, 0xbfb8aa3b, v103
	v_exp_f32_e32 v102, v102
	v_fma_f32 v119, -v111, v118, 1.0
	v_fmac_f32_e32 v118, v119, v118
	v_div_scale_f32 v119, vcc, 1.0, v113, 1.0
	v_mul_f32_e32 v120, v119, v118
	v_fma_f32 v121, -v111, v120, v119
	v_fmac_f32_e32 v120, v121, v118
	v_fma_f32 v111, -v111, v120, v119
	v_div_fmas_f32 v111, v111, v118, v120
	v_div_fixup_f32 v113, v111, v113, 1.0
	v_div_scale_f32 v111, s[2:3], v112, v112, 1.0
	v_rcp_f32_e32 v118, v111
	v_exp_f32_e32 v103, v103
	v_or_b32_e32 v114, 32, v162
	s_waitcnt lgkmcnt(0)
	v_mov_b32_e32 v115, v163
	v_fma_f32 v119, -v111, v118, 1.0
	v_fmac_f32_e32 v118, v119, v118
	v_div_scale_f32 v119, vcc, 1.0, v112, 1.0
	v_mul_f32_e32 v120, v119, v118
	v_fma_f32 v121, -v111, v120, v119
	v_fmac_f32_e32 v120, v121, v118
	v_fma_f32 v111, -v111, v120, v119
	v_div_fmas_f32 v111, v111, v118, v120
	v_lshlrev_b64 v[116:117], 11, v[114:115]
	v_pk_add_f32 v[108:109], v[108:109], v[52:53]
	v_div_fixup_f32 v112, v111, v112, 1.0
	v_pk_mul_f32 v[108:109], v[108:109], v[112:113]
	v_lshl_add_u64 v[112:113], s[0:1], 0, v[116:117]
	v_cvt_pk_f16_f32 v110, v106, v107
	v_cvt_pk_f16_f32 v111, v108, v109
	v_lshl_add_u64 v[112:113], v[160:161], 1, v[112:113]
	v_pk_add_f32 v[102:103], v[102:103], 1.0 op_sel_hi:[1,0]
	global_store_dwordx2 v[112:113], v[110:111], off
	v_div_scale_f32 v110, s[2:3], v103, v103, 1.0
	v_rcp_f32_e32 v111, v110
	v_add_f32_e32 v104, v104, v36
	v_add_f32_e32 v105, v105, v37
	v_mul_f32_e32 v104, 0xbfb8aa3b, v104
	v_fma_f32 v116, -v110, v111, 1.0
	v_fmac_f32_e32 v111, v116, v111
	v_div_scale_f32 v116, vcc, 1.0, v103, 1.0
	v_mul_f32_e32 v117, v116, v111
	v_fma_f32 v118, -v110, v117, v116
	v_fmac_f32_e32 v117, v118, v111
	v_fma_f32 v110, -v110, v117, v116
	v_div_fmas_f32 v110, v110, v111, v117
	v_div_fixup_f32 v103, v110, v103, 1.0
	v_div_scale_f32 v110, s[2:3], v102, v102, 1.0
	v_rcp_f32_e32 v111, v110
	v_mul_f32_e32 v105, 0xbfb8aa3b, v105
	v_exp_f32_e32 v104, v104
	v_exp_f32_e32 v105, v105
	v_fma_f32 v116, -v110, v111, 1.0
	v_fmac_f32_e32 v111, v116, v111
	v_div_scale_f32 v116, vcc, 1.0, v102, 1.0
	v_mul_f32_e32 v117, v116, v111
	v_fma_f32 v118, -v110, v117, v116
	v_fmac_f32_e32 v117, v118, v111
	v_fma_f32 v110, -v110, v117, v116
	v_div_fmas_f32 v110, v110, v111, v117
	v_pk_add_f32 v[98:99], v[98:99], v[62:63]
	v_div_fixup_f32 v102, v110, v102, 1.0
	v_pk_add_f32 v[104:105], v[104:105], 1.0 op_sel_hi:[1,0]
	v_pk_mul_f32 v[98:99], v[98:99], v[102:103]
	v_div_scale_f32 v103, s[2:3], v105, v105, 1.0
	v_rcp_f32_e32 v110, v103
	v_pk_add_f32 v[100:101], v[100:101], v[64:65]
	v_pk_mul_f32 v[106:107], v[106:107], v[106:107]
	v_cvt_pk_f16_f32 v102, v98, v99
	v_fma_f32 v111, -v103, v110, 1.0
	v_fmac_f32_e32 v110, v111, v110
	v_div_scale_f32 v111, vcc, 1.0, v105, 1.0
	v_mul_f32_e32 v116, v111, v110
	v_fma_f32 v117, -v103, v116, v111
	v_fmac_f32_e32 v116, v117, v110
	v_fma_f32 v103, -v103, v116, v111
	v_div_fmas_f32 v103, v103, v110, v116
	v_div_fixup_f32 v105, v103, v105, 1.0
	v_div_scale_f32 v103, s[2:3], v104, v104, 1.0
	v_rcp_f32_e32 v110, v103
	v_pk_mul_f32 v[98:99], v[98:99], v[98:99]
	v_pk_mul_f32 v[108:109], v[108:109], v[108:109]
	v_add_f32_e32 v98, v98, v99
	v_fma_f32 v111, -v103, v110, 1.0
	v_fmac_f32_e32 v110, v111, v110
	v_div_scale_f32 v111, vcc, 1.0, v104, 1.0
	v_mul_f32_e32 v116, v111, v110
	v_fma_f32 v117, -v103, v116, v111
	v_fmac_f32_e32 v116, v117, v110
	v_fma_f32 v103, -v103, v116, v111
	v_div_fmas_f32 v103, v103, v110, v116
	v_div_fixup_f32 v104, v103, v104, 1.0
	v_pk_mul_f32 v[100:101], v[100:101], v[104:105]
	v_add_f32_e32 v99, v106, v107
	v_cvt_pk_f16_f32 v103, v100, v101
	v_pk_mul_f32 v[100:101], v[100:101], v[100:101]
	v_add_f32_e32 v99, v108, v99
	v_add_f32_e32 v98, v100, v98
	v_add_f32_e32 v98, v101, v98
	v_add_f32_e32 v99, v109, v99
	v_add_f32_e32 v98, v99, v98
	v_mov_b32_e32 v99, v98
	s_nop 1
	v_permlane16_swap_b32_e32 v99, v98
	global_store_dwordx2 v[112:113], v[102:103], off offset:128
	s_waitcnt lgkmcnt(0)
	v_add_f32_e32 v98, v98, v99
	ds_bpermute_b32 v99, v173, v98
	s_and_saveexec_b64 s[24:25], s[6:7]
	s_cbranch_execz .LBB0_2291
	s_waitcnt lgkmcnt(0)
	v_add_f32_e32 v100, v98, v99
	v_lshlrev_b64 v[98:99], 6, v[114:115]
	v_lshl_add_u64 v[98:99], s[10:11], 0, v[98:99]
	v_lshl_add_u64 v[98:99], s[22:23], 2, v[98:99]
	s_lshl_b32 s92, s45, 2
	v_lshl_add_u64 v[98:99], v[98:99], 0, s[92:93]
	global_store_dword v[98:99], v100, off
; __device__ __forceinline__ float xor16(float v) { return __int_as_float(__builtin_amdgcn_ds_swizzle(__float_as_int(v), 0x401F)); }
; __device__ __forceinline__ float sigmoidf(float x) { return 1.f / (1.f + __expf(-x)); }
;   __device__ __forceinline__ void operator()(const f32x4 (&acc)[2][2][4][2], const g8::Unit& u, int ui, int wr, int wc, int fr, int fq) const {
;     ...
;       for (int m = 0; m < 4; ++m) {
;         const size_t row = (size_t)u.pm * 256 + 128 * ai + 64 * wr + 16 * m + fr;
;         float ss = 0.f;
; #pragma unroll
;         for (int bj = 0; bj < 2; ++bj) {
;           const f32x4 a = acc[ai][bj][m][0], b = acc[ai][bj][m][1];
;           float o0 = (a[0] + ba[bj].x) * sigmoidf(b[0] + bb[bj].x);
;           float o1 = (a[1] + ba[bj].y) * sigmoidf(b[1] + bb[bj].y);
;           float o2 = (a[2] + ba[bj].z) * sigmoidf(b[2] + bb[bj].z);
;           float o3 = (a[3] + ba[bj].w) * sigmoidf(b[3] + bb[bj].w);
;           *(h16x4*)(OB + row * 1024 + ocb + 64 * bj) = pack4(o0, o1, o2, o3);
;           ss += o0 * o0 + o1 * o1 + o2 * o2 + o3 * o3;
;         }
;         ss += xor16(ss);
;         ss += __shfl_xor(ss, 32);
;         if (fq == 0) ssqb[row * 16 + u.pn * 4 + wc] = ss;
;       }
.LBB0_2291:
	s_or_b64 exec, exec, s[24:25]
	v_add_f32_e32 v94, v94, v46
	v_add_f32_e32 v95, v95, v47
	v_mul_f32_e32 v94, 0xbfb8aa3b, v94
	v_mul_f32_e32 v95, 0xbfb8aa3b, v95
	v_exp_f32_e32 v94, v94
	v_exp_f32_e32 v95, v95
	v_add_f32_e32 v96, v96, v48
	v_add_f32_e32 v97, v97, v49
	v_mul_f32_e32 v96, 0xbfb8aa3b, v96
	v_pk_add_f32 v[94:95], v[94:95], 1.0 op_sel_hi:[1,0]
	v_mul_f32_e32 v97, 0xbfb8aa3b, v97
	v_div_scale_f32 v102, s[2:3], v95, v95, 1.0
	v_rcp_f32_e32 v103, v102
	v_exp_f32_e32 v96, v96
	v_exp_f32_e32 v97, v97
	v_pk_add_f32 v[90:91], v[90:91], v[50:51]
	v_fma_f32 v104, -v102, v103, 1.0
	v_fmac_f32_e32 v103, v104, v103
	v_div_scale_f32 v104, vcc, 1.0, v95, 1.0
	v_mul_f32_e32 v105, v104, v103
	v_fma_f32 v106, -v102, v105, v104
	v_fmac_f32_e32 v105, v106, v103
	v_fma_f32 v102, -v102, v105, v104
	v_div_fmas_f32 v102, v102, v103, v105
	v_div_fixup_f32 v95, v102, v95, 1.0
	v_div_scale_f32 v102, s[2:3], v94, v94, 1.0
	v_rcp_f32_e32 v103, v102
	v_pk_add_f32 v[96:97], v[96:97], 1.0 op_sel_hi:[1,0]
	v_add_f32_e32 v86, v86, v34
	v_add_f32_e32 v87, v87, v35
	v_fma_f32 v104, -v102, v103, 1.0
	v_fmac_f32_e32 v103, v104, v103
	v_div_scale_f32 v104, vcc, 1.0, v94, 1.0
	v_mul_f32_e32 v105, v104, v103
	v_fma_f32 v106, -v102, v105, v104
	v_fmac_f32_e32 v105, v106, v103
	v_fma_f32 v102, -v102, v105, v104
	v_div_fmas_f32 v102, v102, v103, v105
	v_div_fixup_f32 v94, v102, v94, 1.0
	v_pk_mul_f32 v[90:91], v[90:91], v[94:95]
	v_div_scale_f32 v95, s[2:3], v97, v97, 1.0
	v_rcp_f32_e32 v102, v95
	v_mul_f32_e32 v86, 0xbfb8aa3b, v86
	v_mul_f32_e32 v87, 0xbfb8aa3b, v87
	v_exp_f32_e32 v86, v86
	v_fma_f32 v103, -v95, v102, 1.0
	v_fmac_f32_e32 v102, v103, v102
	v_div_scale_f32 v103, vcc, 1.0, v97, 1.0
	v_mul_f32_e32 v104, v103, v102
	v_fma_f32 v105, -v95, v104, v103
	v_fmac_f32_e32 v104, v105, v102
	v_fma_f32 v95, -v95, v104, v103
	v_div_fmas_f32 v95, v95, v102, v104
	v_div_fixup_f32 v97, v95, v97, 1.0
	v_div_scale_f32 v95, s[2:3], v96, v96, 1.0
	v_rcp_f32_e32 v102, v95
	v_exp_f32_e32 v87, v87
	v_or_b32_e32 v98, 48, v162
	s_waitcnt lgkmcnt(0)
	v_mov_b32_e32 v99, v163
	v_fma_f32 v103, -v95, v102, 1.0
	v_fmac_f32_e32 v102, v103, v102
	v_div_scale_f32 v103, vcc, 1.0, v96, 1.0
	v_mul_f32_e32 v104, v103, v102
	v_fma_f32 v105, -v95, v104, v103
	v_fmac_f32_e32 v104, v105, v102
	v_fma_f32 v95, -v95, v104, v103
	v_div_fmas_f32 v95, v95, v102, v104
	v_lshlrev_b64 v[100:101], 11, v[98:99]
	v_pk_add_f32 v[92:93], v[92:93], v[52:53]
	v_div_fixup_f32 v96, v95, v96, 1.0
	v_pk_mul_f32 v[92:93], v[92:93], v[96:97]
	v_lshl_add_u64 v[96:97], s[0:1], 0, v[100:101]
	v_cvt_pk_f16_f32 v94, v90, v91
	v_cvt_pk_f16_f32 v95, v92, v93
	v_lshl_add_u64 v[96:97], v[160:161], 1, v[96:97]
	v_pk_add_f32 v[86:87], v[86:87], 1.0 op_sel_hi:[1,0]
	global_store_dwordx2 v[96:97], v[94:95], off
	v_div_scale_f32 v94, s[2:3], v87, v87, 1.0
	v_rcp_f32_e32 v95, v94
	v_add_f32_e32 v88, v88, v36
	v_add_f32_e32 v89, v89, v37
	v_mul_f32_e32 v88, 0xbfb8aa3b, v88
	v_fma_f32 v100, -v94, v95, 1.0
	v_fmac_f32_e32 v95, v100, v95
	v_div_scale_f32 v100, vcc, 1.0, v87, 1.0
	v_mul_f32_e32 v101, v100, v95
	v_fma_f32 v102, -v94, v101, v100
	v_fmac_f32_e32 v101, v102, v95
	v_fma_f32 v94, -v94, v101, v100
	v_div_fmas_f32 v94, v94, v95, v101
	v_div_fixup_f32 v87, v94, v87, 1.0
	v_div_scale_f32 v94, s[2:3], v86, v86, 1.0
	v_rcp_f32_e32 v95, v94
	v_mul_f32_e32 v89, 0xbfb8aa3b, v89
	v_exp_f32_e32 v88, v88
	v_exp_f32_e32 v89, v89
	v_fma_f32 v100, -v94, v95, 1.0
	v_fmac_f32_e32 v95, v100, v95
	v_div_scale_f32 v100, vcc, 1.0, v86, 1.0
	v_mul_f32_e32 v101, v100, v95
	v_fma_f32 v102, -v94, v101, v100
	v_fmac_f32_e32 v101, v102, v95
	v_fma_f32 v94, -v94, v101, v100
	v_div_fmas_f32 v94, v94, v95, v101
	v_pk_add_f32 v[82:83], v[82:83], v[62:63]
	v_div_fixup_f32 v86, v94, v86, 1.0
	v_pk_add_f32 v[88:89], v[88:89], 1.0 op_sel_hi:[1,0]
	v_pk_mul_f32 v[82:83], v[82:83], v[86:87]
	v_div_scale_f32 v87, s[2:3], v89, v89, 1.0
	v_rcp_f32_e32 v94, v87
	v_pk_add_f32 v[84:85], v[84:85], v[64:65]
	v_pk_mul_f32 v[90:91], v[90:91], v[90:91]
	v_cvt_pk_f16_f32 v86, v82, v83
	v_fma_f32 v95, -v87, v94, 1.0
	v_fmac_f32_e32 v94, v95, v94
	v_div_scale_f32 v95, vcc, 1.0, v89, 1.0
	v_mul_f32_e32 v100, v95, v94
	v_fma_f32 v101, -v87, v100, v95
	v_fmac_f32_e32 v100, v101, v94
	v_fma_f32 v87, -v87, v100, v95
	v_div_fmas_f32 v87, v87, v94, v100
	v_div_fixup_f32 v89, v87, v89, 1.0
	v_div_scale_f32 v87, s[2:3], v88, v88, 1.0
	v_rcp_f32_e32 v94, v87
	v_pk_mul_f32 v[82:83], v[82:83], v[82:83]
	v_pk_mul_f32 v[92:93], v[92:93], v[92:93]
	v_add_f32_e32 v82, v82, v83
	v_fma_f32 v95, -v87, v94, 1.0
	v_fmac_f32_e32 v94, v95, v94
	v_div_scale_f32 v95, vcc, 1.0, v88, 1.0
	v_mul_f32_e32 v100, v95, v94
	v_fma_f32 v101, -v87, v100, v95
	v_fmac_f32_e32 v100, v101, v94
	v_fma_f32 v87, -v87, v100, v95
	v_div_fmas_f32 v87, v87, v94, v100
	v_div_fixup_f32 v88, v87, v88, 1.0
	v_pk_mul_f32 v[84:85], v[84:85], v[88:89]
	v_add_f32_e32 v83, v90, v91
	v_cvt_pk_f16_f32 v87, v84, v85
	v_pk_mul_f32 v[84:85], v[84:85], v[84:85]
	v_add_f32_e32 v83, v92, v83
	v_add_f32_e32 v82, v84, v82
	v_add_f32_e32 v82, v85, v82
	v_add_f32_e32 v83, v93, v83
	v_add_f32_e32 v82, v83, v82
	v_mov_b32_e32 v83, v82
	s_nop 1
	v_permlane16_swap_b32_e32 v83, v82
	global_store_dwordx2 v[96:97], v[86:87], off offset:128
	s_waitcnt lgkmcnt(0)
	v_add_f32_e32 v82, v82, v83
	ds_bpermute_b32 v83, v173, v82
	s_and_saveexec_b64 s[24:25], s[6:7]
	s_cbranch_execz .LBB0_2293
	s_waitcnt lgkmcnt(0)
	v_add_f32_e32 v84, v82, v83
	v_lshlrev_b64 v[82:83], 6, v[98:99]
	v_lshl_add_u64 v[82:83], s[10:11], 0, v[82:83]
	v_lshl_add_u64 v[82:83], s[22:23], 2, v[82:83]
	s_lshl_b32 s92, s45, 2
	v_lshl_add_u64 v[82:83], v[82:83], 0, s[92:93]
	global_store_dword v[82:83], v84, off
; __device__ __forceinline__ float xor16(float v) { return __int_as_float(__builtin_amdgcn_ds_swizzle(__float_as_int(v), 0x401F)); }
; __device__ __forceinline__ float sigmoidf(float x) { return 1.f / (1.f + __expf(-x)); }
;   __device__ __forceinline__ void operator()(const f32x4 (&acc)[2][2][4][2], const g8::Unit& u, int ui, int wr, int wc, int fr, int fq) const {
;     ...
;       for (int m = 0; m < 4; ++m) {
;         const size_t row = (size_t)u.pm * 256 + 128 * ai + 64 * wr + 16 * m + fr;
;         float ss = 0.f;
; #pragma unroll
;         for (int bj = 0; bj < 2; ++bj) {
;           const f32x4 a = acc[ai][bj][m][0], b = acc[ai][bj][m][1];
;           float o0 = (a[0] + ba[bj].x) * sigmoidf(b[0] + bb[bj].x);
;           float o1 = (a[1] + ba[bj].y) * sigmoidf(b[1] + bb[bj].y);
;           float o2 = (a[2] + ba[bj].z) * sigmoidf(b[2] + bb[bj].z);
;           float o3 = (a[3] + ba[bj].w) * sigmoidf(b[3] + bb[bj].w);
;           *(h16x4*)(OB + row * 1024 + ocb + 64 * bj) = pack4(o0, o1, o2, o3);
;           ss += o0 * o0 + o1 * o1 + o2 * o2 + o3 * o3;
;         }
;         ss += xor16(ss);
;         ss += __shfl_xor(ss, 32);
;         if (fq == 0) ssqb[row * 16 + u.pn * 4 + wc] = ss;
;       }
.LBB0_2293:
	s_or_b64 exec, exec, s[24:25]
	v_add_f32_e32 v78, v78, v46
	v_add_f32_e32 v79, v79, v47
	v_mul_f32_e32 v78, 0xbfb8aa3b, v78
	v_mul_f32_e32 v79, 0xbfb8aa3b, v79
	v_exp_f32_e32 v78, v78
	v_exp_f32_e32 v79, v79
	v_add_f32_e32 v80, v80, v48
	v_add_f32_e32 v81, v81, v49
	v_mul_f32_e32 v80, 0xbfb8aa3b, v80
	v_pk_add_f32 v[78:79], v[78:79], 1.0 op_sel_hi:[1,0]
	v_mul_f32_e32 v81, 0xbfb8aa3b, v81
	v_div_scale_f32 v86, s[2:3], v79, v79, 1.0
	v_rcp_f32_e32 v87, v86
	v_exp_f32_e32 v80, v80
	v_exp_f32_e32 v81, v81
	v_pk_add_f32 v[74:75], v[74:75], v[50:51]
	v_fma_f32 v88, -v86, v87, 1.0
	v_fmac_f32_e32 v87, v88, v87
	v_div_scale_f32 v88, vcc, 1.0, v79, 1.0
	v_mul_f32_e32 v89, v88, v87
	v_fma_f32 v90, -v86, v89, v88
	v_fmac_f32_e32 v89, v90, v87
	v_fma_f32 v86, -v86, v89, v88
	v_div_fmas_f32 v86, v86, v87, v89
	v_div_fixup_f32 v79, v86, v79, 1.0
	v_div_scale_f32 v86, s[2:3], v78, v78, 1.0
	v_rcp_f32_e32 v87, v86
	v_pk_add_f32 v[80:81], v[80:81], 1.0 op_sel_hi:[1,0]
	v_add_f32_e32 v70, v70, v34
	v_add_f32_e32 v71, v71, v35
	v_fma_f32 v88, -v86, v87, 1.0
	v_fmac_f32_e32 v87, v88, v87
	v_div_scale_f32 v88, vcc, 1.0, v78, 1.0
	v_mul_f32_e32 v89, v88, v87
	v_fma_f32 v90, -v86, v89, v88
	v_fmac_f32_e32 v89, v90, v87
	v_fma_f32 v86, -v86, v89, v88
	v_div_fmas_f32 v86, v86, v87, v89
	v_div_fixup_f32 v78, v86, v78, 1.0
	v_pk_mul_f32 v[74:75], v[74:75], v[78:79]
	v_div_scale_f32 v79, s[2:3], v81, v81, 1.0
	v_rcp_f32_e32 v86, v79
	v_mul_f32_e32 v70, 0xbfb8aa3b, v70
	v_mul_f32_e32 v71, 0xbfb8aa3b, v71
	v_exp_f32_e32 v70, v70
	v_fma_f32 v87, -v79, v86, 1.0
	v_fmac_f32_e32 v86, v87, v86
	v_div_scale_f32 v87, vcc, 1.0, v81, 1.0
	v_mul_f32_e32 v88, v87, v86
	v_fma_f32 v89, -v79, v88, v87
	v_fmac_f32_e32 v88, v89, v86
	v_fma_f32 v79, -v79, v88, v87
	v_div_fmas_f32 v79, v79, v86, v88
	v_div_fixup_f32 v81, v79, v81, 1.0
	v_div_scale_f32 v79, s[2:3], v80, v80, 1.0
	v_rcp_f32_e32 v86, v79
	v_exp_f32_e32 v71, v71
	s_waitcnt lgkmcnt(0)
	v_lshl_add_u64 v[82:83], v[162:163], 0, s[94:95]
	v_lshlrev_b64 v[84:85], 11, v[82:83]
	v_fma_f32 v87, -v79, v86, 1.0
	v_fmac_f32_e32 v86, v87, v86
	v_div_scale_f32 v87, vcc, 1.0, v80, 1.0
	v_mul_f32_e32 v88, v87, v86
	v_fma_f32 v89, -v79, v88, v87
	v_fmac_f32_e32 v88, v89, v86
	v_fma_f32 v79, -v79, v88, v87
	v_div_fmas_f32 v79, v79, v86, v88
	v_pk_add_f32 v[76:77], v[76:77], v[52:53]
	v_div_fixup_f32 v80, v79, v80, 1.0
	v_pk_mul_f32 v[76:77], v[76:77], v[80:81]
	v_lshl_add_u64 v[80:81], s[0:1], 0, v[84:85]
	v_cvt_pk_f16_f32 v78, v74, v75
	v_cvt_pk_f16_f32 v79, v76, v77
	v_lshl_add_u64 v[80:81], v[160:161], 1, v[80:81]
	v_pk_add_f32 v[70:71], v[70:71], 1.0 op_sel_hi:[1,0]
	global_store_dwordx2 v[80:81], v[78:79], off
	v_div_scale_f32 v78, s[2:3], v71, v71, 1.0
	v_rcp_f32_e32 v79, v78
	v_add_f32_e32 v72, v72, v36
	v_add_f32_e32 v73, v73, v37
	v_mul_f32_e32 v72, 0xbfb8aa3b, v72
	v_fma_f32 v84, -v78, v79, 1.0
	v_fmac_f32_e32 v79, v84, v79
	v_div_scale_f32 v84, vcc, 1.0, v71, 1.0
	v_mul_f32_e32 v85, v84, v79
	v_fma_f32 v86, -v78, v85, v84
	v_fmac_f32_e32 v85, v86, v79
	v_fma_f32 v78, -v78, v85, v84
	v_div_fmas_f32 v78, v78, v79, v85
	v_div_fixup_f32 v71, v78, v71, 1.0
	v_div_scale_f32 v78, s[2:3], v70, v70, 1.0
	v_rcp_f32_e32 v79, v78
	v_mul_f32_e32 v73, 0xbfb8aa3b, v73
	v_exp_f32_e32 v72, v72
	v_exp_f32_e32 v73, v73
	v_fma_f32 v84, -v78, v79, 1.0
	v_fmac_f32_e32 v79, v84, v79
	v_div_scale_f32 v84, vcc, 1.0, v70, 1.0
	v_mul_f32_e32 v85, v84, v79
	v_fma_f32 v86, -v78, v85, v84
	v_fmac_f32_e32 v85, v86, v79
	v_fma_f32 v78, -v78, v85, v84
	v_div_fmas_f32 v78, v78, v79, v85
	v_pk_add_f32 v[66:67], v[66:67], v[62:63]
	v_div_fixup_f32 v70, v78, v70, 1.0
	v_pk_add_f32 v[72:73], v[72:73], 1.0 op_sel_hi:[1,0]
	v_pk_mul_f32 v[66:67], v[66:67], v[70:71]
	v_div_scale_f32 v71, s[2:3], v73, v73, 1.0
	v_rcp_f32_e32 v78, v71
	v_pk_add_f32 v[68:69], v[68:69], v[64:65]
	v_pk_mul_f32 v[74:75], v[74:75], v[74:75]
	v_cvt_pk_f16_f32 v70, v66, v67
	v_fma_f32 v79, -v71, v78, 1.0
	v_fmac_f32_e32 v78, v79, v78
	v_div_scale_f32 v79, vcc, 1.0, v73, 1.0
	v_mul_f32_e32 v84, v79, v78
	v_fma_f32 v85, -v71, v84, v79
	v_fmac_f32_e32 v84, v85, v78
	v_fma_f32 v71, -v71, v84, v79
	v_div_fmas_f32 v71, v71, v78, v84
	v_div_fixup_f32 v73, v71, v73, 1.0
	v_div_scale_f32 v71, s[2:3], v72, v72, 1.0
	v_rcp_f32_e32 v78, v71
	v_pk_mul_f32 v[66:67], v[66:67], v[66:67]
	v_pk_mul_f32 v[76:77], v[76:77], v[76:77]
	v_add_f32_e32 v66, v66, v67
	v_fma_f32 v79, -v71, v78, 1.0
	v_fmac_f32_e32 v78, v79, v78
	v_div_scale_f32 v79, vcc, 1.0, v72, 1.0
	v_mul_f32_e32 v84, v79, v78
	v_fma_f32 v85, -v71, v84, v79
	v_fmac_f32_e32 v84, v85, v78
	v_fma_f32 v71, -v71, v84, v79
	v_div_fmas_f32 v71, v71, v78, v84
	v_div_fixup_f32 v72, v71, v72, 1.0
	v_pk_mul_f32 v[68:69], v[68:69], v[72:73]
	v_add_f32_e32 v67, v74, v75
	v_cvt_pk_f16_f32 v71, v68, v69
	v_pk_mul_f32 v[68:69], v[68:69], v[68:69]
	v_add_f32_e32 v67, v76, v67
	v_add_f32_e32 v66, v68, v66
	v_add_f32_e32 v66, v69, v66
	v_add_f32_e32 v67, v77, v67
	v_add_f32_e32 v66, v67, v66
	v_mov_b32_e32 v67, v66
	s_nop 1
	v_permlane16_swap_b32_e32 v67, v66
	global_store_dwordx2 v[80:81], v[70:71], off offset:128
	s_waitcnt lgkmcnt(0)
	v_add_f32_e32 v66, v66, v67
	ds_bpermute_b32 v67, v173, v66
	s_and_saveexec_b64 s[24:25], s[6:7]
	s_cbranch_execz .LBB0_2295
	s_waitcnt lgkmcnt(0)
	v_add_f32_e32 v68, v66, v67
	v_lshlrev_b64 v[66:67], 6, v[82:83]
	v_lshl_add_u64 v[66:67], s[10:11], 0, v[66:67]
	v_lshl_add_u64 v[66:67], s[22:23], 2, v[66:67]
	s_lshl_b32 s92, s45, 2
	v_lshl_add_u64 v[66:67], v[66:67], 0, s[92:93]
	global_store_dword v[66:67], v68, off
; __device__ __forceinline__ float xor16(float v) { return __int_as_float(__builtin_amdgcn_ds_swizzle(__float_as_int(v), 0x401F)); }
; __device__ __forceinline__ float sigmoidf(float x) { return 1.f / (1.f + __expf(-x)); }
;   __device__ __forceinline__ void operator()(const f32x4 (&acc)[2][2][4][2], const g8::Unit& u, int ui, int wr, int wc, int fr, int fq) const {
;     ...
;       for (int m = 0; m < 4; ++m) {
;         const size_t row = (size_t)u.pm * 256 + 128 * ai + 64 * wr + 16 * m + fr;
;         float ss = 0.f;
; #pragma unroll
;         for (int bj = 0; bj < 2; ++bj) {
;           const f32x4 a = acc[ai][bj][m][0], b = acc[ai][bj][m][1];
;           float o0 = (a[0] + ba[bj].x) * sigmoidf(b[0] + bb[bj].x);
;           float o1 = (a[1] + ba[bj].y) * sigmoidf(b[1] + bb[bj].y);
;           float o2 = (a[2] + ba[bj].z) * sigmoidf(b[2] + bb[bj].z);
;           float o3 = (a[3] + ba[bj].w) * sigmoidf(b[3] + bb[bj].w);
;           *(h16x4*)(OB + row * 1024 + ocb + 64 * bj) = pack4(o0, o1, o2, o3);
;           ss += o0 * o0 + o1 * o1 + o2 * o2 + o3 * o3;
;         }
;         ss += xor16(ss);
;         ss += __shfl_xor(ss, 32);
;         if (fq == 0) ssqb[row * 16 + u.pn * 4 + wc] = ss;
;       }
.LBB0_2295:
	s_or_b64 exec, exec, s[24:25]
	v_add_f32_e32 v58, v58, v46
	v_add_f32_e32 v59, v59, v47
	v_mul_f32_e32 v58, 0xbfb8aa3b, v58
	v_mul_f32_e32 v59, 0xbfb8aa3b, v59
	v_exp_f32_e32 v58, v58
	v_exp_f32_e32 v59, v59
	s_mov_b64 s[2:3], 0x90
	s_waitcnt lgkmcnt(0)
	v_lshl_add_u64 v[66:67], v[162:163], 0, s[2:3]
	v_add_f32_e32 v60, v60, v48
	v_pk_add_f32 v[58:59], v[58:59], 1.0 op_sel_hi:[1,0]
	v_add_f32_e32 v61, v61, v49
	v_div_scale_f32 v70, s[2:3], v59, v59, 1.0
	v_rcp_f32_e32 v71, v70
	v_mul_f32_e32 v60, 0xbfb8aa3b, v60
	v_mul_f32_e32 v61, 0xbfb8aa3b, v61
	v_exp_f32_e32 v60, v60
	v_fma_f32 v72, -v70, v71, 1.0
	v_fmac_f32_e32 v71, v72, v71
	v_div_scale_f32 v72, vcc, 1.0, v59, 1.0
	v_mul_f32_e32 v73, v72, v71
	v_fma_f32 v74, -v70, v73, v72
	v_fmac_f32_e32 v73, v74, v71
	v_fma_f32 v70, -v70, v73, v72
	v_div_fmas_f32 v70, v70, v71, v73
	v_div_fixup_f32 v59, v70, v59, 1.0
	v_div_scale_f32 v70, s[2:3], v58, v58, 1.0
	v_rcp_f32_e32 v71, v70
	v_exp_f32_e32 v61, v61
	v_pk_add_f32 v[54:55], v[54:55], v[50:51]
	v_add_f32_e32 v42, v42, v34
	v_fma_f32 v72, -v70, v71, 1.0
	v_fmac_f32_e32 v71, v72, v71
	v_div_scale_f32 v72, vcc, 1.0, v58, 1.0
	v_mul_f32_e32 v73, v72, v71
	v_fma_f32 v74, -v70, v73, v72
	v_fmac_f32_e32 v73, v74, v71
	v_fma_f32 v70, -v70, v73, v72
	v_div_fmas_f32 v70, v70, v71, v73
	v_div_fixup_f32 v58, v70, v58, 1.0
	v_pk_add_f32 v[60:61], v[60:61], 1.0 op_sel_hi:[1,0]
	v_pk_mul_f32 v[54:55], v[54:55], v[58:59]
	v_div_scale_f32 v59, s[2:3], v61, v61, 1.0
	v_rcp_f32_e32 v70, v59
	v_add_f32_e32 v43, v43, v35
	v_mul_f32_e32 v42, 0xbfb8aa3b, v42
	v_mul_f32_e32 v43, 0xbfb8aa3b, v43
	v_fma_f32 v71, -v59, v70, 1.0
	v_fmac_f32_e32 v70, v71, v70
	v_div_scale_f32 v71, vcc, 1.0, v61, 1.0
	v_mul_f32_e32 v72, v71, v70
	v_fma_f32 v73, -v59, v72, v71
	v_fmac_f32_e32 v72, v73, v70
	v_fma_f32 v59, -v59, v72, v71
	v_div_fmas_f32 v59, v59, v70, v72
	v_div_fixup_f32 v61, v59, v61, 1.0
	v_div_scale_f32 v59, s[2:3], v60, v60, 1.0
	v_rcp_f32_e32 v70, v59
	v_exp_f32_e32 v42, v42
	v_exp_f32_e32 v43, v43
	v_lshlrev_b64 v[68:69], 11, v[66:67]
	v_fma_f32 v71, -v59, v70, 1.0
	v_fmac_f32_e32 v70, v71, v70
	v_div_scale_f32 v71, vcc, 1.0, v60, 1.0
	v_mul_f32_e32 v72, v71, v70
	v_fma_f32 v73, -v59, v72, v71
	v_fmac_f32_e32 v72, v73, v70
	v_fma_f32 v59, -v59, v72, v71
	v_div_fmas_f32 v59, v59, v70, v72
	v_pk_add_f32 v[56:57], v[56:57], v[52:53]
	v_div_fixup_f32 v60, v59, v60, 1.0
	v_pk_mul_f32 v[56:57], v[56:57], v[60:61]
	v_lshl_add_u64 v[60:61], s[0:1], 0, v[68:69]
	v_cvt_pk_f16_f32 v58, v54, v55
	v_cvt_pk_f16_f32 v59, v56, v57
	v_lshl_add_u64 v[60:61], v[160:161], 1, v[60:61]
	v_pk_add_f32 v[42:43], v[42:43], 1.0 op_sel_hi:[1,0]
	global_store_dwordx2 v[60:61], v[58:59], off
	v_div_scale_f32 v58, s[2:3], v43, v43, 1.0
	v_rcp_f32_e32 v59, v58
	v_add_f32_e32 v44, v44, v36
	v_add_f32_e32 v45, v45, v37
	v_mul_f32_e32 v44, 0xbfb8aa3b, v44
	v_fma_f32 v68, -v58, v59, 1.0
	v_fmac_f32_e32 v59, v68, v59
	v_div_scale_f32 v68, vcc, 1.0, v43, 1.0
	v_mul_f32_e32 v69, v68, v59
	v_fma_f32 v70, -v58, v69, v68
	v_fmac_f32_e32 v69, v70, v59
	v_fma_f32 v58, -v58, v69, v68
	v_div_fmas_f32 v58, v58, v59, v69
	v_div_fixup_f32 v43, v58, v43, 1.0
	v_div_scale_f32 v58, s[2:3], v42, v42, 1.0
	v_rcp_f32_e32 v59, v58
	v_mul_f32_e32 v45, 0xbfb8aa3b, v45
	v_exp_f32_e32 v44, v44
	v_exp_f32_e32 v45, v45
	v_fma_f32 v68, -v58, v59, 1.0
	v_fmac_f32_e32 v59, v68, v59
	v_div_scale_f32 v68, vcc, 1.0, v42, 1.0
	v_mul_f32_e32 v69, v68, v59
	v_fma_f32 v70, -v58, v69, v68
	v_fmac_f32_e32 v69, v70, v59
	v_fma_f32 v58, -v58, v69, v68
	v_div_fmas_f32 v58, v58, v59, v69
	v_pk_add_f32 v[38:39], v[38:39], v[62:63]
	v_div_fixup_f32 v42, v58, v42, 1.0
	v_pk_add_f32 v[44:45], v[44:45], 1.0 op_sel_hi:[1,0]
	v_pk_mul_f32 v[38:39], v[38:39], v[42:43]
	v_div_scale_f32 v43, s[2:3], v45, v45, 1.0
	v_rcp_f32_e32 v58, v43
	v_pk_add_f32 v[40:41], v[40:41], v[64:65]
	v_pk_mul_f32 v[54:55], v[54:55], v[54:55]
	v_cvt_pk_f16_f32 v42, v38, v39
	v_fma_f32 v59, -v43, v58, 1.0
	v_fmac_f32_e32 v58, v59, v58
	v_div_scale_f32 v59, vcc, 1.0, v45, 1.0
	v_mul_f32_e32 v68, v59, v58
	v_fma_f32 v69, -v43, v68, v59
	v_fmac_f32_e32 v68, v69, v58
	v_fma_f32 v43, -v43, v68, v59
	v_div_fmas_f32 v43, v43, v58, v68
	v_div_fixup_f32 v45, v43, v45, 1.0
	v_div_scale_f32 v43, s[2:3], v44, v44, 1.0
	v_rcp_f32_e32 v58, v43
	v_pk_mul_f32 v[38:39], v[38:39], v[38:39]
	v_pk_mul_f32 v[56:57], v[56:57], v[56:57]
	v_add_f32_e32 v38, v38, v39
	v_fma_f32 v59, -v43, v58, 1.0
	v_fmac_f32_e32 v58, v59, v58
	v_div_scale_f32 v59, vcc, 1.0, v44, 1.0
	v_mul_f32_e32 v68, v59, v58
	v_fma_f32 v69, -v43, v68, v59
	v_fmac_f32_e32 v68, v69, v58
	v_fma_f32 v43, -v43, v68, v59
	v_div_fmas_f32 v43, v43, v58, v68
	v_div_fixup_f32 v44, v43, v44, 1.0
	v_pk_mul_f32 v[40:41], v[40:41], v[44:45]
	v_add_f32_e32 v39, v54, v55
	v_cvt_pk_f16_f32 v43, v40, v41
	v_pk_mul_f32 v[40:41], v[40:41], v[40:41]
	v_add_f32_e32 v39, v56, v39
	v_add_f32_e32 v38, v40, v38
	v_add_f32_e32 v38, v41, v38
	v_add_f32_e32 v39, v57, v39
	v_add_f32_e32 v38, v39, v38
	v_mov_b32_e32 v39, v38
	s_nop 1
	v_permlane16_swap_b32_e32 v39, v38
	global_store_dwordx2 v[60:61], v[42:43], off offset:128
	s_waitcnt lgkmcnt(0)
	v_add_f32_e32 v38, v38, v39
	ds_bpermute_b32 v39, v173, v38
	s_and_saveexec_b64 s[24:25], s[6:7]
	s_cbranch_execz .LBB0_2297
	s_waitcnt lgkmcnt(0)
	v_add_f32_e32 v40, v38, v39
	v_lshlrev_b64 v[38:39], 6, v[66:67]
	v_lshl_add_u64 v[38:39], s[10:11], 0, v[38:39]
	v_lshl_add_u64 v[38:39], s[22:23], 2, v[38:39]
	s_lshl_b32 s92, s45, 2
	v_lshl_add_u64 v[38:39], v[38:39], 0, s[92:93]
	global_store_dword v[38:39], v40, off
; __device__ __forceinline__ float xor16(float v) { return __int_as_float(__builtin_amdgcn_ds_swizzle(__float_as_int(v), 0x401F)); }
; __device__ __forceinline__ float sigmoidf(float x) { return 1.f / (1.f + __expf(-x)); }
;   __device__ __forceinline__ void operator()(const f32x4 (&acc)[2][2][4][2], const g8::Unit& u, int ui, int wr, int wc, int fr, int fq) const {
;     ...
;       for (int m = 0; m < 4; ++m) {
;         const size_t row = (size_t)u.pm * 256 + 128 * ai + 64 * wr + 16 * m + fr;
;         float ss = 0.f;
; #pragma unroll
;         for (int bj = 0; bj < 2; ++bj) {
;           const f32x4 a = acc[ai][bj][m][0], b = acc[ai][bj][m][1];
;           float o0 = (a[0] + ba[bj].x) * sigmoidf(b[0] + bb[bj].x);
;           float o1 = (a[1] + ba[bj].y) * sigmoidf(b[1] + bb[bj].y);
;           float o2 = (a[2] + ba[bj].z) * sigmoidf(b[2] + bb[bj].z);
;           float o3 = (a[3] + ba[bj].w) * sigmoidf(b[3] + bb[bj].w);
;           *(h16x4*)(OB + row * 1024 + ocb + 64 * bj) = pack4(o0, o1, o2, o3);
;           ss += o0 * o0 + o1 * o1 + o2 * o2 + o3 * o3;
;         }
;         ss += xor16(ss);
;         ss += __shfl_xor(ss, 32);
;         if (fq == 0) ssqb[row * 16 + u.pn * 4 + wc] = ss;
;       }
.LBB0_2297:
	s_or_b64 exec, exec, s[24:25]
	v_add_f32_e32 v30, v30, v46
	v_add_f32_e32 v31, v31, v47
	v_mul_f32_e32 v30, 0xbfb8aa3b, v30
	v_mul_f32_e32 v31, 0xbfb8aa3b, v31
	v_exp_f32_e32 v30, v30
	v_exp_f32_e32 v31, v31
	s_mov_b64 s[2:3], 0xa0
	s_waitcnt lgkmcnt(0)
	v_lshl_add_u64 v[38:39], v[162:163], 0, s[2:3]
	v_add_f32_e32 v32, v32, v48
	v_pk_add_f32 v[30:31], v[30:31], 1.0 op_sel_hi:[1,0]
	v_add_f32_e32 v33, v33, v49
	v_div_scale_f32 v42, s[2:3], v31, v31, 1.0
	v_rcp_f32_e32 v43, v42
	v_mul_f32_e32 v32, 0xbfb8aa3b, v32
	v_mul_f32_e32 v33, 0xbfb8aa3b, v33
	v_exp_f32_e32 v32, v32
	v_fma_f32 v44, -v42, v43, 1.0
	v_fmac_f32_e32 v43, v44, v43
	v_div_scale_f32 v44, vcc, 1.0, v31, 1.0
	v_mul_f32_e32 v45, v44, v43
	v_fma_f32 v54, -v42, v45, v44
	v_fmac_f32_e32 v45, v54, v43
	v_fma_f32 v42, -v42, v45, v44
	v_div_fmas_f32 v42, v42, v43, v45
	v_div_fixup_f32 v31, v42, v31, 1.0
	v_div_scale_f32 v42, s[2:3], v30, v30, 1.0
	v_rcp_f32_e32 v43, v42
	v_exp_f32_e32 v33, v33
	v_pk_add_f32 v[26:27], v[26:27], v[50:51]
	v_add_f32_e32 v22, v22, v34
	v_fma_f32 v44, -v42, v43, 1.0
	v_fmac_f32_e32 v43, v44, v43
	v_div_scale_f32 v44, vcc, 1.0, v30, 1.0
	v_mul_f32_e32 v45, v44, v43
	v_fma_f32 v54, -v42, v45, v44
	v_fmac_f32_e32 v45, v54, v43
	v_fma_f32 v42, -v42, v45, v44
	v_div_fmas_f32 v42, v42, v43, v45
	v_div_fixup_f32 v30, v42, v30, 1.0
	v_pk_add_f32 v[32:33], v[32:33], 1.0 op_sel_hi:[1,0]
	v_pk_mul_f32 v[26:27], v[26:27], v[30:31]
	v_div_scale_f32 v31, s[2:3], v33, v33, 1.0
	v_rcp_f32_e32 v42, v31
	v_add_f32_e32 v23, v23, v35
	v_mul_f32_e32 v22, 0xbfb8aa3b, v22
	v_mul_f32_e32 v23, 0xbfb8aa3b, v23
	v_fma_f32 v43, -v31, v42, 1.0
	v_fmac_f32_e32 v42, v43, v42
	v_div_scale_f32 v43, vcc, 1.0, v33, 1.0
	v_mul_f32_e32 v44, v43, v42
	v_fma_f32 v45, -v31, v44, v43
	v_fmac_f32_e32 v44, v45, v42
	v_fma_f32 v31, -v31, v44, v43
	v_div_fmas_f32 v31, v31, v42, v44
	v_div_fixup_f32 v33, v31, v33, 1.0
	v_div_scale_f32 v31, s[2:3], v32, v32, 1.0
	v_rcp_f32_e32 v42, v31
	v_exp_f32_e32 v22, v22
	v_exp_f32_e32 v23, v23
	v_lshlrev_b64 v[40:41], 11, v[38:39]
	v_fma_f32 v43, -v31, v42, 1.0
	v_fmac_f32_e32 v42, v43, v42
	v_div_scale_f32 v43, vcc, 1.0, v32, 1.0
	v_mul_f32_e32 v44, v43, v42
	v_fma_f32 v45, -v31, v44, v43
	v_fmac_f32_e32 v44, v45, v42
	v_fma_f32 v31, -v31, v44, v43
	v_div_fmas_f32 v31, v31, v42, v44
	v_pk_add_f32 v[28:29], v[28:29], v[52:53]
	v_div_fixup_f32 v32, v31, v32, 1.0
	v_pk_mul_f32 v[28:29], v[28:29], v[32:33]
	v_lshl_add_u64 v[32:33], s[0:1], 0, v[40:41]
	v_cvt_pk_f16_f32 v30, v26, v27
	v_cvt_pk_f16_f32 v31, v28, v29
	v_lshl_add_u64 v[32:33], v[160:161], 1, v[32:33]
	v_pk_add_f32 v[22:23], v[22:23], 1.0 op_sel_hi:[1,0]
	global_store_dwordx2 v[32:33], v[30:31], off
	v_div_scale_f32 v30, s[2:3], v23, v23, 1.0
	v_rcp_f32_e32 v31, v30
	v_add_f32_e32 v24, v24, v36
	v_add_f32_e32 v25, v25, v37
	v_mul_f32_e32 v24, 0xbfb8aa3b, v24
	v_fma_f32 v40, -v30, v31, 1.0
	v_fmac_f32_e32 v31, v40, v31
	v_div_scale_f32 v40, vcc, 1.0, v23, 1.0
	v_mul_f32_e32 v41, v40, v31
	v_fma_f32 v42, -v30, v41, v40
	v_fmac_f32_e32 v41, v42, v31
	v_fma_f32 v30, -v30, v41, v40
	v_div_fmas_f32 v30, v30, v31, v41
	v_div_fixup_f32 v23, v30, v23, 1.0
	v_div_scale_f32 v30, s[2:3], v22, v22, 1.0
	v_rcp_f32_e32 v31, v30
	v_mul_f32_e32 v25, 0xbfb8aa3b, v25
	v_exp_f32_e32 v24, v24
	v_exp_f32_e32 v25, v25
	v_fma_f32 v40, -v30, v31, 1.0
	v_fmac_f32_e32 v31, v40, v31
	v_div_scale_f32 v40, vcc, 1.0, v22, 1.0
	v_mul_f32_e32 v41, v40, v31
	v_fma_f32 v42, -v30, v41, v40
	v_fmac_f32_e32 v41, v42, v31
	v_fma_f32 v30, -v30, v41, v40
	v_div_fmas_f32 v30, v30, v31, v41
	v_pk_add_f32 v[18:19], v[18:19], v[62:63]
	v_div_fixup_f32 v22, v30, v22, 1.0
	v_pk_add_f32 v[24:25], v[24:25], 1.0 op_sel_hi:[1,0]
	v_pk_mul_f32 v[18:19], v[18:19], v[22:23]
	v_div_scale_f32 v23, s[2:3], v25, v25, 1.0
	v_rcp_f32_e32 v30, v23
	v_pk_add_f32 v[20:21], v[20:21], v[64:65]
	v_pk_mul_f32 v[26:27], v[26:27], v[26:27]
	v_cvt_pk_f16_f32 v22, v18, v19
	v_fma_f32 v31, -v23, v30, 1.0
	v_fmac_f32_e32 v30, v31, v30
	v_div_scale_f32 v31, vcc, 1.0, v25, 1.0
	v_mul_f32_e32 v40, v31, v30
	v_fma_f32 v41, -v23, v40, v31
	v_fmac_f32_e32 v40, v41, v30
	v_fma_f32 v23, -v23, v40, v31
	v_div_fmas_f32 v23, v23, v30, v40
	v_div_fixup_f32 v25, v23, v25, 1.0
	v_div_scale_f32 v23, s[2:3], v24, v24, 1.0
	v_rcp_f32_e32 v30, v23
	v_pk_mul_f32 v[18:19], v[18:19], v[18:19]
	v_pk_mul_f32 v[28:29], v[28:29], v[28:29]
	v_add_f32_e32 v18, v18, v19
	v_fma_f32 v31, -v23, v30, 1.0
	v_fmac_f32_e32 v30, v31, v30
	v_div_scale_f32 v31, vcc, 1.0, v24, 1.0
	v_mul_f32_e32 v40, v31, v30
	v_fma_f32 v41, -v23, v40, v31
	v_fmac_f32_e32 v40, v41, v30
	v_fma_f32 v23, -v23, v40, v31
	v_div_fmas_f32 v23, v23, v30, v40
	v_div_fixup_f32 v24, v23, v24, 1.0
	v_pk_mul_f32 v[20:21], v[20:21], v[24:25]
	v_add_f32_e32 v19, v26, v27
	v_cvt_pk_f16_f32 v23, v20, v21
	v_pk_mul_f32 v[20:21], v[20:21], v[20:21]
	v_add_f32_e32 v19, v28, v19
	v_add_f32_e32 v18, v20, v18
	v_add_f32_e32 v18, v21, v18
	v_add_f32_e32 v19, v29, v19
	v_add_f32_e32 v18, v19, v18
	v_mov_b32_e32 v19, v18
	s_nop 1
	v_permlane16_swap_b32_e32 v19, v18
	global_store_dwordx2 v[32:33], v[22:23], off offset:128
	s_waitcnt lgkmcnt(0)
	v_add_f32_e32 v18, v18, v19
	ds_bpermute_b32 v19, v173, v18
	s_and_saveexec_b64 s[24:25], s[6:7]
	s_cbranch_execz .LBB0_2299
	s_waitcnt lgkmcnt(0)
	v_add_f32_e32 v20, v18, v19
	v_lshlrev_b64 v[18:19], 6, v[38:39]
	v_lshl_add_u64 v[18:19], s[10:11], 0, v[18:19]
	v_lshl_add_u64 v[18:19], s[22:23], 2, v[18:19]
	s_lshl_b32 s92, s45, 2
	v_lshl_add_u64 v[18:19], v[18:19], 0, s[92:93]
	global_store_dword v[18:19], v20, off
; __device__ __forceinline__ float xor16(float v) { return __int_as_float(__builtin_amdgcn_ds_swizzle(__float_as_int(v), 0x401F)); }
; __device__ __forceinline__ float sigmoidf(float x) { return 1.f / (1.f + __expf(-x)); }
;   __device__ __forceinline__ void operator()(const f32x4 (&acc)[2][2][4][2], const g8::Unit& u, int ui, int wr, int wc, int fr, int fq) const {
;     ...
;       for (int m = 0; m < 4; ++m) {
;         const size_t row = (size_t)u.pm * 256 + 128 * ai + 64 * wr + 16 * m + fr;
;         float ss = 0.f;
; #pragma unroll
;         for (int bj = 0; bj < 2; ++bj) {
;           const f32x4 a = acc[ai][bj][m][0], b = acc[ai][bj][m][1];
;           float o0 = (a[0] + ba[bj].x) * sigmoidf(b[0] + bb[bj].x);
;           float o1 = (a[1] + ba[bj].y) * sigmoidf(b[1] + bb[bj].y);
;           float o2 = (a[2] + ba[bj].z) * sigmoidf(b[2] + bb[bj].z);
;           float o3 = (a[3] + ba[bj].w) * sigmoidf(b[3] + bb[bj].w);
;           *(h16x4*)(OB + row * 1024 + ocb + 64 * bj) = pack4(o0, o1, o2, o3);
;           ss += o0 * o0 + o1 * o1 + o2 * o2 + o3 * o3;
;         }
;         ss += xor16(ss);
;         ss += __shfl_xor(ss, 32);
;         if (fq == 0) ssqb[row * 16 + u.pn * 4 + wc] = ss;
;       }
.LBB0_2299:
	s_or_b64 exec, exec, s[24:25]
	v_add_f32_e32 v14, v14, v46
	v_add_f32_e32 v15, v15, v47
	v_mul_f32_e32 v14, 0xbfb8aa3b, v14
	v_mul_f32_e32 v15, 0xbfb8aa3b, v15
	v_exp_f32_e32 v14, v14
	v_exp_f32_e32 v15, v15
	s_mov_b64 s[2:3], 0xb0
	s_waitcnt lgkmcnt(0)
	v_lshl_add_u64 v[18:19], v[162:163], 0, s[2:3]
	v_add_f32_e32 v16, v16, v48
	v_pk_add_f32 v[14:15], v[14:15], 1.0 op_sel_hi:[1,0]
	v_add_f32_e32 v17, v17, v49
	v_div_scale_f32 v22, s[2:3], v15, v15, 1.0
	v_rcp_f32_e32 v23, v22
	v_mul_f32_e32 v16, 0xbfb8aa3b, v16
	v_mul_f32_e32 v17, 0xbfb8aa3b, v17
	v_exp_f32_e32 v16, v16
	v_fma_f32 v24, -v22, v23, 1.0
	v_fmac_f32_e32 v23, v24, v23
	v_div_scale_f32 v24, vcc, 1.0, v15, 1.0
	v_mul_f32_e32 v25, v24, v23
	v_fma_f32 v26, -v22, v25, v24
	v_fmac_f32_e32 v25, v26, v23
	v_fma_f32 v22, -v22, v25, v24
	v_div_fmas_f32 v22, v22, v23, v25
	v_div_fixup_f32 v15, v22, v15, 1.0
	v_div_scale_f32 v22, s[2:3], v14, v14, 1.0
	v_rcp_f32_e32 v23, v22
	v_exp_f32_e32 v17, v17
	v_pk_add_f32 v[10:11], v[10:11], v[50:51]
	v_add_f32_e32 v6, v6, v34
	v_fma_f32 v24, -v22, v23, 1.0
	v_fmac_f32_e32 v23, v24, v23
	v_div_scale_f32 v24, vcc, 1.0, v14, 1.0
	v_mul_f32_e32 v25, v24, v23
	v_fma_f32 v26, -v22, v25, v24
	v_fmac_f32_e32 v25, v26, v23
	v_fma_f32 v22, -v22, v25, v24
	v_div_fmas_f32 v22, v22, v23, v25
	v_div_fixup_f32 v14, v22, v14, 1.0
	v_pk_add_f32 v[16:17], v[16:17], 1.0 op_sel_hi:[1,0]
	v_pk_mul_f32 v[10:11], v[10:11], v[14:15]
	v_div_scale_f32 v15, s[2:3], v17, v17, 1.0
	v_rcp_f32_e32 v22, v15
	v_add_f32_e32 v7, v7, v35
	v_mul_f32_e32 v6, 0xbfb8aa3b, v6
	v_mul_f32_e32 v7, 0xbfb8aa3b, v7
	v_fma_f32 v23, -v15, v22, 1.0
	v_fmac_f32_e32 v22, v23, v22
	v_div_scale_f32 v23, vcc, 1.0, v17, 1.0
	v_mul_f32_e32 v24, v23, v22
	v_fma_f32 v25, -v15, v24, v23
	v_fmac_f32_e32 v24, v25, v22
	v_fma_f32 v15, -v15, v24, v23
	v_div_fmas_f32 v15, v15, v22, v24
	v_div_fixup_f32 v17, v15, v17, 1.0
	v_div_scale_f32 v15, s[2:3], v16, v16, 1.0
	v_rcp_f32_e32 v22, v15
	v_exp_f32_e32 v6, v6
	v_exp_f32_e32 v7, v7
	v_lshlrev_b64 v[20:21], 11, v[18:19]
	v_fma_f32 v23, -v15, v22, 1.0
	v_fmac_f32_e32 v22, v23, v22
	v_div_scale_f32 v23, vcc, 1.0, v16, 1.0
	v_mul_f32_e32 v24, v23, v22
	v_fma_f32 v25, -v15, v24, v23
	v_fmac_f32_e32 v24, v25, v22
	v_fma_f32 v15, -v15, v24, v23
	v_div_fmas_f32 v15, v15, v22, v24
	v_pk_add_f32 v[12:13], v[12:13], v[52:53]
	v_div_fixup_f32 v16, v15, v16, 1.0
	v_pk_mul_f32 v[12:13], v[12:13], v[16:17]
	v_lshl_add_u64 v[16:17], s[0:1], 0, v[20:21]
	v_cvt_pk_f16_f32 v14, v10, v11
	v_cvt_pk_f16_f32 v15, v12, v13
	v_lshl_add_u64 v[16:17], v[160:161], 1, v[16:17]
	v_pk_add_f32 v[6:7], v[6:7], 1.0 op_sel_hi:[1,0]
	global_store_dwordx2 v[16:17], v[14:15], off
	v_div_scale_f32 v14, s[2:3], v7, v7, 1.0
	v_rcp_f32_e32 v15, v14
	v_add_f32_e32 v8, v8, v36
	v_add_f32_e32 v9, v9, v37
	v_mul_f32_e32 v8, 0xbfb8aa3b, v8
	v_fma_f32 v20, -v14, v15, 1.0
	v_fmac_f32_e32 v15, v20, v15
	v_div_scale_f32 v20, vcc, 1.0, v7, 1.0
	v_mul_f32_e32 v21, v20, v15
	v_fma_f32 v22, -v14, v21, v20
	v_fmac_f32_e32 v21, v22, v15
	v_fma_f32 v14, -v14, v21, v20
	v_div_fmas_f32 v14, v14, v15, v21
	v_div_fixup_f32 v7, v14, v7, 1.0
	v_div_scale_f32 v14, s[2:3], v6, v6, 1.0
	v_rcp_f32_e32 v15, v14
	v_mul_f32_e32 v9, 0xbfb8aa3b, v9
	v_exp_f32_e32 v8, v8
	v_exp_f32_e32 v9, v9
	v_fma_f32 v20, -v14, v15, 1.0
	v_fmac_f32_e32 v15, v20, v15
	v_div_scale_f32 v20, vcc, 1.0, v6, 1.0
	v_mul_f32_e32 v21, v20, v15
	v_fma_f32 v22, -v14, v21, v20
	v_fmac_f32_e32 v21, v22, v15
	v_fma_f32 v14, -v14, v21, v20
	v_div_fmas_f32 v14, v14, v15, v21
	v_pk_add_f32 v[2:3], v[2:3], v[62:63]
	v_div_fixup_f32 v6, v14, v6, 1.0
	v_pk_add_f32 v[8:9], v[8:9], 1.0 op_sel_hi:[1,0]
	v_pk_mul_f32 v[2:3], v[2:3], v[6:7]
	v_div_scale_f32 v7, s[2:3], v9, v9, 1.0
	v_rcp_f32_e32 v14, v7
	v_pk_add_f32 v[4:5], v[4:5], v[64:65]
	v_pk_mul_f32 v[10:11], v[10:11], v[10:11]
	v_cvt_pk_f16_f32 v6, v2, v3
	v_fma_f32 v15, -v7, v14, 1.0
	v_fmac_f32_e32 v14, v15, v14
	v_div_scale_f32 v15, vcc, 1.0, v9, 1.0
	v_mul_f32_e32 v20, v15, v14
	v_fma_f32 v21, -v7, v20, v15
	v_fmac_f32_e32 v20, v21, v14
	v_fma_f32 v7, -v7, v20, v15
	v_div_fmas_f32 v7, v7, v14, v20
	v_div_fixup_f32 v9, v7, v9, 1.0
	v_div_scale_f32 v7, s[2:3], v8, v8, 1.0
	v_rcp_f32_e32 v14, v7
	v_pk_mul_f32 v[2:3], v[2:3], v[2:3]
	v_pk_mul_f32 v[12:13], v[12:13], v[12:13]
	v_add_f32_e32 v2, v2, v3
	v_fma_f32 v15, -v7, v14, 1.0
	v_fmac_f32_e32 v14, v15, v14
	v_div_scale_f32 v15, vcc, 1.0, v8, 1.0
	v_mul_f32_e32 v20, v15, v14
	v_fma_f32 v21, -v7, v20, v15
	v_fmac_f32_e32 v20, v21, v14
	v_fma_f32 v7, -v7, v20, v15
	v_div_fmas_f32 v7, v7, v14, v20
	v_div_fixup_f32 v8, v7, v8, 1.0
	v_pk_mul_f32 v[4:5], v[4:5], v[8:9]
	v_add_f32_e32 v3, v10, v11
	v_cvt_pk_f16_f32 v7, v4, v5
	v_pk_mul_f32 v[4:5], v[4:5], v[4:5]
	v_add_f32_e32 v3, v12, v3
	v_add_f32_e32 v2, v4, v2
	v_add_f32_e32 v2, v5, v2
	v_add_f32_e32 v3, v13, v3
	v_add_f32_e32 v2, v3, v2
	v_mov_b32_e32 v3, v2
	s_nop 1
	v_permlane16_swap_b32_e32 v3, v2
	global_store_dwordx2 v[16:17], v[6:7], off offset:128
	s_waitcnt lgkmcnt(0)
	v_add_f32_e32 v2, v2, v3
	ds_bpermute_b32 v3, v173, v2
	s_and_saveexec_b64 s[24:25], s[6:7]
	s_cbranch_execz .LBB0_2276
	s_waitcnt lgkmcnt(0)
	v_add_f32_e32 v4, v2, v3
	v_lshlrev_b64 v[2:3], 6, v[18:19]
	v_lshl_add_u64 v[2:3], s[10:11], 0, v[2:3]
	v_lshl_add_u64 v[2:3], s[22:23], 2, v[2:3]
	s_lshl_b32 s92, s45, 2
	v_lshl_add_u64 v[2:3], v[2:3], 0, s[92:93]
	global_store_dword v[2:3], v4, off
	s_branch .LBB0_2276

; __device__ __forceinline__ float xor16(float v) { return __int_as_float(__builtin_amdgcn_ds_swizzle(__float_as_int(v), 0x401F)); }
;   __device__ __forceinline__ void operator()(const f32x4 (&acc)[2][2][4][2], const g8::Unit& u, int ui, int wr, int wc, int fr, int fq) const {
; #pragma unroll
;     for (int ai = 0; ai < 2; ++ai)
; #pragma unroll
;       for (int m = 0; m < 4; ++m) {
;         const size_t row = (size_t)u.pm * 256 + 128 * ai + 64 * wr + 16 * m + fr;
;         const size_t base = row * DM + 256 * u.pn + 32 * wc + 8 * fq;
;         float ss = 0.f;
; #pragma unroll
;         for (int bj = 0; bj < 2; ++bj) {
;           const size_t idx = base + 128 * bj;
;           const h16x8 xv = *(const h16x8*)(xb + idx);
;           f32x4 x0 = acc[ai][bj][m][0], x1 = acc[ai][bj][m][1];
; #pragma unroll
;           for (int j = 0; j < 4; ++j) { x0[j] += (float)xv[j]; x1[j] += (float)xv[4 + j]; ss += x0[j] * x0[j] + x1[j] * x1[j]; }
;           if (final_out) {
;             __builtin_nontemporal_store(x0, (f32x4*)(xo + idx));
;             __builtin_nontemporal_store(x1, (f32x4*)(xo + idx + 4));
;           } else {
;             *(h16x8*)(xb + idx) = pack8(x0, x1);
;           }
;         }
;         ss += xor16(ss);
;         ss += __shfl_xor(ss, 32);
;         if (fq == 0) ssq[row * 16 + u.pn * 4 + wc] = ss;
;       }
.LBB0_2381:
	s_ashr_i32 s23, s22, 31
	s_lshl_b64 s[20:21], s[22:23], 8
	v_and_b32_e32 v156, 64, v199
	v_lshl_add_u64 v[2:3], s[20:21], 0, v[136:137]
	s_lshl_b32 s3, s2, 8
	v_xor_b32_e32 v0, 32, v199
	v_add_u32_e32 v156, 64, v156
	s_ashr_i32 s13, s3, 31
	v_cmp_lt_i32_e32 vcc, v0, v156
	v_lshlrev_b64 v[156:157], 11, v[2:3]
	v_mov_b32_e32 v155, s13
	v_or_b32_e32 v154, s3, v138
	v_lshl_add_u64 v[156:157], s[0:1], 0, v[156:157]
	v_lshl_add_u64 v[156:157], v[154:155], 1, v[156:157]
	v_cndmask_b32_e32 v0, v199, v0, vcc
	v_lshlrev_b32_e32 v0, 2, v0
	s_lshl_b32 s20, s2, 2
	s_ashr_i32 s21, s20, 31
	global_load_dwordx4 v[166:169], v[156:157], off
	global_load_dwordx4 v[170:173], v[156:157], off offset:256
	s_mov_b32 s3, 0
	s_mov_b32 s2, 0x8000
	v_lshl_add_u64 v[242:243], v[156:157], 0, s[2:3]
	global_load_dwordx4 v[174:177], v[242:243], off
	global_load_dwordx4 v[178:181], v[242:243], off offset:256
	s_mov_b32 s2, 0x10000
	v_lshl_add_u64 v[244:245], v[156:157], 0, s[2:3]
	global_load_dwordx4 v[182:185], v[244:245], off
	global_load_dwordx4 v[186:189], v[244:245], off offset:256
	s_mov_b32 s2, 0x18000
	v_lshl_add_u64 v[242:243], v[156:157], 0, s[2:3]
	global_load_dwordx4 v[202:205], v[242:243], off
	global_load_dwordx4 v[206:209], v[242:243], off offset:256
	s_mov_b32 s2, 0x40000
	v_lshl_add_u64 v[244:245], v[156:157], 0, s[2:3]
	global_load_dwordx4 v[210:213], v[244:245], off
	global_load_dwordx4 v[214:217], v[244:245], off offset:256
	s_mov_b32 s2, 0x48000
	v_lshl_add_u64 v[242:243], v[156:157], 0, s[2:3]
	global_load_dwordx4 v[218:221], v[242:243], off
	global_load_dwordx4 v[222:225], v[242:243], off offset:256
	s_mov_b32 s2, 0x50000
	v_lshl_add_u64 v[244:245], v[156:157], 0, s[2:3]
	global_load_dwordx4 v[226:229], v[244:245], off
	global_load_dwordx4 v[230:233], v[244:245], off offset:256
	s_mov_b32 s2, 0x58000
	v_lshl_add_u64 v[242:243], v[156:157], 0, s[2:3]
	global_load_dwordx4 v[234:237], v[242:243], off
	global_load_dwordx4 v[238:241], v[242:243], off offset:256
	s_waitcnt vmcnt(15)
	v_cvt_f32_f16_e32 v164, v166
	v_cvt_f32_f16_sdwa v165, v166 dst_sel:DWORD dst_unused:UNUSED_PAD src0_sel:WORD_1
	v_cvt_f32_f16_e32 v160, v167
	v_cvt_f32_f16_sdwa v161, v167 dst_sel:DWORD dst_unused:UNUSED_PAD src0_sel:WORD_1
	v_pk_add_f32 v[164:165], v[128:129], v[164:165]
	s_nop 0
	v_cvt_pk_f16_f32 v128, v164, v165
	v_pk_add_f32 v[160:161], v[130:131], v[160:161]
	v_cvt_f32_f16_e32 v130, v168
	v_cvt_f32_f16_sdwa v131, v168 dst_sel:DWORD dst_unused:UNUSED_PAD src0_sel:WORD_1
	v_cvt_f32_f16_e32 v162, v169
	v_cvt_f32_f16_sdwa v163, v169 dst_sel:DWORD dst_unused:UNUSED_PAD src0_sel:WORD_1
	v_cvt_pk_f16_f32 v129, v160, v161
	v_pk_add_f32 v[130:131], v[124:125], v[130:131]
	v_pk_add_f32 v[162:163], v[126:127], v[162:163]
	v_pk_mul_f32 v[124:125], v[130:131], v[130:131]
	v_cvt_pk_f16_f32 v130, v130, v131
	v_cvt_pk_f16_f32 v131, v162, v163
	global_store_dwordx4 v[156:157], v[128:131], off
	s_nop 0
	v_pk_mul_f32 v[126:127], v[162:163], v[162:163]
	v_pk_fma_f32 v[124:125], v[164:165], v[164:165], v[124:125]
	v_pk_fma_f32 v[126:127], v[160:161], v[160:161], v[126:127]
	s_waitcnt vmcnt(15)
	v_cvt_f32_f16_e32 v160, v170
	v_cvt_f32_f16_sdwa v161, v170 dst_sel:DWORD dst_unused:UNUSED_PAD src0_sel:WORD_1
	v_cvt_f32_f16_e32 v128, v171
	v_cvt_f32_f16_sdwa v129, v171 dst_sel:DWORD dst_unused:UNUSED_PAD src0_sel:WORD_1
	v_pk_add_f32 v[160:161], v[120:121], v[160:161]
	s_nop 0
	v_cvt_pk_f16_f32 v120, v160, v161
	v_pk_add_f32 v[128:129], v[122:123], v[128:129]
	v_cvt_f32_f16_e32 v122, v172
	v_cvt_f32_f16_sdwa v123, v172 dst_sel:DWORD dst_unused:UNUSED_PAD src0_sel:WORD_1
	v_cvt_pk_f16_f32 v121, v128, v129
	v_pk_add_f32 v[116:117], v[116:117], v[122:123]
	s_nop 0
	v_pk_mul_f32 v[122:123], v[116:117], v[116:117]
	s_nop 0
	v_pk_fma_f32 v[160:161], v[160:161], v[160:161], v[122:123]
	v_cvt_pk_f16_f32 v122, v116, v117
	v_cvt_f32_f16_e32 v116, v173
	v_cvt_f32_f16_sdwa v117, v173 dst_sel:DWORD dst_unused:UNUSED_PAD src0_sel:WORD_1
	v_add_f32_e32 v123, v124, v125
	v_add_f32_e32 v123, v126, v123
	v_add_f32_e32 v123, v127, v123
	v_pk_add_f32 v[116:117], v[118:119], v[116:117]
	v_add_f32_e32 v123, v160, v123
	v_pk_mul_f32 v[118:119], v[116:117], v[116:117]
	v_add_f32_e32 v123, v161, v123
	v_pk_fma_f32 v[118:119], v[128:129], v[128:129], v[118:119]
	s_nop 0
	v_add_f32_e32 v118, v118, v123
	v_add_f32_e32 v118, v119, v118
	v_cvt_pk_f16_f32 v123, v116, v117
	v_mov_b32_e32 v116, v118
	s_nop 1
	v_permlane16_swap_b32_e32 v116, v118
	global_store_dwordx4 v[156:157], v[120:123], off offset:256
	s_waitcnt lgkmcnt(0)
	v_add_f32_e32 v116, v118, v116
	ds_bpermute_b32 v117, v0, v116
	s_and_saveexec_b64 s[22:23], s[6:7]
	s_cbranch_execz .LBB0_2383
	s_waitcnt lgkmcnt(0)
	v_add_f32_e32 v118, v116, v117
	v_lshlrev_b64 v[116:117], 6, v[2:3]
	v_lshl_add_u64 v[116:117], s[10:11], 0, v[116:117]
	v_lshl_add_u64 v[116:117], s[20:21], 2, v[116:117]
	s_lshl_b32 s92, s45, 2
	v_lshl_add_u64 v[116:117], v[116:117], 0, s[92:93]
	global_store_dword v[116:117], v118, off
; __device__ __forceinline__ float xor16(float v) { return __int_as_float(__builtin_amdgcn_ds_swizzle(__float_as_int(v), 0x401F)); }
;   __device__ __forceinline__ void operator()(const f32x4 (&acc)[2][2][4][2], const g8::Unit& u, int ui, int wr, int wc, int fr, int fq) const {
; #pragma unroll
;     for (int ai = 0; ai < 2; ++ai)
; #pragma unroll
;       for (int m = 0; m < 4; ++m) {
;         const size_t row = (size_t)u.pm * 256 + 128 * ai + 64 * wr + 16 * m + fr;
;         const size_t base = row * DM + 256 * u.pn + 32 * wc + 8 * fq;
;         float ss = 0.f;
; #pragma unroll
;         for (int bj = 0; bj < 2; ++bj) {
;           const size_t idx = base + 128 * bj;
;           const h16x8 xv = *(const h16x8*)(xb + idx);
;           f32x4 x0 = acc[ai][bj][m][0], x1 = acc[ai][bj][m][1];
; #pragma unroll
;           for (int j = 0; j < 4; ++j) { x0[j] += (float)xv[j]; x1[j] += (float)xv[4 + j]; ss += x0[j] * x0[j] + x1[j] * x1[j]; }
;           if (final_out) {
;             __builtin_nontemporal_store(x0, (f32x4*)(xo + idx));
;             __builtin_nontemporal_store(x1, (f32x4*)(xo + idx + 4));
;           } else {
;             *(h16x8*)(xb + idx) = pack8(x0, x1);
;           }
;         }
;         ss += xor16(ss);
;         ss += __shfl_xor(ss, 32);
;         if (fq == 0) ssq[row * 16 + u.pn * 4 + wc] = ss;
;       }
.LBB0_2383:
	s_or_b64 exec, exec, s[22:23]
	v_or_b32_e32 v116, 16, v2
	s_waitcnt lgkmcnt(0)
	v_mov_b32_e32 v117, v3
	v_lshlrev_b64 v[118:119], 11, v[116:117]
	v_lshl_add_u64 v[118:119], s[0:1], 0, v[118:119]
	v_lshl_add_u64 v[118:119], v[154:155], 1, v[118:119]
	s_nop 0
	s_waitcnt vmcnt(15)
	v_cvt_f32_f16_e32 v124, v174
	v_cvt_f32_f16_sdwa v125, v174 dst_sel:DWORD dst_unused:UNUSED_PAD src0_sel:WORD_1
	v_cvt_f32_f16_e32 v120, v175
	v_cvt_f32_f16_sdwa v121, v175 dst_sel:DWORD dst_unused:UNUSED_PAD src0_sel:WORD_1
	v_pk_add_f32 v[124:125], v[112:113], v[124:125]
	s_nop 0
	v_cvt_pk_f16_f32 v112, v124, v125
	v_pk_add_f32 v[120:121], v[114:115], v[120:121]
	v_cvt_f32_f16_e32 v114, v176
	v_cvt_f32_f16_sdwa v115, v176 dst_sel:DWORD dst_unused:UNUSED_PAD src0_sel:WORD_1
	v_cvt_f32_f16_e32 v122, v177
	v_cvt_f32_f16_sdwa v123, v177 dst_sel:DWORD dst_unused:UNUSED_PAD src0_sel:WORD_1
	v_cvt_pk_f16_f32 v113, v120, v121
	v_pk_add_f32 v[114:115], v[108:109], v[114:115]
	v_pk_add_f32 v[122:123], v[110:111], v[122:123]
	v_pk_mul_f32 v[108:109], v[114:115], v[114:115]
	v_cvt_pk_f16_f32 v114, v114, v115
	v_cvt_pk_f16_f32 v115, v122, v123
	global_store_dwordx4 v[118:119], v[112:115], off
	s_nop 0
	v_pk_mul_f32 v[110:111], v[122:123], v[122:123]
	v_pk_fma_f32 v[108:109], v[124:125], v[124:125], v[108:109]
	v_pk_fma_f32 v[110:111], v[120:121], v[120:121], v[110:111]
	s_waitcnt vmcnt(15)
	v_cvt_f32_f16_e32 v120, v178
	v_cvt_f32_f16_sdwa v121, v178 dst_sel:DWORD dst_unused:UNUSED_PAD src0_sel:WORD_1
	v_cvt_f32_f16_e32 v112, v179
	v_cvt_f32_f16_sdwa v113, v179 dst_sel:DWORD dst_unused:UNUSED_PAD src0_sel:WORD_1
	v_pk_add_f32 v[120:121], v[104:105], v[120:121]
	s_nop 0
	v_cvt_pk_f16_f32 v104, v120, v121
	v_pk_add_f32 v[112:113], v[106:107], v[112:113]
	v_cvt_f32_f16_e32 v106, v180
	v_cvt_f32_f16_sdwa v107, v180 dst_sel:DWORD dst_unused:UNUSED_PAD src0_sel:WORD_1
	v_cvt_pk_f16_f32 v105, v112, v113
	v_pk_add_f32 v[100:101], v[100:101], v[106:107]
	s_nop 0
	v_pk_mul_f32 v[106:107], v[100:101], v[100:101]
	s_nop 0
	v_pk_fma_f32 v[120:121], v[120:121], v[120:121], v[106:107]
	v_cvt_pk_f16_f32 v106, v100, v101
	v_cvt_f32_f16_e32 v100, v181
	v_cvt_f32_f16_sdwa v101, v181 dst_sel:DWORD dst_unused:UNUSED_PAD src0_sel:WORD_1
	v_add_f32_e32 v107, v108, v109
	v_add_f32_e32 v107, v110, v107
	v_add_f32_e32 v107, v111, v107
	v_pk_add_f32 v[100:101], v[102:103], v[100:101]
	v_add_f32_e32 v107, v120, v107
	v_pk_mul_f32 v[102:103], v[100:101], v[100:101]
	v_add_f32_e32 v107, v121, v107
	v_pk_fma_f32 v[102:103], v[112:113], v[112:113], v[102:103]
	s_nop 0
	v_add_f32_e32 v102, v102, v107
	v_add_f32_e32 v102, v103, v102
	v_cvt_pk_f16_f32 v107, v100, v101
	v_mov_b32_e32 v100, v102
	s_nop 1
	v_permlane16_swap_b32_e32 v100, v102
	global_store_dwordx4 v[118:119], v[104:107], off offset:256
	s_waitcnt lgkmcnt(0)
	v_add_f32_e32 v100, v102, v100
	ds_bpermute_b32 v101, v0, v100
	s_and_saveexec_b64 s[22:23], s[6:7]
	s_cbranch_execz .LBB0_2385
	s_waitcnt lgkmcnt(0)
	v_add_f32_e32 v102, v100, v101
	v_lshlrev_b64 v[100:101], 6, v[116:117]
	v_lshl_add_u64 v[100:101], s[10:11], 0, v[100:101]
	v_lshl_add_u64 v[100:101], s[20:21], 2, v[100:101]
	s_lshl_b32 s92, s45, 2
	v_lshl_add_u64 v[100:101], v[100:101], 0, s[92:93]
	global_store_dword v[100:101], v102, off
.LBB0_2385:
	s_or_b64 exec, exec, s[22:23]
	v_or_b32_e32 v100, 32, v2
	s_waitcnt lgkmcnt(0)
	v_mov_b32_e32 v101, v3
	v_lshlrev_b64 v[102:103], 11, v[100:101]
	v_lshl_add_u64 v[102:103], s[0:1], 0, v[102:103]
	v_lshl_add_u64 v[102:103], v[154:155], 1, v[102:103]
	s_nop 0
	s_waitcnt vmcnt(15)
	v_cvt_f32_f16_e32 v108, v182
	v_cvt_f32_f16_sdwa v109, v182 dst_sel:DWORD dst_unused:UNUSED_PAD src0_sel:WORD_1
	v_cvt_f32_f16_e32 v104, v183
	v_cvt_f32_f16_sdwa v105, v183 dst_sel:DWORD dst_unused:UNUSED_PAD src0_sel:WORD_1
	v_pk_add_f32 v[108:109], v[96:97], v[108:109]
	s_nop 0
	v_cvt_pk_f16_f32 v96, v108, v109
	v_pk_add_f32 v[104:105], v[98:99], v[104:105]
	v_cvt_f32_f16_e32 v98, v184
	v_cvt_f32_f16_sdwa v99, v184 dst_sel:DWORD dst_unused:UNUSED_PAD src0_sel:WORD_1
	v_cvt_f32_f16_e32 v106, v185
	v_cvt_f32_f16_sdwa v107, v185 dst_sel:DWORD dst_unused:UNUSED_PAD src0_sel:WORD_1
	v_cvt_pk_f16_f32 v97, v104, v105
	v_pk_add_f32 v[98:99], v[92:93], v[98:99]
	v_pk_add_f32 v[106:107], v[94:95], v[106:107]
	v_pk_mul_f32 v[92:93], v[98:99], v[98:99]
	v_cvt_pk_f16_f32 v98, v98, v99
	v_cvt_pk_f16_f32 v99, v106, v107
	global_store_dwordx4 v[102:103], v[96:99], off
	s_nop 0
	v_pk_mul_f32 v[94:95], v[106:107], v[106:107]
	v_pk_fma_f32 v[92:93], v[108:109], v[108:109], v[92:93]
	v_pk_fma_f32 v[94:95], v[104:105], v[104:105], v[94:95]
	s_waitcnt vmcnt(15)
	v_cvt_f32_f16_e32 v104, v186
	v_cvt_f32_f16_sdwa v105, v186 dst_sel:DWORD dst_unused:UNUSED_PAD src0_sel:WORD_1
	v_cvt_f32_f16_e32 v96, v187
	v_cvt_f32_f16_sdwa v97, v187 dst_sel:DWORD dst_unused:UNUSED_PAD src0_sel:WORD_1
	v_pk_add_f32 v[104:105], v[88:89], v[104:105]
	s_nop 0
	v_cvt_pk_f16_f32 v88, v104, v105
	v_pk_add_f32 v[96:97], v[90:91], v[96:97]
	v_cvt_f32_f16_e32 v90, v188
	v_cvt_f32_f16_sdwa v91, v188 dst_sel:DWORD dst_unused:UNUSED_PAD src0_sel:WORD_1
	v_cvt_pk_f16_f32 v89, v96, v97
	v_pk_add_f32 v[84:85], v[84:85], v[90:91]
	s_nop 0
	v_pk_mul_f32 v[90:91], v[84:85], v[84:85]
	s_nop 0
	v_pk_fma_f32 v[104:105], v[104:105], v[104:105], v[90:91]
	v_cvt_pk_f16_f32 v90, v84, v85
	v_cvt_f32_f16_e32 v84, v189
	v_cvt_f32_f16_sdwa v85, v189 dst_sel:DWORD dst_unused:UNUSED_PAD src0_sel:WORD_1
	v_add_f32_e32 v91, v92, v93
	v_add_f32_e32 v91, v94, v91
	v_add_f32_e32 v91, v95, v91
	v_pk_add_f32 v[84:85], v[86:87], v[84:85]
	v_add_f32_e32 v91, v104, v91
	v_pk_mul_f32 v[86:87], v[84:85], v[84:85]
	v_add_f32_e32 v91, v105, v91
	v_pk_fma_f32 v[86:87], v[96:97], v[96:97], v[86:87]
	s_nop 0
	v_add_f32_e32 v86, v86, v91
	v_add_f32_e32 v86, v87, v86
	v_cvt_pk_f16_f32 v91, v84, v85
	v_mov_b32_e32 v84, v86
	s_nop 1
	v_permlane16_swap_b32_e32 v84, v86
	global_store_dwordx4 v[102:103], v[88:91], off offset:256
	s_waitcnt lgkmcnt(0)
	v_add_f32_e32 v84, v86, v84
	ds_bpermute_b32 v85, v0, v84
	s_and_saveexec_b64 s[22:23], s[6:7]
	s_cbranch_execz .LBB0_2387
	s_waitcnt lgkmcnt(0)
	v_add_f32_e32 v86, v84, v85
	v_lshlrev_b64 v[84:85], 6, v[100:101]
	v_lshl_add_u64 v[84:85], s[10:11], 0, v[84:85]
	v_lshl_add_u64 v[84:85], s[20:21], 2, v[84:85]
	s_lshl_b32 s92, s45, 2
	v_lshl_add_u64 v[84:85], v[84:85], 0, s[92:93]
	global_store_dword v[84:85], v86, off
; __device__ __forceinline__ float xor16(float v) { return __int_as_float(__builtin_amdgcn_ds_swizzle(__float_as_int(v), 0x401F)); }
;   __device__ __forceinline__ void operator()(const f32x4 (&acc)[2][2][4][2], const g8::Unit& u, int ui, int wr, int wc, int fr, int fq) const {
; #pragma unroll
;     for (int ai = 0; ai < 2; ++ai)
; #pragma unroll
;       for (int m = 0; m < 4; ++m) {
;         const size_t row = (size_t)u.pm * 256 + 128 * ai + 64 * wr + 16 * m + fr;
;         const size_t base = row * DM + 256 * u.pn + 32 * wc + 8 * fq;
;         float ss = 0.f;
; #pragma unroll
;         for (int bj = 0; bj < 2; ++bj) {
;           const size_t idx = base + 128 * bj;
;           const h16x8 xv = *(const h16x8*)(xb + idx);
;           f32x4 x0 = acc[ai][bj][m][0], x1 = acc[ai][bj][m][1];
; #pragma unroll
;           for (int j = 0; j < 4; ++j) { x0[j] += (float)xv[j]; x1[j] += (float)xv[4 + j]; ss += x0[j] * x0[j] + x1[j] * x1[j]; }
;           if (final_out) {
;             __builtin_nontemporal_store(x0, (f32x4*)(xo + idx));
;             __builtin_nontemporal_store(x1, (f32x4*)(xo + idx + 4));
;           } else {
;             *(h16x8*)(xb + idx) = pack8(x0, x1);
;           }
;         }
;         ss += xor16(ss);
;         ss += __shfl_xor(ss, 32);
;         if (fq == 0) ssq[row * 16 + u.pn * 4 + wc] = ss;
;       }
.LBB0_2387:
	s_or_b64 exec, exec, s[22:23]
	v_or_b32_e32 v84, 48, v2
	s_waitcnt lgkmcnt(0)
	v_mov_b32_e32 v85, v3
	v_lshlrev_b64 v[86:87], 11, v[84:85]
	v_lshl_add_u64 v[86:87], s[0:1], 0, v[86:87]
	v_lshl_add_u64 v[86:87], v[154:155], 1, v[86:87]
	s_nop 0
	s_waitcnt vmcnt(15)
	v_cvt_f32_f16_e32 v92, v202
	v_cvt_f32_f16_sdwa v93, v202 dst_sel:DWORD dst_unused:UNUSED_PAD src0_sel:WORD_1
	v_cvt_f32_f16_e32 v88, v203
	v_cvt_f32_f16_sdwa v89, v203 dst_sel:DWORD dst_unused:UNUSED_PAD src0_sel:WORD_1
	v_pk_add_f32 v[92:93], v[80:81], v[92:93]
	s_nop 0
	v_cvt_pk_f16_f32 v80, v92, v93
	v_pk_add_f32 v[88:89], v[82:83], v[88:89]
	v_cvt_f32_f16_e32 v82, v204
	v_cvt_f32_f16_sdwa v83, v204 dst_sel:DWORD dst_unused:UNUSED_PAD src0_sel:WORD_1
	v_cvt_f32_f16_e32 v90, v205
	v_cvt_f32_f16_sdwa v91, v205 dst_sel:DWORD dst_unused:UNUSED_PAD src0_sel:WORD_1
	v_cvt_pk_f16_f32 v81, v88, v89
	v_pk_add_f32 v[82:83], v[76:77], v[82:83]
	v_pk_add_f32 v[90:91], v[78:79], v[90:91]
	v_pk_mul_f32 v[76:77], v[82:83], v[82:83]
	v_cvt_pk_f16_f32 v82, v82, v83
	v_cvt_pk_f16_f32 v83, v90, v91
	global_store_dwordx4 v[86:87], v[80:83], off
	s_nop 0
	v_pk_mul_f32 v[78:79], v[90:91], v[90:91]
	v_pk_fma_f32 v[76:77], v[92:93], v[92:93], v[76:77]
	v_pk_fma_f32 v[78:79], v[88:89], v[88:89], v[78:79]
	s_waitcnt vmcnt(15)
	v_cvt_f32_f16_e32 v88, v206
	v_cvt_f32_f16_sdwa v89, v206 dst_sel:DWORD dst_unused:UNUSED_PAD src0_sel:WORD_1
	v_cvt_f32_f16_e32 v80, v207
	v_cvt_f32_f16_sdwa v81, v207 dst_sel:DWORD dst_unused:UNUSED_PAD src0_sel:WORD_1
	v_pk_add_f32 v[88:89], v[72:73], v[88:89]
	s_nop 0
	v_cvt_pk_f16_f32 v72, v88, v89
	v_pk_add_f32 v[80:81], v[74:75], v[80:81]
	v_cvt_f32_f16_e32 v74, v208
	v_cvt_f32_f16_sdwa v75, v208 dst_sel:DWORD dst_unused:UNUSED_PAD src0_sel:WORD_1
	v_cvt_pk_f16_f32 v73, v80, v81
	v_pk_add_f32 v[68:69], v[68:69], v[74:75]
	s_nop 0
	v_pk_mul_f32 v[74:75], v[68:69], v[68:69]
	s_nop 0
	v_pk_fma_f32 v[88:89], v[88:89], v[88:89], v[74:75]
	v_cvt_pk_f16_f32 v74, v68, v69
	v_cvt_f32_f16_e32 v68, v209
	v_cvt_f32_f16_sdwa v69, v209 dst_sel:DWORD dst_unused:UNUSED_PAD src0_sel:WORD_1
	v_add_f32_e32 v75, v76, v77
	v_add_f32_e32 v75, v78, v75
	v_add_f32_e32 v75, v79, v75
	v_pk_add_f32 v[68:69], v[70:71], v[68:69]
	v_add_f32_e32 v75, v88, v75
	v_pk_mul_f32 v[70:71], v[68:69], v[68:69]
	v_add_f32_e32 v75, v89, v75
	v_pk_fma_f32 v[70:71], v[80:81], v[80:81], v[70:71]
	s_nop 0
	v_add_f32_e32 v70, v70, v75
	v_add_f32_e32 v70, v71, v70
	v_cvt_pk_f16_f32 v75, v68, v69
	v_mov_b32_e32 v68, v70
	s_nop 1
	v_permlane16_swap_b32_e32 v68, v70
	global_store_dwordx4 v[86:87], v[72:75], off offset:256
	s_waitcnt lgkmcnt(0)
	v_add_f32_e32 v68, v70, v68
	ds_bpermute_b32 v69, v0, v68
	s_and_saveexec_b64 s[22:23], s[6:7]
	s_cbranch_execz .LBB0_2389
	s_waitcnt lgkmcnt(0)
	v_add_f32_e32 v70, v68, v69
	v_lshlrev_b64 v[68:69], 6, v[84:85]
	v_lshl_add_u64 v[68:69], s[10:11], 0, v[68:69]
	v_lshl_add_u64 v[68:69], s[20:21], 2, v[68:69]
	s_lshl_b32 s92, s45, 2
	v_lshl_add_u64 v[68:69], v[68:69], 0, s[92:93]
	global_store_dword v[68:69], v70, off
.LBB0_2389:
	s_or_b64 exec, exec, s[22:23]
	s_waitcnt lgkmcnt(0)
	v_lshl_add_u64 v[68:69], v[2:3], 0, s[94:95]
	v_lshlrev_b64 v[70:71], 11, v[68:69]
	v_lshl_add_u64 v[70:71], s[0:1], 0, v[70:71]
	v_lshl_add_u64 v[70:71], v[154:155], 1, v[70:71]
	s_nop 0
	s_waitcnt vmcnt(15)
	v_cvt_f32_f16_e32 v76, v210
	v_cvt_f32_f16_sdwa v77, v210 dst_sel:DWORD dst_unused:UNUSED_PAD src0_sel:WORD_1
	v_cvt_f32_f16_e32 v72, v211
	v_cvt_f32_f16_sdwa v73, v211 dst_sel:DWORD dst_unused:UNUSED_PAD src0_sel:WORD_1
	v_pk_add_f32 v[76:77], v[64:65], v[76:77]
	s_nop 0
	v_cvt_pk_f16_f32 v64, v76, v77
	v_pk_add_f32 v[72:73], v[66:67], v[72:73]
	v_cvt_f32_f16_e32 v66, v212
	v_cvt_f32_f16_sdwa v67, v212 dst_sel:DWORD dst_unused:UNUSED_PAD src0_sel:WORD_1
	v_cvt_f32_f16_e32 v74, v213
	v_cvt_f32_f16_sdwa v75, v213 dst_sel:DWORD dst_unused:UNUSED_PAD src0_sel:WORD_1
	v_cvt_pk_f16_f32 v65, v72, v73
	v_pk_add_f32 v[66:67], v[60:61], v[66:67]
	v_pk_add_f32 v[74:75], v[62:63], v[74:75]
	v_pk_mul_f32 v[60:61], v[66:67], v[66:67]
	v_cvt_pk_f16_f32 v66, v66, v67
	v_cvt_pk_f16_f32 v67, v74, v75
	global_store_dwordx4 v[70:71], v[64:67], off
	s_nop 0
	v_pk_mul_f32 v[62:63], v[74:75], v[74:75]
	v_pk_fma_f32 v[60:61], v[76:77], v[76:77], v[60:61]
	v_pk_fma_f32 v[62:63], v[72:73], v[72:73], v[62:63]
	s_waitcnt vmcnt(15)
	v_cvt_f32_f16_e32 v72, v214
	v_cvt_f32_f16_sdwa v73, v214 dst_sel:DWORD dst_unused:UNUSED_PAD src0_sel:WORD_1
	v_cvt_f32_f16_e32 v64, v215
	v_cvt_f32_f16_sdwa v65, v215 dst_sel:DWORD dst_unused:UNUSED_PAD src0_sel:WORD_1
	v_pk_add_f32 v[72:73], v[56:57], v[72:73]
	s_nop 0
	v_cvt_pk_f16_f32 v56, v72, v73
	v_pk_add_f32 v[64:65], v[58:59], v[64:65]
	v_cvt_f32_f16_e32 v58, v216
	v_cvt_f32_f16_sdwa v59, v216 dst_sel:DWORD dst_unused:UNUSED_PAD src0_sel:WORD_1
	v_cvt_pk_f16_f32 v57, v64, v65
	v_pk_add_f32 v[52:53], v[52:53], v[58:59]
	s_nop 0
	v_pk_mul_f32 v[58:59], v[52:53], v[52:53]
	s_nop 0
	v_pk_fma_f32 v[72:73], v[72:73], v[72:73], v[58:59]
	v_cvt_pk_f16_f32 v58, v52, v53
	v_cvt_f32_f16_e32 v52, v217
	v_cvt_f32_f16_sdwa v53, v217 dst_sel:DWORD dst_unused:UNUSED_PAD src0_sel:WORD_1
	v_add_f32_e32 v59, v60, v61
	v_add_f32_e32 v59, v62, v59
	v_add_f32_e32 v59, v63, v59
	v_pk_add_f32 v[52:53], v[54:55], v[52:53]
	v_add_f32_e32 v59, v72, v59
	v_pk_mul_f32 v[54:55], v[52:53], v[52:53]
	v_add_f32_e32 v59, v73, v59
	v_pk_fma_f32 v[54:55], v[64:65], v[64:65], v[54:55]
	s_nop 0
	v_add_f32_e32 v54, v54, v59
	v_add_f32_e32 v54, v55, v54
	v_cvt_pk_f16_f32 v59, v52, v53
	v_mov_b32_e32 v52, v54
	s_nop 1
	v_permlane16_swap_b32_e32 v52, v54
	global_store_dwordx4 v[70:71], v[56:59], off offset:256
	s_waitcnt lgkmcnt(0)
	v_add_f32_e32 v52, v54, v52
	ds_bpermute_b32 v53, v0, v52
	s_and_saveexec_b64 s[22:23], s[6:7]
	s_cbranch_execz .LBB0_2391
	s_waitcnt lgkmcnt(0)
	v_add_f32_e32 v54, v52, v53
	v_lshlrev_b64 v[52:53], 6, v[68:69]
	v_lshl_add_u64 v[52:53], s[10:11], 0, v[52:53]
	v_lshl_add_u64 v[52:53], s[20:21], 2, v[52:53]
	s_lshl_b32 s92, s45, 2
	v_lshl_add_u64 v[52:53], v[52:53], 0, s[92:93]
	global_store_dword v[52:53], v54, off
; __device__ __forceinline__ float xor16(float v) { return __int_as_float(__builtin_amdgcn_ds_swizzle(__float_as_int(v), 0x401F)); }
;   __device__ __forceinline__ void operator()(const f32x4 (&acc)[2][2][4][2], const g8::Unit& u, int ui, int wr, int wc, int fr, int fq) const {
; #pragma unroll
;     for (int ai = 0; ai < 2; ++ai)
; #pragma unroll
;       for (int m = 0; m < 4; ++m) {
;         const size_t row = (size_t)u.pm * 256 + 128 * ai + 64 * wr + 16 * m + fr;
;         const size_t base = row * DM + 256 * u.pn + 32 * wc + 8 * fq;
;         float ss = 0.f;
; #pragma unroll
;         for (int bj = 0; bj < 2; ++bj) {
;           const size_t idx = base + 128 * bj;
;           const h16x8 xv = *(const h16x8*)(xb + idx);
;           f32x4 x0 = acc[ai][bj][m][0], x1 = acc[ai][bj][m][1];
; #pragma unroll
;           for (int j = 0; j < 4; ++j) { x0[j] += (float)xv[j]; x1[j] += (float)xv[4 + j]; ss += x0[j] * x0[j] + x1[j] * x1[j]; }
;           if (final_out) {
;             __builtin_nontemporal_store(x0, (f32x4*)(xo + idx));
;             __builtin_nontemporal_store(x1, (f32x4*)(xo + idx + 4));
;           } else {
;             *(h16x8*)(xb + idx) = pack8(x0, x1);
;           }
;         }
;         ss += xor16(ss);
;         ss += __shfl_xor(ss, 32);
;         if (fq == 0) ssq[row * 16 + u.pn * 4 + wc] = ss;
;       }
.LBB0_2391:
	s_or_b64 exec, exec, s[22:23]
	s_mov_b64 s[2:3], 0x90
	s_waitcnt lgkmcnt(0)
	v_lshl_add_u64 v[52:53], v[2:3], 0, s[2:3]
	v_lshlrev_b64 v[54:55], 11, v[52:53]
	v_lshl_add_u64 v[54:55], s[0:1], 0, v[54:55]
	v_lshl_add_u64 v[54:55], v[154:155], 1, v[54:55]
	s_nop 0
	s_waitcnt vmcnt(15)
	v_cvt_f32_f16_e32 v60, v218
	v_cvt_f32_f16_sdwa v61, v218 dst_sel:DWORD dst_unused:UNUSED_PAD src0_sel:WORD_1
	v_cvt_f32_f16_e32 v56, v219
	v_cvt_f32_f16_sdwa v57, v219 dst_sel:DWORD dst_unused:UNUSED_PAD src0_sel:WORD_1
	v_pk_add_f32 v[60:61], v[48:49], v[60:61]
	s_nop 0
	v_cvt_pk_f16_f32 v48, v60, v61
	v_pk_add_f32 v[56:57], v[50:51], v[56:57]
	v_cvt_f32_f16_e32 v50, v220
	v_cvt_f32_f16_sdwa v51, v220 dst_sel:DWORD dst_unused:UNUSED_PAD src0_sel:WORD_1
	v_cvt_f32_f16_e32 v58, v221
	v_cvt_f32_f16_sdwa v59, v221 dst_sel:DWORD dst_unused:UNUSED_PAD src0_sel:WORD_1
	v_cvt_pk_f16_f32 v49, v56, v57
	v_pk_add_f32 v[50:51], v[44:45], v[50:51]
	v_pk_add_f32 v[58:59], v[46:47], v[58:59]
	v_pk_mul_f32 v[44:45], v[50:51], v[50:51]
	v_cvt_pk_f16_f32 v50, v50, v51
	v_cvt_pk_f16_f32 v51, v58, v59
	global_store_dwordx4 v[54:55], v[48:51], off
	s_nop 0
	v_pk_mul_f32 v[46:47], v[58:59], v[58:59]
	v_pk_fma_f32 v[44:45], v[60:61], v[60:61], v[44:45]
	v_pk_fma_f32 v[46:47], v[56:57], v[56:57], v[46:47]
	s_waitcnt vmcnt(15)
	v_cvt_f32_f16_e32 v56, v222
	v_cvt_f32_f16_sdwa v57, v222 dst_sel:DWORD dst_unused:UNUSED_PAD src0_sel:WORD_1
	v_cvt_f32_f16_e32 v48, v223
	v_cvt_f32_f16_sdwa v49, v223 dst_sel:DWORD dst_unused:UNUSED_PAD src0_sel:WORD_1
	v_pk_add_f32 v[56:57], v[40:41], v[56:57]
	s_nop 0
	v_cvt_pk_f16_f32 v40, v56, v57
	v_pk_add_f32 v[48:49], v[42:43], v[48:49]
	v_cvt_f32_f16_e32 v42, v224
	v_cvt_f32_f16_sdwa v43, v224 dst_sel:DWORD dst_unused:UNUSED_PAD src0_sel:WORD_1
	v_cvt_pk_f16_f32 v41, v48, v49
	v_pk_add_f32 v[36:37], v[36:37], v[42:43]
	s_nop 0
	v_pk_mul_f32 v[42:43], v[36:37], v[36:37]
	s_nop 0
	v_pk_fma_f32 v[56:57], v[56:57], v[56:57], v[42:43]
	v_cvt_pk_f16_f32 v42, v36, v37
	v_cvt_f32_f16_e32 v36, v225
	v_cvt_f32_f16_sdwa v37, v225 dst_sel:DWORD dst_unused:UNUSED_PAD src0_sel:WORD_1
	v_add_f32_e32 v43, v44, v45
	v_add_f32_e32 v43, v46, v43
	v_add_f32_e32 v43, v47, v43
	v_pk_add_f32 v[36:37], v[38:39], v[36:37]
	v_add_f32_e32 v43, v56, v43
	v_pk_mul_f32 v[38:39], v[36:37], v[36:37]
	v_add_f32_e32 v43, v57, v43
	v_pk_fma_f32 v[38:39], v[48:49], v[48:49], v[38:39]
	s_nop 0
	v_add_f32_e32 v38, v38, v43
	v_add_f32_e32 v38, v39, v38
	v_cvt_pk_f16_f32 v43, v36, v37
	v_mov_b32_e32 v36, v38
	s_nop 1
	v_permlane16_swap_b32_e32 v36, v38
	global_store_dwordx4 v[54:55], v[40:43], off offset:256
	s_waitcnt lgkmcnt(0)
	v_add_f32_e32 v36, v38, v36
	ds_bpermute_b32 v37, v0, v36
	s_and_saveexec_b64 s[22:23], s[6:7]
	s_cbranch_execz .LBB0_2393
	s_waitcnt lgkmcnt(0)
	v_add_f32_e32 v38, v36, v37
	v_lshlrev_b64 v[36:37], 6, v[52:53]
	v_lshl_add_u64 v[36:37], s[10:11], 0, v[36:37]
	v_lshl_add_u64 v[36:37], s[20:21], 2, v[36:37]
	s_lshl_b32 s92, s45, 2
	v_lshl_add_u64 v[36:37], v[36:37], 0, s[92:93]
	global_store_dword v[36:37], v38, off
.LBB0_2393:
	s_or_b64 exec, exec, s[22:23]
	s_mov_b64 s[2:3], 0xa0
	s_waitcnt lgkmcnt(0)
	v_lshl_add_u64 v[36:37], v[2:3], 0, s[2:3]
	v_lshlrev_b64 v[38:39], 11, v[36:37]
	v_lshl_add_u64 v[38:39], s[0:1], 0, v[38:39]
	v_lshl_add_u64 v[38:39], v[154:155], 1, v[38:39]
	s_nop 0
	s_waitcnt vmcnt(15)
	v_cvt_f32_f16_e32 v44, v226
	v_cvt_f32_f16_sdwa v45, v226 dst_sel:DWORD dst_unused:UNUSED_PAD src0_sel:WORD_1
	v_cvt_f32_f16_e32 v40, v227
	v_cvt_f32_f16_sdwa v41, v227 dst_sel:DWORD dst_unused:UNUSED_PAD src0_sel:WORD_1
	v_pk_add_f32 v[44:45], v[32:33], v[44:45]
	s_nop 0
	v_cvt_pk_f16_f32 v32, v44, v45
	v_pk_add_f32 v[40:41], v[34:35], v[40:41]
	v_cvt_f32_f16_e32 v34, v228
	v_cvt_f32_f16_sdwa v35, v228 dst_sel:DWORD dst_unused:UNUSED_PAD src0_sel:WORD_1
	v_cvt_f32_f16_e32 v42, v229
	v_cvt_f32_f16_sdwa v43, v229 dst_sel:DWORD dst_unused:UNUSED_PAD src0_sel:WORD_1
	v_cvt_pk_f16_f32 v33, v40, v41
	v_pk_add_f32 v[34:35], v[28:29], v[34:35]
	v_pk_add_f32 v[42:43], v[30:31], v[42:43]
	v_pk_mul_f32 v[28:29], v[34:35], v[34:35]
	v_cvt_pk_f16_f32 v34, v34, v35
	v_cvt_pk_f16_f32 v35, v42, v43
	global_store_dwordx4 v[38:39], v[32:35], off
	s_nop 0
	v_pk_mul_f32 v[30:31], v[42:43], v[42:43]
	v_pk_fma_f32 v[28:29], v[44:45], v[44:45], v[28:29]
	v_pk_fma_f32 v[30:31], v[40:41], v[40:41], v[30:31]
	s_waitcnt vmcnt(15)
	v_cvt_f32_f16_e32 v40, v230
	v_cvt_f32_f16_sdwa v41, v230 dst_sel:DWORD dst_unused:UNUSED_PAD src0_sel:WORD_1
	v_cvt_f32_f16_e32 v32, v231
	v_cvt_f32_f16_sdwa v33, v231 dst_sel:DWORD dst_unused:UNUSED_PAD src0_sel:WORD_1
	v_pk_add_f32 v[40:41], v[24:25], v[40:41]
	s_nop 0
	v_cvt_pk_f16_f32 v24, v40, v41
	v_pk_add_f32 v[32:33], v[26:27], v[32:33]
	v_cvt_f32_f16_e32 v26, v232
	v_cvt_f32_f16_sdwa v27, v232 dst_sel:DWORD dst_unused:UNUSED_PAD src0_sel:WORD_1
	v_cvt_pk_f16_f32 v25, v32, v33
	v_pk_add_f32 v[20:21], v[20:21], v[26:27]
	s_nop 0
	v_pk_mul_f32 v[26:27], v[20:21], v[20:21]
	s_nop 0
	v_pk_fma_f32 v[40:41], v[40:41], v[40:41], v[26:27]
	v_cvt_pk_f16_f32 v26, v20, v21
	v_cvt_f32_f16_e32 v20, v233
	v_cvt_f32_f16_sdwa v21, v233 dst_sel:DWORD dst_unused:UNUSED_PAD src0_sel:WORD_1
	v_add_f32_e32 v27, v28, v29
	v_add_f32_e32 v27, v30, v27
	v_add_f32_e32 v27, v31, v27
	v_pk_add_f32 v[20:21], v[22:23], v[20:21]
	v_add_f32_e32 v27, v40, v27
	v_pk_mul_f32 v[22:23], v[20:21], v[20:21]
	v_add_f32_e32 v27, v41, v27
	v_pk_fma_f32 v[22:23], v[32:33], v[32:33], v[22:23]
	s_nop 0
	v_add_f32_e32 v22, v22, v27
	v_add_f32_e32 v22, v23, v22
	v_cvt_pk_f16_f32 v27, v20, v21
	v_mov_b32_e32 v20, v22
	s_nop 1
	v_permlane16_swap_b32_e32 v20, v22
	global_store_dwordx4 v[38:39], v[24:27], off offset:256
	s_waitcnt lgkmcnt(0)
	v_add_f32_e32 v20, v22, v20
	ds_bpermute_b32 v21, v0, v20
	s_and_saveexec_b64 s[22:23], s[6:7]
	s_cbranch_execz .LBB0_2395
	s_waitcnt lgkmcnt(0)
	v_add_f32_e32 v22, v20, v21
	v_lshlrev_b64 v[20:21], 6, v[36:37]
	v_lshl_add_u64 v[20:21], s[10:11], 0, v[20:21]
	v_lshl_add_u64 v[20:21], s[20:21], 2, v[20:21]
	s_lshl_b32 s92, s45, 2
	v_lshl_add_u64 v[20:21], v[20:21], 0, s[92:93]
	global_store_dword v[20:21], v22, off

; __device__ __forceinline__ float xor16(float v) { return __int_as_float(__builtin_amdgcn_ds_swizzle(__float_as_int(v), 0x401F)); }
;   __device__ __forceinline__ void operator()(const f32x4 (&acc)[2][2][4][2], const g8::Unit& u, int ui, int wr, int wc, int fr, int fq) const {
;     ...
;           for (int j = 0; j < 4; ++j) { x0[j] += (float)xv[j]; x1[j] += (float)xv[4 + j]; ss += x0[j] * x0[j] + x1[j] * x1[j]; }
;           if (final_out) {
;             __builtin_nontemporal_store(x0, (f32x4*)(xo + idx));
;             __builtin_nontemporal_store(x1, (f32x4*)(xo + idx + 4));
;           } else {
;             *(h16x8*)(xb + idx) = pack8(x0, x1);
;           }
;         }
;         ss += xor16(ss);
;         ss += __shfl_xor(ss, 32);
;         if (fq == 0) ssq[row * 16 + u.pn * 4 + wc] = ss;
.LBB0_2551:
	v_pk_mul_f32 v[122:123], v[122:123], v[122:123]
	v_pk_mul_f32 v[124:125], v[124:125], v[124:125]
	v_pk_fma_f32 v[122:123], v[126:127], v[126:127], v[122:123]
	v_pk_mul_f32 v[114:115], v[114:115], v[114:115]
	v_pk_fma_f32 v[124:125], v[128:129], v[128:129], v[124:125]
	v_pk_fma_f32 v[114:115], v[118:119], v[118:119], v[114:115]
	v_add_f32_e32 v118, v122, v123
	v_add_f32_e32 v118, v124, v118
	v_add_f32_e32 v118, v125, v118
	v_pk_mul_f32 v[116:117], v[116:117], v[116:117]
	v_add_f32_e32 v114, v118, v114
	v_pk_fma_f32 v[116:117], v[120:121], v[120:121], v[116:117]
	v_add_f32_e32 v114, v115, v114
	v_add_f32_e32 v114, v116, v114
	v_add_f32_e32 v114, v117, v114
	v_mov_b32_e32 v117, v114
	s_nop 1
	v_permlane16_swap_b32_e32 v117, v114
	v_and_b32_e32 v116, 64, v199
	v_xor_b32_e32 v115, 32, v199
	v_add_u32_e32 v116, 64, v116
	v_cmp_lt_i32_e32 vcc, v115, v116
	s_waitcnt lgkmcnt(0)
	v_add_f32_e32 v114, v114, v117
	s_lshl_b32 s22, s2, 2
	v_cndmask_b32_e32 v115, v199, v115, vcc
	v_lshlrev_b32_e32 v120, 2, v115
	ds_bpermute_b32 v115, v120, v114
	s_ashr_i32 s23, s22, 31
	s_and_saveexec_b64 s[24:25], s[4:5]
	s_cbranch_execz .LBB0_2553
	s_waitcnt lgkmcnt(0)
	v_add_f32_e32 v116, v114, v115
	v_lshlrev_b64 v[114:115], 6, v[140:141]
	v_lshl_add_u64 v[114:115], s[12:13], 0, v[114:115]
	v_lshl_add_u64 v[114:115], s[22:23], 2, v[114:115]
	s_lshl_b32 s92, s43, 2
	v_lshl_add_u64 v[114:115], v[114:115], 0, s[92:93]
	global_store_dword v[114:115], v116, off

; __device__ __forceinline__ float xor16(float v) { return __int_as_float(__builtin_amdgcn_ds_swizzle(__float_as_int(v), 0x401F)); }
;   __device__ __forceinline__ void operator()(const f32x4 (&acc)[2][2][4][2], const g8::Unit& u, int ui, int wr, int wc, int fr, int fq) const {
;     ...
;           for (int j = 0; j < 4; ++j) { x0[j] += (float)xv[j]; x1[j] += (float)xv[4 + j]; ss += x0[j] * x0[j] + x1[j] * x1[j]; }
;           if (final_out) {
;             __builtin_nontemporal_store(x0, (f32x4*)(xo + idx));
;             __builtin_nontemporal_store(x1, (f32x4*)(xo + idx + 4));
;           } else {
;             *(h16x8*)(xb + idx) = pack8(x0, x1);
;           }
;         }
;         ss += xor16(ss);
;         ss += __shfl_xor(ss, 32);
;         if (fq == 0) ssq[row * 16 + u.pn * 4 + wc] = ss;
.LBB0_2561:
	v_pk_mul_f32 v[106:107], v[106:107], v[106:107]
	v_pk_mul_f32 v[108:109], v[108:109], v[108:109]
	v_pk_fma_f32 v[106:107], v[110:111], v[110:111], v[106:107]
	v_pk_mul_f32 v[98:99], v[98:99], v[98:99]
	v_pk_fma_f32 v[108:109], v[112:113], v[112:113], v[108:109]
	v_pk_fma_f32 v[98:99], v[102:103], v[102:103], v[98:99]
	v_add_f32_e32 v102, v106, v107
	v_add_f32_e32 v102, v108, v102
	v_add_f32_e32 v102, v109, v102
	v_pk_mul_f32 v[100:101], v[100:101], v[100:101]
	v_add_f32_e32 v98, v102, v98
	v_pk_fma_f32 v[100:101], v[104:105], v[104:105], v[100:101]
	v_add_f32_e32 v98, v99, v98
	v_add_f32_e32 v98, v100, v98
	v_add_f32_e32 v98, v101, v98
	v_mov_b32_e32 v99, v98
	s_nop 1
	v_permlane16_swap_b32_e32 v99, v98
	s_waitcnt lgkmcnt(0)
	v_add_f32_e32 v98, v98, v99
	ds_bpermute_b32 v99, v120, v98
	s_and_saveexec_b64 s[24:25], s[4:5]
	s_cbranch_execz .LBB0_2563
	s_waitcnt lgkmcnt(0)
	v_add_f32_e32 v100, v98, v99
	v_lshlrev_b64 v[98:99], 6, v[114:115]
	v_lshl_add_u64 v[98:99], s[12:13], 0, v[98:99]
	v_lshl_add_u64 v[98:99], s[22:23], 2, v[98:99]
	s_lshl_b32 s92, s43, 2
	v_lshl_add_u64 v[98:99], v[98:99], 0, s[92:93]
	global_store_dword v[98:99], v100, off

; __device__ __forceinline__ float xor16(float v) { return __int_as_float(__builtin_amdgcn_ds_swizzle(__float_as_int(v), 0x401F)); }
;   __device__ __forceinline__ void operator()(const f32x4 (&acc)[2][2][4][2], const g8::Unit& u, int ui, int wr, int wc, int fr, int fq) const {
;     ...
;           for (int j = 0; j < 4; ++j) { x0[j] += (float)xv[j]; x1[j] += (float)xv[4 + j]; ss += x0[j] * x0[j] + x1[j] * x1[j]; }
;           if (final_out) {
;             __builtin_nontemporal_store(x0, (f32x4*)(xo + idx));
;             __builtin_nontemporal_store(x1, (f32x4*)(xo + idx + 4));
;           } else {
;             *(h16x8*)(xb + idx) = pack8(x0, x1);
;           }
;         }
;         ss += xor16(ss);
;         ss += __shfl_xor(ss, 32);
;         if (fq == 0) ssq[row * 16 + u.pn * 4 + wc] = ss;
.LBB0_2571:
	v_pk_mul_f32 v[90:91], v[90:91], v[90:91]
	v_pk_mul_f32 v[92:93], v[92:93], v[92:93]
	v_pk_fma_f32 v[90:91], v[94:95], v[94:95], v[90:91]
	v_pk_mul_f32 v[82:83], v[82:83], v[82:83]
	v_pk_fma_f32 v[92:93], v[96:97], v[96:97], v[92:93]
	v_pk_fma_f32 v[82:83], v[86:87], v[86:87], v[82:83]
	v_add_f32_e32 v86, v90, v91
	v_add_f32_e32 v86, v92, v86
	v_add_f32_e32 v86, v93, v86
	v_pk_mul_f32 v[84:85], v[84:85], v[84:85]
	v_add_f32_e32 v82, v86, v82
	v_pk_fma_f32 v[84:85], v[88:89], v[88:89], v[84:85]
	v_add_f32_e32 v82, v83, v82
	v_add_f32_e32 v82, v84, v82
	v_add_f32_e32 v82, v85, v82
	v_mov_b32_e32 v83, v82
	s_nop 1
	v_permlane16_swap_b32_e32 v83, v82
	s_waitcnt lgkmcnt(0)
	v_add_f32_e32 v82, v82, v83
	ds_bpermute_b32 v83, v120, v82
	s_and_saveexec_b64 s[24:25], s[4:5]
	s_cbranch_execz .LBB0_2573
	s_waitcnt lgkmcnt(0)
	v_add_f32_e32 v84, v82, v83
	v_lshlrev_b64 v[82:83], 6, v[98:99]
	v_lshl_add_u64 v[82:83], s[12:13], 0, v[82:83]
	v_lshl_add_u64 v[82:83], s[22:23], 2, v[82:83]
	s_lshl_b32 s92, s43, 2
	v_lshl_add_u64 v[82:83], v[82:83], 0, s[92:93]
	global_store_dword v[82:83], v84, off

; __device__ __forceinline__ float xor16(float v) { return __int_as_float(__builtin_amdgcn_ds_swizzle(__float_as_int(v), 0x401F)); }
;   __device__ __forceinline__ void operator()(const f32x4 (&acc)[2][2][4][2], const g8::Unit& u, int ui, int wr, int wc, int fr, int fq) const {
;     ...
;           for (int j = 0; j < 4; ++j) { x0[j] += (float)xv[j]; x1[j] += (float)xv[4 + j]; ss += x0[j] * x0[j] + x1[j] * x1[j]; }
;           if (final_out) {
;             __builtin_nontemporal_store(x0, (f32x4*)(xo + idx));
;             __builtin_nontemporal_store(x1, (f32x4*)(xo + idx + 4));
;           } else {
;             *(h16x8*)(xb + idx) = pack8(x0, x1);
;           }
;         }
;         ss += xor16(ss);
;         ss += __shfl_xor(ss, 32);
;         if (fq == 0) ssq[row * 16 + u.pn * 4 + wc] = ss;
.LBB0_2581:
	v_pk_mul_f32 v[74:75], v[74:75], v[74:75]
	v_pk_mul_f32 v[76:77], v[76:77], v[76:77]
	v_pk_fma_f32 v[74:75], v[78:79], v[78:79], v[74:75]
	v_pk_mul_f32 v[66:67], v[66:67], v[66:67]
	v_pk_fma_f32 v[76:77], v[80:81], v[80:81], v[76:77]
	v_pk_fma_f32 v[66:67], v[70:71], v[70:71], v[66:67]
	v_add_f32_e32 v70, v74, v75
	v_add_f32_e32 v70, v76, v70
	v_add_f32_e32 v70, v77, v70
	v_pk_mul_f32 v[68:69], v[68:69], v[68:69]
	v_add_f32_e32 v66, v70, v66
	v_pk_fma_f32 v[68:69], v[72:73], v[72:73], v[68:69]
	v_add_f32_e32 v66, v67, v66
	v_add_f32_e32 v66, v68, v66
	v_add_f32_e32 v66, v69, v66
	v_mov_b32_e32 v67, v66
	s_nop 1
	v_permlane16_swap_b32_e32 v67, v66
	s_waitcnt lgkmcnt(0)
	v_add_f32_e32 v66, v66, v67
	ds_bpermute_b32 v67, v120, v66
	s_and_saveexec_b64 s[24:25], s[4:5]
	s_cbranch_execz .LBB0_2583
	s_waitcnt lgkmcnt(0)
	v_add_f32_e32 v68, v66, v67
	v_lshlrev_b64 v[66:67], 6, v[82:83]
	v_lshl_add_u64 v[66:67], s[12:13], 0, v[66:67]
	v_lshl_add_u64 v[66:67], s[22:23], 2, v[66:67]
	s_lshl_b32 s92, s43, 2
	v_lshl_add_u64 v[66:67], v[66:67], 0, s[92:93]
	global_store_dword v[66:67], v68, off

; __device__ __forceinline__ float xor16(float v) { return __int_as_float(__builtin_amdgcn_ds_swizzle(__float_as_int(v), 0x401F)); }
;   __device__ __forceinline__ void operator()(const f32x4 (&acc)[2][2][4][2], const g8::Unit& u, int ui, int wr, int wc, int fr, int fq) const {
;     ...
;           for (int j = 0; j < 4; ++j) { x0[j] += (float)xv[j]; x1[j] += (float)xv[4 + j]; ss += x0[j] * x0[j] + x1[j] * x1[j]; }
;           if (final_out) {
;             __builtin_nontemporal_store(x0, (f32x4*)(xo + idx));
;             __builtin_nontemporal_store(x1, (f32x4*)(xo + idx + 4));
;           } else {
;             *(h16x8*)(xb + idx) = pack8(x0, x1);
;           }
;         }
;         ss += xor16(ss);
;         ss += __shfl_xor(ss, 32);
;         if (fq == 0) ssq[row * 16 + u.pn * 4 + wc] = ss;
.LBB0_2591:
	v_pk_mul_f32 v[58:59], v[58:59], v[58:59]
	v_pk_mul_f32 v[60:61], v[60:61], v[60:61]
	v_pk_fma_f32 v[58:59], v[62:63], v[62:63], v[58:59]
	v_pk_mul_f32 v[50:51], v[50:51], v[50:51]
	v_pk_fma_f32 v[60:61], v[64:65], v[64:65], v[60:61]
	v_pk_fma_f32 v[50:51], v[54:55], v[54:55], v[50:51]
	v_add_f32_e32 v54, v58, v59
	v_add_f32_e32 v54, v60, v54
	v_add_f32_e32 v54, v61, v54
	v_pk_mul_f32 v[52:53], v[52:53], v[52:53]
	v_add_f32_e32 v50, v54, v50
	v_pk_fma_f32 v[52:53], v[56:57], v[56:57], v[52:53]
	v_add_f32_e32 v50, v51, v50
	v_add_f32_e32 v50, v52, v50
	v_add_f32_e32 v50, v53, v50
	v_mov_b32_e32 v51, v50
	s_nop 1
	v_permlane16_swap_b32_e32 v51, v50
	s_waitcnt lgkmcnt(0)
	v_add_f32_e32 v50, v50, v51
	ds_bpermute_b32 v51, v120, v50
	s_and_saveexec_b64 s[24:25], s[4:5]
	s_cbranch_execz .LBB0_2593
	s_waitcnt lgkmcnt(0)
	v_add_f32_e32 v52, v50, v51
	v_lshlrev_b64 v[50:51], 6, v[66:67]
	v_lshl_add_u64 v[50:51], s[12:13], 0, v[50:51]
	v_lshl_add_u64 v[50:51], s[22:23], 2, v[50:51]
	s_lshl_b32 s92, s43, 2
	v_lshl_add_u64 v[50:51], v[50:51], 0, s[92:93]
	global_store_dword v[50:51], v52, off

; __device__ __forceinline__ float xor16(float v) { return __int_as_float(__builtin_amdgcn_ds_swizzle(__float_as_int(v), 0x401F)); }
;   __device__ __forceinline__ void operator()(const f32x4 (&acc)[2][2][4][2], const g8::Unit& u, int ui, int wr, int wc, int fr, int fq) const {
;     ...
;           for (int j = 0; j < 4; ++j) { x0[j] += (float)xv[j]; x1[j] += (float)xv[4 + j]; ss += x0[j] * x0[j] + x1[j] * x1[j]; }
;           if (final_out) {
;             __builtin_nontemporal_store(x0, (f32x4*)(xo + idx));
;             __builtin_nontemporal_store(x1, (f32x4*)(xo + idx + 4));
;           } else {
;             *(h16x8*)(xb + idx) = pack8(x0, x1);
;           }
;         }
;         ss += xor16(ss);
;         ss += __shfl_xor(ss, 32);
;         if (fq == 0) ssq[row * 16 + u.pn * 4 + wc] = ss;
.LBB0_2601:
	v_pk_mul_f32 v[42:43], v[42:43], v[42:43]
	v_pk_mul_f32 v[44:45], v[44:45], v[44:45]
	v_pk_fma_f32 v[42:43], v[46:47], v[46:47], v[42:43]
	v_pk_mul_f32 v[34:35], v[34:35], v[34:35]
	v_pk_fma_f32 v[44:45], v[48:49], v[48:49], v[44:45]
	v_pk_fma_f32 v[34:35], v[38:39], v[38:39], v[34:35]
	v_add_f32_e32 v38, v42, v43
	v_add_f32_e32 v38, v44, v38
	v_add_f32_e32 v38, v45, v38
	v_pk_mul_f32 v[36:37], v[36:37], v[36:37]
	v_add_f32_e32 v34, v38, v34
	v_pk_fma_f32 v[36:37], v[40:41], v[40:41], v[36:37]
	v_add_f32_e32 v34, v35, v34
	v_add_f32_e32 v34, v36, v34
	v_add_f32_e32 v34, v37, v34
	v_mov_b32_e32 v35, v34
	s_nop 1
	v_permlane16_swap_b32_e32 v35, v34
	s_waitcnt lgkmcnt(0)
	v_add_f32_e32 v34, v34, v35
	ds_bpermute_b32 v35, v120, v34
	s_and_saveexec_b64 s[24:25], s[4:5]
	s_cbranch_execz .LBB0_2603
	s_waitcnt lgkmcnt(0)
	v_add_f32_e32 v36, v34, v35
	v_lshlrev_b64 v[34:35], 6, v[50:51]
	v_lshl_add_u64 v[34:35], s[12:13], 0, v[34:35]
	v_lshl_add_u64 v[34:35], s[22:23], 2, v[34:35]
	s_lshl_b32 s92, s43, 2
	v_lshl_add_u64 v[34:35], v[34:35], 0, s[92:93]
	global_store_dword v[34:35], v36, off

; __device__ __forceinline__ float xor16(float v) { return __int_as_float(__builtin_amdgcn_ds_swizzle(__float_as_int(v), 0x401F)); }
;   __device__ __forceinline__ void operator()(const f32x4 (&acc)[2][2][4][2], const g8::Unit& u, int ui, int wr, int wc, int fr, int fq) const {
;     ...
;           for (int j = 0; j < 4; ++j) { x0[j] += (float)xv[j]; x1[j] += (float)xv[4 + j]; ss += x0[j] * x0[j] + x1[j] * x1[j]; }
;           if (final_out) {
;             __builtin_nontemporal_store(x0, (f32x4*)(xo + idx));
;             __builtin_nontemporal_store(x1, (f32x4*)(xo + idx + 4));
;           } else {
;             *(h16x8*)(xb + idx) = pack8(x0, x1);
;           }
;         }
;         ss += xor16(ss);
;         ss += __shfl_xor(ss, 32);
;         if (fq == 0) ssq[row * 16 + u.pn * 4 + wc] = ss;
.LBB0_2611:
	v_pk_mul_f32 v[26:27], v[26:27], v[26:27]
	v_pk_mul_f32 v[28:29], v[28:29], v[28:29]
	v_pk_fma_f32 v[26:27], v[30:31], v[30:31], v[26:27]
	v_pk_mul_f32 v[18:19], v[18:19], v[18:19]
	v_pk_fma_f32 v[28:29], v[32:33], v[32:33], v[28:29]
	v_pk_fma_f32 v[18:19], v[22:23], v[22:23], v[18:19]
	v_add_f32_e32 v22, v26, v27
	v_add_f32_e32 v22, v28, v22
	v_add_f32_e32 v22, v29, v22
	v_pk_mul_f32 v[20:21], v[20:21], v[20:21]
	v_add_f32_e32 v18, v22, v18
	v_pk_fma_f32 v[20:21], v[24:25], v[24:25], v[20:21]
	v_add_f32_e32 v18, v19, v18
	v_add_f32_e32 v18, v20, v18
	v_add_f32_e32 v18, v21, v18
	v_mov_b32_e32 v19, v18
	s_nop 1
	v_permlane16_swap_b32_e32 v19, v18
	s_waitcnt lgkmcnt(0)
	v_add_f32_e32 v18, v18, v19
	ds_bpermute_b32 v19, v120, v18
	s_and_saveexec_b64 s[24:25], s[4:5]
	s_cbranch_execz .LBB0_2613
	s_waitcnt lgkmcnt(0)
	v_add_f32_e32 v20, v18, v19
	v_lshlrev_b64 v[18:19], 6, v[34:35]
	v_lshl_add_u64 v[18:19], s[12:13], 0, v[18:19]
	v_lshl_add_u64 v[18:19], s[22:23], 2, v[18:19]
	s_lshl_b32 s92, s43, 2
	v_lshl_add_u64 v[18:19], v[18:19], 0, s[92:93]
	global_store_dword v[18:19], v20, off

; __device__ __forceinline__ float xor16(float v) { return __int_as_float(__builtin_amdgcn_ds_swizzle(__float_as_int(v), 0x401F)); }
;   __device__ __forceinline__ void operator()(const f32x4 (&acc)[2][2][4][2], const g8::Unit& u, int ui, int wr, int wc, int fr, int fq) const {
;     ...
;           for (int j = 0; j < 4; ++j) { x0[j] += (float)xv[j]; x1[j] += (float)xv[4 + j]; ss += x0[j] * x0[j] + x1[j] * x1[j]; }
;           if (final_out) {
;             __builtin_nontemporal_store(x0, (f32x4*)(xo + idx));
;             __builtin_nontemporal_store(x1, (f32x4*)(xo + idx + 4));
;           } else {
;             *(h16x8*)(xb + idx) = pack8(x0, x1);
;           }
;         }
;         ss += xor16(ss);
;         ss += __shfl_xor(ss, 32);
;         if (fq == 0) ssq[row * 16 + u.pn * 4 + wc] = ss;
.LBB0_2621:
	v_pk_mul_f32 v[10:11], v[10:11], v[10:11]
	v_pk_mul_f32 v[12:13], v[12:13], v[12:13]
	v_pk_fma_f32 v[10:11], v[14:15], v[14:15], v[10:11]
	v_pk_mul_f32 v[2:3], v[2:3], v[2:3]
	v_pk_fma_f32 v[12:13], v[16:17], v[16:17], v[12:13]
	v_pk_fma_f32 v[2:3], v[6:7], v[6:7], v[2:3]
	v_add_f32_e32 v6, v10, v11
	v_add_f32_e32 v6, v12, v6
	v_add_f32_e32 v6, v13, v6
	v_pk_mul_f32 v[4:5], v[4:5], v[4:5]
	v_add_f32_e32 v2, v6, v2
	v_pk_fma_f32 v[4:5], v[8:9], v[8:9], v[4:5]
	v_add_f32_e32 v2, v3, v2
	v_add_f32_e32 v2, v4, v2
	v_add_f32_e32 v2, v5, v2
	v_mov_b32_e32 v3, v2
	s_nop 1
	v_permlane16_swap_b32_e32 v3, v2
	s_waitcnt lgkmcnt(0)
	v_add_f32_e32 v2, v2, v3
	ds_bpermute_b32 v3, v120, v2
	s_and_saveexec_b64 s[8:9], s[4:5]
	s_cbranch_execz .LBB0_2534
	s_waitcnt lgkmcnt(0)
	v_add_f32_e32 v4, v2, v3
	v_lshlrev_b64 v[2:3], 6, v[18:19]
	v_lshl_add_u64 v[2:3], s[12:13], 0, v[2:3]
	v_lshl_add_u64 v[2:3], s[22:23], 2, v[2:3]
	s_lshl_b32 s92, s43, 2
	v_lshl_add_u64 v[2:3], v[2:3], 0, s[92:93]
	global_store_dword v[2:3], v4, off
	s_branch .LBB0_2534
